# speedup vs baseline: 1.0500x; 1.0340x over previous
; #define LAS __attribute__((address_space(3)))
; __device__ __forceinline__ unsigned pk2(float lo, float hi) { return f2bf(lo) | (f2bf(hi) << 16); }
; template <bool MAPPED>
; __device__ __forceinline__ void transpose_item(const float* W, int K, int Nsrc, bf16_t* WT, const float* gk, LAS float* scr, int item, int nblk, int lane) {
;     const int kb = item / nblk, nb = item % nblk, k0 = 64 * kb, j0 = 32 * nb;
;     const int sc = MAPPED ? in_map(j0 + (lane & 31)) : (j0 + (lane & 31));
; #pragma unroll 8
;     for (int i = 0; i < 32; ++i) { const int kk = 2 * i + (lane >> 5); float v = (sc >= 0) ? W[(size_t)(k0 + kk) * Nsrc + sc] : 0.f; if (gk) v *= gk[k0 + kk]; scr[kk * 33 + (lane & 31)] = v; }
;     asm volatile("s_waitcnt lgkmcnt(0)" ::: "memory");
;     const int c = lane & 7;
; #pragma unroll
;     for (int j = 0; j < 4; ++j) { const int n = (lane >> 3) + 8 * j; const LAS float* s = scr + (8 * c) * 33 + n;
;         u32x4 o; o.x = pk2(s[0 * 33], s[1 * 33]); o.y = pk2(s[2 * 33], s[3 * 33]); o.z = pk2(s[4 * 33], s[5 * 33]); o.w = pk2(s[6 * 33], s[7 * 33]);
;         *(u32x4*)(WT + (size_t)(j0 + n) * K + k0 + 8 * c) = o; }
;     asm volatile("s_waitcnt lgkmcnt(0)" ::: "memory");
; }
.LBB0_39:
	v_lshl_add_u64 v[48:49], v[46:47], 0, s[0:1]
	global_load_dword v90, v[48:49], off
	v_lshl_add_u64 v[48:49], v[44:45], 0, s[0:1]
	global_load_dword v91, v[48:49], off
	v_lshl_add_u64 v[48:49], v[42:43], 0, s[0:1]
	global_load_dword v92, v[48:49], off
	v_lshl_add_u64 v[48:49], v[40:41], 0, s[0:1]
	global_load_dword v93, v[48:49], off
	v_lshl_add_u64 v[48:49], v[38:39], 0, s[0:1]
	global_load_dword v94, v[48:49], off
	v_lshl_add_u64 v[48:49], v[36:37], 0, s[0:1]
	global_load_dword v95, v[48:49], off
	v_lshl_add_u64 v[48:49], v[34:35], 0, s[0:1]
	global_load_dword v96, v[48:49], off
	v_lshl_add_u64 v[48:49], v[32:33], 0, s[0:1]
	s_add_u32 s0, s0, 0x10000
	s_addc_u32 s1, s1, 0
	s_cmp_lg_u32 s0, 0x40000
	global_load_dword v97, v[48:49], off
	s_waitcnt vmcnt(7)
	ds_write_b32 v18, v90
	s_waitcnt vmcnt(6)
	ds_write_b32 v18, v91 offset:264
	s_waitcnt vmcnt(5)
	ds_write_b32 v18, v92 offset:528
	s_waitcnt vmcnt(4)
	ds_write_b32 v18, v93 offset:792
	s_waitcnt vmcnt(3)
	ds_write_b32 v18, v94 offset:1056
	s_waitcnt vmcnt(2)
	ds_write_b32 v18, v95 offset:1320
	s_waitcnt vmcnt(1)
	ds_write_b32 v18, v96 offset:1584
	s_waitcnt vmcnt(0)
	ds_write_b32 v18, v97 offset:1848
	v_add_u32_e32 v18, 0x840, v18
	s_cbranch_scc1 .LBB0_39
	s_waitcnt lgkmcnt(0)
	ds_read_b32 v18, v57
	ds_read_b32 v32, v57 offset:132
	ds_read_b32 v33, v57 offset:264
	ds_read_b32 v34, v57 offset:396
	ds_read_b32 v35, v57 offset:528
	ds_read_b32 v38, v57 offset:660
	ds_read_b32 v39, v57 offset:792
	ds_read_b32 v40, v57 offset:924
	s_waitcnt lgkmcnt(7)
	v_bfe_u32 v41, v18, 16, 1
	v_add3_u32 v18, v18, v41, s30
	s_waitcnt lgkmcnt(6)
	v_bfe_u32 v41, v32, 16, 1
	v_lshrrev_b32_e32 v18, 16, v18
	v_add3_u32 v32, v32, v41, s30
	v_and_or_b32 v32, v32, s31, v18
	s_waitcnt lgkmcnt(5)
	v_bfe_u32 v18, v33, 16, 1
	v_add3_u32 v18, v33, v18, s30
	s_waitcnt lgkmcnt(4)
	v_bfe_u32 v33, v34, 16, 1
	v_lshrrev_b32_e32 v18, 16, v18
	v_add3_u32 v33, v34, v33, s30
	v_and_or_b32 v33, v33, s31, v18
	s_waitcnt lgkmcnt(3)
	v_bfe_u32 v18, v35, 16, 1
	v_add3_u32 v18, v35, v18, s30
	s_waitcnt lgkmcnt(2)
	v_bfe_u32 v34, v38, 16, 1
	s_lshl_b32 s0, s14, 1
	v_lshrrev_b32_e32 v18, 16, v18
	v_add3_u32 v34, v38, v34, s30
	s_and_b32 s0, s0, 0x7fffffc0
	v_and_or_b32 v34, v34, s31, v18
	s_waitcnt lgkmcnt(1)
	v_bfe_u32 v18, v39, 16, 1
	s_add_i32 s16, s0, 0xffffa900
	s_lshl_b32 s0, s14, 5
	v_add3_u32 v18, v39, v18, s30
	s_waitcnt lgkmcnt(0)
	v_bfe_u32 v35, v40, 16, 1
	s_and_b32 s0, s0, 0x3e0
	v_lshrrev_b32_e32 v18, 16, v18
	v_add3_u32 v35, v40, v35, s30
	v_and_or_b32 v35, v35, s31, v18
	v_or_b32_e32 v18, s0, v17
	v_lshl_add_u64 v[36:37], s[16:17], 1, v[20:21]
	v_mul_u32_u24_e32 v18, 0x1600, v18
	v_lshl_add_u64 v[38:39], v[36:37], 0, v[18:19]
	flat_store_dwordx4 v[38:39], v[32:35]
	ds_read_b32 v18, v57 offset:32
	ds_read_b32 v32, v57 offset:164
	ds_read_b32 v33, v57 offset:296
	ds_read_b32 v34, v57 offset:428
	ds_read_b32 v35, v57 offset:560
	ds_read_b32 v38, v57 offset:692
	ds_read_b32 v39, v57 offset:824
	ds_read_b32 v40, v57 offset:956
	s_waitcnt lgkmcnt(0)
	v_bfe_u32 v41, v18, 16, 1
	v_add3_u32 v18, v18, v41, s30
	v_bfe_u32 v41, v32, 16, 1
	v_lshrrev_b32_e32 v18, 16, v18
	v_add3_u32 v32, v32, v41, s30
	v_and_or_b32 v32, v32, s31, v18
	v_bfe_u32 v18, v33, 16, 1
	v_add3_u32 v18, v33, v18, s30
	v_bfe_u32 v33, v34, 16, 1
	v_lshrrev_b32_e32 v18, 16, v18
	v_add3_u32 v33, v34, v33, s30
	v_and_or_b32 v33, v33, s31, v18
	v_bfe_u32 v18, v35, 16, 1
	v_add3_u32 v18, v35, v18, s30
	v_bfe_u32 v34, v38, 16, 1
	v_lshrrev_b32_e32 v18, 16, v18
	v_add3_u32 v34, v38, v34, s30
	v_and_or_b32 v34, v34, s31, v18
	v_bfe_u32 v18, v39, 16, 1
	v_add3_u32 v18, v39, v18, s30
	v_bfe_u32 v35, v40, 16, 1
	v_lshrrev_b32_e32 v18, 16, v18
	v_add3_u32 v35, v40, v35, s30
	v_and_or_b32 v35, v35, s31, v18
	v_or_b32_e32 v18, s0, v58
	v_mul_u32_u24_e32 v18, 0x1600, v18
	v_lshl_add_u64 v[38:39], v[36:37], 0, v[18:19]
	flat_store_dwordx4 v[38:39], v[32:35]
	ds_read_b32 v18, v57 offset:64
	ds_read_b32 v32, v57 offset:196
	ds_read_b32 v33, v57 offset:328
	ds_read_b32 v34, v57 offset:460
	ds_read_b32 v35, v57 offset:592
	ds_read_b32 v38, v57 offset:724
	ds_read_b32 v39, v57 offset:856
	ds_read_b32 v40, v57 offset:988
	s_waitcnt lgkmcnt(0)
	v_bfe_u32 v41, v18, 16, 1
	v_add3_u32 v18, v18, v41, s30
	v_bfe_u32 v41, v32, 16, 1
	v_lshrrev_b32_e32 v18, 16, v18
	v_add3_u32 v32, v32, v41, s30
	v_and_or_b32 v32, v32, s31, v18
	v_bfe_u32 v18, v33, 16, 1
	v_add3_u32 v18, v33, v18, s30
	v_bfe_u32 v33, v34, 16, 1
	v_lshrrev_b32_e32 v18, 16, v18
	v_add3_u32 v33, v34, v33, s30
	v_and_or_b32 v33, v33, s31, v18
	v_bfe_u32 v18, v35, 16, 1
	v_add3_u32 v18, v35, v18, s30
	v_bfe_u32 v34, v38, 16, 1
	v_lshrrev_b32_e32 v18, 16, v18
	v_add3_u32 v34, v38, v34, s30
	v_and_or_b32 v34, v34, s31, v18
	v_bfe_u32 v18, v39, 16, 1
	v_add3_u32 v18, v39, v18, s30
	v_bfe_u32 v35, v40, 16, 1
	v_lshrrev_b32_e32 v18, 16, v18
	v_add3_u32 v35, v40, v35, s30
	v_and_or_b32 v35, v35, s31, v18
	v_or_b32_e32 v18, s0, v59
	v_mul_u32_u24_e32 v18, 0x1600, v18
	v_lshl_add_u64 v[38:39], v[36:37], 0, v[18:19]
	flat_store_dwordx4 v[38:39], v[32:35]
	ds_read_b32 v18, v57 offset:96
	ds_read_b32 v32, v57 offset:228
	ds_read_b32 v33, v57 offset:360
	ds_read_b32 v34, v57 offset:492
	ds_read_b32 v35, v57 offset:624
	ds_read_b32 v38, v57 offset:756
	ds_read_b32 v39, v57 offset:888
	ds_read_b32 v40, v57 offset:1020
	s_waitcnt lgkmcnt(0)
	v_bfe_u32 v41, v18, 16, 1
	v_add3_u32 v18, v18, v41, s30
	v_bfe_u32 v41, v32, 16, 1
	v_lshrrev_b32_e32 v18, 16, v18
	v_add3_u32 v32, v32, v41, s30
	v_and_or_b32 v32, v32, s31, v18
	v_bfe_u32 v18, v33, 16, 1
	v_add3_u32 v18, v33, v18, s30
	v_bfe_u32 v33, v34, 16, 1
	v_lshrrev_b32_e32 v18, 16, v18
	v_add3_u32 v33, v34, v33, s30
	v_and_or_b32 v33, v33, s31, v18
	v_bfe_u32 v18, v35, 16, 1
	v_add3_u32 v18, v35, v18, s30
	v_bfe_u32 v34, v38, 16, 1
	v_lshrrev_b32_e32 v18, 16, v18
	v_add3_u32 v34, v38, v34, s30
	v_and_or_b32 v34, v34, s31, v18
	v_bfe_u32 v18, v39, 16, 1
	v_add3_u32 v18, v39, v18, s30
	v_bfe_u32 v35, v40, 16, 1
	v_lshrrev_b32_e32 v18, 16, v18
	v_add3_u32 v35, v40, v35, s30
	v_and_or_b32 v35, v35, s31, v18
	v_or_b32_e32 v18, s0, v60
	v_mul_u32_u24_e32 v18, 0x1600, v18
	v_lshl_add_u64 v[36:37], v[36:37], 0, v[18:19]
	flat_store_dwordx4 v[36:37], v[32:35]
	s_waitcnt lgkmcnt(0)
	s_mov_b64 s[0:1], 0

; template <bool MAPPED>
; __device__ __forceinline__ void transpose_item(const float* W, int K, int Nsrc, bf16_t* WT, const float* gk, LAS float* scr, int item, int nblk, int lane) {
;     ...
; #pragma unroll 8
;     for (int i = 0; i < 32; ++i) { const int kk = 2 * i + (lane >> 5); float v = (sc >= 0) ? W[(size_t)(k0 + kk) * Nsrc + sc] : 0.f; if (gk) v *= gk[k0 + kk]; scr[kk * 33 + (lane & 31)] = v; }
;     asm volatile("s_waitcnt lgkmcnt(0)" ::: "memory");
.LBB0_43:
	s_add_u32 s8, s8, 0x58000
	s_addc_u32 s9, s9, 0
	v_add_u32_e32 v18, 0x840, v18
	s_cmp_lg_u32 s8, 0x160000
	v_lshl_add_u64 v[34:35], v[34:35], 0, 64
	s_cbranch_scc0 .LBB0_60
.LBB0_44:
	v_cndmask_b32_e64 v51, 0, 1, s[10:11]
	v_cmp_ne_u32_e64 s[6:7], 1, v51
	v_lshl_add_u64 v[50:51], v[38:39], 0, s[8:9]
	global_load_dword v90, v[50:51], off
	v_lshl_add_u64 v[50:51], v[42:43], 0, s[8:9]
	global_load_dword v91, v[50:51], off
	v_lshl_add_u64 v[50:51], v[46:47], 0, s[8:9]
	global_load_dword v92, v[50:51], off
	v_lshl_add_u64 v[50:51], v[48:49], 0, s[8:9]
	global_load_dword v93, v[50:51], off
	v_lshl_add_u64 v[50:51], v[44:45], 0, s[8:9]
	global_load_dword v94, v[50:51], off
	v_lshl_add_u64 v[50:51], v[40:41], 0, s[8:9]
	global_load_dword v95, v[50:51], off
	v_lshl_add_u64 v[50:51], v[36:37], 0, s[8:9]
	global_load_dword v96, v[50:51], off
	v_lshl_add_u64 v[50:51], v[32:33], 0, s[8:9]
	global_load_dword v97, v[50:51], off
	s_andn2_b64 vcc, exec, s[10:11]
	s_cbranch_vccnz .Ltpn_4
	global_load_dword v98, v[34:35], off
	global_load_dword v99, v[34:35], off offset:8
	global_load_dword v100, v[34:35], off offset:16
	global_load_dword v101, v[34:35], off offset:24
	global_load_dword v102, v[34:35], off offset:32
	global_load_dword v103, v[34:35], off offset:40
	global_load_dword v104, v[34:35], off offset:48
	global_load_dword v105, v[34:35], off offset:56
	s_waitcnt vmcnt(7)
	v_mul_f32_e32 v90, v90, v98
	ds_write_b32 v18, v90
	s_waitcnt vmcnt(6)
	v_mul_f32_e32 v91, v91, v99
	ds_write_b32 v18, v91 offset:264
	s_waitcnt vmcnt(5)
	v_mul_f32_e32 v92, v92, v100
	ds_write_b32 v18, v92 offset:528
	s_waitcnt vmcnt(4)
	v_mul_f32_e32 v93, v93, v101
	ds_write_b32 v18, v93 offset:792
	s_waitcnt vmcnt(3)
	v_mul_f32_e32 v94, v94, v102
	ds_write_b32 v18, v94 offset:1056
	s_waitcnt vmcnt(2)
	v_mul_f32_e32 v95, v95, v103
	ds_write_b32 v18, v95 offset:1320
	s_waitcnt vmcnt(1)
	v_mul_f32_e32 v96, v96, v104
	ds_write_b32 v18, v96 offset:1584
	s_waitcnt vmcnt(0)
	v_mul_f32_e32 v97, v97, v105
	ds_write_b32 v18, v97 offset:1848
	s_branch .LBB0_43
.Ltpn_4:
	s_waitcnt vmcnt(7)
	ds_write_b32 v18, v90
	s_waitcnt vmcnt(6)
	ds_write_b32 v18, v91 offset:264
	s_waitcnt vmcnt(5)
	ds_write_b32 v18, v92 offset:528
	s_waitcnt vmcnt(4)
	ds_write_b32 v18, v93 offset:792
	s_waitcnt vmcnt(3)
	ds_write_b32 v18, v94 offset:1056
	s_waitcnt vmcnt(2)
	ds_write_b32 v18, v95 offset:1320
	s_waitcnt vmcnt(1)
	ds_write_b32 v18, v96 offset:1584
	s_waitcnt vmcnt(0)
	ds_write_b32 v18, v97 offset:1848
	s_branch .LBB0_43

; #define LAS __attribute__((address_space(3)))
; __device__ __forceinline__ unsigned pk2(float lo, float hi) { return f2bf(lo) | (f2bf(hi) << 16); }
; template <bool MAPPED>
; __device__ __forceinline__ void transpose_item(const float* W, int K, int Nsrc, bf16_t* WT, const float* gk, LAS float* scr, int item, int nblk, int lane) {
;     const int kb = item / nblk, nb = item % nblk, k0 = 64 * kb, j0 = 32 * nb;
;     const int sc = MAPPED ? in_map(j0 + (lane & 31)) : (j0 + (lane & 31));
; #pragma unroll 8
;     for (int i = 0; i < 32; ++i) { const int kk = 2 * i + (lane >> 5); float v = (sc >= 0) ? W[(size_t)(k0 + kk) * Nsrc + sc] : 0.f; if (gk) v *= gk[k0 + kk]; scr[kk * 33 + (lane & 31)] = v; }
;     asm volatile("s_waitcnt lgkmcnt(0)" ::: "memory");
;     const int c = lane & 7;
; #pragma unroll
;     for (int j = 0; j < 4; ++j) { const int n = (lane >> 3) + 8 * j; const LAS float* s = scr + (8 * c) * 33 + n;
;         u32x4 o; o.x = pk2(s[0 * 33], s[1 * 33]); o.y = pk2(s[2 * 33], s[3 * 33]); o.z = pk2(s[4 * 33], s[5 * 33]); o.w = pk2(s[6 * 33], s[7 * 33]);
;         *(u32x4*)(WT + (size_t)(j0 + n) * K + k0 + 8 * c) = o; }
;     asm volatile("s_waitcnt lgkmcnt(0)" ::: "memory");
; }
.LBB0_64:
	v_lshl_add_u64 v[48:49], v[46:47], 0, s[0:1]
	global_load_dword v90, v[48:49], off
	v_lshl_add_u64 v[48:49], v[44:45], 0, s[0:1]
	global_load_dword v91, v[48:49], off
	v_lshl_add_u64 v[48:49], v[42:43], 0, s[0:1]
	global_load_dword v92, v[48:49], off
	v_lshl_add_u64 v[48:49], v[40:41], 0, s[0:1]
	global_load_dword v93, v[48:49], off
	v_lshl_add_u64 v[48:49], v[38:39], 0, s[0:1]
	global_load_dword v94, v[48:49], off
	v_lshl_add_u64 v[48:49], v[36:37], 0, s[0:1]
	global_load_dword v95, v[48:49], off
	v_lshl_add_u64 v[48:49], v[34:35], 0, s[0:1]
	global_load_dword v96, v[48:49], off
	v_lshl_add_u64 v[48:49], v[32:33], 0, s[0:1]
	s_add_u32 s0, s0, 0x10000
	s_addc_u32 s1, s1, 0
	s_cmp_lg_u32 s0, 0x40000
	global_load_dword v97, v[48:49], off
	s_waitcnt vmcnt(7)
	ds_write_b32 v18, v90
	s_waitcnt vmcnt(6)
	ds_write_b32 v18, v91 offset:264
	s_waitcnt vmcnt(5)
	ds_write_b32 v18, v92 offset:528
	s_waitcnt vmcnt(4)
	ds_write_b32 v18, v93 offset:792
	s_waitcnt vmcnt(3)
	ds_write_b32 v18, v94 offset:1056
	s_waitcnt vmcnt(2)
	ds_write_b32 v18, v95 offset:1320
	s_waitcnt vmcnt(1)
	ds_write_b32 v18, v96 offset:1584
	s_waitcnt vmcnt(0)
	ds_write_b32 v18, v97 offset:1848
	v_add_u32_e32 v18, 0x840, v18
	s_cbranch_scc1 .LBB0_64
	s_waitcnt lgkmcnt(0)
	ds_read_b32 v18, v57
	ds_read_b32 v32, v57 offset:132
	ds_read_b32 v33, v57 offset:264
	ds_read_b32 v34, v57 offset:396
	ds_read_b32 v35, v57 offset:528
	ds_read_b32 v38, v57 offset:660
	ds_read_b32 v39, v57 offset:792
	ds_read_b32 v40, v57 offset:924
	s_waitcnt lgkmcnt(7)
	v_bfe_u32 v41, v18, 16, 1
	v_add3_u32 v18, v18, v41, s30
	s_waitcnt lgkmcnt(6)
	v_bfe_u32 v41, v32, 16, 1
	v_lshrrev_b32_e32 v18, 16, v18
	v_add3_u32 v32, v32, v41, s30
	v_and_or_b32 v32, v32, s31, v18
	s_waitcnt lgkmcnt(5)
	v_bfe_u32 v18, v33, 16, 1
	v_add3_u32 v18, v33, v18, s30
	s_waitcnt lgkmcnt(4)
	v_bfe_u32 v33, v34, 16, 1
	v_lshrrev_b32_e32 v18, 16, v18
	v_add3_u32 v33, v34, v33, s30
	v_and_or_b32 v33, v33, s31, v18
	s_waitcnt lgkmcnt(3)
	v_bfe_u32 v18, v35, 16, 1
	v_add3_u32 v18, v35, v18, s30
	s_waitcnt lgkmcnt(2)
	v_bfe_u32 v34, v38, 16, 1
	s_lshl_b32 s0, s14, 1
	v_lshrrev_b32_e32 v18, 16, v18
	v_add3_u32 v34, v38, v34, s30
	s_add_i32 s0, s0, 0x1c300
	v_and_or_b32 v34, v34, s31, v18
	s_waitcnt lgkmcnt(1)
	v_bfe_u32 v18, v39, 16, 1
	s_and_b32 s1, s0, 0x1ffc0
	s_lshl_b32 s0, s14, 5
	v_add3_u32 v18, v39, v18, s30
	s_waitcnt lgkmcnt(0)
	v_bfe_u32 v35, v40, 16, 1
	s_and_b32 s0, s0, 0x3e0
	v_lshrrev_b32_e32 v18, 16, v18
	v_add3_u32 v35, v40, v35, s30
	s_lshl_b32 s16, s1, 1
	v_and_or_b32 v35, v35, s31, v18
	v_or_b32_e32 v18, s0, v17
	v_lshl_add_u64 v[36:37], v[24:25], 0, s[16:17]
	v_lshlrev_b32_e32 v18, 11, v18
	v_lshl_add_u64 v[38:39], v[36:37], 0, v[18:19]
	flat_store_dwordx4 v[38:39], v[32:35]
	ds_read_b32 v18, v57 offset:32
	ds_read_b32 v32, v57 offset:164
	ds_read_b32 v33, v57 offset:296
	ds_read_b32 v34, v57 offset:428
	ds_read_b32 v35, v57 offset:560
	ds_read_b32 v38, v57 offset:692
	ds_read_b32 v39, v57 offset:824
	ds_read_b32 v40, v57 offset:956
	s_waitcnt lgkmcnt(0)
	v_bfe_u32 v41, v18, 16, 1
	v_add3_u32 v18, v18, v41, s30
	v_bfe_u32 v41, v32, 16, 1
	v_lshrrev_b32_e32 v18, 16, v18
	v_add3_u32 v32, v32, v41, s30
	v_and_or_b32 v32, v32, s31, v18
	v_bfe_u32 v18, v33, 16, 1
	v_add3_u32 v18, v33, v18, s30
	v_bfe_u32 v33, v34, 16, 1
	v_lshrrev_b32_e32 v18, 16, v18
	v_add3_u32 v33, v34, v33, s30
	v_and_or_b32 v33, v33, s31, v18
	v_bfe_u32 v18, v35, 16, 1
	v_add3_u32 v18, v35, v18, s30
	v_bfe_u32 v34, v38, 16, 1
	v_lshrrev_b32_e32 v18, 16, v18
	v_add3_u32 v34, v38, v34, s30
	v_and_or_b32 v34, v34, s31, v18
	v_bfe_u32 v18, v39, 16, 1
	v_add3_u32 v18, v39, v18, s30
	v_bfe_u32 v35, v40, 16, 1
	v_lshrrev_b32_e32 v18, 16, v18
	v_add3_u32 v35, v40, v35, s30
	v_and_or_b32 v35, v35, s31, v18
	v_or_b32_e32 v18, s0, v58
	v_lshlrev_b32_e32 v18, 11, v18
	v_lshl_add_u64 v[38:39], v[36:37], 0, v[18:19]
	flat_store_dwordx4 v[38:39], v[32:35]
	ds_read_b32 v18, v57 offset:64
	ds_read_b32 v32, v57 offset:196
	ds_read_b32 v33, v57 offset:328
	ds_read_b32 v34, v57 offset:460
	ds_read_b32 v35, v57 offset:592
	ds_read_b32 v38, v57 offset:724
	ds_read_b32 v39, v57 offset:856
	ds_read_b32 v40, v57 offset:988
	s_waitcnt lgkmcnt(0)
	v_bfe_u32 v41, v18, 16, 1
	v_add3_u32 v18, v18, v41, s30
	v_bfe_u32 v41, v32, 16, 1
	v_lshrrev_b32_e32 v18, 16, v18
	v_add3_u32 v32, v32, v41, s30
	v_and_or_b32 v32, v32, s31, v18
	v_bfe_u32 v18, v33, 16, 1
	v_add3_u32 v18, v33, v18, s30
	v_bfe_u32 v33, v34, 16, 1
	v_lshrrev_b32_e32 v18, 16, v18
	v_add3_u32 v33, v34, v33, s30
	v_and_or_b32 v33, v33, s31, v18
	v_bfe_u32 v18, v35, 16, 1
	v_add3_u32 v18, v35, v18, s30
	v_bfe_u32 v34, v38, 16, 1
	v_lshrrev_b32_e32 v18, 16, v18
	v_add3_u32 v34, v38, v34, s30
	v_and_or_b32 v34, v34, s31, v18
	v_bfe_u32 v18, v39, 16, 1
	v_add3_u32 v18, v39, v18, s30
	v_bfe_u32 v35, v40, 16, 1
	v_lshrrev_b32_e32 v18, 16, v18
	v_add3_u32 v35, v40, v35, s30
	v_and_or_b32 v35, v35, s31, v18
	v_or_b32_e32 v18, s0, v59
	v_lshlrev_b32_e32 v18, 11, v18
	v_lshl_add_u64 v[38:39], v[36:37], 0, v[18:19]
	flat_store_dwordx4 v[38:39], v[32:35]
	ds_read_b32 v18, v57 offset:96
	ds_read_b32 v32, v57 offset:228
	ds_read_b32 v33, v57 offset:360
	ds_read_b32 v34, v57 offset:492
	ds_read_b32 v35, v57 offset:624
	ds_read_b32 v38, v57 offset:756
	ds_read_b32 v39, v57 offset:888
	ds_read_b32 v40, v57 offset:1020
	s_waitcnt lgkmcnt(0)
	v_bfe_u32 v41, v18, 16, 1
	v_add3_u32 v18, v18, v41, s30
	v_bfe_u32 v41, v32, 16, 1
	v_lshrrev_b32_e32 v18, 16, v18
	v_add3_u32 v32, v32, v41, s30
	v_and_or_b32 v32, v32, s31, v18
	v_bfe_u32 v18, v33, 16, 1
	v_add3_u32 v18, v33, v18, s30
	v_bfe_u32 v33, v34, 16, 1
	v_lshrrev_b32_e32 v18, 16, v18
	v_add3_u32 v33, v34, v33, s30
	v_and_or_b32 v33, v33, s31, v18
	v_bfe_u32 v18, v35, 16, 1
	v_add3_u32 v18, v35, v18, s30
	v_bfe_u32 v34, v38, 16, 1
	v_lshrrev_b32_e32 v18, 16, v18
	v_add3_u32 v34, v38, v34, s30
	v_and_or_b32 v34, v34, s31, v18
	v_bfe_u32 v18, v39, 16, 1
	v_add3_u32 v18, v39, v18, s30
	v_bfe_u32 v35, v40, 16, 1
	v_lshrrev_b32_e32 v18, 16, v18
	v_add3_u32 v35, v40, v35, s30
	v_and_or_b32 v35, v35, s31, v18
	v_or_b32_e32 v18, s0, v60
	v_lshlrev_b32_e32 v18, 11, v18
	v_lshl_add_u64 v[36:37], v[36:37], 0, v[18:19]
	flat_store_dwordx4 v[36:37], v[32:35]
	s_waitcnt lgkmcnt(0)

; #define LAS __attribute__((address_space(3)))
; __device__ __forceinline__ unsigned pk2(float lo, float hi) { return f2bf(lo) | (f2bf(hi) << 16); }
; template <bool MAPPED>
; __device__ __forceinline__ void transpose_item(const float* W, int K, int Nsrc, bf16_t* WT, const float* gk, LAS float* scr, int item, int nblk, int lane) {
;     const int kb = item / nblk, nb = item % nblk, k0 = 64 * kb, j0 = 32 * nb;
;     const int sc = MAPPED ? in_map(j0 + (lane & 31)) : (j0 + (lane & 31));
; #pragma unroll 8
;     for (int i = 0; i < 32; ++i) { const int kk = 2 * i + (lane >> 5); float v = (sc >= 0) ? W[(size_t)(k0 + kk) * Nsrc + sc] : 0.f; if (gk) v *= gk[k0 + kk]; scr[kk * 33 + (lane & 31)] = v; }
;     asm volatile("s_waitcnt lgkmcnt(0)" ::: "memory");
;     const int c = lane & 7;
; #pragma unroll
;     for (int j = 0; j < 4; ++j) { const int n = (lane >> 3) + 8 * j; const LAS float* s = scr + (8 * c) * 33 + n;
;         u32x4 o; o.x = pk2(s[0 * 33], s[1 * 33]); o.y = pk2(s[2 * 33], s[3 * 33]); o.z = pk2(s[4 * 33], s[5 * 33]); o.w = pk2(s[6 * 33], s[7 * 33]);
;         *(u32x4*)(WT + (size_t)(j0 + n) * K + k0 + 8 * c) = o; }
;     asm volatile("s_waitcnt lgkmcnt(0)" ::: "memory");
; }
; __device__ __forceinline__ void weights_phase(Frame& F, int layer, int part, int nparts, int gw, int NGW) {
;     ...
;         if (r < 3 * N_BR) { const int n = r / N_BR; transpose_item<false>(w_br + (size_t)n * D * D, D, D, WSP(bf16_t, OFF_WBR + layer * W_LAYER) + (size_t)n * D * D, nullptr, scr, r % N_BR, 32, F.lane); continue; } r -= 3 * N_BR;
.LBB0_69:
	v_lshl_add_u64 v[48:49], v[46:47], 0, s[0:1]
	global_load_dword v90, v[48:49], off
	v_lshl_add_u64 v[48:49], v[44:45], 0, s[0:1]
	global_load_dword v91, v[48:49], off
	v_lshl_add_u64 v[48:49], v[42:43], 0, s[0:1]
	global_load_dword v92, v[48:49], off
	v_lshl_add_u64 v[48:49], v[40:41], 0, s[0:1]
	global_load_dword v93, v[48:49], off
	v_lshl_add_u64 v[48:49], v[38:39], 0, s[0:1]
	global_load_dword v94, v[48:49], off
	v_lshl_add_u64 v[48:49], v[36:37], 0, s[0:1]
	global_load_dword v95, v[48:49], off
	v_lshl_add_u64 v[48:49], v[34:35], 0, s[0:1]
	global_load_dword v96, v[48:49], off
	v_lshl_add_u64 v[48:49], v[32:33], 0, s[0:1]
	s_add_u32 s0, s0, 0x10000
	s_addc_u32 s1, s1, 0
	s_cmp_lg_u32 s0, 0x40000
	global_load_dword v97, v[48:49], off
	s_waitcnt vmcnt(7)
	ds_write_b32 v18, v90
	s_waitcnt vmcnt(6)
	ds_write_b32 v18, v91 offset:264
	s_waitcnt vmcnt(5)
	ds_write_b32 v18, v92 offset:528
	s_waitcnt vmcnt(4)
	ds_write_b32 v18, v93 offset:792
	s_waitcnt vmcnt(3)
	ds_write_b32 v18, v94 offset:1056
	s_waitcnt vmcnt(2)
	ds_write_b32 v18, v95 offset:1320
	s_waitcnt vmcnt(1)
	ds_write_b32 v18, v96 offset:1584
	s_waitcnt vmcnt(0)
	ds_write_b32 v18, v97 offset:1848
	v_add_u32_e32 v18, 0x840, v18
	s_cbranch_scc1 .LBB0_69
	s_add_i32 s1, s14, 0xffffe780
	s_lshr_b32 s16, s1, 9
	s_lshl_b32 s0, s14, 5
	s_and_b32 s0, s0, 0x3e0
	s_lshl_b64 s[6:7], s[16:17], 21
	s_add_u32 s6, s15, s6
	s_addc_u32 s7, s22, s7
	s_lshl_b32 s1, s1, 2
	s_and_b32 s1, s1, 0x780
	s_add_u32 s6, s6, s1
	s_waitcnt lgkmcnt(0)
	s_addc_u32 s7, s7, 0
	v_mov_b32_e32 v31, v19
	v_lshl_add_u64 v[36:37], s[6:7], 0, v[30:31]
	ds_read_b32 v18, v57
	ds_read_b32 v31, v57 offset:132
	ds_read_b32 v33, v57 offset:264
	ds_read_b32 v34, v57 offset:396
	ds_read_b32 v35, v57 offset:528
	ds_read_b32 v38, v57 offset:660
	ds_read_b32 v39, v57 offset:792
	ds_read_b32 v40, v57 offset:924
	s_waitcnt lgkmcnt(7)
	v_bfe_u32 v32, v18, 16, 1
	v_add3_u32 v18, v18, v32, s30
	s_waitcnt lgkmcnt(6)
	v_bfe_u32 v32, v31, 16, 1
	v_lshrrev_b32_e32 v18, 16, v18
	v_add3_u32 v31, v31, v32, s30
	v_and_or_b32 v32, v31, s31, v18
	s_waitcnt lgkmcnt(5)
	v_bfe_u32 v18, v33, 16, 1
	v_add3_u32 v18, v33, v18, s30
	s_waitcnt lgkmcnt(4)
	v_bfe_u32 v31, v34, 16, 1
	v_lshrrev_b32_e32 v18, 16, v18
	v_add3_u32 v31, v34, v31, s30
	v_and_or_b32 v33, v31, s31, v18
	s_waitcnt lgkmcnt(3)
	v_bfe_u32 v18, v35, 16, 1
	v_add3_u32 v18, v35, v18, s30
	s_waitcnt lgkmcnt(2)
	v_bfe_u32 v31, v38, 16, 1
	v_lshrrev_b32_e32 v18, 16, v18
	v_add3_u32 v31, v38, v31, s30
	v_and_or_b32 v34, v31, s31, v18
	s_waitcnt lgkmcnt(1)
	v_bfe_u32 v18, v39, 16, 1
	v_add3_u32 v18, v39, v18, s30
	s_waitcnt lgkmcnt(0)
	v_bfe_u32 v31, v40, 16, 1
	v_lshrrev_b32_e32 v18, 16, v18
	v_add3_u32 v31, v40, v31, s30
	v_and_or_b32 v35, v31, s31, v18
	v_or_b32_e32 v18, s0, v17
	v_lshlrev_b32_e32 v18, 11, v18
	v_lshl_add_u64 v[38:39], v[36:37], 0, v[18:19]
	flat_store_dwordx4 v[38:39], v[32:35]
	ds_read_b32 v18, v57 offset:32
	ds_read_b32 v31, v57 offset:164
	ds_read_b32 v33, v57 offset:296
	ds_read_b32 v34, v57 offset:428
	ds_read_b32 v35, v57 offset:560
	ds_read_b32 v38, v57 offset:692
	ds_read_b32 v39, v57 offset:824
	ds_read_b32 v40, v57 offset:956
	s_waitcnt lgkmcnt(0)
	v_bfe_u32 v32, v18, 16, 1
	v_add3_u32 v18, v18, v32, s30
	v_bfe_u32 v32, v31, 16, 1
	v_lshrrev_b32_e32 v18, 16, v18
	v_add3_u32 v31, v31, v32, s30
	v_and_or_b32 v32, v31, s31, v18
	v_bfe_u32 v18, v33, 16, 1
	v_add3_u32 v18, v33, v18, s30
	v_bfe_u32 v31, v34, 16, 1
	v_lshrrev_b32_e32 v18, 16, v18
	v_add3_u32 v31, v34, v31, s30
	v_and_or_b32 v33, v31, s31, v18
	v_bfe_u32 v18, v35, 16, 1
	v_add3_u32 v18, v35, v18, s30
	v_bfe_u32 v31, v38, 16, 1
	v_lshrrev_b32_e32 v18, 16, v18
	v_add3_u32 v31, v38, v31, s30
	v_and_or_b32 v34, v31, s31, v18
	v_bfe_u32 v18, v39, 16, 1
	v_add3_u32 v18, v39, v18, s30
	v_bfe_u32 v31, v40, 16, 1
	v_lshrrev_b32_e32 v18, 16, v18
	v_add3_u32 v31, v40, v31, s30
	v_and_or_b32 v35, v31, s31, v18
	v_or_b32_e32 v18, s0, v58
	v_lshlrev_b32_e32 v18, 11, v18
	v_lshl_add_u64 v[38:39], v[36:37], 0, v[18:19]
	flat_store_dwordx4 v[38:39], v[32:35]
	ds_read_b32 v18, v57 offset:64
	ds_read_b32 v31, v57 offset:196
	ds_read_b32 v33, v57 offset:328
	ds_read_b32 v34, v57 offset:460
	ds_read_b32 v35, v57 offset:592
	ds_read_b32 v38, v57 offset:724
	ds_read_b32 v39, v57 offset:856
	ds_read_b32 v40, v57 offset:988
	s_waitcnt lgkmcnt(0)
	v_bfe_u32 v32, v18, 16, 1
	v_add3_u32 v18, v18, v32, s30
	v_bfe_u32 v32, v31, 16, 1
	v_lshrrev_b32_e32 v18, 16, v18
	v_add3_u32 v31, v31, v32, s30
	v_and_or_b32 v32, v31, s31, v18
	v_bfe_u32 v18, v33, 16, 1
	v_add3_u32 v18, v33, v18, s30
	v_bfe_u32 v31, v34, 16, 1
	v_lshrrev_b32_e32 v18, 16, v18
	v_add3_u32 v31, v34, v31, s30
	v_and_or_b32 v33, v31, s31, v18
	v_bfe_u32 v18, v35, 16, 1
	v_add3_u32 v18, v35, v18, s30
	v_bfe_u32 v31, v38, 16, 1
	v_lshrrev_b32_e32 v18, 16, v18
	v_add3_u32 v31, v38, v31, s30
	v_and_or_b32 v34, v31, s31, v18
	v_bfe_u32 v18, v39, 16, 1
	v_add3_u32 v18, v39, v18, s30
	v_bfe_u32 v31, v40, 16, 1
	v_lshrrev_b32_e32 v18, 16, v18
	v_add3_u32 v31, v40, v31, s30
	v_and_or_b32 v35, v31, s31, v18
	v_or_b32_e32 v18, s0, v59
	v_lshlrev_b32_e32 v18, 11, v18
	v_lshl_add_u64 v[38:39], v[36:37], 0, v[18:19]
	flat_store_dwordx4 v[38:39], v[32:35]
	ds_read_b32 v18, v57 offset:96
	ds_read_b32 v31, v57 offset:228
	ds_read_b32 v33, v57 offset:360
	ds_read_b32 v34, v57 offset:492
	ds_read_b32 v35, v57 offset:624
	ds_read_b32 v38, v57 offset:756
	ds_read_b32 v39, v57 offset:888
	ds_read_b32 v40, v57 offset:1020
	s_waitcnt lgkmcnt(0)
	v_bfe_u32 v32, v18, 16, 1
	v_add3_u32 v18, v18, v32, s30
	v_bfe_u32 v32, v31, 16, 1
	v_lshrrev_b32_e32 v18, 16, v18
	v_add3_u32 v31, v31, v32, s30
	v_and_or_b32 v32, v31, s31, v18
	v_bfe_u32 v18, v33, 16, 1
	v_add3_u32 v18, v33, v18, s30
	v_bfe_u32 v31, v34, 16, 1
	v_lshrrev_b32_e32 v18, 16, v18
	v_add3_u32 v31, v34, v31, s30
	v_and_or_b32 v33, v31, s31, v18
	v_bfe_u32 v18, v35, 16, 1
	v_add3_u32 v18, v35, v18, s30
	v_bfe_u32 v31, v38, 16, 1
	v_lshrrev_b32_e32 v18, 16, v18
	v_add3_u32 v31, v38, v31, s30
	v_and_or_b32 v34, v31, s31, v18
	v_bfe_u32 v18, v39, 16, 1
	v_add3_u32 v18, v39, v18, s30
	v_bfe_u32 v31, v40, 16, 1
	v_lshrrev_b32_e32 v18, 16, v18
	v_add3_u32 v31, v40, v31, s30
	v_and_or_b32 v35, v31, s31, v18
	v_or_b32_e32 v18, s0, v60
	v_lshlrev_b32_e32 v18, 11, v18
	v_lshl_add_u64 v[36:37], v[36:37], 0, v[18:19]
	flat_store_dwordx4 v[36:37], v[32:35]
	s_waitcnt lgkmcnt(0)

; template <bool MAPPED>
; __device__ __forceinline__ void transpose_item(const float* W, int K, int Nsrc, bf16_t* WT, const float* gk, LAS float* scr, int item, int nblk, int lane) {
;     ...
;     const int sc = MAPPED ? in_map(j0 + (lane & 31)) : (j0 + (lane & 31));
; #pragma unroll 8
;     for (int i = 0; i < 32; ++i) { const int kk = 2 * i + (lane >> 5); float v = (sc >= 0) ? W[(size_t)(k0 + kk) * Nsrc + sc] : 0.f; if (gk) v *= gk[k0 + kk]; scr[kk * 33 + (lane & 31)] = v; }
;     asm volatile("s_waitcnt lgkmcnt(0)" ::: "memory");
.LBB0_84:
	s_add_u32 s20, s20, 0xc0600
	s_addc_u32 s21, s21, 0
	v_add_u32_e32 v18, 0x840, v18
	s_cmp_lg_u32 s20, 0x301800
	v_lshl_add_u64 v[52:53], v[52:53], 0, 64
	s_cbranch_scc0 .LBB0_32
.LBB0_85:
	v_cndmask_b32_e64 v54, 0, 1, s[4:5]
	v_cmp_ne_u32_e64 s[8:9], 1, v54
	v_mov_b32_e32 v90, 0
	v_mov_b32_e32 v91, 0
	v_mov_b32_e32 v92, 0
	v_mov_b32_e32 v93, 0
	v_mov_b32_e32 v94, 0
	v_mov_b32_e32 v95, 0
	v_mov_b32_e32 v96, 0
	v_mov_b32_e32 v97, 0
	s_and_saveexec_b64 s[0:1], s[6:7]
	s_cbranch_execz .Ltpx_3
	v_lshl_add_u64 v[54:55], v[50:51], 0, s[20:21]
	global_load_dword v90, v[54:55], off
	v_lshl_add_u64 v[54:55], v[46:47], 0, s[20:21]
	global_load_dword v91, v[54:55], off
	v_lshl_add_u64 v[78:79], v[44:45], 0, s[20:21]
	global_load_dword v92, v[78:79], off
	v_lshl_add_u64 v[78:79], v[42:43], 0, s[20:21]
	global_load_dword v93, v[78:79], off
	v_lshl_add_u64 v[78:79], v[40:41], 0, s[20:21]
	global_load_dword v94, v[78:79], off
	v_lshl_add_u64 v[78:79], v[38:39], 0, s[20:21]
	global_load_dword v95, v[78:79], off
	v_lshl_add_u64 v[78:79], v[36:37], 0, s[20:21]
	global_load_dword v96, v[78:79], off
	v_lshl_add_u64 v[78:79], v[32:33], 0, s[20:21]
	global_load_dword v97, v[78:79], off
.Ltpx_3:
	s_or_b64 exec, exec, s[0:1]
	s_andn2_b64 vcc, exec, s[4:5]
	s_cbranch_vccnz .Ltpn_3
	v_lshl_add_u64 v[54:55], v[52:53], 0, v[48:49]
	global_load_dword v98, v[54:55], off
	v_lshl_add_u64 v[54:55], v[52:53], 0, v[34:35]
	global_load_dword v99, v[54:55], off offset:8
	global_load_dword v100, v[54:55], off offset:16
	global_load_dword v101, v[54:55], off offset:24
	global_load_dword v102, v[54:55], off offset:32
	global_load_dword v103, v[54:55], off offset:40
	global_load_dword v104, v[54:55], off offset:48
	global_load_dword v105, v[54:55], off offset:56
	s_waitcnt vmcnt(7)
	v_mul_f32_e32 v90, v90, v98
	ds_write_b32 v18, v90
	s_waitcnt vmcnt(6)
	v_mul_f32_e32 v91, v91, v99
	ds_write_b32 v18, v91 offset:264
	s_waitcnt vmcnt(5)
	v_mul_f32_e32 v92, v92, v100
	ds_write_b32 v18, v92 offset:528
	s_waitcnt vmcnt(4)
	v_mul_f32_e32 v93, v93, v101
	ds_write_b32 v18, v93 offset:792
	s_waitcnt vmcnt(3)
	v_mul_f32_e32 v94, v94, v102
	ds_write_b32 v18, v94 offset:1056
	s_waitcnt vmcnt(2)
	v_mul_f32_e32 v95, v95, v103
	ds_write_b32 v18, v95 offset:1320
	s_waitcnt vmcnt(1)
	v_mul_f32_e32 v96, v96, v104
	ds_write_b32 v18, v96 offset:1584
	s_waitcnt vmcnt(0)
	v_mul_f32_e32 v97, v97, v105
	ds_write_b32 v18, v97 offset:1848
	s_branch .LBB0_84

; __device__ __forceinline__ unsigned pk2hw(float lo, float hi) { unsigned r; asm("s_nop 1\n\tv_cvt_pk_bf16_f32 %0, %1, %2" : "=v"(r) : "v"(lo), "v"(hi)); return r; }
;     __device__ __forceinline__ void operator()(const f32x4 (&acc)[2][2][4][2], const Unit& u, int wr, int wc, int fr, int fq) const {
;         asm volatile("" : "+v"(fr), "+v"(fq));
;         const int row0 = u.pm * 256 + wr * 64 + fr, col0 = u.pn * 256 + wc * 32 + 8 * fq;
; #pragma unroll
;         for (int ai = 0; ai < 2; ++ai)
; #pragma unroll
;             for (int m = 0; m < 4; ++m) { const int row = row0 + ai * 128 + m * 16; float sq = 0.f;
; #pragma unroll
;                 for (int bj = 0; bj < 2; ++bj) { const size_t off = (size_t)row * D + col0 + bj * 128;
;                     const f32x4 x0 = *(const f32x4*)(xin + off) + acc[ai][bj][m][0], x1 = *(const f32x4*)(xin + off + 4) + acc[ai][bj][m][1];
;                     *(f32x4*)(xout + off) = x0; *(f32x4*)(xout + off + 4) = x1;
;                     u32x4 w; w.x = pk2hw(x0[0], x0[1]); w.y = pk2hw(x0[2], x0[3]); w.z = pk2hw(x1[0], x1[1]); w.w = pk2hw(x1[2], x1[3]); *(u32x4*)(xb + off) = w;
;                     sq += ((x0[0] * x0[0] + x0[1] * x0[1]) + (x0[2] * x0[2] + x0[3] * x0[3])) + ((x1[0] * x1[0] + x1[1] * x1[1]) + (x1[2] * x1[2] + x1[3] * x1[3])); }
;                 sq += __shfl_xor(sq, 16); sq += __shfl_xor(sq, 32);
;                 if (fq == 0) ssn[(size_t)row * 16 + u.pn * 4 + wc] = sq; }
;     }
.LBB0_251:
	s_lshl_b32 s0, s30, 8
	v_mov_b32_e32 v145, v148
	v_mov_b32_e32 v142, v149
	s_add_i32 s0, s0, s53
	s_nop 0
	v_add_u32_e32 v144, s0, v142
	s_lshl_b32 s0, s28, 8
	s_or_b32 s0, s0, s54
	v_lshl_add_u32 v142, v145, 3, s0
	v_cmp_eq_u32_e32 vcc, 0, v145
	v_ashrrev_i32_e32 v145, 31, v144
	v_ashrrev_i32_e32 v143, 31, v142
	v_lshlrev_b64 v[166:167], 10, v[144:145]
	v_lshl_add_u64 v[166:167], v[166:167], 0, v[142:143]
	v_lshlrev_b64 v[176:177], 2, v[166:167]
	v_lshl_add_u64 v[178:179], v[136:137], 0, v[176:177]
	s_mov_b64 s[36:37], vcc
	s_mov_b32 s35, 0
	v_lshl_add_u64 v[176:177], s[12:13], 0, v[176:177]
	s_lshl_b32 s28, s28, 2
	s_ashr_i32 s29, s28, 31
	v_lshl_add_u64 v[166:167], v[166:167], 1, s[14:15]
	v_lshlrev_b64 v[248:249], 6, v[144:145]
	v_lshl_add_u64 v[248:249], s[16:17], 0, v[248:249]
	v_lshl_add_u64 v[248:249], s[28:29], 2, v[248:249]
	s_lshl_b32 s62, s52, 2
	v_lshl_add_u64 v[248:249], v[248:249], 0, s[62:63]
	s_movk_i32 s34, 0x2000
	v_lshl_add_u64 v[144:145], s[34:35], 0, v[248:249]
	v_xor_b32_e32 v235, 16, v225
	v_xor_b32_e32 v236, 32, v225
	v_lshlrev_b32_e32 v235, 2, v235
	v_lshlrev_b32_e32 v236, 2, v236
	s_mov_b32 s34, 0x0
	v_lshl_add_u64 v[242:243], s[34:35], 0, v[178:179]
	global_load_dwordx4 v[180:183], v[242:243], off
	global_load_dwordx4 v[184:187], v[242:243], off offset:16
	global_load_dwordx4 v[188:191], v[242:243], off offset:512
	global_load_dwordx4 v[192:195], v[242:243], off offset:528
	s_mov_b32 s34, 0x10000
	v_lshl_add_u64 v[242:243], s[34:35], 0, v[178:179]
	global_load_dwordx4 v[196:199], v[242:243], off
	global_load_dwordx4 v[200:203], v[242:243], off offset:16
	global_load_dwordx4 v[204:207], v[242:243], off offset:512
	global_load_dwordx4 v[208:211], v[242:243], off offset:528
	s_mov_b32 s34, 0x20000
	v_lshl_add_u64 v[242:243], s[34:35], 0, v[178:179]
	global_load_dwordx4 v[212:215], v[242:243], off
	global_load_dwordx4 v[216:219], v[242:243], off offset:16
	s_waitcnt vmcnt(8)
	v_pk_add_f32 v[126:127], v[126:127], v[180:181]
	v_pk_add_f32 v[128:129], v[128:129], v[182:183]
	v_pk_add_f32 v[122:123], v[122:123], v[184:185]
	v_pk_add_f32 v[124:125], v[124:125], v[186:187]
	s_mov_b32 s34, 0x0
	v_lshl_add_u64 v[244:245], s[34:35], 0, v[176:177]
	s_mov_b32 s34, 0x0
	v_lshl_add_u64 v[246:247], s[34:35], 0, v[166:167]
	global_store_dwordx4 v[244:245], v[126:129], off
	global_store_dwordx4 v[244:245], v[122:125], off offset:16
	v_cvt_pk_bf16_f32 v172, v126, v127
	v_cvt_pk_bf16_f32 v173, v128, v129
	v_cvt_pk_bf16_f32 v174, v122, v123
	v_cvt_pk_bf16_f32 v175, v124, v125
	v_mul_f32_e32 v238, v127, v127
	v_mul_f32_e32 v240, v123, v123
	v_fmac_f32_e32 v238, v126, v126
	v_mul_f32_e32 v239, v129, v129
	v_fmac_f32_e32 v240, v122, v122
	v_mul_f32_e32 v241, v125, v125
	v_fmac_f32_e32 v239, v128, v128
	v_fmac_f32_e32 v241, v124, v124
	global_store_dwordx4 v[246:247], v[172:175], off
	v_add_f32_e32 v238, v238, v239
	v_add_f32_e32 v240, v240, v241
	v_add_f32_e32 v237, v238, v240
	global_load_dwordx4 v[126:129], v[242:243], off offset:512
	global_load_dwordx4 v[122:125], v[242:243], off offset:528
	s_waitcnt vmcnt(11)
	v_pk_add_f32 v[118:119], v[118:119], v[188:189]
	v_pk_add_f32 v[120:121], v[120:121], v[190:191]
	v_pk_add_f32 v[114:115], v[114:115], v[192:193]
	v_pk_add_f32 v[116:117], v[116:117], v[194:195]
	global_store_dwordx4 v[244:245], v[118:121], off offset:512
	global_store_dwordx4 v[244:245], v[114:117], off offset:528
	v_cvt_pk_bf16_f32 v220, v118, v119
	v_cvt_pk_bf16_f32 v221, v120, v121
	v_cvt_pk_bf16_f32 v222, v114, v115
	v_cvt_pk_bf16_f32 v223, v116, v117
	v_mul_f32_e32 v238, v119, v119
	v_mul_f32_e32 v240, v115, v115
	v_fmac_f32_e32 v238, v118, v118
	v_mul_f32_e32 v239, v121, v121
	v_fmac_f32_e32 v240, v114, v114
	v_mul_f32_e32 v241, v117, v117
	v_fmac_f32_e32 v239, v120, v120
	v_fmac_f32_e32 v241, v116, v116
	global_store_dwordx4 v[246:247], v[220:223], off offset:256
	v_add_f32_e32 v238, v238, v239
	v_add_f32_e32 v240, v240, v241
	v_add_f32_e32 v238, v238, v240
	v_add_f32_e32 v237, v237, v238
	ds_bpermute_b32 v250, v235, v237
	s_mov_b32 s34, 0x30000
	v_lshl_add_u64 v[242:243], s[34:35], 0, v[178:179]
	global_load_dwordx4 v[118:121], v[242:243], off
	global_load_dwordx4 v[114:117], v[242:243], off offset:16
	s_waitcnt lgkmcnt(0)
	v_add_f32_e32 v237, v237, v250
	ds_bpermute_b32 v250, v236, v237
	s_waitcnt lgkmcnt(0)
	s_and_saveexec_b64 s[0:1], s[36:37]
	v_add_f32_e32 v237, v237, v250
	global_store_dword v[248:249], v237, off
	s_or_b64 exec, exec, s[0:1]
	s_waitcnt vmcnt(14)
	v_pk_add_f32 v[110:111], v[110:111], v[196:197]
	v_pk_add_f32 v[112:113], v[112:113], v[198:199]
	v_pk_add_f32 v[106:107], v[106:107], v[200:201]
	v_pk_add_f32 v[108:109], v[108:109], v[202:203]
	s_mov_b32 s34, 0x10000
	v_lshl_add_u64 v[244:245], s[34:35], 0, v[176:177]
	s_mov_b32 s34, 0x8000
	v_lshl_add_u64 v[246:247], s[34:35], 0, v[166:167]
	global_store_dwordx4 v[244:245], v[110:113], off
	global_store_dwordx4 v[244:245], v[106:109], off offset:16
	v_cvt_pk_bf16_f32 v172, v110, v111
	v_cvt_pk_bf16_f32 v173, v112, v113
	v_cvt_pk_bf16_f32 v174, v106, v107
	v_cvt_pk_bf16_f32 v175, v108, v109
	v_mul_f32_e32 v238, v111, v111
	v_mul_f32_e32 v240, v107, v107
	v_fmac_f32_e32 v238, v110, v110
	v_mul_f32_e32 v239, v113, v113
	v_fmac_f32_e32 v240, v106, v106
	v_mul_f32_e32 v241, v109, v109
	v_fmac_f32_e32 v239, v112, v112
	v_fmac_f32_e32 v241, v108, v108
	global_store_dwordx4 v[246:247], v[172:175], off
	v_add_f32_e32 v238, v238, v239
	v_add_f32_e32 v240, v240, v241
	v_add_f32_e32 v237, v238, v240
	global_load_dwordx4 v[110:113], v[242:243], off offset:512
	global_load_dwordx4 v[106:109], v[242:243], off offset:528
	s_waitcnt vmcnt(17)
; __device__ __forceinline__ unsigned pk2hw(float lo, float hi) { unsigned r; asm("s_nop 1\n\tv_cvt_pk_bf16_f32 %0, %1, %2" : "=v"(r) : "v"(lo), "v"(hi)); return r; }
;     __device__ __forceinline__ void operator()(const f32x4 (&acc)[2][2][4][2], const Unit& u, int wr, int wc, int fr, int fq) const {
;         asm volatile("" : "+v"(fr), "+v"(fq));
;         const int row0 = u.pm * 256 + wr * 64 + fr, col0 = u.pn * 256 + wc * 32 + 8 * fq;
; #pragma unroll
;         for (int ai = 0; ai < 2; ++ai)
; #pragma unroll
;             for (int m = 0; m < 4; ++m) { const int row = row0 + ai * 128 + m * 16; float sq = 0.f;
; #pragma unroll
;                 for (int bj = 0; bj < 2; ++bj) { const size_t off = (size_t)row * D + col0 + bj * 128;
;                     const f32x4 x0 = *(const f32x4*)(xin + off) + acc[ai][bj][m][0], x1 = *(const f32x4*)(xin + off + 4) + acc[ai][bj][m][1];
;                     *(f32x4*)(xout + off) = x0; *(f32x4*)(xout + off + 4) = x1;
;                     u32x4 w; w.x = pk2hw(x0[0], x0[1]); w.y = pk2hw(x0[2], x0[3]); w.z = pk2hw(x1[0], x1[1]); w.w = pk2hw(x1[2], x1[3]); *(u32x4*)(xb + off) = w;
;                     sq += ((x0[0] * x0[0] + x0[1] * x0[1]) + (x0[2] * x0[2] + x0[3] * x0[3])) + ((x1[0] * x1[0] + x1[1] * x1[1]) + (x1[2] * x1[2] + x1[3] * x1[3])); }
;                 sq += __shfl_xor(sq, 16); sq += __shfl_xor(sq, 32);
;                 if (fq == 0) ssn[(size_t)row * 16 + u.pn * 4 + wc] = sq; }
;     }
	v_pk_add_f32 v[102:103], v[102:103], v[204:205]
	v_pk_add_f32 v[104:105], v[104:105], v[206:207]
	v_pk_add_f32 v[98:99], v[98:99], v[208:209]
	v_pk_add_f32 v[100:101], v[100:101], v[210:211]
	global_store_dwordx4 v[244:245], v[102:105], off offset:512
	global_store_dwordx4 v[244:245], v[98:101], off offset:528
	v_cvt_pk_bf16_f32 v220, v102, v103
	v_cvt_pk_bf16_f32 v221, v104, v105
	v_cvt_pk_bf16_f32 v222, v98, v99
	v_cvt_pk_bf16_f32 v223, v100, v101
	v_mul_f32_e32 v238, v103, v103
	v_mul_f32_e32 v240, v99, v99
	v_fmac_f32_e32 v238, v102, v102
	v_mul_f32_e32 v239, v105, v105
	v_fmac_f32_e32 v240, v98, v98
	v_mul_f32_e32 v241, v101, v101
	v_fmac_f32_e32 v239, v104, v104
	v_fmac_f32_e32 v241, v100, v100
	global_store_dwordx4 v[246:247], v[220:223], off offset:256
	v_add_f32_e32 v238, v238, v239
	v_add_f32_e32 v240, v240, v241
	v_add_f32_e32 v238, v238, v240
	v_add_f32_e32 v237, v237, v238
	ds_bpermute_b32 v250, v235, v237
	s_mov_b32 s34, 0x80000
	v_lshl_add_u64 v[242:243], s[34:35], 0, v[178:179]
	global_load_dwordx4 v[102:105], v[242:243], off
	global_load_dwordx4 v[98:101], v[242:243], off offset:16
	s_waitcnt lgkmcnt(0)
	v_add_f32_e32 v237, v237, v250
	ds_bpermute_b32 v250, v236, v237
	s_waitcnt lgkmcnt(0)
	s_and_saveexec_b64 s[0:1], s[36:37]
	v_add_f32_e32 v237, v237, v250
	global_store_dword v[248:249], v237, off offset:1024
	s_or_b64 exec, exec, s[0:1]
	s_waitcnt vmcnt(20)
	v_pk_add_f32 v[94:95], v[94:95], v[212:213]
	v_pk_add_f32 v[96:97], v[96:97], v[214:215]
	v_pk_add_f32 v[90:91], v[90:91], v[216:217]
	v_pk_add_f32 v[92:93], v[92:93], v[218:219]
	s_mov_b32 s34, 0x20000
	v_lshl_add_u64 v[244:245], s[34:35], 0, v[176:177]
	s_mov_b32 s34, 0x10000
	v_lshl_add_u64 v[246:247], s[34:35], 0, v[166:167]
	global_store_dwordx4 v[244:245], v[94:97], off
	global_store_dwordx4 v[244:245], v[90:93], off offset:16
	v_cvt_pk_bf16_f32 v172, v94, v95
	v_cvt_pk_bf16_f32 v173, v96, v97
	v_cvt_pk_bf16_f32 v174, v90, v91
	v_cvt_pk_bf16_f32 v175, v92, v93
	v_mul_f32_e32 v238, v95, v95
	v_mul_f32_e32 v240, v91, v91
	v_fmac_f32_e32 v238, v94, v94
	v_mul_f32_e32 v239, v97, v97
	v_fmac_f32_e32 v240, v90, v90
	v_mul_f32_e32 v241, v93, v93
	v_fmac_f32_e32 v239, v96, v96
	v_fmac_f32_e32 v241, v92, v92
	global_store_dwordx4 v[246:247], v[172:175], off
	v_add_f32_e32 v238, v238, v239
	v_add_f32_e32 v240, v240, v241
	v_add_f32_e32 v237, v238, v240
	global_load_dwordx4 v[94:97], v[242:243], off offset:512
	global_load_dwordx4 v[90:93], v[242:243], off offset:528
	s_waitcnt vmcnt(20)
	v_pk_add_f32 v[86:87], v[86:87], v[126:127]
	v_pk_add_f32 v[88:89], v[88:89], v[128:129]
	v_pk_add_f32 v[82:83], v[82:83], v[122:123]
	v_pk_add_f32 v[84:85], v[84:85], v[124:125]
	global_store_dwordx4 v[244:245], v[86:89], off offset:512
	global_store_dwordx4 v[244:245], v[82:85], off offset:528
	v_cvt_pk_bf16_f32 v220, v86, v87
	v_cvt_pk_bf16_f32 v221, v88, v89
	v_cvt_pk_bf16_f32 v222, v82, v83
	v_cvt_pk_bf16_f32 v223, v84, v85
	v_mul_f32_e32 v238, v87, v87
	v_mul_f32_e32 v240, v83, v83
	v_fmac_f32_e32 v238, v86, v86
	v_mul_f32_e32 v239, v89, v89
	v_fmac_f32_e32 v240, v82, v82
	v_mul_f32_e32 v241, v85, v85
	v_fmac_f32_e32 v239, v88, v88
	v_fmac_f32_e32 v241, v84, v84
	global_store_dwordx4 v[246:247], v[220:223], off offset:256
	v_add_f32_e32 v238, v238, v239
	v_add_f32_e32 v240, v240, v241
	v_add_f32_e32 v238, v238, v240
	v_add_f32_e32 v237, v237, v238
	ds_bpermute_b32 v250, v235, v237
	s_mov_b32 s34, 0x90000
	v_lshl_add_u64 v[242:243], s[34:35], 0, v[178:179]
	global_load_dwordx4 v[86:89], v[242:243], off
	global_load_dwordx4 v[82:85], v[242:243], off offset:16
	s_waitcnt lgkmcnt(0)
	v_add_f32_e32 v237, v237, v250
	ds_bpermute_b32 v250, v236, v237
	s_waitcnt lgkmcnt(0)
	s_and_saveexec_b64 s[0:1], s[36:37]
	v_add_f32_e32 v237, v237, v250
	global_store_dword v[248:249], v237, off offset:2048
	s_or_b64 exec, exec, s[0:1]
	s_waitcnt vmcnt(20)
	v_pk_add_f32 v[78:79], v[78:79], v[118:119]
	v_pk_add_f32 v[80:81], v[80:81], v[120:121]
	v_pk_add_f32 v[74:75], v[74:75], v[114:115]
	v_pk_add_f32 v[76:77], v[76:77], v[116:117]
	s_mov_b32 s34, 0x30000
	v_lshl_add_u64 v[244:245], s[34:35], 0, v[176:177]
	s_mov_b32 s34, 0x18000
	v_lshl_add_u64 v[246:247], s[34:35], 0, v[166:167]
	global_store_dwordx4 v[244:245], v[78:81], off
	global_store_dwordx4 v[244:245], v[74:77], off offset:16
	v_cvt_pk_bf16_f32 v172, v78, v79
	v_cvt_pk_bf16_f32 v173, v80, v81
	v_cvt_pk_bf16_f32 v174, v74, v75
	v_cvt_pk_bf16_f32 v175, v76, v77
	v_mul_f32_e32 v238, v79, v79
	v_mul_f32_e32 v240, v75, v75
	v_fmac_f32_e32 v238, v78, v78
	v_mul_f32_e32 v239, v81, v81
	v_fmac_f32_e32 v240, v74, v74
	v_mul_f32_e32 v241, v77, v77
	v_fmac_f32_e32 v239, v80, v80
	v_fmac_f32_e32 v241, v76, v76
	global_store_dwordx4 v[246:247], v[172:175], off
	v_add_f32_e32 v238, v238, v239
	v_add_f32_e32 v240, v240, v241
	v_add_f32_e32 v237, v238, v240
	global_load_dwordx4 v[78:81], v[242:243], off offset:512
	global_load_dwordx4 v[74:77], v[242:243], off offset:528
	s_waitcnt vmcnt(20)
	v_pk_add_f32 v[70:71], v[70:71], v[110:111]
	v_pk_add_f32 v[72:73], v[72:73], v[112:113]
	v_pk_add_f32 v[66:67], v[66:67], v[106:107]
	v_pk_add_f32 v[68:69], v[68:69], v[108:109]
	global_store_dwordx4 v[244:245], v[70:73], off offset:512
	global_store_dwordx4 v[244:245], v[66:69], off offset:528
	v_cvt_pk_bf16_f32 v220, v70, v71
	v_cvt_pk_bf16_f32 v221, v72, v73
	v_cvt_pk_bf16_f32 v222, v66, v67
	v_cvt_pk_bf16_f32 v223, v68, v69
	v_mul_f32_e32 v238, v71, v71
	v_mul_f32_e32 v240, v67, v67
	v_fmac_f32_e32 v238, v70, v70
	v_mul_f32_e32 v239, v73, v73
	v_fmac_f32_e32 v240, v66, v66
	v_mul_f32_e32 v241, v69, v69
	v_fmac_f32_e32 v239, v72, v72
	v_fmac_f32_e32 v241, v68, v68
	global_store_dwordx4 v[246:247], v[220:223], off offset:256
	v_add_f32_e32 v238, v238, v239
	v_add_f32_e32 v240, v240, v241
	v_add_f32_e32 v238, v238, v240
	v_add_f32_e32 v237, v237, v238
	ds_bpermute_b32 v250, v235, v237
	s_mov_b32 s34, 0xa0000
	v_lshl_add_u64 v[242:243], s[34:35], 0, v[178:179]
	global_load_dwordx4 v[70:73], v[242:243], off
	global_load_dwordx4 v[66:69], v[242:243], off offset:16
	s_waitcnt lgkmcnt(0)
; __device__ __forceinline__ unsigned pk2hw(float lo, float hi) { unsigned r; asm("s_nop 1\n\tv_cvt_pk_bf16_f32 %0, %1, %2" : "=v"(r) : "v"(lo), "v"(hi)); return r; }
;     __device__ __forceinline__ void operator()(const f32x4 (&acc)[2][2][4][2], const Unit& u, int wr, int wc, int fr, int fq) const {
;         asm volatile("" : "+v"(fr), "+v"(fq));
;         const int row0 = u.pm * 256 + wr * 64 + fr, col0 = u.pn * 256 + wc * 32 + 8 * fq;
; #pragma unroll
;         for (int ai = 0; ai < 2; ++ai)
; #pragma unroll
;             for (int m = 0; m < 4; ++m) { const int row = row0 + ai * 128 + m * 16; float sq = 0.f;
; #pragma unroll
;                 for (int bj = 0; bj < 2; ++bj) { const size_t off = (size_t)row * D + col0 + bj * 128;
;                     const f32x4 x0 = *(const f32x4*)(xin + off) + acc[ai][bj][m][0], x1 = *(const f32x4*)(xin + off + 4) + acc[ai][bj][m][1];
;                     *(f32x4*)(xout + off) = x0; *(f32x4*)(xout + off + 4) = x1;
;                     u32x4 w; w.x = pk2hw(x0[0], x0[1]); w.y = pk2hw(x0[2], x0[3]); w.z = pk2hw(x1[0], x1[1]); w.w = pk2hw(x1[2], x1[3]); *(u32x4*)(xb + off) = w;
;                     sq += ((x0[0] * x0[0] + x0[1] * x0[1]) + (x0[2] * x0[2] + x0[3] * x0[3])) + ((x1[0] * x1[0] + x1[1] * x1[1]) + (x1[2] * x1[2] + x1[3] * x1[3])); }
;                 sq += __shfl_xor(sq, 16); sq += __shfl_xor(sq, 32);
;                 if (fq == 0) ssn[(size_t)row * 16 + u.pn * 4 + wc] = sq; }
;     }
	v_add_f32_e32 v237, v237, v250
	ds_bpermute_b32 v250, v236, v237
	s_waitcnt lgkmcnt(0)
	s_and_saveexec_b64 s[0:1], s[36:37]
	v_add_f32_e32 v237, v237, v250
	global_store_dword v[248:249], v237, off offset:3072
	s_or_b64 exec, exec, s[0:1]
	s_waitcnt vmcnt(20)
	v_pk_add_f32 v[62:63], v[62:63], v[102:103]
	v_pk_add_f32 v[64:65], v[64:65], v[104:105]
	v_pk_add_f32 v[58:59], v[58:59], v[98:99]
	v_pk_add_f32 v[60:61], v[60:61], v[100:101]
	s_mov_b32 s34, 0x80000
	v_lshl_add_u64 v[244:245], s[34:35], 0, v[176:177]
	s_mov_b32 s34, 0x40000
	v_lshl_add_u64 v[246:247], s[34:35], 0, v[166:167]
	global_store_dwordx4 v[244:245], v[62:65], off
	global_store_dwordx4 v[244:245], v[58:61], off offset:16
	v_cvt_pk_bf16_f32 v172, v62, v63
	v_cvt_pk_bf16_f32 v173, v64, v65
	v_cvt_pk_bf16_f32 v174, v58, v59
	v_cvt_pk_bf16_f32 v175, v60, v61
	v_mul_f32_e32 v238, v63, v63
	v_mul_f32_e32 v240, v59, v59
	v_fmac_f32_e32 v238, v62, v62
	v_mul_f32_e32 v239, v65, v65
	v_fmac_f32_e32 v240, v58, v58
	v_mul_f32_e32 v241, v61, v61
	v_fmac_f32_e32 v239, v64, v64
	v_fmac_f32_e32 v241, v60, v60
	global_store_dwordx4 v[246:247], v[172:175], off
	v_add_f32_e32 v238, v238, v239
	v_add_f32_e32 v240, v240, v241
	v_add_f32_e32 v237, v238, v240
	global_load_dwordx4 v[62:65], v[242:243], off offset:512
	global_load_dwordx4 v[58:61], v[242:243], off offset:528
	s_waitcnt vmcnt(20)
	v_pk_add_f32 v[54:55], v[54:55], v[94:95]
	v_pk_add_f32 v[56:57], v[56:57], v[96:97]
	v_pk_add_f32 v[50:51], v[50:51], v[90:91]
	v_pk_add_f32 v[52:53], v[52:53], v[92:93]
	global_store_dwordx4 v[244:245], v[54:57], off offset:512
	global_store_dwordx4 v[244:245], v[50:53], off offset:528
	v_cvt_pk_bf16_f32 v220, v54, v55
	v_cvt_pk_bf16_f32 v221, v56, v57
	v_cvt_pk_bf16_f32 v222, v50, v51
	v_cvt_pk_bf16_f32 v223, v52, v53
	v_mul_f32_e32 v238, v55, v55
	v_mul_f32_e32 v240, v51, v51
	v_fmac_f32_e32 v238, v54, v54
	v_mul_f32_e32 v239, v57, v57
	v_fmac_f32_e32 v240, v50, v50
	v_mul_f32_e32 v241, v53, v53
	v_fmac_f32_e32 v239, v56, v56
	v_fmac_f32_e32 v241, v52, v52
	global_store_dwordx4 v[246:247], v[220:223], off offset:256
	v_add_f32_e32 v238, v238, v239
	v_add_f32_e32 v240, v240, v241
	v_add_f32_e32 v238, v238, v240
	v_add_f32_e32 v237, v237, v238
	ds_bpermute_b32 v250, v235, v237
	s_mov_b32 s34, 0xb0000
	v_lshl_add_u64 v[242:243], s[34:35], 0, v[178:179]
	global_load_dwordx4 v[54:57], v[242:243], off
	global_load_dwordx4 v[50:53], v[242:243], off offset:16
	s_waitcnt lgkmcnt(0)
	v_add_f32_e32 v237, v237, v250
	ds_bpermute_b32 v250, v236, v237
	s_waitcnt lgkmcnt(0)
	s_and_saveexec_b64 s[0:1], s[36:37]
	v_add_f32_e32 v237, v237, v250
	global_store_dword v[144:145], v237, off
	s_or_b64 exec, exec, s[0:1]
	s_waitcnt vmcnt(20)
	v_pk_add_f32 v[46:47], v[46:47], v[86:87]
	v_pk_add_f32 v[48:49], v[48:49], v[88:89]
	v_pk_add_f32 v[42:43], v[42:43], v[82:83]
	v_pk_add_f32 v[44:45], v[44:45], v[84:85]
	s_mov_b32 s34, 0x90000
	v_lshl_add_u64 v[244:245], s[34:35], 0, v[176:177]
	s_mov_b32 s34, 0x48000
	v_lshl_add_u64 v[246:247], s[34:35], 0, v[166:167]
	global_store_dwordx4 v[244:245], v[46:49], off
	global_store_dwordx4 v[244:245], v[42:45], off offset:16
	v_cvt_pk_bf16_f32 v172, v46, v47
	v_cvt_pk_bf16_f32 v173, v48, v49
	v_cvt_pk_bf16_f32 v174, v42, v43
	v_cvt_pk_bf16_f32 v175, v44, v45
	v_mul_f32_e32 v238, v47, v47
	v_mul_f32_e32 v240, v43, v43
	v_fmac_f32_e32 v238, v46, v46
	v_mul_f32_e32 v239, v49, v49
	v_fmac_f32_e32 v240, v42, v42
	v_mul_f32_e32 v241, v45, v45
	v_fmac_f32_e32 v239, v48, v48
	v_fmac_f32_e32 v241, v44, v44
	global_store_dwordx4 v[246:247], v[172:175], off
	v_add_f32_e32 v238, v238, v239
	v_add_f32_e32 v240, v240, v241
	v_add_f32_e32 v237, v238, v240
	global_load_dwordx4 v[46:49], v[242:243], off offset:512
	global_load_dwordx4 v[42:45], v[242:243], off offset:528
	s_waitcnt vmcnt(20)
	v_pk_add_f32 v[38:39], v[38:39], v[78:79]
	v_pk_add_f32 v[40:41], v[40:41], v[80:81]
	v_pk_add_f32 v[34:35], v[34:35], v[74:75]
	v_pk_add_f32 v[36:37], v[36:37], v[76:77]
	global_store_dwordx4 v[244:245], v[38:41], off offset:512
	global_store_dwordx4 v[244:245], v[34:37], off offset:528
	v_cvt_pk_bf16_f32 v220, v38, v39
	v_cvt_pk_bf16_f32 v221, v40, v41
	v_cvt_pk_bf16_f32 v222, v34, v35
	v_cvt_pk_bf16_f32 v223, v36, v37
	v_mul_f32_e32 v238, v39, v39
	v_mul_f32_e32 v240, v35, v35
	v_fmac_f32_e32 v238, v38, v38
	v_mul_f32_e32 v239, v41, v41
	v_fmac_f32_e32 v240, v34, v34
	v_mul_f32_e32 v241, v37, v37
	v_fmac_f32_e32 v239, v40, v40
	v_fmac_f32_e32 v241, v36, v36
	global_store_dwordx4 v[246:247], v[220:223], off offset:256
	v_add_f32_e32 v238, v238, v239
	v_add_f32_e32 v240, v240, v241
	v_add_f32_e32 v238, v238, v240
	v_add_f32_e32 v237, v237, v238
	ds_bpermute_b32 v250, v235, v237
	s_waitcnt lgkmcnt(0)
; __device__ __forceinline__ unsigned pk2hw(float lo, float hi) { unsigned r; asm("s_nop 1\n\tv_cvt_pk_bf16_f32 %0, %1, %2" : "=v"(r) : "v"(lo), "v"(hi)); return r; }
;     __device__ __forceinline__ void operator()(const f32x4 (&acc)[2][2][4][2], const Unit& u, int wr, int wc, int fr, int fq) const {
;         asm volatile("" : "+v"(fr), "+v"(fq));
;         const int row0 = u.pm * 256 + wr * 64 + fr, col0 = u.pn * 256 + wc * 32 + 8 * fq;
; #pragma unroll
;         for (int ai = 0; ai < 2; ++ai)
; #pragma unroll
;             for (int m = 0; m < 4; ++m) { const int row = row0 + ai * 128 + m * 16; float sq = 0.f;
; #pragma unroll
;                 for (int bj = 0; bj < 2; ++bj) { const size_t off = (size_t)row * D + col0 + bj * 128;
;                     const f32x4 x0 = *(const f32x4*)(xin + off) + acc[ai][bj][m][0], x1 = *(const f32x4*)(xin + off + 4) + acc[ai][bj][m][1];
;                     *(f32x4*)(xout + off) = x0; *(f32x4*)(xout + off + 4) = x1;
;                     u32x4 w; w.x = pk2hw(x0[0], x0[1]); w.y = pk2hw(x0[2], x0[3]); w.z = pk2hw(x1[0], x1[1]); w.w = pk2hw(x1[2], x1[3]); *(u32x4*)(xb + off) = w;
;                     sq += ((x0[0] * x0[0] + x0[1] * x0[1]) + (x0[2] * x0[2] + x0[3] * x0[3])) + ((x1[0] * x1[0] + x1[1] * x1[1]) + (x1[2] * x1[2] + x1[3] * x1[3])); }
;                 sq += __shfl_xor(sq, 16); sq += __shfl_xor(sq, 32);
;                 if (fq == 0) ssn[(size_t)row * 16 + u.pn * 4 + wc] = sq; }
;     }
	v_add_f32_e32 v237, v237, v250
	ds_bpermute_b32 v250, v236, v237
	s_waitcnt lgkmcnt(0)
	s_and_saveexec_b64 s[0:1], s[36:37]
	v_add_f32_e32 v237, v237, v250
	global_store_dword v[144:145], v237, off offset:1024
	s_or_b64 exec, exec, s[0:1]
	s_waitcnt vmcnt(18)
	v_pk_add_f32 v[30:31], v[30:31], v[70:71]
	v_pk_add_f32 v[32:33], v[32:33], v[72:73]
	v_pk_add_f32 v[26:27], v[26:27], v[66:67]
	v_pk_add_f32 v[28:29], v[28:29], v[68:69]
	s_mov_b32 s34, 0xa0000
	v_lshl_add_u64 v[244:245], s[34:35], 0, v[176:177]
	s_mov_b32 s34, 0x50000
	v_lshl_add_u64 v[246:247], s[34:35], 0, v[166:167]
	global_store_dwordx4 v[244:245], v[30:33], off
	global_store_dwordx4 v[244:245], v[26:29], off offset:16
	v_cvt_pk_bf16_f32 v172, v30, v31
	v_cvt_pk_bf16_f32 v173, v32, v33
	v_cvt_pk_bf16_f32 v174, v26, v27
	v_cvt_pk_bf16_f32 v175, v28, v29
	v_mul_f32_e32 v238, v31, v31
	v_mul_f32_e32 v240, v27, v27
	v_fmac_f32_e32 v238, v30, v30
	v_mul_f32_e32 v239, v33, v33
	v_fmac_f32_e32 v240, v26, v26
	v_mul_f32_e32 v241, v29, v29
	v_fmac_f32_e32 v239, v32, v32
	v_fmac_f32_e32 v241, v28, v28
	global_store_dwordx4 v[246:247], v[172:175], off
	v_add_f32_e32 v238, v238, v239
	v_add_f32_e32 v240, v240, v241
	v_add_f32_e32 v237, v238, v240
	s_waitcnt vmcnt(16)
	v_pk_add_f32 v[22:23], v[22:23], v[62:63]
	v_pk_add_f32 v[24:25], v[24:25], v[64:65]
	v_pk_add_f32 v[18:19], v[18:19], v[58:59]
	v_pk_add_f32 v[20:21], v[20:21], v[60:61]
	global_store_dwordx4 v[244:245], v[22:25], off offset:512
	global_store_dwordx4 v[244:245], v[18:21], off offset:528
	v_cvt_pk_bf16_f32 v220, v22, v23
	v_cvt_pk_bf16_f32 v221, v24, v25
	v_cvt_pk_bf16_f32 v222, v18, v19
	v_cvt_pk_bf16_f32 v223, v20, v21
	v_mul_f32_e32 v238, v23, v23
	v_mul_f32_e32 v240, v19, v19
	v_fmac_f32_e32 v238, v22, v22
	v_mul_f32_e32 v239, v25, v25
	v_fmac_f32_e32 v240, v18, v18
	v_mul_f32_e32 v241, v21, v21
	v_fmac_f32_e32 v239, v24, v24
	v_fmac_f32_e32 v241, v20, v20
	global_store_dwordx4 v[246:247], v[220:223], off offset:256
	v_add_f32_e32 v238, v238, v239
	v_add_f32_e32 v240, v240, v241
	v_add_f32_e32 v238, v238, v240
	v_add_f32_e32 v237, v237, v238
	ds_bpermute_b32 v250, v235, v237
	s_waitcnt lgkmcnt(0)
	v_add_f32_e32 v237, v237, v250
	ds_bpermute_b32 v250, v236, v237
	s_waitcnt lgkmcnt(0)
	s_and_saveexec_b64 s[0:1], s[36:37]
	v_add_f32_e32 v237, v237, v250
	global_store_dword v[144:145], v237, off offset:2048
	s_or_b64 exec, exec, s[0:1]
	s_waitcnt vmcnt(14)
	v_pk_add_f32 v[14:15], v[14:15], v[54:55]
	v_pk_add_f32 v[16:17], v[16:17], v[56:57]
	v_pk_add_f32 v[10:11], v[10:11], v[50:51]
	v_pk_add_f32 v[12:13], v[12:13], v[52:53]
	s_mov_b32 s34, 0xb0000
	v_lshl_add_u64 v[244:245], s[34:35], 0, v[176:177]
	s_mov_b32 s34, 0x58000
	v_lshl_add_u64 v[246:247], s[34:35], 0, v[166:167]
	global_store_dwordx4 v[244:245], v[14:17], off
	global_store_dwordx4 v[244:245], v[10:13], off offset:16
	v_cvt_pk_bf16_f32 v172, v14, v15
	v_cvt_pk_bf16_f32 v173, v16, v17
	v_cvt_pk_bf16_f32 v174, v10, v11
	v_cvt_pk_bf16_f32 v175, v12, v13
	v_mul_f32_e32 v238, v15, v15
	v_mul_f32_e32 v240, v11, v11
	v_fmac_f32_e32 v238, v14, v14
	v_mul_f32_e32 v239, v17, v17
	v_fmac_f32_e32 v240, v10, v10
	v_mul_f32_e32 v241, v13, v13
	v_fmac_f32_e32 v239, v16, v16
	v_fmac_f32_e32 v241, v12, v12
	global_store_dwordx4 v[246:247], v[172:175], off
	v_add_f32_e32 v238, v238, v239
	v_add_f32_e32 v240, v240, v241
	v_add_f32_e32 v237, v238, v240
	s_waitcnt vmcnt(12)
	v_pk_add_f32 v[6:7], v[6:7], v[46:47]
	v_pk_add_f32 v[8:9], v[8:9], v[48:49]
	v_pk_add_f32 v[2:3], v[2:3], v[42:43]
	v_pk_add_f32 v[4:5], v[4:5], v[44:45]
	global_store_dwordx4 v[244:245], v[6:9], off offset:512
	global_store_dwordx4 v[244:245], v[2:5], off offset:528
	v_cvt_pk_bf16_f32 v220, v6, v7
	v_cvt_pk_bf16_f32 v221, v8, v9
	v_cvt_pk_bf16_f32 v222, v2, v3
	v_cvt_pk_bf16_f32 v223, v4, v5
	v_mul_f32_e32 v238, v7, v7
	v_mul_f32_e32 v240, v3, v3
	v_fmac_f32_e32 v238, v6, v6
	v_mul_f32_e32 v239, v9, v9
	v_fmac_f32_e32 v240, v2, v2
	v_mul_f32_e32 v241, v5, v5
	v_fmac_f32_e32 v239, v8, v8
	v_fmac_f32_e32 v241, v4, v4
	global_store_dwordx4 v[246:247], v[220:223], off offset:256
	v_add_f32_e32 v238, v238, v239
	v_add_f32_e32 v240, v240, v241
	v_add_f32_e32 v238, v238, v240
	v_add_f32_e32 v237, v237, v238
	ds_bpermute_b32 v250, v235, v237
	s_waitcnt lgkmcnt(0)
	v_add_f32_e32 v237, v237, v250
	ds_bpermute_b32 v250, v236, v237
	s_waitcnt lgkmcnt(0)
	s_and_saveexec_b64 s[0:1], s[36:37]
	v_add_f32_e32 v237, v237, v250
	global_store_dword v[144:145], v237, off offset:3072
	s_or_b64 exec, exec, s[0:1]
	s_andn2_b64 vcc, exec, s[6:7]
	s_mov_b64 s[0:1], -1
	s_cbranch_vccnz .LBB0_240
	s_andn2_b64 vcc, exec, s[10:11]
	s_cbranch_vccnz .LBB0_239
	s_barrier
	s_branch .LBB0_239

; __device__ __forceinline__ void preproc_phase(Frame& F, int layer, int b, int cu_lo, int ncu) {
;     ...
;             for (int r = 0; r < 7; ++r) { const int t = t0 - 3 + r;
;                 if (t >= 0) { const u32x2 w = *(const u32x2*)(proj + (size_t)t * NP + C_MX + cc); xm[r][0] = bflo(w.x); xm[r][1] = bfhi(w.x); xm[r][2] = bflo(w.y); xm[r][3] = bfhi(w.y); }
;                 else { xm[r][0] = xm[r][1] = xm[r][2] = xm[r][3] = 0.f; } }
;     ...
;         for (int a = 0; a < 4; ++a)
; #pragma unroll
;             for (int hh = 0; hh < 4; ++hh) { ai[a][hh] = wave_sum(ai[a][hh]); af[a][hh] = wave_sum(af[a][hh]); }
.LBB0_299:
	v_mov_b32_e32 v2, s78
	v_mov_b32_e32 v6, s66
	v_readfirstlane_b32 s0, v2
	v_mov_b32_e32 v2, s33
	v_mov_b32_e32 v10, s67
	v_mov_b32_e32 v14, s80
	s_waitcnt lgkmcnt(0)
	ds_read2_b64 v[2:5], v2 offset1:1
	ds_read2_b64 v[6:9], v6 offset1:1
	ds_read2_b64 v[10:13], v10 offset1:1
	ds_read_b64 v[14:15], v14
	v_mov_b32_e32 v18, 0
	v_mov_b32_e32 v19, 0
	v_mov_b32_e32 v20, 0
	v_mov_b32_e32 v21, 0
	v_mov_b32_e32 v22, 0
	v_mov_b32_e32 v23, 0
	v_mov_b32_e32 v24, 0
	v_mov_b32_e32 v25, 0
	v_mov_b32_e32 v26, 0
	v_mov_b32_e32 v27, 0
	v_mov_b32_e32 v28, 0
	v_mov_b32_e32 v29, 0
	v_mov_b32_e32 v30, 0
	v_mov_b32_e32 v31, 0
	s_andn2_b64 vcc, exec, s[90:91]
	s_cbranch_vccnz .Lxm_skipA_a
	v_lshl_add_u64 v[16:17], s[76:77], 0, v[0:1]
	global_load_dwordx2 v[18:19], v[16:17], off
	v_lshl_add_u64 v[16:17], s[72:73], 0, v[0:1]
	global_load_dwordx2 v[20:21], v[16:17], off
	v_lshl_add_u64 v[16:17], s[60:61], 0, v[0:1]
	global_load_dwordx2 v[22:23], v[16:17], off
.Lxm_skipA_a:
	s_andn2_b64 vcc, exec, s[94:95]
	s_cbranch_vccnz .Lxm_skipB_a
	v_lshl_add_u64 v[16:17], s[52:53], 0, v[0:1]
	global_load_dwordx2 v[24:25], v[16:17], off
	v_lshl_add_u64 v[16:17], s[42:43], 0, v[0:1]
	global_load_dwordx2 v[26:27], v[16:17], off
	v_lshl_add_u64 v[16:17], s[40:41], 0, v[0:1]
	global_load_dwordx2 v[28:29], v[16:17], off
	v_lshl_add_u64 v[16:17], s[38:39], 0, v[0:1]
	global_load_dwordx2 v[30:31], v[16:17], off
.Lxm_skipB_a:
	s_waitcnt vmcnt(0) lgkmcnt(0)
	v_lshlrev_b32_e32 v148, 16, v18
	v_and_b32_e32 v144, 0xffff0000, v18
	v_lshlrev_b32_e32 v138, 16, v19
	v_and_b32_e32 v136, 0xffff0000, v19
	v_lshlrev_b32_e32 v149, 16, v20
	v_and_b32_e32 v145, 0xffff0000, v20
	v_lshlrev_b32_e32 v139, 16, v21
	v_and_b32_e32 v137, 0xffff0000, v21
	v_lshlrev_b32_e32 v124, 16, v22
	v_and_b32_e32 v130, 0xffff0000, v22
	v_lshlrev_b32_e32 v128, 16, v23
	v_and_b32_e32 v126, 0xffff0000, v23
	v_lshlrev_b32_e32 v125, 16, v24
	v_and_b32_e32 v131, 0xffff0000, v24
	v_lshlrev_b32_e32 v129, 16, v25
	v_and_b32_e32 v127, 0xffff0000, v25
	v_lshlrev_b32_e32 v133, 16, v26
	v_and_b32_e32 v143, 0xffff0000, v26
	v_lshlrev_b32_e32 v141, 16, v27
	v_and_b32_e32 v135, 0xffff0000, v27
	v_lshlrev_b32_e32 v79, 16, v28
	v_and_b32_e32 v81, 0xffff0000, v28
	v_lshlrev_b32_e32 v77, 16, v29
	v_and_b32_e32 v75, 0xffff0000, v29
	v_lshlrev_b32_e32 v63, 16, v30
	v_and_b32_e32 v69, 0xffff0000, v30
	v_lshlrev_b32_e32 v67, 16, v31
	v_and_b32_e32 v65, 0xffff0000, v31
	v_cndmask_b32_e64 v16, 0, 1, s[94:95]
	v_cmp_ne_u32_e64 s[10:11], 1, v16
	s_nop 1
	s_and_b64 vcc, exec, s[10:11]
	s_branch .LBB0_298
.LBB0_313:
	ds_bpermute_b32 v6, v235, v121
	ds_bpermute_b32 v7, v235, v119
	ds_bpermute_b32 v10, v235, v116
	ds_bpermute_b32 v2, v235, v120
	ds_bpermute_b32 v3, v235, v118
	s_waitcnt lgkmcnt(4)
	v_add_f32_e32 v6, v121, v6
	ds_bpermute_b32 v8, v236, v6
	s_waitcnt lgkmcnt(4)
	v_add_f32_e32 v7, v119, v7
	ds_bpermute_b32 v9, v236, v7
	s_waitcnt lgkmcnt(4)
	v_add_f32_e32 v10, v116, v10
	ds_bpermute_b32 v11, v236, v10
	s_waitcnt lgkmcnt(2)
	v_add_f32_e32 v6, v6, v8
	ds_bpermute_b32 v8, v237, v6
	s_waitcnt lgkmcnt(2)
	v_add_f32_e32 v7, v7, v9
	ds_bpermute_b32 v9, v237, v7
	s_waitcnt lgkmcnt(2)
	v_add_f32_e32 v10, v10, v11
	ds_bpermute_b32 v11, v237, v10
	s_waitcnt lgkmcnt(2)
	v_add_f32_e32 v6, v6, v8
	ds_bpermute_b32 v8, v238, v6
	s_waitcnt lgkmcnt(2)
	v_add_f32_e32 v7, v7, v9
	ds_bpermute_b32 v9, v238, v7
	v_add_f32_e32 v2, v120, v2
	v_add_f32_e32 v3, v118, v3
	s_waitcnt lgkmcnt(1)
	v_add_f32_e32 v6, v6, v8
	ds_bpermute_b32 v8, v239, v6
	s_waitcnt lgkmcnt(1)
	v_add_f32_e32 v9, v7, v9
	ds_bpermute_b32 v12, v239, v9
	ds_bpermute_b32 v4, v236, v2
	ds_bpermute_b32 v5, v236, v3
	s_waitcnt lgkmcnt(3)
	v_add_f32_e32 v6, v6, v8
	ds_bpermute_b32 v8, v235, v114
	s_waitcnt lgkmcnt(3)
	v_add_f32_e32 v36, v9, v12
	v_add_f32_e32 v9, v10, v11
	ds_bpermute_b32 v10, v238, v9
	ds_bpermute_b32 v12, v235, v117
	s_waitcnt lgkmcnt(2)
	v_add_f32_e32 v8, v114, v8
	ds_bpermute_b32 v13, v236, v8
	v_add_f32_e32 v2, v2, v4
	s_waitcnt lgkmcnt(2)
	v_add_f32_e32 v9, v9, v10
	ds_bpermute_b32 v10, v239, v9
	s_waitcnt lgkmcnt(2)
	v_add_f32_e32 v12, v117, v12
	s_waitcnt lgkmcnt(1)
	v_add_f32_e32 v8, v8, v13
	ds_bpermute_b32 v11, v237, v8
	ds_bpermute_b32 v13, v236, v12
	s_waitcnt lgkmcnt(2)
	v_add_f32_e32 v35, v9, v10
	ds_bpermute_b32 v9, v235, v115
	v_add_f32_e32 v3, v3, v5
	s_waitcnt lgkmcnt(2)
	v_add_f32_e32 v8, v8, v11
	ds_bpermute_b32 v11, v238, v8
	ds_bpermute_b32 v4, v237, v2
	s_waitcnt lgkmcnt(2)
	v_add_f32_e32 v9, v115, v9
	ds_bpermute_b32 v5, v237, v3
	ds_bpermute_b32 v7, v240, v6
	s_waitcnt lgkmcnt(3)
	v_add_f32_e32 v8, v8, v11
	v_add_f32_e32 v11, v12, v13
	ds_bpermute_b32 v10, v239, v8
	ds_bpermute_b32 v12, v237, v11
	ds_bpermute_b32 v13, v236, v9
	s_waitcnt lgkmcnt(5)
	v_add_f32_e32 v2, v2, v4
	s_waitcnt lgkmcnt(4)
	v_add_f32_e32 v3, v3, v5
	s_waitcnt lgkmcnt(2)
	v_add_f32_e32 v34, v8, v10
	s_waitcnt lgkmcnt(1)
	v_add_f32_e32 v8, v11, v12
	ds_bpermute_b32 v10, v238, v8
	s_waitcnt lgkmcnt(1)
	v_add_f32_e32 v9, v9, v13
	ds_bpermute_b32 v11, v237, v9
	ds_bpermute_b32 v12, v235, v112
	ds_bpermute_b32 v4, v238, v2
	s_waitcnt lgkmcnt(3)
	v_add_f32_e32 v8, v8, v10
	ds_bpermute_b32 v10, v239, v8
	s_waitcnt lgkmcnt(3)
	v_add_f32_e32 v9, v9, v11
	s_waitcnt lgkmcnt(2)
	v_add_f32_e32 v12, v112, v12
	ds_bpermute_b32 v11, v238, v9
	ds_bpermute_b32 v13, v236, v12
	s_waitcnt lgkmcnt(2)
	v_add_f32_e32 v33, v8, v10
	ds_bpermute_b32 v8, v235, v110
	ds_bpermute_b32 v5, v238, v3
	s_waitcnt lgkmcnt(3)
	v_add_f32_e32 v9, v9, v11
	s_waitcnt lgkmcnt(2)
	v_add_f32_e32 v11, v12, v13
	ds_bpermute_b32 v10, v239, v9
	ds_bpermute_b32 v12, v237, v11
	s_waitcnt lgkmcnt(3)
; __device__ __forceinline__ void preproc_phase(Frame& F, int layer, int b, int cu_lo, int ncu) {
;     ...
;         for (int a = 0; a < 4; ++a)
; #pragma unroll
;             for (int hh = 0; hh < 4; ++hh) { ai[a][hh] = wave_sum(ai[a][hh]); af[a][hh] = wave_sum(af[a][hh]); }
	v_add_f32_e32 v8, v110, v8
	ds_bpermute_b32 v13, v236, v8
	v_add_f32_e32 v2, v2, v4
	s_waitcnt lgkmcnt(2)
	v_add_f32_e32 v32, v9, v10
	s_waitcnt lgkmcnt(1)
	v_add_f32_e32 v9, v11, v12
	ds_bpermute_b32 v10, v238, v9
	s_waitcnt lgkmcnt(1)
	v_add_f32_e32 v8, v8, v13
	ds_bpermute_b32 v11, v237, v8
	ds_bpermute_b32 v12, v235, v113
	v_add_f32_e32 v3, v3, v5
	s_waitcnt lgkmcnt(2)
	v_add_f32_e32 v9, v9, v10
	ds_bpermute_b32 v10, v239, v9
	s_waitcnt lgkmcnt(2)
	v_add_f32_e32 v8, v8, v11
	s_waitcnt lgkmcnt(1)
	v_add_f32_e32 v12, v113, v12
	ds_bpermute_b32 v11, v238, v8
	ds_bpermute_b32 v13, v236, v12
	s_waitcnt lgkmcnt(2)
	v_add_f32_e32 v31, v9, v10
	ds_bpermute_b32 v9, v235, v111
	ds_bpermute_b32 v4, v239, v2
	s_waitcnt lgkmcnt(3)
	v_add_f32_e32 v8, v8, v11
	s_waitcnt lgkmcnt(2)
	v_add_f32_e32 v11, v12, v13
	ds_bpermute_b32 v10, v239, v8
	ds_bpermute_b32 v12, v237, v11
	s_waitcnt lgkmcnt(3)
	v_add_f32_e32 v9, v111, v9
	ds_bpermute_b32 v13, v236, v9
	ds_bpermute_b32 v5, v239, v3
	s_waitcnt lgkmcnt(3)
	v_add_f32_e32 v30, v8, v10
	s_waitcnt lgkmcnt(2)
	v_add_f32_e32 v8, v11, v12
	ds_bpermute_b32 v10, v238, v8
	s_waitcnt lgkmcnt(2)
	v_add_f32_e32 v9, v9, v13
	ds_bpermute_b32 v11, v237, v9
	ds_bpermute_b32 v12, v235, v108
	v_add_f32_e32 v2, v2, v4
	s_waitcnt lgkmcnt(2)
	v_add_f32_e32 v8, v8, v10
	ds_bpermute_b32 v10, v239, v8
	s_waitcnt lgkmcnt(2)
	v_add_f32_e32 v9, v9, v11
	s_waitcnt lgkmcnt(1)
	v_add_f32_e32 v12, v108, v12
	ds_bpermute_b32 v11, v238, v9
	ds_bpermute_b32 v13, v236, v12
	s_waitcnt lgkmcnt(2)
	v_add_f32_e32 v29, v8, v10
	ds_bpermute_b32 v8, v235, v106
	v_add_f32_e32 v4, v3, v5
	s_waitcnt lgkmcnt(2)
	v_add_f32_e32 v9, v9, v11
	s_waitcnt lgkmcnt(1)
	v_add_f32_e32 v11, v12, v13
	ds_bpermute_b32 v10, v239, v9
	ds_bpermute_b32 v12, v237, v11
	s_waitcnt lgkmcnt(2)
	v_add_f32_e32 v8, v106, v8
	ds_bpermute_b32 v13, v236, v8
	ds_bpermute_b32 v3, v240, v2
	s_waitcnt lgkmcnt(3)
	v_add_f32_e32 v28, v9, v10
	s_waitcnt lgkmcnt(2)
	v_add_f32_e32 v9, v11, v12
	ds_bpermute_b32 v10, v238, v9
	s_waitcnt lgkmcnt(2)
	v_add_f32_e32 v8, v8, v13
	ds_bpermute_b32 v11, v237, v8
	ds_bpermute_b32 v12, v235, v109
	ds_bpermute_b32 v5, v240, v4
	s_waitcnt lgkmcnt(3)
	v_add_f32_e32 v9, v9, v10
	ds_bpermute_b32 v10, v239, v9
	s_waitcnt lgkmcnt(3)
	v_add_f32_e32 v8, v8, v11
	s_waitcnt lgkmcnt(2)
	v_add_f32_e32 v12, v109, v12
	ds_bpermute_b32 v11, v238, v8
	ds_bpermute_b32 v13, v236, v12
	s_waitcnt lgkmcnt(2)
	v_add_f32_e32 v27, v9, v10
	ds_bpermute_b32 v9, v235, v107
	ds_bpermute_b32 v37, v240, v36
	s_waitcnt lgkmcnt(3)
	v_add_f32_e32 v8, v8, v11
	s_waitcnt lgkmcnt(2)
	v_add_f32_e32 v11, v12, v13
	ds_bpermute_b32 v10, v239, v8
	ds_bpermute_b32 v12, v237, v11
	s_waitcnt lgkmcnt(3)
	v_add_f32_e32 v9, v107, v9
	ds_bpermute_b32 v13, v236, v9
	ds_bpermute_b32 v38, v240, v35
	s_waitcnt lgkmcnt(3)
	v_add_f32_e32 v26, v8, v10
	s_waitcnt lgkmcnt(2)
	v_add_f32_e32 v8, v11, v12
	ds_bpermute_b32 v10, v238, v8
	s_waitcnt lgkmcnt(2)
	v_add_f32_e32 v9, v9, v13
	ds_bpermute_b32 v11, v237, v9
	ds_bpermute_b32 v12, v235, v104
	ds_bpermute_b32 v39, v240, v34
	s_waitcnt lgkmcnt(3)
	v_add_f32_e32 v8, v8, v10
	ds_bpermute_b32 v10, v239, v8
	s_waitcnt lgkmcnt(3)
	v_add_f32_e32 v9, v9, v11
	s_waitcnt lgkmcnt(2)
	v_add_f32_e32 v12, v104, v12
	ds_bpermute_b32 v11, v238, v9
	ds_bpermute_b32 v13, v236, v12
	s_waitcnt lgkmcnt(2)
	v_add_f32_e32 v25, v8, v10
	ds_bpermute_b32 v8, v235, v102
	ds_bpermute_b32 v40, v240, v33
	s_waitcnt lgkmcnt(3)
	v_add_f32_e32 v9, v9, v11
	s_waitcnt lgkmcnt(2)
	v_add_f32_e32 v11, v12, v13
	ds_bpermute_b32 v10, v239, v9
	ds_bpermute_b32 v12, v237, v11
	s_waitcnt lgkmcnt(3)
	v_add_f32_e32 v8, v102, v8
	ds_bpermute_b32 v13, v236, v8
	ds_bpermute_b32 v41, v240, v32
	s_waitcnt lgkmcnt(3)
	v_add_f32_e32 v24, v9, v10
	s_waitcnt lgkmcnt(2)
	v_add_f32_e32 v9, v11, v12
	ds_bpermute_b32 v10, v238, v9
	s_waitcnt lgkmcnt(2)
	v_add_f32_e32 v8, v8, v13
	ds_bpermute_b32 v11, v237, v8
	ds_bpermute_b32 v12, v235, v105
	ds_bpermute_b32 v42, v240, v31
	s_waitcnt lgkmcnt(3)
	v_add_f32_e32 v9, v9, v10
	ds_bpermute_b32 v10, v239, v9
	s_waitcnt lgkmcnt(3)
	v_add_f32_e32 v8, v8, v11
	s_waitcnt lgkmcnt(2)
	v_add_f32_e32 v12, v105, v12
	ds_bpermute_b32 v11, v238, v8
	ds_bpermute_b32 v13, v236, v12
	s_waitcnt lgkmcnt(2)
	v_add_f32_e32 v23, v9, v10
	ds_bpermute_b32 v9, v235, v103
	ds_bpermute_b32 v43, v240, v30
	s_waitcnt lgkmcnt(3)
	v_add_f32_e32 v8, v8, v11
	s_waitcnt lgkmcnt(2)
	v_add_f32_e32 v11, v12, v13
	ds_bpermute_b32 v10, v239, v8
	ds_bpermute_b32 v12, v237, v11
	s_waitcnt lgkmcnt(3)
	v_add_f32_e32 v9, v103, v9
	ds_bpermute_b32 v13, v236, v9
	ds_bpermute_b32 v44, v240, v29
	s_waitcnt lgkmcnt(3)
	v_add_f32_e32 v22, v8, v10
	s_waitcnt lgkmcnt(2)
	v_add_f32_e32 v8, v11, v12
	ds_bpermute_b32 v10, v238, v8
	s_waitcnt lgkmcnt(2)
	v_add_f32_e32 v9, v9, v13
	ds_bpermute_b32 v11, v237, v9
	ds_bpermute_b32 v12, v235, v100
	ds_bpermute_b32 v45, v240, v28
	s_waitcnt lgkmcnt(3)
	v_add_f32_e32 v8, v8, v10
	ds_bpermute_b32 v10, v239, v8
	s_waitcnt lgkmcnt(3)
	v_add_f32_e32 v9, v9, v11
	s_waitcnt lgkmcnt(2)
	v_add_f32_e32 v12, v100, v12
	ds_bpermute_b32 v11, v238, v9
	ds_bpermute_b32 v13, v236, v12
	s_waitcnt lgkmcnt(2)
	v_add_f32_e32 v21, v8, v10
	ds_bpermute_b32 v8, v235, v98
	ds_bpermute_b32 v46, v240, v27
	s_waitcnt lgkmcnt(3)
	v_add_f32_e32 v9, v9, v11
	s_waitcnt lgkmcnt(2)
	v_add_f32_e32 v11, v12, v13
	ds_bpermute_b32 v10, v239, v9
	ds_bpermute_b32 v12, v237, v11
	s_waitcnt lgkmcnt(3)
	v_add_f32_e32 v8, v98, v8
	ds_bpermute_b32 v13, v236, v8
	ds_bpermute_b32 v47, v240, v26
	s_waitcnt lgkmcnt(3)
	v_add_f32_e32 v20, v9, v10
	s_waitcnt lgkmcnt(2)
	v_add_f32_e32 v9, v11, v12
	ds_bpermute_b32 v10, v238, v9
	s_waitcnt lgkmcnt(2)
; __device__ __forceinline__ void preproc_phase(Frame& F, int layer, int b, int cu_lo, int ncu) {
;     ...
;         for (int a = 0; a < 4; ++a)
; #pragma unroll
;             for (int hh = 0; hh < 4; ++hh) { ai[a][hh] = wave_sum(ai[a][hh]); af[a][hh] = wave_sum(af[a][hh]); }
	v_add_f32_e32 v8, v8, v13
	ds_bpermute_b32 v11, v237, v8
	ds_bpermute_b32 v12, v235, v101
	ds_bpermute_b32 v48, v240, v25
	s_waitcnt lgkmcnt(3)
	v_add_f32_e32 v9, v9, v10
	ds_bpermute_b32 v10, v239, v9
	s_waitcnt lgkmcnt(3)
	v_add_f32_e32 v8, v8, v11
	s_waitcnt lgkmcnt(2)
	v_add_f32_e32 v12, v101, v12
	ds_bpermute_b32 v11, v238, v8
	ds_bpermute_b32 v13, v236, v12
	s_waitcnt lgkmcnt(2)
	v_add_f32_e32 v19, v9, v10
	ds_bpermute_b32 v9, v235, v99
	ds_bpermute_b32 v49, v240, v24
	s_waitcnt lgkmcnt(3)
	v_add_f32_e32 v8, v8, v11
	s_waitcnt lgkmcnt(2)
	v_add_f32_e32 v11, v12, v13
	ds_bpermute_b32 v10, v239, v8
	ds_bpermute_b32 v12, v237, v11
	s_waitcnt lgkmcnt(3)
	v_add_f32_e32 v9, v99, v9
	ds_bpermute_b32 v13, v236, v9
	ds_bpermute_b32 v50, v240, v23
	s_waitcnt lgkmcnt(3)
	v_add_f32_e32 v18, v8, v10
	s_waitcnt lgkmcnt(2)
	v_add_f32_e32 v8, v11, v12
	ds_bpermute_b32 v10, v238, v8
	s_waitcnt lgkmcnt(2)
	v_add_f32_e32 v9, v9, v13
	ds_bpermute_b32 v11, v237, v9
	ds_bpermute_b32 v12, v235, v96
	ds_bpermute_b32 v51, v240, v22
	s_waitcnt lgkmcnt(3)
	v_add_f32_e32 v8, v8, v10
	ds_bpermute_b32 v10, v239, v8
	s_waitcnt lgkmcnt(3)
	v_add_f32_e32 v9, v9, v11
	s_waitcnt lgkmcnt(2)
	v_add_f32_e32 v12, v96, v12
	ds_bpermute_b32 v11, v238, v9
	ds_bpermute_b32 v13, v236, v12
	s_waitcnt lgkmcnt(2)
	v_add_f32_e32 v17, v8, v10
	ds_bpermute_b32 v8, v235, v94
	ds_bpermute_b32 v52, v240, v21
	s_waitcnt lgkmcnt(3)
	v_add_f32_e32 v9, v9, v11
	s_waitcnt lgkmcnt(2)
	v_add_f32_e32 v11, v12, v13
	ds_bpermute_b32 v10, v239, v9
	ds_bpermute_b32 v12, v237, v11
	s_waitcnt lgkmcnt(3)
	v_add_f32_e32 v8, v94, v8
	ds_bpermute_b32 v13, v236, v8
	ds_bpermute_b32 v53, v240, v20
	s_waitcnt lgkmcnt(3)
	v_add_f32_e32 v16, v9, v10
	s_waitcnt lgkmcnt(2)
	v_add_f32_e32 v9, v11, v12
	ds_bpermute_b32 v10, v238, v9
	s_waitcnt lgkmcnt(2)
	v_add_f32_e32 v8, v8, v13
	ds_bpermute_b32 v12, v235, v97
	ds_bpermute_b32 v11, v237, v8
	ds_bpermute_b32 v54, v240, v19
	s_waitcnt lgkmcnt(3)
	v_add_f32_e32 v9, v9, v10
	ds_bpermute_b32 v10, v239, v9
	s_waitcnt lgkmcnt(3)
	v_add_f32_e32 v12, v97, v12
	s_waitcnt lgkmcnt(2)
	v_add_f32_e32 v8, v8, v11
	ds_bpermute_b32 v13, v236, v12
	ds_bpermute_b32 v11, v238, v8
	s_waitcnt lgkmcnt(2)
	v_add_f32_e32 v15, v9, v10
	ds_bpermute_b32 v9, v235, v95
	ds_bpermute_b32 v55, v240, v18
	s_waitcnt lgkmcnt(3)
	v_add_f32_e32 v10, v12, v13
	s_waitcnt lgkmcnt(2)
	v_add_f32_e32 v8, v8, v11
	ds_bpermute_b32 v11, v237, v10
	ds_bpermute_b32 v12, v235, v92
	s_waitcnt lgkmcnt(3)
	v_add_f32_e32 v9, v95, v9
	ds_bpermute_b32 v13, v239, v8
	ds_bpermute_b32 v14, v236, v9
	s_waitcnt lgkmcnt(3)
	v_add_f32_e32 v10, v10, v11
	s_waitcnt lgkmcnt(2)
	v_add_f32_e32 v11, v92, v12
	ds_bpermute_b32 v12, v236, v11
	ds_bpermute_b32 v59, v238, v10
	s_waitcnt lgkmcnt(2)
	v_add_f32_e32 v9, v9, v14
	v_add_f32_e32 v14, v8, v13
	ds_bpermute_b32 v60, v237, v9
	s_waitcnt lgkmcnt(2)
	v_add_f32_e32 v8, v11, v12
	ds_bpermute_b32 v11, v237, v8
	s_waitcnt lgkmcnt(2)
	v_add_f32_e32 v10, v10, v59
	ds_bpermute_b32 v13, v239, v10
	s_waitcnt lgkmcnt(2)
	v_add_f32_e32 v9, v9, v60
	ds_bpermute_b32 v12, v238, v9
	s_waitcnt lgkmcnt(2)
	v_add_f32_e32 v8, v8, v11
	ds_bpermute_b32 v11, v238, v8
	s_waitcnt lgkmcnt(2)
	v_add_f32_e32 v13, v10, v13
	ds_bpermute_b32 v56, v240, v17
	s_waitcnt lgkmcnt(2)
	v_add_f32_e32 v9, v9, v12
	ds_bpermute_b32 v12, v239, v9
	s_waitcnt lgkmcnt(2)
	v_add_f32_e32 v8, v8, v11
	ds_bpermute_b32 v10, v239, v8
	ds_bpermute_b32 v57, v240, v16
	ds_bpermute_b32 v58, v240, v15
	s_waitcnt lgkmcnt(3)
	v_add_f32_e32 v12, v9, v12
	ds_bpermute_b32 v9, v235, v90
	s_waitcnt lgkmcnt(3)
	v_add_f32_e32 v11, v8, v10
	ds_bpermute_b32 v8, v235, v93
	ds_bpermute_b32 v10, v235, v91
	ds_bpermute_b32 v59, v240, v14
	s_waitcnt lgkmcnt(3)
	v_add_f32_e32 v9, v90, v9
	ds_bpermute_b32 v63, v236, v9
	s_waitcnt lgkmcnt(3)
	v_add_f32_e32 v8, v93, v8
	s_waitcnt lgkmcnt(2)
	v_add_f32_e32 v10, v91, v10
	ds_bpermute_b32 v64, v236, v8
	ds_bpermute_b32 v65, v236, v10
	s_waitcnt lgkmcnt(2)
	v_add_f32_e32 v9, v9, v63
	ds_bpermute_b32 v63, v237, v9
	ds_bpermute_b32 v60, v240, v13
	s_waitcnt lgkmcnt(3)
	v_add_f32_e32 v8, v8, v64
	s_waitcnt lgkmcnt(2)
	v_add_f32_e32 v10, v10, v65
	ds_bpermute_b32 v64, v237, v8
	ds_bpermute_b32 v65, v237, v10
	s_waitcnt lgkmcnt(3)
	v_add_f32_e32 v9, v9, v63
	ds_bpermute_b32 v63, v238, v9
	ds_bpermute_b32 v61, v240, v12
	s_waitcnt lgkmcnt(3)
	v_add_f32_e32 v8, v8, v64
	s_waitcnt lgkmcnt(2)
	v_add_f32_e32 v10, v10, v65
	ds_bpermute_b32 v64, v238, v8
	ds_bpermute_b32 v65, v238, v10
	s_waitcnt lgkmcnt(3)
	v_add_f32_e32 v9, v9, v63
	ds_bpermute_b32 v63, v239, v9
	ds_bpermute_b32 v62, v240, v11
	s_waitcnt lgkmcnt(3)
	v_add_f32_e32 v8, v8, v64
	s_waitcnt lgkmcnt(2)
	v_add_f32_e32 v65, v10, v65
	ds_bpermute_b32 v64, v239, v8
	ds_bpermute_b32 v66, v239, v65
	s_waitcnt lgkmcnt(3)
	v_add_f32_e32 v10, v9, v63
	ds_bpermute_b32 v63, v240, v10
	s_waitcnt lgkmcnt(2)
	v_add_f32_e32 v9, v8, v64
	s_waitcnt lgkmcnt(1)
	v_add_f32_e32 v8, v65, v66
	ds_bpermute_b32 v64, v240, v9
	ds_bpermute_b32 v65, v240, v8
	s_and_saveexec_b64 s[10:11], s[8:9]
	s_cbranch_execz .LBB0_294
; __device__ __forceinline__ float logsigmoidf_(float x) { return fminf(x, 0.f) - log1pf(__expf(-fabsf(x))); }
; __device__ __forceinline__ void preproc_phase(Frame& F, int layer, int b, int cu_lo, int ncu) {
;     ...
;         if (F.lane == 0) {
; #pragma unroll
;             for (int a = 0; a < 4; ++a)
; #pragma unroll
;                 for (int hh = 0; hh < 4; ++hh) { MG[(size_t)(t0 + a) * 8 + hh] = ai[a][hh] + INP(I_M_B_I)[layer * 4 + hh]; MG[(size_t)(t0 + a) * 8 + 4 + hh] = logsigmoidf_(af[a][hh] + INP(I_M_B_F)[layer * 4 + hh]); }
;         }
	v_readlane_b32 s0, v253, 31
	v_add_f32_e32 v36, v36, v37
	v_add_f32_e32 v37, v6, v7
	v_add_f32_e32 v6, v2, v3
	v_mov_b32_e32 v2, s0
	ds_read_b64 v[2:3], v2
	v_readlane_b32 s0, v253, 32
	v_add_f32_e32 v35, v35, v38
	v_add_f32_e32 v38, v4, v5
	v_mov_b32_e32 v4, s0
	s_lshl_b64 s[0:1], s[26:27], 5
	v_readlane_b32 s4, v254, 27
	s_add_u32 s0, s49, s0
	v_readlane_b32 s5, v254, 28
	s_addc_u32 s1, s54, s1
	s_lshl_b64 s[4:5], s[4:5], 2
	ds_read_b64 v[4:5], v4
	s_waitcnt lgkmcnt(1)
	v_lshl_add_u64 v[2:3], v[2:3], 0, s[4:5]
	flat_load_dword v7, v[2:3]
	v_add_f32_e32 v34, v34, v39
	v_add_f32_e32 v31, v31, v42
	s_waitcnt lgkmcnt(0)
	v_lshl_add_u64 v[4:5], v[4:5], 0, s[4:5]
	global_load_dword v110, v[2:3], off
	global_load_dword v111, v[2:3], off offset:4
	global_load_dword v112, v[2:3], off offset:8
	global_load_dword v113, v[2:3], off offset:12
	global_load_dword v114, v[4:5], off
	global_load_dword v115, v[4:5], off offset:4
	global_load_dword v116, v[4:5], off offset:8
	global_load_dword v117, v[4:5], off offset:12
	v_add_f32_e32 v33, v33, v40
	v_add_f32_e32 v32, v32, v41
	v_add_f32_e32 v30, v30, v43
	s_mov_b32 s4, 0x3f2aaaab
	v_add_f32_e32 v29, v29, v44
	v_add_f32_e32 v28, v28, v45
	v_add_f32_e32 v27, v27, v46
	v_add_f32_e32 v26, v26, v47
	v_add_f32_e32 v25, v25, v48
	v_add_f32_e32 v24, v24, v49
	v_add_f32_e32 v23, v23, v50
	s_mov_b32 s5, 0x3f317218
	s_mov_b32 s13, 0x33800000
	v_add_f32_e32 v22, v22, v51
	v_add_f32_e32 v21, v21, v52
	v_add_f32_e32 v20, v20, v53
	v_add_f32_e32 v19, v19, v54
	v_add_f32_e32 v18, v18, v55
	v_add_f32_e32 v17, v17, v56
	v_add_f32_e32 v16, v16, v57
	v_add_f32_e32 v15, v15, v58
	v_add_f32_e32 v14, v14, v59
	v_add_f32_e32 v13, v13, v60
	v_add_f32_e32 v12, v12, v61
	v_add_f32_e32 v11, v11, v62
	v_add_f32_e32 v10, v10, v63
	v_add_f32_e32 v9, v9, v64
	v_add_f32_e32 v8, v8, v65
	s_waitcnt vmcnt(0)
	v_add_f32_e32 v39, v6, v7
	v_mov_b64_e32 v[6:7], s[0:1]
	flat_store_dword v[6:7], v39
	v_mov_b32_e32 v39, v114
	s_lshl_b64 s[0:1], s[24:25], 5
	s_add_u32 s0, s49, s0
	s_addc_u32 s1, s54, s1
	v_add_f32_e32 v39, v38, v39
	v_min_f32_e32 v38, 0, v39
	v_mul_f32_e64 v39, |v39|, s65
	v_exp_f32_e32 v39, v39
	s_nop 0
	v_add_f32_e32 v42, 1.0, v39
	v_add_f32_e32 v40, -1.0, v42
	v_sub_f32_e32 v41, v40, v42
	v_add_f32_e32 v41, 1.0, v41
	v_sub_f32_e32 v40, v39, v40
	v_add_f32_e32 v43, v40, v41
	v_frexp_mant_f32_e32 v40, v42
	v_cmp_gt_f32_e32 vcc, s4, v40
	v_cvt_f64_f32_e32 v[40:41], v42
	v_frexp_exp_i32_f64_e32 v40, v[40:41]
	v_subbrev_co_u32_e32 v40, vcc, 0, v40, vcc
	v_sub_u32_e32 v41, 0, v40
	v_ldexp_f32 v42, v42, v41
	v_ldexp_f32 v41, v43, v41
	v_add_f32_e32 v43, -1.0, v42
	v_add_f32_e32 v44, 1.0, v43
	v_sub_f32_e32 v44, v42, v44
	v_add_f32_e32 v44, v41, v44
	v_add_f32_e32 v45, v43, v44
	v_sub_f32_e32 v43, v45, v43
	v_sub_f32_e32 v43, v44, v43
	v_add_f32_e32 v44, 1.0, v42
	v_add_f32_e32 v46, -1.0, v44
	v_sub_f32_e32 v42, v42, v46
	v_add_f32_e32 v41, v41, v42
	v_add_f32_e32 v42, v44, v41
	v_sub_f32_e32 v44, v42, v44
	v_sub_f32_e32 v41, v41, v44
	v_rcp_f32_e32 v44, v42
	v_cvt_f32_i32_e32 v40, v40
	v_cmp_neq_f32_e32 vcc, s51, v39
	v_mul_f32_e32 v46, v45, v44
	v_mul_f32_e32 v47, v42, v46
	v_fma_f32 v48, v46, v42, -v47
	v_fmac_f32_e32 v48, v46, v41
	v_add_f32_e32 v49, v47, v48
	v_sub_f32_e32 v50, v45, v49
	v_sub_f32_e32 v45, v45, v50
	v_sub_f32_e32 v47, v49, v47
	v_sub_f32_e32 v45, v45, v49
	v_add_f32_e32 v43, v43, v45
	v_sub_f32_e32 v45, v47, v48
	v_add_f32_e32 v43, v45, v43
	v_add_f32_e32 v45, v50, v43
	v_mul_f32_e32 v47, v44, v45
	v_mul_f32_e32 v48, v42, v47
	v_fma_f32 v42, v47, v42, -v48
	v_fmac_f32_e32 v42, v47, v41
	v_sub_f32_e32 v41, v50, v45
	v_add_f32_e32 v41, v43, v41
	v_add_f32_e32 v43, v48, v42
	v_sub_f32_e32 v49, v45, v43
	v_sub_f32_e32 v45, v45, v49
	v_sub_f32_e32 v48, v43, v48
	v_sub_f32_e32 v43, v45, v43
	v_add_f32_e32 v41, v41, v43
	v_sub_f32_e32 v42, v48, v42
	v_add_f32_e32 v41, v42, v41
	v_add_f32_e32 v42, v46, v47
	v_add_f32_e32 v41, v49, v41
	v_sub_f32_e32 v43, v42, v46
	v_mul_f32_e32 v41, v44, v41
	v_sub_f32_e32 v43, v47, v43
	v_add_f32_e32 v41, v43, v41
	v_mul_f32_e32 v46, 0x3f317218, v40
	v_add_f32_e32 v43, v42, v41
	v_fma_f32 v47, v40, s5, -v46
	v_mul_f32_e32 v44, v43, v43
	v_fmac_f32_e32 v47, 0xb102e308, v40
	v_sub_f32_e32 v40, v43, v42
	v_fmamk_f32 v45, v44, 0x3e9b6dac, v226
	v_sub_f32_e32 v40, v41, v40
	v_add_f32_e32 v41, v46, v47
	v_fmaak_f32 v45, v44, v45, 0x3f2aaada
	v_sub_f32_e32 v42, v41, v46
	v_ldexp_f32 v46, v43, 1
	v_mul_f32_e32 v43, v43, v44
	v_mul_f32_e32 v43, v43, v45
	v_add_f32_e32 v44, v46, v43
	v_sub_f32_e32 v45, v44, v46
	v_ldexp_f32 v40, v40, 1
	v_sub_f32_e32 v43, v43, v45
	v_add_f32_e32 v40, v40, v43
	v_add_f32_e32 v43, v44, v40
	v_sub_f32_e32 v44, v43, v44
	v_sub_f32_e32 v40, v40, v44
	v_add_f32_e32 v44, v41, v43
	v_sub_f32_e32 v45, v44, v41
	v_sub_f32_e32 v46, v44, v45
	v_sub_f32_e32 v42, v47, v42
	v_sub_f32_e32 v41, v41, v46
	v_sub_f32_e32 v43, v43, v45
	v_add_f32_e32 v41, v43, v41
	v_add_f32_e32 v43, v42, v40
	v_sub_f32_e32 v45, v43, v42
	v_sub_f32_e32 v46, v43, v45
	v_sub_f32_e32 v42, v42, v46
	v_sub_f32_e32 v40, v40, v45
	v_add_f32_e32 v41, v43, v41
	v_add_f32_e32 v40, v40, v42
	v_add_f32_e32 v42, v44, v41
	v_sub_f32_e32 v43, v42, v44
	v_sub_f32_e32 v41, v41, v43
	v_add_f32_e32 v40, v40, v41
	v_add_f32_e32 v40, v42, v40
	v_cndmask_b32_e32 v40, v227, v40, vcc
	v_cmp_ngt_f32_e32 vcc, -1.0, v39
	s_nop 1
	v_cndmask_b32_e32 v40, v228, v40, vcc
	v_cmp_neq_f32_e32 vcc, -1.0, v39
	s_nop 1
	v_cndmask_b32_e32 v40, v229, v40, vcc
	v_cmp_lt_f32_e64 vcc, |v39|, s13
	s_nop 1
	v_cndmask_b32_e32 v39, v40, v39, vcc
	v_sub_f32_e32 v38, v38, v39
	flat_store_dword v[6:7], v38 offset:16
	v_mov_b32_e32 v38, v111
; __device__ __forceinline__ float logsigmoidf_(float x) { return fminf(x, 0.f) - log1pf(__expf(-fabsf(x))); }
; __device__ __forceinline__ void preproc_phase(Frame& F, int layer, int b, int cu_lo, int ncu) {
;     ...
;         if (F.lane == 0) {
; #pragma unroll
;             for (int a = 0; a < 4; ++a)
; #pragma unroll
;                 for (int hh = 0; hh < 4; ++hh) { MG[(size_t)(t0 + a) * 8 + hh] = ai[a][hh] + INP(I_M_B_I)[layer * 4 + hh]; MG[(size_t)(t0 + a) * 8 + 4 + hh] = logsigmoidf_(af[a][hh] + INP(I_M_B_F)[layer * 4 + hh]); }
;         }
	v_add_f32_e32 v37, v37, v38
	flat_store_dword v[6:7], v37 offset:4
	v_mov_b32_e32 v37, v115
	v_add_f32_e32 v37, v36, v37
	v_min_f32_e32 v36, 0, v37
	v_mul_f32_e64 v37, |v37|, s65
	v_exp_f32_e32 v37, v37
	s_nop 0
	v_add_f32_e32 v40, 1.0, v37
	v_add_f32_e32 v38, -1.0, v40
	v_sub_f32_e32 v39, v38, v40
	v_add_f32_e32 v39, 1.0, v39
	v_sub_f32_e32 v38, v37, v38
	v_add_f32_e32 v41, v38, v39
	v_frexp_mant_f32_e32 v38, v40
	v_cmp_gt_f32_e32 vcc, s4, v38
	v_cvt_f64_f32_e32 v[38:39], v40
	v_frexp_exp_i32_f64_e32 v38, v[38:39]
	v_subbrev_co_u32_e32 v38, vcc, 0, v38, vcc
	v_sub_u32_e32 v39, 0, v38
	v_ldexp_f32 v40, v40, v39
	v_ldexp_f32 v39, v41, v39
	v_add_f32_e32 v41, -1.0, v40
	v_add_f32_e32 v42, 1.0, v41
	v_sub_f32_e32 v42, v40, v42
	v_add_f32_e32 v42, v39, v42
	v_add_f32_e32 v43, v41, v42
	v_sub_f32_e32 v41, v43, v41
	v_sub_f32_e32 v41, v42, v41
	v_add_f32_e32 v42, 1.0, v40
	v_add_f32_e32 v44, -1.0, v42
	v_sub_f32_e32 v40, v40, v44
	v_add_f32_e32 v39, v39, v40
	v_add_f32_e32 v40, v42, v39
	v_sub_f32_e32 v42, v40, v42
	v_sub_f32_e32 v39, v39, v42
	v_rcp_f32_e32 v42, v40
	v_cvt_f32_i32_e32 v38, v38
	v_cmp_neq_f32_e32 vcc, s51, v37
	v_mul_f32_e32 v44, v43, v42
	v_mul_f32_e32 v45, v40, v44
	v_fma_f32 v46, v44, v40, -v45
	v_fmac_f32_e32 v46, v44, v39
	v_add_f32_e32 v47, v45, v46
	v_sub_f32_e32 v48, v43, v47
	v_sub_f32_e32 v43, v43, v48
	v_sub_f32_e32 v45, v47, v45
	v_sub_f32_e32 v43, v43, v47
	v_add_f32_e32 v41, v41, v43
	v_sub_f32_e32 v43, v45, v46
	v_add_f32_e32 v41, v43, v41
	v_add_f32_e32 v43, v48, v41
	v_mul_f32_e32 v45, v42, v43
	v_mul_f32_e32 v46, v40, v45
	v_fma_f32 v40, v45, v40, -v46
	v_fmac_f32_e32 v40, v45, v39
	v_sub_f32_e32 v39, v48, v43
	v_add_f32_e32 v39, v41, v39
	v_add_f32_e32 v41, v46, v40
	v_sub_f32_e32 v47, v43, v41
	v_sub_f32_e32 v43, v43, v47
	v_sub_f32_e32 v46, v41, v46
	v_sub_f32_e32 v41, v43, v41
	v_add_f32_e32 v39, v39, v41
	v_sub_f32_e32 v40, v46, v40
	v_add_f32_e32 v39, v40, v39
	v_add_f32_e32 v40, v44, v45
	v_add_f32_e32 v39, v47, v39
	v_sub_f32_e32 v41, v40, v44
	v_mul_f32_e32 v39, v42, v39
	v_sub_f32_e32 v41, v45, v41
	v_add_f32_e32 v39, v41, v39
	v_mul_f32_e32 v44, 0x3f317218, v38
	v_add_f32_e32 v41, v40, v39
	v_fma_f32 v45, v38, s5, -v44
	v_mul_f32_e32 v42, v41, v41
	v_fmac_f32_e32 v45, 0xb102e308, v38
	v_sub_f32_e32 v38, v41, v40
	v_fmamk_f32 v43, v42, 0x3e9b6dac, v226
	v_sub_f32_e32 v38, v39, v38
	v_add_f32_e32 v39, v44, v45
	v_fmaak_f32 v43, v42, v43, 0x3f2aaada
	v_sub_f32_e32 v40, v39, v44
	v_ldexp_f32 v44, v41, 1
	v_mul_f32_e32 v41, v41, v42
	v_mul_f32_e32 v41, v41, v43
	v_add_f32_e32 v42, v44, v41
	v_sub_f32_e32 v43, v42, v44
	v_ldexp_f32 v38, v38, 1
	v_sub_f32_e32 v41, v41, v43
	v_add_f32_e32 v38, v38, v41
	v_add_f32_e32 v41, v42, v38
	v_sub_f32_e32 v42, v41, v42
	v_sub_f32_e32 v38, v38, v42
	v_add_f32_e32 v42, v39, v41
	v_sub_f32_e32 v43, v42, v39
	v_sub_f32_e32 v44, v42, v43
	v_sub_f32_e32 v40, v45, v40
	v_sub_f32_e32 v39, v39, v44
	v_sub_f32_e32 v41, v41, v43
	v_add_f32_e32 v39, v41, v39
	v_add_f32_e32 v41, v40, v38
	v_sub_f32_e32 v43, v41, v40
	v_sub_f32_e32 v44, v41, v43
	v_sub_f32_e32 v40, v40, v44
	v_sub_f32_e32 v38, v38, v43
	v_add_f32_e32 v39, v41, v39
	v_add_f32_e32 v38, v38, v40
	v_add_f32_e32 v40, v42, v39
	v_sub_f32_e32 v41, v40, v42
	v_sub_f32_e32 v39, v39, v41
	v_add_f32_e32 v38, v38, v39
	v_add_f32_e32 v38, v40, v38
	v_cndmask_b32_e32 v38, v227, v38, vcc
	v_cmp_ngt_f32_e32 vcc, -1.0, v37
	s_nop 1
	v_cndmask_b32_e32 v38, v228, v38, vcc
	v_cmp_neq_f32_e32 vcc, -1.0, v37
	s_nop 1
	v_cndmask_b32_e32 v38, v229, v38, vcc
	v_cmp_lt_f32_e64 vcc, |v37|, s13
	s_nop 1
	v_cndmask_b32_e32 v37, v38, v37, vcc
	v_sub_f32_e32 v36, v36, v37
	flat_store_dword v[6:7], v36 offset:20
	v_mov_b32_e32 v36, v112
	v_add_f32_e32 v35, v35, v36
	flat_store_dword v[6:7], v35 offset:8
	v_mov_b32_e32 v35, v116
	v_add_f32_e32 v35, v34, v35
	v_min_f32_e32 v34, 0, v35
	v_mul_f32_e64 v35, |v35|, s65
	v_exp_f32_e32 v35, v35
	s_nop 0
	v_add_f32_e32 v38, 1.0, v35
	v_add_f32_e32 v36, -1.0, v38
	v_sub_f32_e32 v37, v36, v38
	v_add_f32_e32 v37, 1.0, v37
	v_sub_f32_e32 v36, v35, v36
	v_add_f32_e32 v39, v36, v37
	v_frexp_mant_f32_e32 v36, v38
	v_cmp_gt_f32_e32 vcc, s4, v36
	v_cvt_f64_f32_e32 v[36:37], v38
	v_frexp_exp_i32_f64_e32 v36, v[36:37]
	v_subbrev_co_u32_e32 v36, vcc, 0, v36, vcc
	v_sub_u32_e32 v37, 0, v36
	v_ldexp_f32 v38, v38, v37
	v_ldexp_f32 v37, v39, v37
	v_add_f32_e32 v39, -1.0, v38
	v_add_f32_e32 v40, 1.0, v39
	v_sub_f32_e32 v40, v38, v40
	v_add_f32_e32 v40, v37, v40
	v_add_f32_e32 v41, v39, v40
	v_sub_f32_e32 v39, v41, v39
	v_sub_f32_e32 v39, v40, v39
	v_add_f32_e32 v40, 1.0, v38
	v_add_f32_e32 v42, -1.0, v40
	v_sub_f32_e32 v38, v38, v42
	v_add_f32_e32 v37, v37, v38
	v_add_f32_e32 v38, v40, v37
	v_sub_f32_e32 v40, v38, v40
	v_sub_f32_e32 v37, v37, v40
	v_rcp_f32_e32 v40, v38
	v_cvt_f32_i32_e32 v36, v36
	v_cmp_neq_f32_e32 vcc, s51, v35
	v_mul_f32_e32 v42, v41, v40
	v_mul_f32_e32 v43, v38, v42
	v_fma_f32 v44, v42, v38, -v43
	v_fmac_f32_e32 v44, v42, v37
	v_add_f32_e32 v45, v43, v44
	v_sub_f32_e32 v46, v41, v45
	v_sub_f32_e32 v41, v41, v46
	v_sub_f32_e32 v43, v45, v43
	v_sub_f32_e32 v41, v41, v45
	v_add_f32_e32 v39, v39, v41
	v_sub_f32_e32 v41, v43, v44
	v_add_f32_e32 v39, v41, v39
	v_add_f32_e32 v41, v46, v39
	v_mul_f32_e32 v43, v40, v41
	v_mul_f32_e32 v44, v38, v43
	v_fma_f32 v38, v43, v38, -v44
	v_fmac_f32_e32 v38, v43, v37
	v_sub_f32_e32 v37, v46, v41
	v_add_f32_e32 v37, v39, v37
	v_add_f32_e32 v39, v44, v38
	v_sub_f32_e32 v45, v41, v39
	v_sub_f32_e32 v41, v41, v45
	v_sub_f32_e32 v44, v39, v44
	v_sub_f32_e32 v39, v41, v39
	v_add_f32_e32 v37, v37, v39
	v_sub_f32_e32 v38, v44, v38
	v_add_f32_e32 v37, v38, v37
; __device__ __forceinline__ float logsigmoidf_(float x) { return fminf(x, 0.f) - log1pf(__expf(-fabsf(x))); }
; __device__ __forceinline__ void preproc_phase(Frame& F, int layer, int b, int cu_lo, int ncu) {
;     ...
;         if (F.lane == 0) {
; #pragma unroll
;             for (int a = 0; a < 4; ++a)
; #pragma unroll
;                 for (int hh = 0; hh < 4; ++hh) { MG[(size_t)(t0 + a) * 8 + hh] = ai[a][hh] + INP(I_M_B_I)[layer * 4 + hh]; MG[(size_t)(t0 + a) * 8 + 4 + hh] = logsigmoidf_(af[a][hh] + INP(I_M_B_F)[layer * 4 + hh]); }
;         }
	v_add_f32_e32 v38, v42, v43
	v_add_f32_e32 v37, v45, v37
	v_sub_f32_e32 v39, v38, v42
	v_mul_f32_e32 v37, v40, v37
	v_sub_f32_e32 v39, v43, v39
	v_add_f32_e32 v37, v39, v37
	v_mul_f32_e32 v42, 0x3f317218, v36
	v_add_f32_e32 v39, v38, v37
	v_fma_f32 v43, v36, s5, -v42
	v_mul_f32_e32 v40, v39, v39
	v_fmac_f32_e32 v43, 0xb102e308, v36
	v_sub_f32_e32 v36, v39, v38
	v_fmamk_f32 v41, v40, 0x3e9b6dac, v226
	v_sub_f32_e32 v36, v37, v36
	v_add_f32_e32 v37, v42, v43
	v_fmaak_f32 v41, v40, v41, 0x3f2aaada
	v_sub_f32_e32 v38, v37, v42
	v_ldexp_f32 v42, v39, 1
	v_mul_f32_e32 v39, v39, v40
	v_mul_f32_e32 v39, v39, v41
	v_add_f32_e32 v40, v42, v39
	v_sub_f32_e32 v41, v40, v42
	v_ldexp_f32 v36, v36, 1
	v_sub_f32_e32 v39, v39, v41
	v_add_f32_e32 v36, v36, v39
	v_add_f32_e32 v39, v40, v36
	v_sub_f32_e32 v40, v39, v40
	v_sub_f32_e32 v36, v36, v40
	v_add_f32_e32 v40, v37, v39
	v_sub_f32_e32 v41, v40, v37
	v_sub_f32_e32 v42, v40, v41
	v_sub_f32_e32 v38, v43, v38
	v_sub_f32_e32 v37, v37, v42
	v_sub_f32_e32 v39, v39, v41
	v_add_f32_e32 v37, v39, v37
	v_add_f32_e32 v39, v38, v36
	v_sub_f32_e32 v41, v39, v38
	v_sub_f32_e32 v42, v39, v41
	v_sub_f32_e32 v38, v38, v42
	v_sub_f32_e32 v36, v36, v41
	v_add_f32_e32 v37, v39, v37
	v_add_f32_e32 v36, v36, v38
	v_add_f32_e32 v38, v40, v37
	v_sub_f32_e32 v39, v38, v40
	v_sub_f32_e32 v37, v37, v39
	v_add_f32_e32 v36, v36, v37
	v_add_f32_e32 v36, v38, v36
	v_cndmask_b32_e32 v36, v227, v36, vcc
	v_cmp_ngt_f32_e32 vcc, -1.0, v35
	s_nop 1
	v_cndmask_b32_e32 v36, v228, v36, vcc
	v_cmp_neq_f32_e32 vcc, -1.0, v35
	s_nop 1
	v_cndmask_b32_e32 v36, v229, v36, vcc
	v_cmp_lt_f32_e64 vcc, |v35|, s13
	s_nop 1
	v_cndmask_b32_e32 v35, v36, v35, vcc
	v_sub_f32_e32 v34, v34, v35
	flat_store_dword v[6:7], v34 offset:24
	v_mov_b32_e32 v34, v113
	v_add_f32_e32 v33, v33, v34
	flat_store_dword v[6:7], v33 offset:12
	v_mov_b32_e32 v33, v117
	v_add_f32_e32 v33, v32, v33
	v_min_f32_e32 v32, 0, v33
	v_mul_f32_e64 v33, |v33|, s65
	v_exp_f32_e32 v33, v33
	s_nop 0
	v_add_f32_e32 v36, 1.0, v33
	v_add_f32_e32 v34, -1.0, v36
	v_sub_f32_e32 v35, v34, v36
	v_add_f32_e32 v35, 1.0, v35
	v_sub_f32_e32 v34, v33, v34
	v_add_f32_e32 v37, v34, v35
	v_frexp_mant_f32_e32 v34, v36
	v_cmp_gt_f32_e32 vcc, s4, v34
	v_cvt_f64_f32_e32 v[34:35], v36
	v_frexp_exp_i32_f64_e32 v34, v[34:35]
	v_subbrev_co_u32_e32 v34, vcc, 0, v34, vcc
	v_sub_u32_e32 v35, 0, v34
	v_ldexp_f32 v36, v36, v35
	v_ldexp_f32 v35, v37, v35
	v_add_f32_e32 v37, -1.0, v36
	v_add_f32_e32 v38, 1.0, v37
	v_sub_f32_e32 v38, v36, v38
	v_add_f32_e32 v38, v35, v38
	v_add_f32_e32 v39, v37, v38
	v_sub_f32_e32 v37, v39, v37
	v_sub_f32_e32 v37, v38, v37
	v_add_f32_e32 v38, 1.0, v36
	v_add_f32_e32 v40, -1.0, v38
	v_sub_f32_e32 v36, v36, v40
	v_add_f32_e32 v35, v35, v36
	v_add_f32_e32 v36, v38, v35
	v_sub_f32_e32 v38, v36, v38
	v_sub_f32_e32 v35, v35, v38
	v_rcp_f32_e32 v38, v36
	v_cvt_f32_i32_e32 v34, v34
	v_cmp_neq_f32_e32 vcc, s51, v33
	v_mul_f32_e32 v40, v39, v38
	v_mul_f32_e32 v41, v36, v40
	v_fma_f32 v42, v40, v36, -v41
	v_fmac_f32_e32 v42, v40, v35
	v_add_f32_e32 v43, v41, v42
	v_sub_f32_e32 v44, v39, v43
	v_sub_f32_e32 v39, v39, v44
	v_sub_f32_e32 v41, v43, v41
	v_sub_f32_e32 v39, v39, v43
	v_add_f32_e32 v37, v37, v39
	v_sub_f32_e32 v39, v41, v42
	v_add_f32_e32 v37, v39, v37
	v_add_f32_e32 v39, v44, v37
	v_mul_f32_e32 v41, v38, v39
	v_mul_f32_e32 v42, v36, v41
	v_fma_f32 v36, v41, v36, -v42
	v_fmac_f32_e32 v36, v41, v35
	v_sub_f32_e32 v35, v44, v39
	v_add_f32_e32 v35, v37, v35
	v_add_f32_e32 v37, v42, v36
	v_sub_f32_e32 v43, v39, v37
	v_sub_f32_e32 v39, v39, v43
	v_sub_f32_e32 v42, v37, v42
	v_sub_f32_e32 v37, v39, v37
	v_add_f32_e32 v35, v35, v37
	v_sub_f32_e32 v36, v42, v36
	v_add_f32_e32 v35, v36, v35
	v_add_f32_e32 v36, v40, v41
	v_add_f32_e32 v35, v43, v35
	v_sub_f32_e32 v37, v36, v40
	v_mul_f32_e32 v35, v38, v35
	v_sub_f32_e32 v37, v41, v37
	v_add_f32_e32 v35, v37, v35
	v_mul_f32_e32 v40, 0x3f317218, v34
	v_add_f32_e32 v37, v36, v35
	v_fma_f32 v41, v34, s5, -v40
	v_mul_f32_e32 v38, v37, v37
	v_fmac_f32_e32 v41, 0xb102e308, v34
	v_sub_f32_e32 v34, v37, v36
	v_fmamk_f32 v39, v38, 0x3e9b6dac, v226
	v_sub_f32_e32 v34, v35, v34
	v_add_f32_e32 v35, v40, v41
	v_fmaak_f32 v39, v38, v39, 0x3f2aaada
	v_sub_f32_e32 v36, v35, v40
	v_ldexp_f32 v40, v37, 1
	v_mul_f32_e32 v37, v37, v38
	v_mul_f32_e32 v37, v37, v39
	v_add_f32_e32 v38, v40, v37
	v_sub_f32_e32 v39, v38, v40
	v_ldexp_f32 v34, v34, 1
	v_sub_f32_e32 v37, v37, v39
	v_add_f32_e32 v34, v34, v37
	v_add_f32_e32 v37, v38, v34
	v_sub_f32_e32 v38, v37, v38
	v_sub_f32_e32 v34, v34, v38
	v_add_f32_e32 v38, v35, v37
	v_sub_f32_e32 v39, v38, v35
	v_sub_f32_e32 v40, v38, v39
	v_sub_f32_e32 v36, v41, v36
	v_sub_f32_e32 v35, v35, v40
	v_sub_f32_e32 v37, v37, v39
	v_add_f32_e32 v35, v37, v35
	v_add_f32_e32 v37, v36, v34
	v_sub_f32_e32 v39, v37, v36
	v_sub_f32_e32 v40, v37, v39
	v_sub_f32_e32 v36, v36, v40
	v_sub_f32_e32 v34, v34, v39
	v_add_f32_e32 v35, v37, v35
	v_add_f32_e32 v34, v34, v36
	v_add_f32_e32 v36, v38, v35
	v_sub_f32_e32 v37, v36, v38
	v_sub_f32_e32 v35, v35, v37
	v_add_f32_e32 v34, v34, v35
	v_add_f32_e32 v34, v36, v34
	v_cndmask_b32_e32 v34, v227, v34, vcc
	v_cmp_ngt_f32_e32 vcc, -1.0, v33
	s_nop 1
	v_cndmask_b32_e32 v34, v228, v34, vcc
	v_cmp_neq_f32_e32 vcc, -1.0, v33
	s_nop 1
	v_cndmask_b32_e32 v34, v229, v34, vcc
	v_cmp_lt_f32_e64 vcc, |v33|, s13
	s_nop 1
	v_cndmask_b32_e32 v33, v34, v33, vcc
	v_sub_f32_e32 v32, v32, v33
	flat_store_dword v[6:7], v32 offset:28
	v_mov_b32_e32 v6, v110
	v_add_f32_e32 v31, v31, v6
	v_mov_b64_e32 v[6:7], s[0:1]
	flat_store_dword v[6:7], v31
	v_mov_b32_e32 v31, v114
	s_lshl_b64 s[0:1], s[22:23], 5
	s_add_u32 s0, s49, s0
; __device__ __forceinline__ float logsigmoidf_(float x) { return fminf(x, 0.f) - log1pf(__expf(-fabsf(x))); }
; __device__ __forceinline__ void preproc_phase(Frame& F, int layer, int b, int cu_lo, int ncu) {
;     ...
;         if (F.lane == 0) {
; #pragma unroll
;             for (int a = 0; a < 4; ++a)
; #pragma unroll
;                 for (int hh = 0; hh < 4; ++hh) { MG[(size_t)(t0 + a) * 8 + hh] = ai[a][hh] + INP(I_M_B_I)[layer * 4 + hh]; MG[(size_t)(t0 + a) * 8 + 4 + hh] = logsigmoidf_(af[a][hh] + INP(I_M_B_F)[layer * 4 + hh]); }
;         }
	s_addc_u32 s1, s54, s1
	v_add_f32_e32 v31, v30, v31
	v_min_f32_e32 v30, 0, v31
	v_mul_f32_e64 v31, |v31|, s65
	v_exp_f32_e32 v31, v31
	s_nop 0
	v_add_f32_e32 v34, 1.0, v31
	v_add_f32_e32 v32, -1.0, v34
	v_sub_f32_e32 v33, v32, v34
	v_add_f32_e32 v33, 1.0, v33
	v_sub_f32_e32 v32, v31, v32
	v_add_f32_e32 v35, v32, v33
	v_frexp_mant_f32_e32 v32, v34
	v_cmp_gt_f32_e32 vcc, s4, v32
	v_cvt_f64_f32_e32 v[32:33], v34
	v_frexp_exp_i32_f64_e32 v32, v[32:33]
	v_subbrev_co_u32_e32 v32, vcc, 0, v32, vcc
	v_sub_u32_e32 v33, 0, v32
	v_ldexp_f32 v34, v34, v33
	v_ldexp_f32 v33, v35, v33
	v_add_f32_e32 v35, -1.0, v34
	v_add_f32_e32 v36, 1.0, v35
	v_sub_f32_e32 v36, v34, v36
	v_add_f32_e32 v36, v33, v36
	v_add_f32_e32 v37, v35, v36
	v_sub_f32_e32 v35, v37, v35
	v_sub_f32_e32 v35, v36, v35
	v_add_f32_e32 v36, 1.0, v34
	v_add_f32_e32 v38, -1.0, v36
	v_sub_f32_e32 v34, v34, v38
	v_add_f32_e32 v33, v33, v34
	v_add_f32_e32 v34, v36, v33
	v_sub_f32_e32 v36, v34, v36
	v_sub_f32_e32 v33, v33, v36
	v_rcp_f32_e32 v36, v34
	v_cvt_f32_i32_e32 v32, v32
	v_cmp_neq_f32_e32 vcc, s51, v31
	v_mul_f32_e32 v38, v37, v36
	v_mul_f32_e32 v39, v34, v38
	v_fma_f32 v40, v38, v34, -v39
	v_fmac_f32_e32 v40, v38, v33
	v_add_f32_e32 v41, v39, v40
	v_sub_f32_e32 v42, v37, v41
	v_sub_f32_e32 v37, v37, v42
	v_sub_f32_e32 v39, v41, v39
	v_sub_f32_e32 v37, v37, v41
	v_add_f32_e32 v35, v35, v37
	v_sub_f32_e32 v37, v39, v40
	v_add_f32_e32 v35, v37, v35
	v_add_f32_e32 v37, v42, v35
	v_mul_f32_e32 v39, v36, v37
	v_mul_f32_e32 v40, v34, v39
	v_fma_f32 v34, v39, v34, -v40
	v_fmac_f32_e32 v34, v39, v33
	v_sub_f32_e32 v33, v42, v37
	v_add_f32_e32 v33, v35, v33
	v_add_f32_e32 v35, v40, v34
	v_sub_f32_e32 v41, v37, v35
	v_sub_f32_e32 v37, v37, v41
	v_sub_f32_e32 v40, v35, v40
	v_sub_f32_e32 v35, v37, v35
	v_add_f32_e32 v33, v33, v35
	v_sub_f32_e32 v34, v40, v34
	v_add_f32_e32 v33, v34, v33
	v_add_f32_e32 v34, v38, v39
	v_add_f32_e32 v33, v41, v33
	v_sub_f32_e32 v35, v34, v38
	v_mul_f32_e32 v33, v36, v33
	v_sub_f32_e32 v35, v39, v35
	v_add_f32_e32 v33, v35, v33
	v_mul_f32_e32 v38, 0x3f317218, v32
	v_add_f32_e32 v35, v34, v33
	v_fma_f32 v39, v32, s5, -v38
	v_mul_f32_e32 v36, v35, v35
	v_fmac_f32_e32 v39, 0xb102e308, v32
	v_sub_f32_e32 v32, v35, v34
	v_fmamk_f32 v37, v36, 0x3e9b6dac, v226
	v_sub_f32_e32 v32, v33, v32
	v_add_f32_e32 v33, v38, v39
	v_fmaak_f32 v37, v36, v37, 0x3f2aaada
	v_sub_f32_e32 v34, v33, v38
	v_ldexp_f32 v38, v35, 1
	v_mul_f32_e32 v35, v35, v36
	v_mul_f32_e32 v35, v35, v37
	v_add_f32_e32 v36, v38, v35
	v_sub_f32_e32 v37, v36, v38
	v_ldexp_f32 v32, v32, 1
	v_sub_f32_e32 v35, v35, v37
	v_add_f32_e32 v32, v32, v35
	v_add_f32_e32 v35, v36, v32
	v_sub_f32_e32 v36, v35, v36
	v_sub_f32_e32 v32, v32, v36
	v_add_f32_e32 v36, v33, v35
	v_sub_f32_e32 v37, v36, v33
	v_sub_f32_e32 v38, v36, v37
	v_sub_f32_e32 v34, v39, v34
	v_sub_f32_e32 v33, v33, v38
	v_sub_f32_e32 v35, v35, v37
	v_add_f32_e32 v33, v35, v33
	v_add_f32_e32 v35, v34, v32
	v_sub_f32_e32 v37, v35, v34
	v_sub_f32_e32 v38, v35, v37
	v_sub_f32_e32 v34, v34, v38
	v_sub_f32_e32 v32, v32, v37
	v_add_f32_e32 v33, v35, v33
	v_add_f32_e32 v32, v32, v34
	v_add_f32_e32 v34, v36, v33
	v_sub_f32_e32 v35, v34, v36
	v_sub_f32_e32 v33, v33, v35
	v_add_f32_e32 v32, v32, v33
	v_add_f32_e32 v32, v34, v32
	v_cndmask_b32_e32 v32, v227, v32, vcc
	v_cmp_ngt_f32_e32 vcc, -1.0, v31
	s_nop 1
	v_cndmask_b32_e32 v32, v228, v32, vcc
	v_cmp_neq_f32_e32 vcc, -1.0, v31
	s_nop 1
	v_cndmask_b32_e32 v32, v229, v32, vcc
	v_cmp_lt_f32_e64 vcc, |v31|, s13
	s_nop 1
	v_cndmask_b32_e32 v31, v32, v31, vcc
	v_sub_f32_e32 v30, v30, v31
	flat_store_dword v[6:7], v30 offset:16
	v_mov_b32_e32 v30, v111
	v_add_f32_e32 v29, v29, v30
	flat_store_dword v[6:7], v29 offset:4
	v_mov_b32_e32 v29, v115
	v_add_f32_e32 v29, v28, v29
	v_min_f32_e32 v28, 0, v29
	v_mul_f32_e64 v29, |v29|, s65
	v_exp_f32_e32 v29, v29
	s_nop 0
	v_add_f32_e32 v32, 1.0, v29
	v_add_f32_e32 v30, -1.0, v32
	v_sub_f32_e32 v31, v30, v32
	v_add_f32_e32 v31, 1.0, v31
	v_sub_f32_e32 v30, v29, v30
	v_add_f32_e32 v33, v30, v31
	v_frexp_mant_f32_e32 v30, v32
	v_cmp_gt_f32_e32 vcc, s4, v30
	v_cvt_f64_f32_e32 v[30:31], v32
	v_frexp_exp_i32_f64_e32 v30, v[30:31]
	v_subbrev_co_u32_e32 v30, vcc, 0, v30, vcc
	v_sub_u32_e32 v31, 0, v30
	v_ldexp_f32 v32, v32, v31
	v_ldexp_f32 v31, v33, v31
	v_add_f32_e32 v33, -1.0, v32
	v_add_f32_e32 v34, 1.0, v33
	v_sub_f32_e32 v34, v32, v34
	v_add_f32_e32 v34, v31, v34
	v_add_f32_e32 v35, v33, v34
	v_sub_f32_e32 v33, v35, v33
	v_sub_f32_e32 v33, v34, v33
	v_add_f32_e32 v34, 1.0, v32
	v_add_f32_e32 v36, -1.0, v34
	v_sub_f32_e32 v32, v32, v36
	v_add_f32_e32 v31, v31, v32
	v_add_f32_e32 v32, v34, v31
	v_sub_f32_e32 v34, v32, v34
	v_sub_f32_e32 v31, v31, v34
	v_rcp_f32_e32 v34, v32
	v_cvt_f32_i32_e32 v30, v30
	v_cmp_neq_f32_e32 vcc, s51, v29
	v_mul_f32_e32 v36, v35, v34
	v_mul_f32_e32 v37, v32, v36
	v_fma_f32 v38, v36, v32, -v37
	v_fmac_f32_e32 v38, v36, v31
	v_add_f32_e32 v39, v37, v38
	v_sub_f32_e32 v40, v35, v39
	v_sub_f32_e32 v35, v35, v40
	v_sub_f32_e32 v37, v39, v37
	v_sub_f32_e32 v35, v35, v39
	v_add_f32_e32 v33, v33, v35
	v_sub_f32_e32 v35, v37, v38
	v_add_f32_e32 v33, v35, v33
	v_add_f32_e32 v35, v40, v33
	v_mul_f32_e32 v37, v34, v35
	v_mul_f32_e32 v38, v32, v37
	v_fma_f32 v32, v37, v32, -v38
	v_fmac_f32_e32 v32, v37, v31
	v_sub_f32_e32 v31, v40, v35
	v_add_f32_e32 v31, v33, v31
	v_add_f32_e32 v33, v38, v32
	v_sub_f32_e32 v39, v35, v33
	v_sub_f32_e32 v35, v35, v39
	v_sub_f32_e32 v38, v33, v38
	v_sub_f32_e32 v33, v35, v33
	v_add_f32_e32 v31, v31, v33
	v_sub_f32_e32 v32, v38, v32
	v_add_f32_e32 v31, v32, v31
	v_add_f32_e32 v32, v36, v37
	v_add_f32_e32 v31, v39, v31
	v_sub_f32_e32 v33, v32, v36
; __device__ __forceinline__ float logsigmoidf_(float x) { return fminf(x, 0.f) - log1pf(__expf(-fabsf(x))); }
; __device__ __forceinline__ void preproc_phase(Frame& F, int layer, int b, int cu_lo, int ncu) {
;     ...
;         if (F.lane == 0) {
; #pragma unroll
;             for (int a = 0; a < 4; ++a)
; #pragma unroll
;                 for (int hh = 0; hh < 4; ++hh) { MG[(size_t)(t0 + a) * 8 + hh] = ai[a][hh] + INP(I_M_B_I)[layer * 4 + hh]; MG[(size_t)(t0 + a) * 8 + 4 + hh] = logsigmoidf_(af[a][hh] + INP(I_M_B_F)[layer * 4 + hh]); }
;         }
	v_mul_f32_e32 v31, v34, v31
	v_sub_f32_e32 v33, v37, v33
	v_add_f32_e32 v31, v33, v31
	v_mul_f32_e32 v36, 0x3f317218, v30
	v_add_f32_e32 v33, v32, v31
	v_fma_f32 v37, v30, s5, -v36
	v_mul_f32_e32 v34, v33, v33
	v_fmac_f32_e32 v37, 0xb102e308, v30
	v_sub_f32_e32 v30, v33, v32
	v_fmamk_f32 v35, v34, 0x3e9b6dac, v226
	v_sub_f32_e32 v30, v31, v30
	v_add_f32_e32 v31, v36, v37
	v_fmaak_f32 v35, v34, v35, 0x3f2aaada
	v_sub_f32_e32 v32, v31, v36
	v_ldexp_f32 v36, v33, 1
	v_mul_f32_e32 v33, v33, v34
	v_mul_f32_e32 v33, v33, v35
	v_add_f32_e32 v34, v36, v33
	v_sub_f32_e32 v35, v34, v36
	v_ldexp_f32 v30, v30, 1
	v_sub_f32_e32 v33, v33, v35
	v_add_f32_e32 v30, v30, v33
	v_add_f32_e32 v33, v34, v30
	v_sub_f32_e32 v34, v33, v34
	v_sub_f32_e32 v30, v30, v34
	v_add_f32_e32 v34, v31, v33
	v_sub_f32_e32 v35, v34, v31
	v_sub_f32_e32 v36, v34, v35
	v_sub_f32_e32 v32, v37, v32
	v_sub_f32_e32 v31, v31, v36
	v_sub_f32_e32 v33, v33, v35
	v_add_f32_e32 v31, v33, v31
	v_add_f32_e32 v33, v32, v30
	v_sub_f32_e32 v35, v33, v32
	v_sub_f32_e32 v36, v33, v35
	v_sub_f32_e32 v32, v32, v36
	v_sub_f32_e32 v30, v30, v35
	v_add_f32_e32 v31, v33, v31
	v_add_f32_e32 v30, v30, v32
	v_add_f32_e32 v32, v34, v31
	v_sub_f32_e32 v33, v32, v34
	v_sub_f32_e32 v31, v31, v33
	v_add_f32_e32 v30, v30, v31
	v_add_f32_e32 v30, v32, v30
	v_cndmask_b32_e32 v30, v227, v30, vcc
	v_cmp_ngt_f32_e32 vcc, -1.0, v29
	s_nop 1
	v_cndmask_b32_e32 v30, v228, v30, vcc
	v_cmp_neq_f32_e32 vcc, -1.0, v29
	s_nop 1
	v_cndmask_b32_e32 v30, v229, v30, vcc
	v_cmp_lt_f32_e64 vcc, |v29|, s13
	s_nop 1
	v_cndmask_b32_e32 v29, v30, v29, vcc
	v_sub_f32_e32 v28, v28, v29
	flat_store_dword v[6:7], v28 offset:20
	v_mov_b32_e32 v28, v112
	v_add_f32_e32 v27, v27, v28
	flat_store_dword v[6:7], v27 offset:8
	v_mov_b32_e32 v27, v116
	v_add_f32_e32 v27, v26, v27
	v_min_f32_e32 v26, 0, v27
	v_mul_f32_e64 v27, |v27|, s65
	v_exp_f32_e32 v27, v27
	s_nop 0
	v_add_f32_e32 v30, 1.0, v27
	v_add_f32_e32 v28, -1.0, v30
	v_sub_f32_e32 v29, v28, v30
	v_add_f32_e32 v29, 1.0, v29
	v_sub_f32_e32 v28, v27, v28
	v_add_f32_e32 v31, v28, v29
	v_frexp_mant_f32_e32 v28, v30
	v_cmp_gt_f32_e32 vcc, s4, v28
	v_cvt_f64_f32_e32 v[28:29], v30
	v_frexp_exp_i32_f64_e32 v28, v[28:29]
	v_subbrev_co_u32_e32 v28, vcc, 0, v28, vcc
	v_sub_u32_e32 v29, 0, v28
	v_ldexp_f32 v30, v30, v29
	v_ldexp_f32 v29, v31, v29
	v_add_f32_e32 v31, -1.0, v30
	v_add_f32_e32 v32, 1.0, v31
	v_sub_f32_e32 v32, v30, v32
	v_add_f32_e32 v32, v29, v32
	v_add_f32_e32 v33, v31, v32
	v_sub_f32_e32 v31, v33, v31
	v_sub_f32_e32 v31, v32, v31
	v_add_f32_e32 v32, 1.0, v30
	v_add_f32_e32 v34, -1.0, v32
	v_sub_f32_e32 v30, v30, v34
	v_add_f32_e32 v29, v29, v30
	v_add_f32_e32 v30, v32, v29
	v_sub_f32_e32 v32, v30, v32
	v_sub_f32_e32 v29, v29, v32
	v_rcp_f32_e32 v32, v30
	v_cvt_f32_i32_e32 v28, v28
	v_cmp_neq_f32_e32 vcc, s51, v27
	v_mul_f32_e32 v34, v33, v32
	v_mul_f32_e32 v35, v30, v34
	v_fma_f32 v36, v34, v30, -v35
	v_fmac_f32_e32 v36, v34, v29
	v_add_f32_e32 v37, v35, v36
	v_sub_f32_e32 v38, v33, v37
	v_sub_f32_e32 v33, v33, v38
	v_sub_f32_e32 v35, v37, v35
	v_sub_f32_e32 v33, v33, v37
	v_add_f32_e32 v31, v31, v33
	v_sub_f32_e32 v33, v35, v36
	v_add_f32_e32 v31, v33, v31
	v_add_f32_e32 v33, v38, v31
	v_mul_f32_e32 v35, v32, v33
	v_mul_f32_e32 v36, v30, v35
	v_fma_f32 v30, v35, v30, -v36
	v_fmac_f32_e32 v30, v35, v29
	v_sub_f32_e32 v29, v38, v33
	v_add_f32_e32 v29, v31, v29
	v_add_f32_e32 v31, v36, v30
	v_sub_f32_e32 v37, v33, v31
	v_sub_f32_e32 v33, v33, v37
	v_sub_f32_e32 v36, v31, v36
	v_sub_f32_e32 v31, v33, v31
	v_add_f32_e32 v29, v29, v31
	v_sub_f32_e32 v30, v36, v30
	v_add_f32_e32 v29, v30, v29
	v_add_f32_e32 v30, v34, v35
	v_add_f32_e32 v29, v37, v29
	v_sub_f32_e32 v31, v30, v34
	v_mul_f32_e32 v29, v32, v29
	v_sub_f32_e32 v31, v35, v31
	v_add_f32_e32 v29, v31, v29
	v_mul_f32_e32 v34, 0x3f317218, v28
	v_add_f32_e32 v31, v30, v29
	v_fma_f32 v35, v28, s5, -v34
	v_mul_f32_e32 v32, v31, v31
	v_fmac_f32_e32 v35, 0xb102e308, v28
	v_sub_f32_e32 v28, v31, v30
	v_fmamk_f32 v33, v32, 0x3e9b6dac, v226
	v_sub_f32_e32 v28, v29, v28
	v_add_f32_e32 v29, v34, v35
	v_fmaak_f32 v33, v32, v33, 0x3f2aaada
	v_sub_f32_e32 v30, v29, v34
	v_ldexp_f32 v34, v31, 1
	v_mul_f32_e32 v31, v31, v32
	v_mul_f32_e32 v31, v31, v33
	v_add_f32_e32 v32, v34, v31
	v_sub_f32_e32 v33, v32, v34
	v_ldexp_f32 v28, v28, 1
	v_sub_f32_e32 v31, v31, v33
	v_add_f32_e32 v28, v28, v31
	v_add_f32_e32 v31, v32, v28
	v_sub_f32_e32 v32, v31, v32
	v_sub_f32_e32 v28, v28, v32
	v_add_f32_e32 v32, v29, v31
	v_sub_f32_e32 v33, v32, v29
	v_sub_f32_e32 v34, v32, v33
	v_sub_f32_e32 v30, v35, v30
	v_sub_f32_e32 v29, v29, v34
	v_sub_f32_e32 v31, v31, v33
	v_add_f32_e32 v29, v31, v29
	v_add_f32_e32 v31, v30, v28
	v_sub_f32_e32 v33, v31, v30
	v_sub_f32_e32 v34, v31, v33
	v_sub_f32_e32 v30, v30, v34
	v_sub_f32_e32 v28, v28, v33
	v_add_f32_e32 v29, v31, v29
	v_add_f32_e32 v28, v28, v30
	v_add_f32_e32 v30, v32, v29
	v_sub_f32_e32 v31, v30, v32
	v_sub_f32_e32 v29, v29, v31
	v_add_f32_e32 v28, v28, v29
	v_add_f32_e32 v28, v30, v28
	v_cndmask_b32_e32 v28, v227, v28, vcc
	v_cmp_ngt_f32_e32 vcc, -1.0, v27
	s_nop 1
	v_cndmask_b32_e32 v28, v228, v28, vcc
	v_cmp_neq_f32_e32 vcc, -1.0, v27
	s_nop 1
	v_cndmask_b32_e32 v28, v229, v28, vcc
	v_cmp_lt_f32_e64 vcc, |v27|, s13
	s_nop 1
	v_cndmask_b32_e32 v27, v28, v27, vcc
	v_sub_f32_e32 v26, v26, v27
	flat_store_dword v[6:7], v26 offset:24
	v_mov_b32_e32 v26, v113
	v_add_f32_e32 v25, v25, v26
	flat_store_dword v[6:7], v25 offset:12
	v_mov_b32_e32 v25, v117
	v_add_f32_e32 v25, v24, v25
	v_min_f32_e32 v24, 0, v25
	v_mul_f32_e64 v25, |v25|, s65
	v_exp_f32_e32 v25, v25
	s_nop 0
	v_add_f32_e32 v28, 1.0, v25
; __device__ __forceinline__ float logsigmoidf_(float x) { return fminf(x, 0.f) - log1pf(__expf(-fabsf(x))); }
; __device__ __forceinline__ void preproc_phase(Frame& F, int layer, int b, int cu_lo, int ncu) {
;     ...
;         if (F.lane == 0) {
; #pragma unroll
;             for (int a = 0; a < 4; ++a)
; #pragma unroll
;                 for (int hh = 0; hh < 4; ++hh) { MG[(size_t)(t0 + a) * 8 + hh] = ai[a][hh] + INP(I_M_B_I)[layer * 4 + hh]; MG[(size_t)(t0 + a) * 8 + 4 + hh] = logsigmoidf_(af[a][hh] + INP(I_M_B_F)[layer * 4 + hh]); }
;         }
	v_add_f32_e32 v26, -1.0, v28
	v_sub_f32_e32 v27, v26, v28
	v_add_f32_e32 v27, 1.0, v27
	v_sub_f32_e32 v26, v25, v26
	v_add_f32_e32 v29, v26, v27
	v_frexp_mant_f32_e32 v26, v28
	v_cmp_gt_f32_e32 vcc, s4, v26
	v_cvt_f64_f32_e32 v[26:27], v28
	v_frexp_exp_i32_f64_e32 v26, v[26:27]
	v_subbrev_co_u32_e32 v26, vcc, 0, v26, vcc
	v_sub_u32_e32 v27, 0, v26
	v_ldexp_f32 v28, v28, v27
	v_ldexp_f32 v27, v29, v27
	v_add_f32_e32 v29, -1.0, v28
	v_add_f32_e32 v30, 1.0, v29
	v_sub_f32_e32 v30, v28, v30
	v_add_f32_e32 v30, v27, v30
	v_add_f32_e32 v31, v29, v30
	v_sub_f32_e32 v29, v31, v29
	v_sub_f32_e32 v29, v30, v29
	v_add_f32_e32 v30, 1.0, v28
	v_add_f32_e32 v32, -1.0, v30
	v_sub_f32_e32 v28, v28, v32
	v_add_f32_e32 v27, v27, v28
	v_add_f32_e32 v28, v30, v27
	v_sub_f32_e32 v30, v28, v30
	v_sub_f32_e32 v27, v27, v30
	v_rcp_f32_e32 v30, v28
	v_cvt_f32_i32_e32 v26, v26
	v_cmp_neq_f32_e32 vcc, s51, v25
	v_mul_f32_e32 v32, v31, v30
	v_mul_f32_e32 v33, v28, v32
	v_fma_f32 v34, v32, v28, -v33
	v_fmac_f32_e32 v34, v32, v27
	v_add_f32_e32 v35, v33, v34
	v_sub_f32_e32 v36, v31, v35
	v_sub_f32_e32 v31, v31, v36
	v_sub_f32_e32 v33, v35, v33
	v_sub_f32_e32 v31, v31, v35
	v_add_f32_e32 v29, v29, v31
	v_sub_f32_e32 v31, v33, v34
	v_add_f32_e32 v29, v31, v29
	v_add_f32_e32 v31, v36, v29
	v_mul_f32_e32 v33, v30, v31
	v_mul_f32_e32 v34, v28, v33
	v_fma_f32 v28, v33, v28, -v34
	v_fmac_f32_e32 v28, v33, v27
	v_sub_f32_e32 v27, v36, v31
	v_add_f32_e32 v27, v29, v27
	v_add_f32_e32 v29, v34, v28
	v_sub_f32_e32 v35, v31, v29
	v_sub_f32_e32 v31, v31, v35
	v_sub_f32_e32 v34, v29, v34
	v_sub_f32_e32 v29, v31, v29
	v_add_f32_e32 v27, v27, v29
	v_sub_f32_e32 v28, v34, v28
	v_add_f32_e32 v27, v28, v27
	v_add_f32_e32 v28, v32, v33
	v_add_f32_e32 v27, v35, v27
	v_sub_f32_e32 v29, v28, v32
	v_mul_f32_e32 v27, v30, v27
	v_sub_f32_e32 v29, v33, v29
	v_add_f32_e32 v27, v29, v27
	v_mul_f32_e32 v32, 0x3f317218, v26
	v_add_f32_e32 v29, v28, v27
	v_fma_f32 v33, v26, s5, -v32
	v_mul_f32_e32 v30, v29, v29
	v_fmac_f32_e32 v33, 0xb102e308, v26
	v_sub_f32_e32 v26, v29, v28
	v_fmamk_f32 v31, v30, 0x3e9b6dac, v226
	v_sub_f32_e32 v26, v27, v26
	v_add_f32_e32 v27, v32, v33
	v_fmaak_f32 v31, v30, v31, 0x3f2aaada
	v_sub_f32_e32 v28, v27, v32
	v_ldexp_f32 v32, v29, 1
	v_mul_f32_e32 v29, v29, v30
	v_mul_f32_e32 v29, v29, v31
	v_add_f32_e32 v30, v32, v29
	v_sub_f32_e32 v31, v30, v32
	v_ldexp_f32 v26, v26, 1
	v_sub_f32_e32 v29, v29, v31
	v_add_f32_e32 v26, v26, v29
	v_add_f32_e32 v29, v30, v26
	v_sub_f32_e32 v30, v29, v30
	v_sub_f32_e32 v26, v26, v30
	v_add_f32_e32 v30, v27, v29
	v_sub_f32_e32 v31, v30, v27
	v_sub_f32_e32 v32, v30, v31
	v_sub_f32_e32 v28, v33, v28
	v_sub_f32_e32 v27, v27, v32
	v_sub_f32_e32 v29, v29, v31
	v_add_f32_e32 v27, v29, v27
	v_add_f32_e32 v29, v28, v26
	v_sub_f32_e32 v31, v29, v28
	v_sub_f32_e32 v32, v29, v31
	v_sub_f32_e32 v28, v28, v32
	v_sub_f32_e32 v26, v26, v31
	v_add_f32_e32 v27, v29, v27
	v_add_f32_e32 v26, v26, v28
	v_add_f32_e32 v28, v30, v27
	v_sub_f32_e32 v29, v28, v30
	v_sub_f32_e32 v27, v27, v29
	v_add_f32_e32 v26, v26, v27
	v_add_f32_e32 v26, v28, v26
	v_cndmask_b32_e32 v26, v227, v26, vcc
	v_cmp_ngt_f32_e32 vcc, -1.0, v25
	s_nop 1
	v_cndmask_b32_e32 v26, v228, v26, vcc
	v_cmp_neq_f32_e32 vcc, -1.0, v25
	s_nop 1
	v_cndmask_b32_e32 v26, v229, v26, vcc
	v_cmp_lt_f32_e64 vcc, |v25|, s13
	s_nop 1
	v_cndmask_b32_e32 v25, v26, v25, vcc
	v_sub_f32_e32 v24, v24, v25
	flat_store_dword v[6:7], v24 offset:28
	v_mov_b32_e32 v6, v110
	v_add_f32_e32 v23, v23, v6
	v_mov_b64_e32 v[6:7], s[0:1]
	flat_store_dword v[6:7], v23
	v_mov_b32_e32 v23, v114
	s_lshl_b64 s[0:1], s[20:21], 5
	s_add_u32 s0, s49, s0
	s_addc_u32 s1, s54, s1
	v_add_f32_e32 v23, v22, v23
	v_min_f32_e32 v22, 0, v23
	v_mul_f32_e64 v23, |v23|, s65
	v_exp_f32_e32 v23, v23
	s_nop 0
	v_add_f32_e32 v26, 1.0, v23
	v_add_f32_e32 v24, -1.0, v26
	v_sub_f32_e32 v25, v24, v26
	v_add_f32_e32 v25, 1.0, v25
	v_sub_f32_e32 v24, v23, v24
	v_add_f32_e32 v27, v24, v25
	v_frexp_mant_f32_e32 v24, v26
	v_cmp_gt_f32_e32 vcc, s4, v24
	v_cvt_f64_f32_e32 v[24:25], v26
	v_frexp_exp_i32_f64_e32 v24, v[24:25]
	v_subbrev_co_u32_e32 v24, vcc, 0, v24, vcc
	v_sub_u32_e32 v25, 0, v24
	v_ldexp_f32 v26, v26, v25
	v_ldexp_f32 v25, v27, v25
	v_add_f32_e32 v27, -1.0, v26
	v_add_f32_e32 v28, 1.0, v27
	v_sub_f32_e32 v28, v26, v28
	v_add_f32_e32 v28, v25, v28
	v_add_f32_e32 v29, v27, v28
	v_sub_f32_e32 v27, v29, v27
	v_sub_f32_e32 v27, v28, v27
	v_add_f32_e32 v28, 1.0, v26
	v_add_f32_e32 v30, -1.0, v28
	v_sub_f32_e32 v26, v26, v30
	v_add_f32_e32 v25, v25, v26
	v_add_f32_e32 v26, v28, v25
	v_sub_f32_e32 v28, v26, v28
	v_sub_f32_e32 v25, v25, v28
	v_rcp_f32_e32 v28, v26
	v_cvt_f32_i32_e32 v24, v24
	v_cmp_neq_f32_e32 vcc, s51, v23
	v_mul_f32_e32 v30, v29, v28
	v_mul_f32_e32 v31, v26, v30
	v_fma_f32 v32, v30, v26, -v31
	v_fmac_f32_e32 v32, v30, v25
	v_add_f32_e32 v33, v31, v32
	v_sub_f32_e32 v34, v29, v33
	v_sub_f32_e32 v29, v29, v34
	v_sub_f32_e32 v31, v33, v31
	v_sub_f32_e32 v29, v29, v33
	v_add_f32_e32 v27, v27, v29
	v_sub_f32_e32 v29, v31, v32
	v_add_f32_e32 v27, v29, v27
	v_add_f32_e32 v29, v34, v27
	v_mul_f32_e32 v31, v28, v29
	v_mul_f32_e32 v32, v26, v31
	v_fma_f32 v26, v31, v26, -v32
	v_fmac_f32_e32 v26, v31, v25
	v_sub_f32_e32 v25, v34, v29
	v_add_f32_e32 v25, v27, v25
	v_add_f32_e32 v27, v32, v26
	v_sub_f32_e32 v33, v29, v27
	v_sub_f32_e32 v29, v29, v33
	v_sub_f32_e32 v32, v27, v32
	v_sub_f32_e32 v27, v29, v27
	v_add_f32_e32 v25, v25, v27
	v_sub_f32_e32 v26, v32, v26
	v_add_f32_e32 v25, v26, v25
	v_add_f32_e32 v26, v30, v31
	v_add_f32_e32 v25, v33, v25
	v_sub_f32_e32 v27, v26, v30
	v_mul_f32_e32 v25, v28, v25
	v_sub_f32_e32 v27, v31, v27
; __device__ __forceinline__ float logsigmoidf_(float x) { return fminf(x, 0.f) - log1pf(__expf(-fabsf(x))); }
; __device__ __forceinline__ void preproc_phase(Frame& F, int layer, int b, int cu_lo, int ncu) {
;     ...
;         if (F.lane == 0) {
; #pragma unroll
;             for (int a = 0; a < 4; ++a)
; #pragma unroll
;                 for (int hh = 0; hh < 4; ++hh) { MG[(size_t)(t0 + a) * 8 + hh] = ai[a][hh] + INP(I_M_B_I)[layer * 4 + hh]; MG[(size_t)(t0 + a) * 8 + 4 + hh] = logsigmoidf_(af[a][hh] + INP(I_M_B_F)[layer * 4 + hh]); }
;         }
	v_add_f32_e32 v25, v27, v25
	v_mul_f32_e32 v30, 0x3f317218, v24
	v_add_f32_e32 v27, v26, v25
	v_fma_f32 v31, v24, s5, -v30
	v_mul_f32_e32 v28, v27, v27
	v_fmac_f32_e32 v31, 0xb102e308, v24
	v_sub_f32_e32 v24, v27, v26
	v_fmamk_f32 v29, v28, 0x3e9b6dac, v226
	v_sub_f32_e32 v24, v25, v24
	v_add_f32_e32 v25, v30, v31
	v_fmaak_f32 v29, v28, v29, 0x3f2aaada
	v_sub_f32_e32 v26, v25, v30
	v_ldexp_f32 v30, v27, 1
	v_mul_f32_e32 v27, v27, v28
	v_mul_f32_e32 v27, v27, v29
	v_add_f32_e32 v28, v30, v27
	v_sub_f32_e32 v29, v28, v30
	v_ldexp_f32 v24, v24, 1
	v_sub_f32_e32 v27, v27, v29
	v_add_f32_e32 v24, v24, v27
	v_add_f32_e32 v27, v28, v24
	v_sub_f32_e32 v28, v27, v28
	v_sub_f32_e32 v24, v24, v28
	v_add_f32_e32 v28, v25, v27
	v_sub_f32_e32 v29, v28, v25
	v_sub_f32_e32 v30, v28, v29
	v_sub_f32_e32 v26, v31, v26
	v_sub_f32_e32 v25, v25, v30
	v_sub_f32_e32 v27, v27, v29
	v_add_f32_e32 v25, v27, v25
	v_add_f32_e32 v27, v26, v24
	v_sub_f32_e32 v29, v27, v26
	v_sub_f32_e32 v30, v27, v29
	v_sub_f32_e32 v26, v26, v30
	v_sub_f32_e32 v24, v24, v29
	v_add_f32_e32 v25, v27, v25
	v_add_f32_e32 v24, v24, v26
	v_add_f32_e32 v26, v28, v25
	v_sub_f32_e32 v27, v26, v28
	v_sub_f32_e32 v25, v25, v27
	v_add_f32_e32 v24, v24, v25
	v_add_f32_e32 v24, v26, v24
	v_cndmask_b32_e32 v24, v227, v24, vcc
	v_cmp_ngt_f32_e32 vcc, -1.0, v23
	s_nop 1
	v_cndmask_b32_e32 v24, v228, v24, vcc
	v_cmp_neq_f32_e32 vcc, -1.0, v23
	s_nop 1
	v_cndmask_b32_e32 v24, v229, v24, vcc
	v_cmp_lt_f32_e64 vcc, |v23|, s13
	s_nop 1
	v_cndmask_b32_e32 v23, v24, v23, vcc
	v_sub_f32_e32 v22, v22, v23
	flat_store_dword v[6:7], v22 offset:16
	v_mov_b32_e32 v22, v111
	v_add_f32_e32 v21, v21, v22
	flat_store_dword v[6:7], v21 offset:4
	v_mov_b32_e32 v21, v115
	v_add_f32_e32 v21, v20, v21
	v_min_f32_e32 v20, 0, v21
	v_mul_f32_e64 v21, |v21|, s65
	v_exp_f32_e32 v21, v21
	s_nop 0
	v_add_f32_e32 v24, 1.0, v21
	v_add_f32_e32 v22, -1.0, v24
	v_sub_f32_e32 v23, v22, v24
	v_add_f32_e32 v23, 1.0, v23
	v_sub_f32_e32 v22, v21, v22
	v_add_f32_e32 v25, v22, v23
	v_frexp_mant_f32_e32 v22, v24
	v_cmp_gt_f32_e32 vcc, s4, v22
	v_cvt_f64_f32_e32 v[22:23], v24
	v_frexp_exp_i32_f64_e32 v22, v[22:23]
	v_subbrev_co_u32_e32 v22, vcc, 0, v22, vcc
	v_sub_u32_e32 v23, 0, v22
	v_ldexp_f32 v24, v24, v23
	v_ldexp_f32 v23, v25, v23
	v_add_f32_e32 v25, -1.0, v24
	v_add_f32_e32 v26, 1.0, v25
	v_sub_f32_e32 v26, v24, v26
	v_add_f32_e32 v26, v23, v26
	v_add_f32_e32 v27, v25, v26
	v_sub_f32_e32 v25, v27, v25
	v_sub_f32_e32 v25, v26, v25
	v_add_f32_e32 v26, 1.0, v24
	v_add_f32_e32 v28, -1.0, v26
	v_sub_f32_e32 v24, v24, v28
	v_add_f32_e32 v23, v23, v24
	v_add_f32_e32 v24, v26, v23
	v_sub_f32_e32 v26, v24, v26
	v_sub_f32_e32 v23, v23, v26
	v_rcp_f32_e32 v26, v24
	v_cvt_f32_i32_e32 v22, v22
	v_cmp_neq_f32_e32 vcc, s51, v21
	v_mul_f32_e32 v28, v27, v26
	v_mul_f32_e32 v29, v24, v28
	v_fma_f32 v30, v28, v24, -v29
	v_fmac_f32_e32 v30, v28, v23
	v_add_f32_e32 v31, v29, v30
	v_sub_f32_e32 v32, v27, v31
	v_sub_f32_e32 v27, v27, v32
	v_sub_f32_e32 v29, v31, v29
	v_sub_f32_e32 v27, v27, v31
	v_add_f32_e32 v25, v25, v27
	v_sub_f32_e32 v27, v29, v30
	v_add_f32_e32 v25, v27, v25
	v_add_f32_e32 v27, v32, v25
	v_mul_f32_e32 v29, v26, v27
	v_mul_f32_e32 v30, v24, v29
	v_fma_f32 v24, v29, v24, -v30
	v_fmac_f32_e32 v24, v29, v23
	v_sub_f32_e32 v23, v32, v27
	v_add_f32_e32 v23, v25, v23
	v_add_f32_e32 v25, v30, v24
	v_sub_f32_e32 v31, v27, v25
	v_sub_f32_e32 v27, v27, v31
	v_sub_f32_e32 v30, v25, v30
	v_sub_f32_e32 v25, v27, v25
	v_add_f32_e32 v23, v23, v25
	v_sub_f32_e32 v24, v30, v24
	v_add_f32_e32 v23, v24, v23
	v_add_f32_e32 v24, v28, v29
	v_add_f32_e32 v23, v31, v23
	v_sub_f32_e32 v25, v24, v28
	v_mul_f32_e32 v23, v26, v23
	v_sub_f32_e32 v25, v29, v25
	v_add_f32_e32 v23, v25, v23
	v_mul_f32_e32 v28, 0x3f317218, v22
	v_add_f32_e32 v25, v24, v23
	v_fma_f32 v29, v22, s5, -v28
	v_mul_f32_e32 v26, v25, v25
	v_fmac_f32_e32 v29, 0xb102e308, v22
	v_sub_f32_e32 v22, v25, v24
	v_fmamk_f32 v27, v26, 0x3e9b6dac, v226
	v_sub_f32_e32 v22, v23, v22
	v_add_f32_e32 v23, v28, v29
	v_fmaak_f32 v27, v26, v27, 0x3f2aaada
	v_sub_f32_e32 v24, v23, v28
	v_ldexp_f32 v28, v25, 1
	v_mul_f32_e32 v25, v25, v26
	v_mul_f32_e32 v25, v25, v27
	v_add_f32_e32 v26, v28, v25
	v_sub_f32_e32 v27, v26, v28
	v_ldexp_f32 v22, v22, 1
	v_sub_f32_e32 v25, v25, v27
	v_add_f32_e32 v22, v22, v25
	v_add_f32_e32 v25, v26, v22
	v_sub_f32_e32 v26, v25, v26
	v_sub_f32_e32 v22, v22, v26
	v_add_f32_e32 v26, v23, v25
	v_sub_f32_e32 v27, v26, v23
	v_sub_f32_e32 v28, v26, v27
	v_sub_f32_e32 v24, v29, v24
	v_sub_f32_e32 v23, v23, v28
	v_sub_f32_e32 v25, v25, v27
	v_add_f32_e32 v23, v25, v23
	v_add_f32_e32 v25, v24, v22
	v_sub_f32_e32 v27, v25, v24
	v_sub_f32_e32 v28, v25, v27
	v_sub_f32_e32 v24, v24, v28
	v_sub_f32_e32 v22, v22, v27
	v_add_f32_e32 v23, v25, v23
	v_add_f32_e32 v22, v22, v24
	v_add_f32_e32 v24, v26, v23
	v_sub_f32_e32 v25, v24, v26
	v_sub_f32_e32 v23, v23, v25
	v_add_f32_e32 v22, v22, v23
	v_add_f32_e32 v22, v24, v22
	v_cndmask_b32_e32 v22, v227, v22, vcc
	v_cmp_ngt_f32_e32 vcc, -1.0, v21
	s_nop 1
	v_cndmask_b32_e32 v22, v228, v22, vcc
	v_cmp_neq_f32_e32 vcc, -1.0, v21
	s_nop 1
	v_cndmask_b32_e32 v22, v229, v22, vcc
	v_cmp_lt_f32_e64 vcc, |v21|, s13
	s_nop 1
	v_cndmask_b32_e32 v21, v22, v21, vcc
	v_sub_f32_e32 v20, v20, v21
	flat_store_dword v[6:7], v20 offset:20
	v_mov_b32_e32 v20, v112
	v_add_f32_e32 v19, v19, v20
	flat_store_dword v[6:7], v19 offset:8
	v_mov_b32_e32 v19, v116
	v_add_f32_e32 v19, v18, v19
	v_min_f32_e32 v18, 0, v19
	v_mul_f32_e64 v19, |v19|, s65
	v_exp_f32_e32 v19, v19
	s_nop 0
	v_add_f32_e32 v22, 1.0, v19
	v_add_f32_e32 v20, -1.0, v22
	v_sub_f32_e32 v21, v20, v22
	v_add_f32_e32 v21, 1.0, v21
; __device__ __forceinline__ float logsigmoidf_(float x) { return fminf(x, 0.f) - log1pf(__expf(-fabsf(x))); }
; __device__ __forceinline__ void preproc_phase(Frame& F, int layer, int b, int cu_lo, int ncu) {
;     ...
;         if (F.lane == 0) {
; #pragma unroll
;             for (int a = 0; a < 4; ++a)
; #pragma unroll
;                 for (int hh = 0; hh < 4; ++hh) { MG[(size_t)(t0 + a) * 8 + hh] = ai[a][hh] + INP(I_M_B_I)[layer * 4 + hh]; MG[(size_t)(t0 + a) * 8 + 4 + hh] = logsigmoidf_(af[a][hh] + INP(I_M_B_F)[layer * 4 + hh]); }
;         }
	v_sub_f32_e32 v20, v19, v20
	v_add_f32_e32 v23, v20, v21
	v_frexp_mant_f32_e32 v20, v22
	v_cmp_gt_f32_e32 vcc, s4, v20
	v_cvt_f64_f32_e32 v[20:21], v22
	v_frexp_exp_i32_f64_e32 v20, v[20:21]
	v_subbrev_co_u32_e32 v20, vcc, 0, v20, vcc
	v_sub_u32_e32 v21, 0, v20
	v_ldexp_f32 v22, v22, v21
	v_ldexp_f32 v21, v23, v21
	v_add_f32_e32 v23, -1.0, v22
	v_add_f32_e32 v24, 1.0, v23
	v_sub_f32_e32 v24, v22, v24
	v_add_f32_e32 v24, v21, v24
	v_add_f32_e32 v25, v23, v24
	v_sub_f32_e32 v23, v25, v23
	v_sub_f32_e32 v23, v24, v23
	v_add_f32_e32 v24, 1.0, v22
	v_add_f32_e32 v26, -1.0, v24
	v_sub_f32_e32 v22, v22, v26
	v_add_f32_e32 v21, v21, v22
	v_add_f32_e32 v22, v24, v21
	v_sub_f32_e32 v24, v22, v24
	v_sub_f32_e32 v21, v21, v24
	v_rcp_f32_e32 v24, v22
	v_cvt_f32_i32_e32 v20, v20
	v_cmp_neq_f32_e32 vcc, s51, v19
	v_mul_f32_e32 v26, v25, v24
	v_mul_f32_e32 v27, v22, v26
	v_fma_f32 v28, v26, v22, -v27
	v_fmac_f32_e32 v28, v26, v21
	v_add_f32_e32 v29, v27, v28
	v_sub_f32_e32 v30, v25, v29
	v_sub_f32_e32 v25, v25, v30
	v_sub_f32_e32 v27, v29, v27
	v_sub_f32_e32 v25, v25, v29
	v_add_f32_e32 v23, v23, v25
	v_sub_f32_e32 v25, v27, v28
	v_add_f32_e32 v23, v25, v23
	v_add_f32_e32 v25, v30, v23
	v_mul_f32_e32 v27, v24, v25
	v_mul_f32_e32 v28, v22, v27
	v_fma_f32 v22, v27, v22, -v28
	v_fmac_f32_e32 v22, v27, v21
	v_sub_f32_e32 v21, v30, v25
	v_add_f32_e32 v21, v23, v21
	v_add_f32_e32 v23, v28, v22
	v_sub_f32_e32 v29, v25, v23
	v_sub_f32_e32 v25, v25, v29
	v_sub_f32_e32 v28, v23, v28
	v_sub_f32_e32 v23, v25, v23
	v_add_f32_e32 v21, v21, v23
	v_sub_f32_e32 v22, v28, v22
	v_add_f32_e32 v21, v22, v21
	v_add_f32_e32 v22, v26, v27
	v_add_f32_e32 v21, v29, v21
	v_sub_f32_e32 v23, v22, v26
	v_mul_f32_e32 v21, v24, v21
	v_sub_f32_e32 v23, v27, v23
	v_add_f32_e32 v21, v23, v21
	v_mul_f32_e32 v26, 0x3f317218, v20
	v_add_f32_e32 v23, v22, v21
	v_fma_f32 v27, v20, s5, -v26
	v_mul_f32_e32 v24, v23, v23
	v_fmac_f32_e32 v27, 0xb102e308, v20
	v_sub_f32_e32 v20, v23, v22
	v_fmamk_f32 v25, v24, 0x3e9b6dac, v226
	v_sub_f32_e32 v20, v21, v20
	v_add_f32_e32 v21, v26, v27
	v_fmaak_f32 v25, v24, v25, 0x3f2aaada
	v_sub_f32_e32 v22, v21, v26
	v_ldexp_f32 v26, v23, 1
	v_mul_f32_e32 v23, v23, v24
	v_mul_f32_e32 v23, v23, v25
	v_add_f32_e32 v24, v26, v23
	v_sub_f32_e32 v25, v24, v26
	v_ldexp_f32 v20, v20, 1
	v_sub_f32_e32 v23, v23, v25
	v_add_f32_e32 v20, v20, v23
	v_add_f32_e32 v23, v24, v20
	v_sub_f32_e32 v24, v23, v24
	v_sub_f32_e32 v20, v20, v24
	v_add_f32_e32 v24, v21, v23
	v_sub_f32_e32 v25, v24, v21
	v_sub_f32_e32 v26, v24, v25
	v_sub_f32_e32 v22, v27, v22
	v_sub_f32_e32 v21, v21, v26
	v_sub_f32_e32 v23, v23, v25
	v_add_f32_e32 v21, v23, v21
	v_add_f32_e32 v23, v22, v20
	v_sub_f32_e32 v25, v23, v22
	v_sub_f32_e32 v26, v23, v25
	v_sub_f32_e32 v22, v22, v26
	v_sub_f32_e32 v20, v20, v25
	v_add_f32_e32 v21, v23, v21
	v_add_f32_e32 v20, v20, v22
	v_add_f32_e32 v22, v24, v21
	v_sub_f32_e32 v23, v22, v24
	v_sub_f32_e32 v21, v21, v23
	v_add_f32_e32 v20, v20, v21
	v_add_f32_e32 v20, v22, v20
	v_cndmask_b32_e32 v20, v227, v20, vcc
	v_cmp_ngt_f32_e32 vcc, -1.0, v19
	s_nop 1
	v_cndmask_b32_e32 v20, v228, v20, vcc
	v_cmp_neq_f32_e32 vcc, -1.0, v19
	s_nop 1
	v_cndmask_b32_e32 v20, v229, v20, vcc
	v_cmp_lt_f32_e64 vcc, |v19|, s13
	s_nop 1
	v_cndmask_b32_e32 v19, v20, v19, vcc
	v_sub_f32_e32 v18, v18, v19
	flat_store_dword v[6:7], v18 offset:24
	v_mov_b32_e32 v18, v113
	v_add_f32_e32 v17, v17, v18
	flat_store_dword v[6:7], v17 offset:12
	v_mov_b32_e32 v17, v117
	v_add_f32_e32 v17, v16, v17
	v_min_f32_e32 v16, 0, v17
	v_mul_f32_e64 v17, |v17|, s65
	v_exp_f32_e32 v17, v17
	s_nop 0
	v_add_f32_e32 v20, 1.0, v17
	v_add_f32_e32 v18, -1.0, v20
	v_sub_f32_e32 v19, v18, v20
	v_add_f32_e32 v19, 1.0, v19
	v_sub_f32_e32 v18, v17, v18
	v_add_f32_e32 v21, v18, v19
	v_frexp_mant_f32_e32 v18, v20
	v_cmp_gt_f32_e32 vcc, s4, v18
	v_cvt_f64_f32_e32 v[18:19], v20
	v_frexp_exp_i32_f64_e32 v18, v[18:19]
	v_subbrev_co_u32_e32 v18, vcc, 0, v18, vcc
	v_sub_u32_e32 v19, 0, v18
	v_ldexp_f32 v20, v20, v19
	v_ldexp_f32 v19, v21, v19
	v_add_f32_e32 v21, -1.0, v20
	v_add_f32_e32 v22, 1.0, v21
	v_sub_f32_e32 v22, v20, v22
	v_add_f32_e32 v22, v19, v22
	v_add_f32_e32 v23, v21, v22
	v_sub_f32_e32 v21, v23, v21
	v_sub_f32_e32 v21, v22, v21
	v_add_f32_e32 v22, 1.0, v20
	v_add_f32_e32 v24, -1.0, v22
	v_sub_f32_e32 v20, v20, v24
	v_add_f32_e32 v19, v19, v20
	v_add_f32_e32 v20, v22, v19
	v_sub_f32_e32 v22, v20, v22
	v_sub_f32_e32 v19, v19, v22
	v_rcp_f32_e32 v22, v20
	v_cvt_f32_i32_e32 v18, v18
	v_cmp_neq_f32_e32 vcc, s51, v17
	v_mul_f32_e32 v24, v23, v22
	v_mul_f32_e32 v25, v20, v24
	v_fma_f32 v26, v24, v20, -v25
	v_fmac_f32_e32 v26, v24, v19
	v_add_f32_e32 v27, v25, v26
	v_sub_f32_e32 v28, v23, v27
	v_sub_f32_e32 v23, v23, v28
	v_sub_f32_e32 v25, v27, v25
	v_sub_f32_e32 v23, v23, v27
	v_add_f32_e32 v21, v21, v23
	v_sub_f32_e32 v23, v25, v26
	v_add_f32_e32 v21, v23, v21
	v_add_f32_e32 v23, v28, v21
	v_mul_f32_e32 v25, v22, v23
	v_mul_f32_e32 v26, v20, v25
	v_fma_f32 v20, v25, v20, -v26
	v_fmac_f32_e32 v20, v25, v19
	v_sub_f32_e32 v19, v28, v23
	v_add_f32_e32 v19, v21, v19
	v_add_f32_e32 v21, v26, v20
	v_sub_f32_e32 v27, v23, v21
	v_sub_f32_e32 v23, v23, v27
	v_sub_f32_e32 v26, v21, v26
	v_sub_f32_e32 v21, v23, v21
	v_add_f32_e32 v19, v19, v21
	v_sub_f32_e32 v20, v26, v20
	v_add_f32_e32 v19, v20, v19
	v_add_f32_e32 v20, v24, v25
	v_add_f32_e32 v19, v27, v19
	v_sub_f32_e32 v21, v20, v24
	v_mul_f32_e32 v19, v22, v19
	v_sub_f32_e32 v21, v25, v21
	v_add_f32_e32 v19, v21, v19
	v_mul_f32_e32 v24, 0x3f317218, v18
	v_add_f32_e32 v21, v20, v19
	v_fma_f32 v25, v18, s5, -v24
	v_mul_f32_e32 v22, v21, v21
	v_fmac_f32_e32 v25, 0xb102e308, v18
; __device__ __forceinline__ float logsigmoidf_(float x) { return fminf(x, 0.f) - log1pf(__expf(-fabsf(x))); }
; __device__ __forceinline__ void preproc_phase(Frame& F, int layer, int b, int cu_lo, int ncu) {
;     ...
;         if (F.lane == 0) {
; #pragma unroll
;             for (int a = 0; a < 4; ++a)
; #pragma unroll
;                 for (int hh = 0; hh < 4; ++hh) { MG[(size_t)(t0 + a) * 8 + hh] = ai[a][hh] + INP(I_M_B_I)[layer * 4 + hh]; MG[(size_t)(t0 + a) * 8 + 4 + hh] = logsigmoidf_(af[a][hh] + INP(I_M_B_F)[layer * 4 + hh]); }
;         }
	v_sub_f32_e32 v18, v21, v20
	v_fmamk_f32 v23, v22, 0x3e9b6dac, v226
	v_sub_f32_e32 v18, v19, v18
	v_add_f32_e32 v19, v24, v25
	v_fmaak_f32 v23, v22, v23, 0x3f2aaada
	v_sub_f32_e32 v20, v19, v24
	v_ldexp_f32 v24, v21, 1
	v_mul_f32_e32 v21, v21, v22
	v_mul_f32_e32 v21, v21, v23
	v_add_f32_e32 v22, v24, v21
	v_sub_f32_e32 v23, v22, v24
	v_ldexp_f32 v18, v18, 1
	v_sub_f32_e32 v21, v21, v23
	v_add_f32_e32 v18, v18, v21
	v_add_f32_e32 v21, v22, v18
	v_sub_f32_e32 v22, v21, v22
	v_sub_f32_e32 v18, v18, v22
	v_add_f32_e32 v22, v19, v21
	v_sub_f32_e32 v23, v22, v19
	v_sub_f32_e32 v24, v22, v23
	v_sub_f32_e32 v20, v25, v20
	v_sub_f32_e32 v19, v19, v24
	v_sub_f32_e32 v21, v21, v23
	v_add_f32_e32 v19, v21, v19
	v_add_f32_e32 v21, v20, v18
	v_sub_f32_e32 v23, v21, v20
	v_sub_f32_e32 v24, v21, v23
	v_sub_f32_e32 v20, v20, v24
	v_sub_f32_e32 v18, v18, v23
	v_add_f32_e32 v19, v21, v19
	v_add_f32_e32 v18, v18, v20
	v_add_f32_e32 v20, v22, v19
	v_sub_f32_e32 v21, v20, v22
	v_sub_f32_e32 v19, v19, v21
	v_add_f32_e32 v18, v18, v19
	v_add_f32_e32 v18, v20, v18
	v_cndmask_b32_e32 v18, v227, v18, vcc
	v_cmp_ngt_f32_e32 vcc, -1.0, v17
	s_nop 1
	v_cndmask_b32_e32 v18, v228, v18, vcc
	v_cmp_neq_f32_e32 vcc, -1.0, v17
	s_nop 1
	v_cndmask_b32_e32 v18, v229, v18, vcc
	v_cmp_lt_f32_e64 vcc, |v17|, s13
	s_nop 1
	v_cndmask_b32_e32 v17, v18, v17, vcc
	v_sub_f32_e32 v16, v16, v17
	flat_store_dword v[6:7], v16 offset:28
	v_mov_b32_e32 v6, v110
	v_add_f32_e32 v15, v15, v6
	v_mov_b64_e32 v[6:7], s[0:1]
	flat_store_dword v[6:7], v15
	v_mov_b32_e32 v15, v114
	v_add_f32_e32 v15, v14, v15
	v_min_f32_e32 v14, 0, v15
	v_mul_f32_e64 v15, |v15|, s65
	v_exp_f32_e32 v15, v15
	s_nop 0
	v_add_f32_e32 v18, 1.0, v15
	v_add_f32_e32 v16, -1.0, v18
	v_sub_f32_e32 v17, v16, v18
	v_add_f32_e32 v17, 1.0, v17
	v_sub_f32_e32 v16, v15, v16
	v_add_f32_e32 v19, v16, v17
	v_frexp_mant_f32_e32 v16, v18
	v_cmp_gt_f32_e32 vcc, s4, v16
	v_cvt_f64_f32_e32 v[16:17], v18
	v_frexp_exp_i32_f64_e32 v16, v[16:17]
	v_subbrev_co_u32_e32 v16, vcc, 0, v16, vcc
	v_sub_u32_e32 v17, 0, v16
	v_ldexp_f32 v18, v18, v17
	v_ldexp_f32 v17, v19, v17
	v_add_f32_e32 v19, -1.0, v18
	v_add_f32_e32 v20, 1.0, v19
	v_sub_f32_e32 v20, v18, v20
	v_add_f32_e32 v20, v17, v20
	v_add_f32_e32 v21, v19, v20
	v_sub_f32_e32 v19, v21, v19
	v_sub_f32_e32 v19, v20, v19
	v_add_f32_e32 v20, 1.0, v18
	v_add_f32_e32 v22, -1.0, v20
	v_sub_f32_e32 v18, v18, v22
	v_add_f32_e32 v17, v17, v18
	v_add_f32_e32 v18, v20, v17
	v_sub_f32_e32 v20, v18, v20
	v_sub_f32_e32 v17, v17, v20
	v_rcp_f32_e32 v20, v18
	v_cvt_f32_i32_e32 v16, v16
	v_cmp_neq_f32_e32 vcc, s51, v15
	v_mul_f32_e32 v22, v21, v20
	v_mul_f32_e32 v23, v18, v22
	v_fma_f32 v24, v22, v18, -v23
	v_fmac_f32_e32 v24, v22, v17
	v_add_f32_e32 v25, v23, v24
	v_sub_f32_e32 v26, v21, v25
	v_sub_f32_e32 v21, v21, v26
	v_sub_f32_e32 v23, v25, v23
	v_sub_f32_e32 v21, v21, v25
	v_add_f32_e32 v19, v19, v21
	v_sub_f32_e32 v21, v23, v24
	v_add_f32_e32 v19, v21, v19
	v_add_f32_e32 v21, v26, v19
	v_mul_f32_e32 v23, v20, v21
	v_mul_f32_e32 v24, v18, v23
	v_fma_f32 v18, v23, v18, -v24
	v_fmac_f32_e32 v18, v23, v17
	v_sub_f32_e32 v17, v26, v21
	v_add_f32_e32 v17, v19, v17
	v_add_f32_e32 v19, v24, v18
	v_sub_f32_e32 v25, v21, v19
	v_sub_f32_e32 v21, v21, v25
	v_sub_f32_e32 v24, v19, v24
	v_sub_f32_e32 v19, v21, v19
	v_add_f32_e32 v17, v17, v19
	v_sub_f32_e32 v18, v24, v18
	v_add_f32_e32 v17, v18, v17
	v_add_f32_e32 v18, v22, v23
	v_add_f32_e32 v17, v25, v17
	v_sub_f32_e32 v19, v18, v22
	v_mul_f32_e32 v17, v20, v17
	v_sub_f32_e32 v19, v23, v19
	v_add_f32_e32 v17, v19, v17
	v_mul_f32_e32 v22, 0x3f317218, v16
	v_add_f32_e32 v19, v18, v17
	v_fma_f32 v23, v16, s5, -v22
	v_mul_f32_e32 v20, v19, v19
	v_fmac_f32_e32 v23, 0xb102e308, v16
	v_sub_f32_e32 v16, v19, v18
	v_fmamk_f32 v21, v20, 0x3e9b6dac, v226
	v_sub_f32_e32 v16, v17, v16
	v_add_f32_e32 v17, v22, v23
	v_fmaak_f32 v21, v20, v21, 0x3f2aaada
	v_sub_f32_e32 v18, v17, v22
	v_ldexp_f32 v22, v19, 1
	v_mul_f32_e32 v19, v19, v20
	v_mul_f32_e32 v19, v19, v21
	v_add_f32_e32 v20, v22, v19
	v_sub_f32_e32 v21, v20, v22
	v_ldexp_f32 v16, v16, 1
	v_sub_f32_e32 v19, v19, v21
	v_add_f32_e32 v16, v16, v19
	v_add_f32_e32 v19, v20, v16
	v_sub_f32_e32 v20, v19, v20
	v_sub_f32_e32 v16, v16, v20
	v_add_f32_e32 v20, v17, v19
	v_sub_f32_e32 v21, v20, v17
	v_sub_f32_e32 v22, v20, v21
	v_sub_f32_e32 v18, v23, v18
	v_sub_f32_e32 v17, v17, v22
	v_sub_f32_e32 v19, v19, v21
	v_add_f32_e32 v17, v19, v17
	v_add_f32_e32 v19, v18, v16
	v_sub_f32_e32 v21, v19, v18
	v_sub_f32_e32 v22, v19, v21
	v_sub_f32_e32 v18, v18, v22
	v_sub_f32_e32 v16, v16, v21
	v_add_f32_e32 v17, v19, v17
	v_add_f32_e32 v16, v16, v18
	v_add_f32_e32 v18, v20, v17
	v_sub_f32_e32 v19, v18, v20
	v_sub_f32_e32 v17, v17, v19
	v_add_f32_e32 v16, v16, v17
	v_add_f32_e32 v16, v18, v16
	v_cndmask_b32_e32 v16, v227, v16, vcc
	v_cmp_ngt_f32_e32 vcc, -1.0, v15
	s_nop 1
	v_cndmask_b32_e32 v16, v228, v16, vcc
	v_cmp_neq_f32_e32 vcc, -1.0, v15
	s_nop 1
	v_cndmask_b32_e32 v16, v229, v16, vcc
	v_cmp_lt_f32_e64 vcc, |v15|, s13
	s_nop 1
	v_cndmask_b32_e32 v15, v16, v15, vcc
	v_sub_f32_e32 v14, v14, v15
	flat_store_dword v[6:7], v14 offset:16
	v_mov_b32_e32 v14, v111
	v_add_f32_e32 v13, v13, v14
	flat_store_dword v[6:7], v13 offset:4
	v_mov_b32_e32 v13, v115
	v_add_f32_e32 v13, v12, v13
	v_min_f32_e32 v12, 0, v13
	v_mul_f32_e64 v13, |v13|, s65
	v_exp_f32_e32 v13, v13
	s_nop 0
	v_add_f32_e32 v16, 1.0, v13
	v_add_f32_e32 v14, -1.0, v16
	v_sub_f32_e32 v15, v14, v16
	v_add_f32_e32 v15, 1.0, v15
	v_sub_f32_e32 v14, v13, v14
	v_add_f32_e32 v17, v14, v15
	v_frexp_mant_f32_e32 v14, v16
	v_cmp_gt_f32_e32 vcc, s4, v14
	v_cvt_f64_f32_e32 v[14:15], v16
; __device__ __forceinline__ float logsigmoidf_(float x) { return fminf(x, 0.f) - log1pf(__expf(-fabsf(x))); }
; __device__ __forceinline__ void preproc_phase(Frame& F, int layer, int b, int cu_lo, int ncu) {
;     ...
;         if (F.lane == 0) {
; #pragma unroll
;             for (int a = 0; a < 4; ++a)
; #pragma unroll
;                 for (int hh = 0; hh < 4; ++hh) { MG[(size_t)(t0 + a) * 8 + hh] = ai[a][hh] + INP(I_M_B_I)[layer * 4 + hh]; MG[(size_t)(t0 + a) * 8 + 4 + hh] = logsigmoidf_(af[a][hh] + INP(I_M_B_F)[layer * 4 + hh]); }
;         }
	v_frexp_exp_i32_f64_e32 v14, v[14:15]
	v_subbrev_co_u32_e32 v14, vcc, 0, v14, vcc
	v_sub_u32_e32 v15, 0, v14
	v_ldexp_f32 v16, v16, v15
	v_ldexp_f32 v15, v17, v15
	v_add_f32_e32 v17, -1.0, v16
	v_add_f32_e32 v18, 1.0, v17
	v_sub_f32_e32 v18, v16, v18
	v_add_f32_e32 v18, v15, v18
	v_add_f32_e32 v19, v17, v18
	v_sub_f32_e32 v17, v19, v17
	v_sub_f32_e32 v17, v18, v17
	v_add_f32_e32 v18, 1.0, v16
	v_add_f32_e32 v20, -1.0, v18
	v_sub_f32_e32 v16, v16, v20
	v_add_f32_e32 v15, v15, v16
	v_add_f32_e32 v16, v18, v15
	v_sub_f32_e32 v18, v16, v18
	v_sub_f32_e32 v15, v15, v18
	v_rcp_f32_e32 v18, v16
	v_cvt_f32_i32_e32 v14, v14
	v_cmp_neq_f32_e32 vcc, s51, v13
	v_mul_f32_e32 v20, v19, v18
	v_mul_f32_e32 v21, v16, v20
	v_fma_f32 v22, v20, v16, -v21
	v_fmac_f32_e32 v22, v20, v15
	v_add_f32_e32 v23, v21, v22
	v_sub_f32_e32 v24, v19, v23
	v_sub_f32_e32 v19, v19, v24
	v_sub_f32_e32 v21, v23, v21
	v_sub_f32_e32 v19, v19, v23
	v_add_f32_e32 v17, v17, v19
	v_sub_f32_e32 v19, v21, v22
	v_add_f32_e32 v17, v19, v17
	v_add_f32_e32 v19, v24, v17
	v_mul_f32_e32 v21, v18, v19
	v_mul_f32_e32 v22, v16, v21
	v_fma_f32 v16, v21, v16, -v22
	v_fmac_f32_e32 v16, v21, v15
	v_sub_f32_e32 v15, v24, v19
	v_add_f32_e32 v15, v17, v15
	v_add_f32_e32 v17, v22, v16
	v_sub_f32_e32 v23, v19, v17
	v_sub_f32_e32 v19, v19, v23
	v_sub_f32_e32 v22, v17, v22
	v_sub_f32_e32 v17, v19, v17
	v_add_f32_e32 v15, v15, v17
	v_sub_f32_e32 v16, v22, v16
	v_add_f32_e32 v15, v16, v15
	v_add_f32_e32 v16, v20, v21
	v_add_f32_e32 v15, v23, v15
	v_sub_f32_e32 v17, v16, v20
	v_mul_f32_e32 v15, v18, v15
	v_sub_f32_e32 v17, v21, v17
	v_add_f32_e32 v15, v17, v15
	v_mul_f32_e32 v20, 0x3f317218, v14
	v_add_f32_e32 v17, v16, v15
	v_fma_f32 v21, v14, s5, -v20
	v_mul_f32_e32 v18, v17, v17
	v_fmac_f32_e32 v21, 0xb102e308, v14
	v_sub_f32_e32 v14, v17, v16
	v_fmamk_f32 v19, v18, 0x3e9b6dac, v226
	v_sub_f32_e32 v14, v15, v14
	v_add_f32_e32 v15, v20, v21
	v_fmaak_f32 v19, v18, v19, 0x3f2aaada
	v_sub_f32_e32 v16, v15, v20
	v_ldexp_f32 v20, v17, 1
	v_mul_f32_e32 v17, v17, v18
	v_mul_f32_e32 v17, v17, v19
	v_add_f32_e32 v18, v20, v17
	v_sub_f32_e32 v19, v18, v20
	v_ldexp_f32 v14, v14, 1
	v_sub_f32_e32 v17, v17, v19
	v_add_f32_e32 v14, v14, v17
	v_add_f32_e32 v17, v18, v14
	v_sub_f32_e32 v18, v17, v18
	v_sub_f32_e32 v14, v14, v18
	v_add_f32_e32 v18, v15, v17
	v_sub_f32_e32 v19, v18, v15
	v_sub_f32_e32 v20, v18, v19
	v_sub_f32_e32 v16, v21, v16
	v_sub_f32_e32 v15, v15, v20
	v_sub_f32_e32 v17, v17, v19
	v_add_f32_e32 v15, v17, v15
	v_add_f32_e32 v17, v16, v14
	v_sub_f32_e32 v19, v17, v16
	v_sub_f32_e32 v20, v17, v19
	v_sub_f32_e32 v16, v16, v20
	v_sub_f32_e32 v14, v14, v19
	v_add_f32_e32 v15, v17, v15
	v_add_f32_e32 v14, v14, v16
	v_add_f32_e32 v16, v18, v15
	v_sub_f32_e32 v17, v16, v18
	v_sub_f32_e32 v15, v15, v17
	v_add_f32_e32 v14, v14, v15
	v_add_f32_e32 v14, v16, v14
	v_cndmask_b32_e32 v14, v227, v14, vcc
	v_cmp_ngt_f32_e32 vcc, -1.0, v13
	s_nop 1
	v_cndmask_b32_e32 v14, v228, v14, vcc
	v_cmp_neq_f32_e32 vcc, -1.0, v13
	s_nop 1
	v_cndmask_b32_e32 v14, v229, v14, vcc
	v_cmp_lt_f32_e64 vcc, |v13|, s13
	s_nop 1
	v_cndmask_b32_e32 v13, v14, v13, vcc
	v_sub_f32_e32 v12, v12, v13
	flat_store_dword v[6:7], v12 offset:20
	v_mov_b32_e32 v12, v112
	v_add_f32_e32 v11, v11, v12
	flat_store_dword v[6:7], v11 offset:8
	v_mov_b32_e32 v11, v116
	v_add_f32_e32 v11, v10, v11
	v_min_f32_e32 v10, 0, v11
	v_mul_f32_e64 v11, |v11|, s65
	v_exp_f32_e32 v11, v11
	s_nop 0
	v_add_f32_e32 v14, 1.0, v11
	v_add_f32_e32 v12, -1.0, v14
	v_sub_f32_e32 v13, v12, v14
	v_add_f32_e32 v13, 1.0, v13
	v_sub_f32_e32 v12, v11, v12
	v_add_f32_e32 v15, v12, v13
	v_frexp_mant_f32_e32 v12, v14
	v_cmp_gt_f32_e32 vcc, s4, v12
	v_cvt_f64_f32_e32 v[12:13], v14
	v_frexp_exp_i32_f64_e32 v12, v[12:13]
	v_subbrev_co_u32_e32 v12, vcc, 0, v12, vcc
	v_sub_u32_e32 v13, 0, v12
	v_ldexp_f32 v14, v14, v13
	v_ldexp_f32 v13, v15, v13
	v_add_f32_e32 v15, -1.0, v14
	v_add_f32_e32 v16, 1.0, v15
	v_sub_f32_e32 v16, v14, v16
	v_add_f32_e32 v16, v13, v16
	v_add_f32_e32 v17, v15, v16
	v_sub_f32_e32 v15, v17, v15
	v_sub_f32_e32 v15, v16, v15
	v_add_f32_e32 v16, 1.0, v14
	v_add_f32_e32 v18, -1.0, v16
	v_sub_f32_e32 v14, v14, v18
	v_add_f32_e32 v13, v13, v14
	v_add_f32_e32 v14, v16, v13
	v_sub_f32_e32 v16, v14, v16
	v_sub_f32_e32 v13, v13, v16
	v_rcp_f32_e32 v16, v14
	v_cvt_f32_i32_e32 v12, v12
	v_cmp_neq_f32_e32 vcc, s51, v11
	v_mul_f32_e32 v18, v17, v16
	v_mul_f32_e32 v19, v14, v18
	v_fma_f32 v20, v18, v14, -v19
	v_fmac_f32_e32 v20, v18, v13
	v_add_f32_e32 v21, v19, v20
	v_sub_f32_e32 v22, v17, v21
	v_sub_f32_e32 v17, v17, v22
	v_sub_f32_e32 v19, v21, v19
	v_sub_f32_e32 v17, v17, v21
	v_add_f32_e32 v15, v15, v17
	v_sub_f32_e32 v17, v19, v20
	v_add_f32_e32 v15, v17, v15
	v_add_f32_e32 v17, v22, v15
	v_mul_f32_e32 v19, v16, v17
	v_mul_f32_e32 v20, v14, v19
	v_fma_f32 v14, v19, v14, -v20
	v_fmac_f32_e32 v14, v19, v13
	v_sub_f32_e32 v13, v22, v17
	v_add_f32_e32 v13, v15, v13
	v_add_f32_e32 v15, v20, v14
	v_sub_f32_e32 v21, v17, v15
	v_sub_f32_e32 v17, v17, v21
	v_sub_f32_e32 v20, v15, v20
	v_sub_f32_e32 v15, v17, v15
	v_add_f32_e32 v13, v13, v15
	v_sub_f32_e32 v14, v20, v14
	v_add_f32_e32 v13, v14, v13
	v_add_f32_e32 v14, v18, v19
	v_add_f32_e32 v13, v21, v13
; __device__ __forceinline__ float logsigmoidf_(float x) { return fminf(x, 0.f) - log1pf(__expf(-fabsf(x))); }
; __device__ __forceinline__ void preproc_phase(Frame& F, int layer, int b, int cu_lo, int ncu) {
;     ...
;         if (F.lane == 0) {
; #pragma unroll
;             for (int a = 0; a < 4; ++a)
; #pragma unroll
;                 for (int hh = 0; hh < 4; ++hh) { MG[(size_t)(t0 + a) * 8 + hh] = ai[a][hh] + INP(I_M_B_I)[layer * 4 + hh]; MG[(size_t)(t0 + a) * 8 + 4 + hh] = logsigmoidf_(af[a][hh] + INP(I_M_B_F)[layer * 4 + hh]); }
;         }
	v_sub_f32_e32 v15, v14, v18
	v_mul_f32_e32 v13, v16, v13
	v_sub_f32_e32 v15, v19, v15
	v_add_f32_e32 v13, v15, v13
	v_mul_f32_e32 v18, 0x3f317218, v12
	v_add_f32_e32 v15, v14, v13
	v_fma_f32 v19, v12, s5, -v18
	v_mul_f32_e32 v16, v15, v15
	v_fmac_f32_e32 v19, 0xb102e308, v12
	v_sub_f32_e32 v12, v15, v14
	v_fmamk_f32 v17, v16, 0x3e9b6dac, v226
	v_sub_f32_e32 v12, v13, v12
	v_add_f32_e32 v13, v18, v19
	v_fmaak_f32 v17, v16, v17, 0x3f2aaada
	v_sub_f32_e32 v14, v13, v18
	v_ldexp_f32 v18, v15, 1
	v_mul_f32_e32 v15, v15, v16
	v_mul_f32_e32 v15, v15, v17
	v_add_f32_e32 v16, v18, v15
	v_sub_f32_e32 v17, v16, v18
	v_ldexp_f32 v12, v12, 1
	v_sub_f32_e32 v15, v15, v17
	v_add_f32_e32 v12, v12, v15
	v_add_f32_e32 v15, v16, v12
	v_sub_f32_e32 v16, v15, v16
	v_sub_f32_e32 v12, v12, v16
	v_add_f32_e32 v16, v13, v15
	v_sub_f32_e32 v17, v16, v13
	v_sub_f32_e32 v18, v16, v17
	v_sub_f32_e32 v14, v19, v14
	v_sub_f32_e32 v13, v13, v18
	v_sub_f32_e32 v15, v15, v17
	v_add_f32_e32 v13, v15, v13
	v_add_f32_e32 v15, v14, v12
	v_sub_f32_e32 v17, v15, v14
	v_sub_f32_e32 v18, v15, v17
	v_sub_f32_e32 v14, v14, v18
	v_sub_f32_e32 v12, v12, v17
	v_add_f32_e32 v13, v15, v13
	v_add_f32_e32 v12, v12, v14
	v_add_f32_e32 v14, v16, v13
	v_sub_f32_e32 v15, v14, v16
	v_sub_f32_e32 v13, v13, v15
	v_add_f32_e32 v12, v12, v13
	v_add_f32_e32 v12, v14, v12
	v_cndmask_b32_e32 v12, v227, v12, vcc
	v_cmp_ngt_f32_e32 vcc, -1.0, v11
	s_nop 1
	v_cndmask_b32_e32 v12, v228, v12, vcc
	v_cmp_neq_f32_e32 vcc, -1.0, v11
	s_nop 1
	v_cndmask_b32_e32 v12, v229, v12, vcc
	v_cmp_lt_f32_e64 vcc, |v11|, s13
	s_nop 1
	v_cndmask_b32_e32 v11, v12, v11, vcc
	v_sub_f32_e32 v10, v10, v11
	flat_store_dword v[6:7], v10 offset:24
	v_mov_b32_e32 v2, v113
	v_add_f32_e32 v2, v9, v2
	flat_store_dword v[6:7], v2 offset:12
	v_mov_b32_e32 v2, v117
	v_add_f32_e32 v3, v8, v2
	v_min_f32_e32 v2, 0, v3
	v_mul_f32_e64 v3, |v3|, s65
	v_exp_f32_e32 v3, v3
	s_nop 0
	v_add_f32_e32 v8, 1.0, v3
	v_add_f32_e32 v4, -1.0, v8
	v_sub_f32_e32 v5, v4, v8
	v_add_f32_e32 v5, 1.0, v5
	v_sub_f32_e32 v4, v3, v4
	v_add_f32_e32 v9, v4, v5
	v_frexp_mant_f32_e32 v4, v8
	v_cmp_gt_f32_e32 vcc, s4, v4
	v_cvt_f64_f32_e32 v[4:5], v8
	v_frexp_exp_i32_f64_e32 v4, v[4:5]
	v_subbrev_co_u32_e32 v4, vcc, 0, v4, vcc
	v_sub_u32_e32 v5, 0, v4
	v_ldexp_f32 v8, v8, v5
	v_ldexp_f32 v5, v9, v5
	v_add_f32_e32 v9, -1.0, v8
	v_add_f32_e32 v10, 1.0, v9
	v_sub_f32_e32 v10, v8, v10
	v_add_f32_e32 v10, v5, v10
	v_add_f32_e32 v11, v9, v10
	v_sub_f32_e32 v9, v11, v9
	v_sub_f32_e32 v9, v10, v9
	v_add_f32_e32 v10, 1.0, v8
	v_add_f32_e32 v12, -1.0, v10
	v_sub_f32_e32 v8, v8, v12
	v_add_f32_e32 v5, v5, v8
	v_add_f32_e32 v8, v10, v5
	v_sub_f32_e32 v10, v8, v10
	v_sub_f32_e32 v5, v5, v10
	v_rcp_f32_e32 v10, v8
	v_cvt_f32_i32_e32 v4, v4
	v_cmp_neq_f32_e32 vcc, s51, v3
	v_mul_f32_e32 v12, v11, v10
	v_mul_f32_e32 v13, v8, v12
	v_fma_f32 v14, v12, v8, -v13
	v_fmac_f32_e32 v14, v12, v5
	v_add_f32_e32 v15, v13, v14
	v_sub_f32_e32 v16, v11, v15
	v_sub_f32_e32 v11, v11, v16
	v_sub_f32_e32 v13, v15, v13
	v_sub_f32_e32 v11, v11, v15
	v_add_f32_e32 v9, v9, v11
	v_sub_f32_e32 v11, v13, v14
	v_add_f32_e32 v9, v11, v9
	v_add_f32_e32 v11, v16, v9
	v_mul_f32_e32 v13, v10, v11
	v_mul_f32_e32 v14, v8, v13
	v_fma_f32 v8, v13, v8, -v14
	v_fmac_f32_e32 v8, v13, v5
	v_sub_f32_e32 v5, v16, v11
	v_add_f32_e32 v5, v9, v5
	v_add_f32_e32 v9, v14, v8
	v_sub_f32_e32 v15, v11, v9
	v_sub_f32_e32 v11, v11, v15
	v_sub_f32_e32 v14, v9, v14
	v_sub_f32_e32 v9, v11, v9
	v_add_f32_e32 v5, v5, v9
	v_sub_f32_e32 v8, v14, v8
	v_add_f32_e32 v5, v8, v5
	v_add_f32_e32 v8, v12, v13
	v_add_f32_e32 v5, v15, v5
	v_sub_f32_e32 v9, v8, v12
	v_mul_f32_e32 v5, v10, v5
	v_sub_f32_e32 v9, v13, v9
	v_add_f32_e32 v5, v9, v5
	v_mul_f32_e32 v12, 0x3f317218, v4
	v_add_f32_e32 v9, v8, v5
	v_fma_f32 v13, v4, s5, -v12
	v_mul_f32_e32 v10, v9, v9
	v_fmac_f32_e32 v13, 0xb102e308, v4
	v_sub_f32_e32 v4, v9, v8
	v_fmamk_f32 v11, v10, 0x3e9b6dac, v226
	v_sub_f32_e32 v4, v5, v4
	v_add_f32_e32 v5, v12, v13
	v_fmaak_f32 v11, v10, v11, 0x3f2aaada
	v_sub_f32_e32 v8, v5, v12
	v_ldexp_f32 v12, v9, 1
	v_mul_f32_e32 v9, v9, v10
	v_mul_f32_e32 v9, v9, v11
	v_add_f32_e32 v10, v12, v9
	v_sub_f32_e32 v11, v10, v12
	v_ldexp_f32 v4, v4, 1
	v_sub_f32_e32 v9, v9, v11
	v_add_f32_e32 v4, v4, v9
	v_add_f32_e32 v9, v10, v4
	v_sub_f32_e32 v10, v9, v10
	v_sub_f32_e32 v4, v4, v10
	v_add_f32_e32 v10, v5, v9
	v_sub_f32_e32 v11, v10, v5
	v_sub_f32_e32 v12, v10, v11
	v_sub_f32_e32 v8, v13, v8
	v_sub_f32_e32 v5, v5, v12
	v_sub_f32_e32 v9, v9, v11
	v_add_f32_e32 v5, v9, v5
	v_add_f32_e32 v9, v8, v4
	v_sub_f32_e32 v11, v9, v8
	v_sub_f32_e32 v12, v9, v11
	v_sub_f32_e32 v8, v8, v12
	v_sub_f32_e32 v4, v4, v11
	v_add_f32_e32 v5, v9, v5
	v_add_f32_e32 v4, v4, v8
	v_add_f32_e32 v8, v10, v5
	v_sub_f32_e32 v9, v8, v10
	v_sub_f32_e32 v5, v5, v9
	v_add_f32_e32 v4, v4, v5
	v_add_f32_e32 v4, v8, v4
	v_cndmask_b32_e32 v4, v227, v4, vcc
	v_cmp_ngt_f32_e32 vcc, -1.0, v3
	s_nop 1
	v_cndmask_b32_e32 v4, v228, v4, vcc
	v_cmp_neq_f32_e32 vcc, -1.0, v3
	s_nop 1
	v_cndmask_b32_e32 v4, v229, v4, vcc
	v_cmp_lt_f32_e64 vcc, |v3|, s13
	s_nop 1
	v_cndmask_b32_e32 v3, v4, v3, vcc
	v_sub_f32_e32 v2, v2, v3
	flat_store_dword v[6:7], v2 offset:28
	s_branch .LBB0_294

; __device__ __forceinline__ float wave_sum(float v) {
; #pragma unroll
;     for (int o = 1; o < 64; o <<= 1) v += __shfl_xor(v, o);
;     return v;
; }
; __device__ __forceinline__ void preproc_phase(Frame& F, int layer, int b, int cu_lo, int ncu) {
;     ...
;         for (int a = 0; a < 4; ++a)
; #pragma unroll
;             for (int hh = 0; hh < 4; ++hh) { ai[a][hh] = wave_sum(ai[a][hh]); af[a][hh] = wave_sum(af[a][hh]); }
.LBB0_341:
	ds_bpermute_b32 v6, v235, v121
	ds_bpermute_b32 v7, v235, v119
	ds_bpermute_b32 v10, v235, v116
	ds_bpermute_b32 v2, v235, v120
	ds_bpermute_b32 v3, v235, v118
	s_waitcnt lgkmcnt(4)
	v_add_f32_e32 v6, v121, v6
	ds_bpermute_b32 v8, v236, v6
	s_waitcnt lgkmcnt(4)
	v_add_f32_e32 v7, v119, v7
	ds_bpermute_b32 v9, v236, v7
	s_waitcnt lgkmcnt(4)
	v_add_f32_e32 v10, v116, v10
	ds_bpermute_b32 v11, v236, v10
	s_waitcnt lgkmcnt(2)
	v_add_f32_e32 v6, v6, v8
	ds_bpermute_b32 v8, v237, v6
	s_waitcnt lgkmcnt(2)
	v_add_f32_e32 v7, v7, v9
	ds_bpermute_b32 v9, v237, v7
	s_waitcnt lgkmcnt(2)
	v_add_f32_e32 v10, v10, v11
	ds_bpermute_b32 v11, v237, v10
	s_waitcnt lgkmcnt(2)
	v_add_f32_e32 v6, v6, v8
	ds_bpermute_b32 v8, v238, v6
	s_waitcnt lgkmcnt(2)
	v_add_f32_e32 v7, v7, v9
	ds_bpermute_b32 v9, v238, v7
	v_add_f32_e32 v2, v120, v2
	v_add_f32_e32 v3, v118, v3
	s_waitcnt lgkmcnt(1)
	v_add_f32_e32 v6, v6, v8
	ds_bpermute_b32 v8, v239, v6
	s_waitcnt lgkmcnt(1)
	v_add_f32_e32 v9, v7, v9
	ds_bpermute_b32 v12, v239, v9
	ds_bpermute_b32 v4, v236, v2
	ds_bpermute_b32 v5, v236, v3
	s_waitcnt lgkmcnt(3)
	v_add_f32_e32 v6, v6, v8
	ds_bpermute_b32 v8, v235, v114
	s_waitcnt lgkmcnt(3)
	v_add_f32_e32 v36, v9, v12
	v_add_f32_e32 v9, v10, v11
	ds_bpermute_b32 v10, v238, v9
	ds_bpermute_b32 v12, v235, v117
	s_waitcnt lgkmcnt(2)
	v_add_f32_e32 v8, v114, v8
	ds_bpermute_b32 v13, v236, v8
	v_add_f32_e32 v2, v2, v4
	s_waitcnt lgkmcnt(2)
	v_add_f32_e32 v9, v9, v10
	ds_bpermute_b32 v10, v239, v9
	s_waitcnt lgkmcnt(2)
	v_add_f32_e32 v12, v117, v12
	s_waitcnt lgkmcnt(1)
	v_add_f32_e32 v8, v8, v13
	ds_bpermute_b32 v11, v237, v8
	ds_bpermute_b32 v13, v236, v12
	s_waitcnt lgkmcnt(2)
	v_add_f32_e32 v35, v9, v10
	ds_bpermute_b32 v9, v235, v115
	v_add_f32_e32 v3, v3, v5
	s_waitcnt lgkmcnt(2)
	v_add_f32_e32 v8, v8, v11
	ds_bpermute_b32 v11, v238, v8
	ds_bpermute_b32 v4, v237, v2
	s_waitcnt lgkmcnt(2)
	v_add_f32_e32 v9, v115, v9
	ds_bpermute_b32 v5, v237, v3
	ds_bpermute_b32 v7, v240, v6
	s_waitcnt lgkmcnt(3)
	v_add_f32_e32 v8, v8, v11
	v_add_f32_e32 v11, v12, v13
	ds_bpermute_b32 v10, v239, v8
	ds_bpermute_b32 v12, v237, v11
	ds_bpermute_b32 v13, v236, v9
	s_waitcnt lgkmcnt(5)
	v_add_f32_e32 v2, v2, v4
	s_waitcnt lgkmcnt(4)
	v_add_f32_e32 v3, v3, v5
	s_waitcnt lgkmcnt(2)
	v_add_f32_e32 v34, v8, v10
	s_waitcnt lgkmcnt(1)
	v_add_f32_e32 v8, v11, v12
	ds_bpermute_b32 v10, v238, v8
	s_waitcnt lgkmcnt(1)
	v_add_f32_e32 v9, v9, v13
	ds_bpermute_b32 v11, v237, v9
	ds_bpermute_b32 v12, v235, v112
	ds_bpermute_b32 v4, v238, v2
	s_waitcnt lgkmcnt(3)
	v_add_f32_e32 v8, v8, v10
	ds_bpermute_b32 v10, v239, v8
	s_waitcnt lgkmcnt(3)
	v_add_f32_e32 v9, v9, v11
	s_waitcnt lgkmcnt(2)
	v_add_f32_e32 v12, v112, v12
	ds_bpermute_b32 v11, v238, v9
	ds_bpermute_b32 v13, v236, v12
	s_waitcnt lgkmcnt(2)
	v_add_f32_e32 v33, v8, v10
	ds_bpermute_b32 v8, v235, v110
	ds_bpermute_b32 v5, v238, v3
	s_waitcnt lgkmcnt(3)
	v_add_f32_e32 v9, v9, v11
	s_waitcnt lgkmcnt(2)
	v_add_f32_e32 v11, v12, v13
	ds_bpermute_b32 v10, v239, v9
	ds_bpermute_b32 v12, v237, v11
	s_waitcnt lgkmcnt(3)
	v_add_f32_e32 v8, v110, v8
	ds_bpermute_b32 v13, v236, v8
	v_add_f32_e32 v2, v2, v4
	s_waitcnt lgkmcnt(2)
	v_add_f32_e32 v32, v9, v10
	s_waitcnt lgkmcnt(1)
	v_add_f32_e32 v9, v11, v12
	ds_bpermute_b32 v10, v238, v9
	s_waitcnt lgkmcnt(1)
	v_add_f32_e32 v8, v8, v13
	ds_bpermute_b32 v11, v237, v8
	ds_bpermute_b32 v12, v235, v113
	v_add_f32_e32 v3, v3, v5
	s_waitcnt lgkmcnt(2)
	v_add_f32_e32 v9, v9, v10
	ds_bpermute_b32 v10, v239, v9
	s_waitcnt lgkmcnt(2)
	v_add_f32_e32 v8, v8, v11
	s_waitcnt lgkmcnt(1)
	v_add_f32_e32 v12, v113, v12
	ds_bpermute_b32 v11, v238, v8
	ds_bpermute_b32 v13, v236, v12
	s_waitcnt lgkmcnt(2)
	v_add_f32_e32 v31, v9, v10
	ds_bpermute_b32 v9, v235, v111
	ds_bpermute_b32 v4, v239, v2
	s_waitcnt lgkmcnt(3)
	v_add_f32_e32 v8, v8, v11
	s_waitcnt lgkmcnt(2)
	v_add_f32_e32 v11, v12, v13
	ds_bpermute_b32 v10, v239, v8
	ds_bpermute_b32 v12, v237, v11
	s_waitcnt lgkmcnt(3)
	v_add_f32_e32 v9, v111, v9
	ds_bpermute_b32 v13, v236, v9
	ds_bpermute_b32 v5, v239, v3
	s_waitcnt lgkmcnt(3)
	v_add_f32_e32 v30, v8, v10
	s_waitcnt lgkmcnt(2)
	v_add_f32_e32 v8, v11, v12
	ds_bpermute_b32 v10, v238, v8
	s_waitcnt lgkmcnt(2)
	v_add_f32_e32 v9, v9, v13
	ds_bpermute_b32 v11, v237, v9
	ds_bpermute_b32 v12, v235, v108
	v_add_f32_e32 v2, v2, v4
	s_waitcnt lgkmcnt(2)
	v_add_f32_e32 v8, v8, v10
	ds_bpermute_b32 v10, v239, v8
	s_waitcnt lgkmcnt(2)
	v_add_f32_e32 v9, v9, v11
	s_waitcnt lgkmcnt(1)
	v_add_f32_e32 v12, v108, v12
	ds_bpermute_b32 v11, v238, v9
	ds_bpermute_b32 v13, v236, v12
	s_waitcnt lgkmcnt(2)
	v_add_f32_e32 v29, v8, v10
	ds_bpermute_b32 v8, v235, v106
	v_add_f32_e32 v4, v3, v5
	s_waitcnt lgkmcnt(2)
	v_add_f32_e32 v9, v9, v11
	s_waitcnt lgkmcnt(1)
	v_add_f32_e32 v11, v12, v13
	ds_bpermute_b32 v10, v239, v9
	ds_bpermute_b32 v12, v237, v11
	s_waitcnt lgkmcnt(2)
	v_add_f32_e32 v8, v106, v8
	ds_bpermute_b32 v13, v236, v8
	ds_bpermute_b32 v3, v240, v2
	s_waitcnt lgkmcnt(3)
	v_add_f32_e32 v28, v9, v10
	s_waitcnt lgkmcnt(2)
	v_add_f32_e32 v9, v11, v12
	ds_bpermute_b32 v10, v238, v9
	s_waitcnt lgkmcnt(2)
	v_add_f32_e32 v8, v8, v13
	ds_bpermute_b32 v11, v237, v8
	ds_bpermute_b32 v12, v235, v109
	ds_bpermute_b32 v5, v240, v4
	s_waitcnt lgkmcnt(3)
	v_add_f32_e32 v9, v9, v10
	ds_bpermute_b32 v10, v239, v9
	s_waitcnt lgkmcnt(3)
	v_add_f32_e32 v8, v8, v11
	s_waitcnt lgkmcnt(2)
	v_add_f32_e32 v12, v109, v12
	ds_bpermute_b32 v11, v238, v8
	ds_bpermute_b32 v13, v236, v12
	s_waitcnt lgkmcnt(2)
	v_add_f32_e32 v27, v9, v10
	ds_bpermute_b32 v9, v235, v107
	ds_bpermute_b32 v37, v240, v36
	s_waitcnt lgkmcnt(3)
	v_add_f32_e32 v8, v8, v11
	s_waitcnt lgkmcnt(2)
; __device__ __forceinline__ float wave_sum(float v) {
; #pragma unroll
;     for (int o = 1; o < 64; o <<= 1) v += __shfl_xor(v, o);
;     return v;
; }
; __device__ __forceinline__ void preproc_phase(Frame& F, int layer, int b, int cu_lo, int ncu) {
;     ...
;         for (int a = 0; a < 4; ++a)
; #pragma unroll
;             for (int hh = 0; hh < 4; ++hh) { ai[a][hh] = wave_sum(ai[a][hh]); af[a][hh] = wave_sum(af[a][hh]); }
	v_add_f32_e32 v11, v12, v13
	ds_bpermute_b32 v10, v239, v8
	ds_bpermute_b32 v12, v237, v11
	s_waitcnt lgkmcnt(3)
	v_add_f32_e32 v9, v107, v9
	ds_bpermute_b32 v13, v236, v9
	ds_bpermute_b32 v38, v240, v35
	s_waitcnt lgkmcnt(3)
	v_add_f32_e32 v26, v8, v10
	s_waitcnt lgkmcnt(2)
	v_add_f32_e32 v8, v11, v12
	ds_bpermute_b32 v10, v238, v8
	s_waitcnt lgkmcnt(2)
	v_add_f32_e32 v9, v9, v13
	ds_bpermute_b32 v11, v237, v9
	ds_bpermute_b32 v12, v235, v104
	ds_bpermute_b32 v39, v240, v34
	s_waitcnt lgkmcnt(3)
	v_add_f32_e32 v8, v8, v10
	ds_bpermute_b32 v10, v239, v8
	s_waitcnt lgkmcnt(3)
	v_add_f32_e32 v9, v9, v11
	s_waitcnt lgkmcnt(2)
	v_add_f32_e32 v12, v104, v12
	ds_bpermute_b32 v11, v238, v9
	ds_bpermute_b32 v13, v236, v12
	s_waitcnt lgkmcnt(2)
	v_add_f32_e32 v25, v8, v10
	ds_bpermute_b32 v8, v235, v102
	ds_bpermute_b32 v40, v240, v33
	s_waitcnt lgkmcnt(3)
	v_add_f32_e32 v9, v9, v11
	s_waitcnt lgkmcnt(2)
	v_add_f32_e32 v11, v12, v13
	ds_bpermute_b32 v10, v239, v9
	ds_bpermute_b32 v12, v237, v11
	s_waitcnt lgkmcnt(3)
	v_add_f32_e32 v8, v102, v8
	ds_bpermute_b32 v13, v236, v8
	ds_bpermute_b32 v41, v240, v32
	s_waitcnt lgkmcnt(3)
	v_add_f32_e32 v24, v9, v10
	s_waitcnt lgkmcnt(2)
	v_add_f32_e32 v9, v11, v12
	ds_bpermute_b32 v10, v238, v9
	s_waitcnt lgkmcnt(2)
	v_add_f32_e32 v8, v8, v13
	ds_bpermute_b32 v11, v237, v8
	ds_bpermute_b32 v12, v235, v105
	ds_bpermute_b32 v42, v240, v31
	s_waitcnt lgkmcnt(3)
	v_add_f32_e32 v9, v9, v10
	ds_bpermute_b32 v10, v239, v9
	s_waitcnt lgkmcnt(3)
	v_add_f32_e32 v8, v8, v11
	s_waitcnt lgkmcnt(2)
	v_add_f32_e32 v12, v105, v12
	ds_bpermute_b32 v11, v238, v8
	ds_bpermute_b32 v13, v236, v12
	s_waitcnt lgkmcnt(2)
	v_add_f32_e32 v23, v9, v10
	ds_bpermute_b32 v9, v235, v103
	ds_bpermute_b32 v43, v240, v30
	s_waitcnt lgkmcnt(3)
	v_add_f32_e32 v8, v8, v11
	s_waitcnt lgkmcnt(2)
	v_add_f32_e32 v11, v12, v13
	ds_bpermute_b32 v10, v239, v8
	ds_bpermute_b32 v12, v237, v11
	s_waitcnt lgkmcnt(3)
	v_add_f32_e32 v9, v103, v9
	ds_bpermute_b32 v13, v236, v9
	ds_bpermute_b32 v44, v240, v29
	s_waitcnt lgkmcnt(3)
	v_add_f32_e32 v22, v8, v10
	s_waitcnt lgkmcnt(2)
	v_add_f32_e32 v8, v11, v12
	ds_bpermute_b32 v10, v238, v8
	s_waitcnt lgkmcnt(2)
	v_add_f32_e32 v9, v9, v13
	ds_bpermute_b32 v11, v237, v9
	ds_bpermute_b32 v12, v235, v100
	ds_bpermute_b32 v45, v240, v28
	s_waitcnt lgkmcnt(3)
	v_add_f32_e32 v8, v8, v10
	ds_bpermute_b32 v10, v239, v8
	s_waitcnt lgkmcnt(3)
	v_add_f32_e32 v9, v9, v11
	s_waitcnt lgkmcnt(2)
	v_add_f32_e32 v12, v100, v12
	ds_bpermute_b32 v11, v238, v9
	ds_bpermute_b32 v13, v236, v12
	s_waitcnt lgkmcnt(2)
	v_add_f32_e32 v21, v8, v10
	ds_bpermute_b32 v8, v235, v98
	ds_bpermute_b32 v46, v240, v27
	s_waitcnt lgkmcnt(3)
	v_add_f32_e32 v9, v9, v11
	s_waitcnt lgkmcnt(2)
	v_add_f32_e32 v11, v12, v13
	ds_bpermute_b32 v10, v239, v9
	ds_bpermute_b32 v12, v237, v11
	s_waitcnt lgkmcnt(3)
	v_add_f32_e32 v8, v98, v8
	ds_bpermute_b32 v13, v236, v8
	ds_bpermute_b32 v47, v240, v26
	s_waitcnt lgkmcnt(3)
	v_add_f32_e32 v20, v9, v10
	s_waitcnt lgkmcnt(2)
	v_add_f32_e32 v9, v11, v12
	ds_bpermute_b32 v10, v238, v9
	s_waitcnt lgkmcnt(2)
	v_add_f32_e32 v8, v8, v13
	ds_bpermute_b32 v11, v237, v8
	ds_bpermute_b32 v12, v235, v101
	ds_bpermute_b32 v48, v240, v25
	s_waitcnt lgkmcnt(3)
	v_add_f32_e32 v9, v9, v10
	ds_bpermute_b32 v10, v239, v9
	s_waitcnt lgkmcnt(3)
	v_add_f32_e32 v8, v8, v11
	s_waitcnt lgkmcnt(2)
	v_add_f32_e32 v12, v101, v12
	ds_bpermute_b32 v11, v238, v8
	ds_bpermute_b32 v13, v236, v12
	s_waitcnt lgkmcnt(2)
	v_add_f32_e32 v19, v9, v10
	ds_bpermute_b32 v9, v235, v99
	ds_bpermute_b32 v49, v240, v24
	s_waitcnt lgkmcnt(3)
	v_add_f32_e32 v8, v8, v11
	s_waitcnt lgkmcnt(2)
	v_add_f32_e32 v11, v12, v13
	ds_bpermute_b32 v10, v239, v8
	ds_bpermute_b32 v12, v237, v11
	s_waitcnt lgkmcnt(3)
	v_add_f32_e32 v9, v99, v9
	ds_bpermute_b32 v13, v236, v9
	ds_bpermute_b32 v50, v240, v23
	s_waitcnt lgkmcnt(3)
	v_add_f32_e32 v18, v8, v10
	s_waitcnt lgkmcnt(2)
	v_add_f32_e32 v8, v11, v12
	ds_bpermute_b32 v10, v238, v8
	s_waitcnt lgkmcnt(2)
	v_add_f32_e32 v9, v9, v13
	ds_bpermute_b32 v11, v237, v9
	ds_bpermute_b32 v12, v235, v96
	ds_bpermute_b32 v51, v240, v22
	s_waitcnt lgkmcnt(3)
	v_add_f32_e32 v8, v8, v10
	ds_bpermute_b32 v10, v239, v8
	s_waitcnt lgkmcnt(3)
	v_add_f32_e32 v9, v9, v11
	s_waitcnt lgkmcnt(2)
	v_add_f32_e32 v12, v96, v12
	ds_bpermute_b32 v11, v238, v9
	ds_bpermute_b32 v13, v236, v12
	s_waitcnt lgkmcnt(2)
	v_add_f32_e32 v17, v8, v10
	ds_bpermute_b32 v8, v235, v94
	ds_bpermute_b32 v52, v240, v21
	s_waitcnt lgkmcnt(3)
	v_add_f32_e32 v9, v9, v11
	s_waitcnt lgkmcnt(2)
	v_add_f32_e32 v11, v12, v13
	ds_bpermute_b32 v10, v239, v9
	ds_bpermute_b32 v12, v237, v11
	s_waitcnt lgkmcnt(3)
	v_add_f32_e32 v8, v94, v8
	ds_bpermute_b32 v13, v236, v8
	ds_bpermute_b32 v53, v240, v20
	s_waitcnt lgkmcnt(3)
	v_add_f32_e32 v16, v9, v10
	s_waitcnt lgkmcnt(2)
	v_add_f32_e32 v9, v11, v12
	ds_bpermute_b32 v10, v238, v9
	s_waitcnt lgkmcnt(2)
	v_add_f32_e32 v8, v8, v13
	ds_bpermute_b32 v12, v235, v97
	ds_bpermute_b32 v11, v237, v8
	ds_bpermute_b32 v54, v240, v19
	s_waitcnt lgkmcnt(3)
	v_add_f32_e32 v9, v9, v10
	ds_bpermute_b32 v10, v239, v9
	s_waitcnt lgkmcnt(3)
	v_add_f32_e32 v12, v97, v12
	s_waitcnt lgkmcnt(2)
	v_add_f32_e32 v8, v8, v11
	ds_bpermute_b32 v13, v236, v12
	ds_bpermute_b32 v11, v238, v8
	s_waitcnt lgkmcnt(2)
	v_add_f32_e32 v15, v9, v10
	ds_bpermute_b32 v9, v235, v95
	ds_bpermute_b32 v55, v240, v18
	s_waitcnt lgkmcnt(3)
	v_add_f32_e32 v10, v12, v13
	s_waitcnt lgkmcnt(2)
	v_add_f32_e32 v8, v8, v11
	ds_bpermute_b32 v11, v237, v10
	ds_bpermute_b32 v12, v235, v92
	s_waitcnt lgkmcnt(3)
	v_add_f32_e32 v9, v95, v9
	ds_bpermute_b32 v13, v239, v8
	ds_bpermute_b32 v14, v236, v9
	s_waitcnt lgkmcnt(3)
; __device__ __forceinline__ float logsigmoidf_(float x) { return fminf(x, 0.f) - log1pf(__expf(-fabsf(x))); }
; __device__ __forceinline__ void preproc_phase(Frame& F, int layer, int b, int cu_lo, int ncu) {
;     ...
;         for (int a = 0; a < 4; ++a)
; #pragma unroll
;             for (int hh = 0; hh < 4; ++hh) { ai[a][hh] = wave_sum(ai[a][hh]); af[a][hh] = wave_sum(af[a][hh]); }
;         if (F.lane == 0) {
; #pragma unroll
;             for (int a = 0; a < 4; ++a)
; #pragma unroll
;                 for (int hh = 0; hh < 4; ++hh) { MG[(size_t)(t0 + a) * 8 + hh] = ai[a][hh] + INP(I_M_B_I)[layer * 4 + hh]; MG[(size_t)(t0 + a) * 8 + 4 + hh] = logsigmoidf_(af[a][hh] + INP(I_M_B_F)[layer * 4 + hh]); }
;         }
	v_add_f32_e32 v10, v10, v11
	s_waitcnt lgkmcnt(2)
	v_add_f32_e32 v11, v92, v12
	ds_bpermute_b32 v12, v236, v11
	ds_bpermute_b32 v59, v238, v10
	s_waitcnt lgkmcnt(2)
	v_add_f32_e32 v9, v9, v14
	v_add_f32_e32 v14, v8, v13
	ds_bpermute_b32 v60, v237, v9
	s_waitcnt lgkmcnt(2)
	v_add_f32_e32 v8, v11, v12
	ds_bpermute_b32 v11, v237, v8
	s_waitcnt lgkmcnt(2)
	v_add_f32_e32 v10, v10, v59
	ds_bpermute_b32 v13, v239, v10
	s_waitcnt lgkmcnt(2)
	v_add_f32_e32 v9, v9, v60
	ds_bpermute_b32 v12, v238, v9
	s_waitcnt lgkmcnt(2)
	v_add_f32_e32 v8, v8, v11
	ds_bpermute_b32 v11, v238, v8
	s_waitcnt lgkmcnt(2)
	v_add_f32_e32 v13, v10, v13
	ds_bpermute_b32 v56, v240, v17
	s_waitcnt lgkmcnt(2)
	v_add_f32_e32 v9, v9, v12
	ds_bpermute_b32 v12, v239, v9
	s_waitcnt lgkmcnt(2)
	v_add_f32_e32 v8, v8, v11
	ds_bpermute_b32 v10, v239, v8
	ds_bpermute_b32 v57, v240, v16
	ds_bpermute_b32 v58, v240, v15
	s_waitcnt lgkmcnt(3)
	v_add_f32_e32 v12, v9, v12
	ds_bpermute_b32 v9, v235, v90
	s_waitcnt lgkmcnt(3)
	v_add_f32_e32 v11, v8, v10
	ds_bpermute_b32 v8, v235, v93
	ds_bpermute_b32 v10, v235, v91
	ds_bpermute_b32 v59, v240, v14
	s_waitcnt lgkmcnt(3)
	v_add_f32_e32 v9, v90, v9
	ds_bpermute_b32 v63, v236, v9
	s_waitcnt lgkmcnt(3)
	v_add_f32_e32 v8, v93, v8
	s_waitcnt lgkmcnt(2)
	v_add_f32_e32 v10, v91, v10
	ds_bpermute_b32 v64, v236, v8
	ds_bpermute_b32 v65, v236, v10
	s_waitcnt lgkmcnt(2)
	v_add_f32_e32 v9, v9, v63
	ds_bpermute_b32 v63, v237, v9
	ds_bpermute_b32 v60, v240, v13
	s_waitcnt lgkmcnt(3)
	v_add_f32_e32 v8, v8, v64
	s_waitcnt lgkmcnt(2)
	v_add_f32_e32 v10, v10, v65
	ds_bpermute_b32 v64, v237, v8
	ds_bpermute_b32 v65, v237, v10
	s_waitcnt lgkmcnt(3)
	v_add_f32_e32 v9, v9, v63
	ds_bpermute_b32 v63, v238, v9
	ds_bpermute_b32 v61, v240, v12
	s_waitcnt lgkmcnt(3)
	v_add_f32_e32 v8, v8, v64
	s_waitcnt lgkmcnt(2)
	v_add_f32_e32 v10, v10, v65
	ds_bpermute_b32 v64, v238, v8
	ds_bpermute_b32 v65, v238, v10
	s_waitcnt lgkmcnt(3)
	v_add_f32_e32 v9, v9, v63
	ds_bpermute_b32 v63, v239, v9
	ds_bpermute_b32 v62, v240, v11
	s_waitcnt lgkmcnt(3)
	v_add_f32_e32 v8, v8, v64
	s_waitcnt lgkmcnt(2)
	v_add_f32_e32 v65, v10, v65
	ds_bpermute_b32 v64, v239, v8
	ds_bpermute_b32 v66, v239, v65
	s_waitcnt lgkmcnt(3)
	v_add_f32_e32 v10, v9, v63
	ds_bpermute_b32 v63, v240, v10
	s_waitcnt lgkmcnt(2)
	v_add_f32_e32 v9, v8, v64
	s_waitcnt lgkmcnt(1)
	v_add_f32_e32 v8, v65, v66
	ds_bpermute_b32 v64, v240, v9
	ds_bpermute_b32 v65, v240, v8
	s_and_saveexec_b64 s[10:11], s[8:9]
	s_cbranch_execz .LBB0_322
	v_readlane_b32 s0, v253, 31
	v_add_f32_e32 v36, v36, v37
	v_add_f32_e32 v37, v6, v7
	v_add_f32_e32 v6, v2, v3
	v_mov_b32_e32 v2, s0
	ds_read_b64 v[2:3], v2
	v_readlane_b32 s0, v253, 32
	v_add_f32_e32 v35, v35, v38
	v_add_f32_e32 v38, v4, v5
	v_mov_b32_e32 v4, s0
	s_lshl_b64 s[0:1], s[26:27], 5
	v_readlane_b32 s4, v254, 27
	s_add_u32 s0, s45, s0
	v_readlane_b32 s5, v254, 28
	s_addc_u32 s1, s49, s1
	s_lshl_b64 s[4:5], s[4:5], 2
	ds_read_b64 v[4:5], v4
	s_waitcnt lgkmcnt(1)
	v_lshl_add_u64 v[2:3], v[2:3], 0, s[4:5]
	flat_load_dword v7, v[2:3]
	v_add_f32_e32 v34, v34, v39
	v_add_f32_e32 v31, v31, v42
	s_waitcnt lgkmcnt(0)
	v_lshl_add_u64 v[4:5], v[4:5], 0, s[4:5]
	global_load_dword v110, v[2:3], off
	global_load_dword v111, v[2:3], off offset:4
	global_load_dword v112, v[2:3], off offset:8
	global_load_dword v113, v[2:3], off offset:12
	global_load_dword v114, v[4:5], off
	global_load_dword v115, v[4:5], off offset:4
	global_load_dword v116, v[4:5], off offset:8
	global_load_dword v117, v[4:5], off offset:12
	v_add_f32_e32 v33, v33, v40
	v_add_f32_e32 v32, v32, v41
	v_add_f32_e32 v30, v30, v43
	s_mov_b32 s4, 0x3f2aaaab
	v_add_f32_e32 v29, v29, v44
	v_add_f32_e32 v28, v28, v45
	v_add_f32_e32 v27, v27, v46
	v_add_f32_e32 v26, v26, v47
	v_add_f32_e32 v25, v25, v48
	v_add_f32_e32 v24, v24, v49
	v_add_f32_e32 v23, v23, v50
	s_mov_b32 s5, 0x3f317218
	s_mov_b32 s13, 0x33800000
	v_add_f32_e32 v22, v22, v51
	v_add_f32_e32 v21, v21, v52
	v_add_f32_e32 v20, v20, v53
	v_add_f32_e32 v19, v19, v54
	v_add_f32_e32 v18, v18, v55
	v_add_f32_e32 v17, v17, v56
	v_add_f32_e32 v16, v16, v57
	v_add_f32_e32 v15, v15, v58
	v_add_f32_e32 v14, v14, v59
	v_add_f32_e32 v13, v13, v60
	v_add_f32_e32 v12, v12, v61
	v_add_f32_e32 v11, v11, v62
	v_add_f32_e32 v10, v10, v63
	v_add_f32_e32 v9, v9, v64
	v_add_f32_e32 v8, v8, v65
	s_waitcnt vmcnt(0)
; __device__ __forceinline__ float logsigmoidf_(float x) { return fminf(x, 0.f) - log1pf(__expf(-fabsf(x))); }
; __device__ __forceinline__ void preproc_phase(Frame& F, int layer, int b, int cu_lo, int ncu) {
;     ...
;         if (F.lane == 0) {
; #pragma unroll
;             for (int a = 0; a < 4; ++a)
; #pragma unroll
;                 for (int hh = 0; hh < 4; ++hh) { MG[(size_t)(t0 + a) * 8 + hh] = ai[a][hh] + INP(I_M_B_I)[layer * 4 + hh]; MG[(size_t)(t0 + a) * 8 + 4 + hh] = logsigmoidf_(af[a][hh] + INP(I_M_B_F)[layer * 4 + hh]); }
;         }
	v_add_f32_e32 v39, v6, v7
	v_mov_b64_e32 v[6:7], s[0:1]
	flat_store_dword v[6:7], v39
	v_mov_b32_e32 v39, v114
	s_lshl_b64 s[0:1], s[24:25], 5
	s_add_u32 s0, s45, s0
	s_addc_u32 s1, s49, s1
	v_add_f32_e32 v39, v38, v39
	v_min_f32_e32 v38, 0, v39
	v_mul_f32_e64 v39, |v39|, s65
	v_exp_f32_e32 v39, v39
	s_nop 0
	v_add_f32_e32 v42, 1.0, v39
	v_add_f32_e32 v40, -1.0, v42
	v_sub_f32_e32 v41, v40, v42
	v_add_f32_e32 v41, 1.0, v41
	v_sub_f32_e32 v40, v39, v40
	v_add_f32_e32 v43, v40, v41
	v_frexp_mant_f32_e32 v40, v42
	v_cmp_gt_f32_e32 vcc, s4, v40
	v_cvt_f64_f32_e32 v[40:41], v42
	v_frexp_exp_i32_f64_e32 v40, v[40:41]
	v_subbrev_co_u32_e32 v40, vcc, 0, v40, vcc
	v_sub_u32_e32 v41, 0, v40
	v_ldexp_f32 v42, v42, v41
	v_ldexp_f32 v41, v43, v41
	v_add_f32_e32 v43, -1.0, v42
	v_add_f32_e32 v44, 1.0, v43
	v_sub_f32_e32 v44, v42, v44
	v_add_f32_e32 v44, v41, v44
	v_add_f32_e32 v45, v43, v44
	v_sub_f32_e32 v43, v45, v43
	v_sub_f32_e32 v43, v44, v43
	v_add_f32_e32 v44, 1.0, v42
	v_add_f32_e32 v46, -1.0, v44
	v_sub_f32_e32 v42, v42, v46
	v_add_f32_e32 v41, v41, v42
	v_add_f32_e32 v42, v44, v41
	v_sub_f32_e32 v44, v42, v44
	v_sub_f32_e32 v41, v41, v44
	v_rcp_f32_e32 v44, v42
	v_cvt_f32_i32_e32 v40, v40
	v_cmp_neq_f32_e32 vcc, s51, v39
	v_mul_f32_e32 v46, v45, v44
	v_mul_f32_e32 v47, v42, v46
	v_fma_f32 v48, v46, v42, -v47
	v_fmac_f32_e32 v48, v46, v41
	v_add_f32_e32 v49, v47, v48
	v_sub_f32_e32 v50, v45, v49
	v_sub_f32_e32 v45, v45, v50
	v_sub_f32_e32 v47, v49, v47
	v_sub_f32_e32 v45, v45, v49
	v_add_f32_e32 v43, v43, v45
	v_sub_f32_e32 v45, v47, v48
	v_add_f32_e32 v43, v45, v43
	v_add_f32_e32 v45, v50, v43
	v_mul_f32_e32 v47, v44, v45
	v_mul_f32_e32 v48, v42, v47
	v_fma_f32 v42, v47, v42, -v48
	v_fmac_f32_e32 v42, v47, v41
	v_sub_f32_e32 v41, v50, v45
	v_add_f32_e32 v41, v43, v41
	v_add_f32_e32 v43, v48, v42
	v_sub_f32_e32 v49, v45, v43
	v_sub_f32_e32 v45, v45, v49
	v_sub_f32_e32 v48, v43, v48
	v_sub_f32_e32 v43, v45, v43
	v_add_f32_e32 v41, v41, v43
	v_sub_f32_e32 v42, v48, v42
	v_add_f32_e32 v41, v42, v41
	v_add_f32_e32 v42, v46, v47
	v_add_f32_e32 v41, v49, v41
	v_sub_f32_e32 v43, v42, v46
	v_mul_f32_e32 v41, v44, v41
	v_sub_f32_e32 v43, v47, v43
	v_add_f32_e32 v41, v43, v41
	v_mul_f32_e32 v46, 0x3f317218, v40
	v_add_f32_e32 v43, v42, v41
	v_fma_f32 v47, v40, s5, -v46
	v_mul_f32_e32 v44, v43, v43
	v_fmac_f32_e32 v47, 0xb102e308, v40
	v_sub_f32_e32 v40, v43, v42
	v_fmamk_f32 v45, v44, 0x3e9b6dac, v226
	v_sub_f32_e32 v40, v41, v40
	v_add_f32_e32 v41, v46, v47
	v_fmaak_f32 v45, v44, v45, 0x3f2aaada
	v_sub_f32_e32 v42, v41, v46
	v_ldexp_f32 v46, v43, 1
	v_mul_f32_e32 v43, v43, v44
	v_mul_f32_e32 v43, v43, v45
	v_add_f32_e32 v44, v46, v43
	v_sub_f32_e32 v45, v44, v46
	v_ldexp_f32 v40, v40, 1
	v_sub_f32_e32 v43, v43, v45
	v_add_f32_e32 v40, v40, v43
	v_add_f32_e32 v43, v44, v40
	v_sub_f32_e32 v44, v43, v44
	v_sub_f32_e32 v40, v40, v44
	v_add_f32_e32 v44, v41, v43
	v_sub_f32_e32 v45, v44, v41
	v_sub_f32_e32 v46, v44, v45
	v_sub_f32_e32 v42, v47, v42
	v_sub_f32_e32 v41, v41, v46
	v_sub_f32_e32 v43, v43, v45
	v_add_f32_e32 v41, v43, v41
	v_add_f32_e32 v43, v42, v40
	v_sub_f32_e32 v45, v43, v42
	v_sub_f32_e32 v46, v43, v45
	v_sub_f32_e32 v42, v42, v46
	v_sub_f32_e32 v40, v40, v45
	v_add_f32_e32 v41, v43, v41
	v_add_f32_e32 v40, v40, v42
	v_add_f32_e32 v42, v44, v41
	v_sub_f32_e32 v43, v42, v44
	v_sub_f32_e32 v41, v41, v43
	v_add_f32_e32 v40, v40, v41
	v_add_f32_e32 v40, v42, v40
	v_cndmask_b32_e32 v40, v227, v40, vcc
	v_cmp_ngt_f32_e32 vcc, -1.0, v39
	s_nop 1
	v_cndmask_b32_e32 v40, v228, v40, vcc
	v_cmp_neq_f32_e32 vcc, -1.0, v39
	s_nop 1
	v_cndmask_b32_e32 v40, v229, v40, vcc
	v_cmp_lt_f32_e64 vcc, |v39|, s13
	s_nop 1
	v_cndmask_b32_e32 v39, v40, v39, vcc
	v_sub_f32_e32 v38, v38, v39
	flat_store_dword v[6:7], v38 offset:16
	v_mov_b32_e32 v38, v111
	v_add_f32_e32 v37, v37, v38
	flat_store_dword v[6:7], v37 offset:4
	v_mov_b32_e32 v37, v115
	v_add_f32_e32 v37, v36, v37
	v_min_f32_e32 v36, 0, v37
	v_mul_f32_e64 v37, |v37|, s65
	v_exp_f32_e32 v37, v37
	s_nop 0
	v_add_f32_e32 v40, 1.0, v37
	v_add_f32_e32 v38, -1.0, v40
	v_sub_f32_e32 v39, v38, v40
	v_add_f32_e32 v39, 1.0, v39
	v_sub_f32_e32 v38, v37, v38
	v_add_f32_e32 v41, v38, v39
	v_frexp_mant_f32_e32 v38, v40
	v_cmp_gt_f32_e32 vcc, s4, v38
	v_cvt_f64_f32_e32 v[38:39], v40
	v_frexp_exp_i32_f64_e32 v38, v[38:39]
	v_subbrev_co_u32_e32 v38, vcc, 0, v38, vcc
	v_sub_u32_e32 v39, 0, v38
	v_ldexp_f32 v40, v40, v39
	v_ldexp_f32 v39, v41, v39
	v_add_f32_e32 v41, -1.0, v40
	v_add_f32_e32 v42, 1.0, v41
	v_sub_f32_e32 v42, v40, v42
	v_add_f32_e32 v42, v39, v42
	v_add_f32_e32 v43, v41, v42
	v_sub_f32_e32 v41, v43, v41
	v_sub_f32_e32 v41, v42, v41
	v_add_f32_e32 v42, 1.0, v40
	v_add_f32_e32 v44, -1.0, v42
	v_sub_f32_e32 v40, v40, v44
	v_add_f32_e32 v39, v39, v40
	v_add_f32_e32 v40, v42, v39
	v_sub_f32_e32 v42, v40, v42
	v_sub_f32_e32 v39, v39, v42
	v_rcp_f32_e32 v42, v40
	v_cvt_f32_i32_e32 v38, v38
	v_cmp_neq_f32_e32 vcc, s51, v37
	v_mul_f32_e32 v44, v43, v42
	v_mul_f32_e32 v45, v40, v44
	v_fma_f32 v46, v44, v40, -v45
	v_fmac_f32_e32 v46, v44, v39
	v_add_f32_e32 v47, v45, v46
	v_sub_f32_e32 v48, v43, v47
	v_sub_f32_e32 v43, v43, v48
	v_sub_f32_e32 v45, v47, v45
	v_sub_f32_e32 v43, v43, v47
	v_add_f32_e32 v41, v41, v43
	v_sub_f32_e32 v43, v45, v46
	v_add_f32_e32 v41, v43, v41
	v_add_f32_e32 v43, v48, v41
	v_mul_f32_e32 v45, v42, v43
	v_mul_f32_e32 v46, v40, v45
	v_fma_f32 v40, v45, v40, -v46
	v_fmac_f32_e32 v40, v45, v39
	v_sub_f32_e32 v39, v48, v43
	v_add_f32_e32 v39, v41, v39
	v_add_f32_e32 v41, v46, v40
	v_sub_f32_e32 v47, v43, v41
	v_sub_f32_e32 v43, v43, v47
	v_sub_f32_e32 v46, v41, v46
	v_sub_f32_e32 v41, v43, v41
; __device__ __forceinline__ float logsigmoidf_(float x) { return fminf(x, 0.f) - log1pf(__expf(-fabsf(x))); }
; __device__ __forceinline__ void preproc_phase(Frame& F, int layer, int b, int cu_lo, int ncu) {
;     ...
;         if (F.lane == 0) {
; #pragma unroll
;             for (int a = 0; a < 4; ++a)
; #pragma unroll
;                 for (int hh = 0; hh < 4; ++hh) { MG[(size_t)(t0 + a) * 8 + hh] = ai[a][hh] + INP(I_M_B_I)[layer * 4 + hh]; MG[(size_t)(t0 + a) * 8 + 4 + hh] = logsigmoidf_(af[a][hh] + INP(I_M_B_F)[layer * 4 + hh]); }
;         }
	v_add_f32_e32 v39, v39, v41
	v_sub_f32_e32 v40, v46, v40
	v_add_f32_e32 v39, v40, v39
	v_add_f32_e32 v40, v44, v45
	v_add_f32_e32 v39, v47, v39
	v_sub_f32_e32 v41, v40, v44
	v_mul_f32_e32 v39, v42, v39
	v_sub_f32_e32 v41, v45, v41
	v_add_f32_e32 v39, v41, v39
	v_mul_f32_e32 v44, 0x3f317218, v38
	v_add_f32_e32 v41, v40, v39
	v_fma_f32 v45, v38, s5, -v44
	v_mul_f32_e32 v42, v41, v41
	v_fmac_f32_e32 v45, 0xb102e308, v38
	v_sub_f32_e32 v38, v41, v40
	v_fmamk_f32 v43, v42, 0x3e9b6dac, v226
	v_sub_f32_e32 v38, v39, v38
	v_add_f32_e32 v39, v44, v45
	v_fmaak_f32 v43, v42, v43, 0x3f2aaada
	v_sub_f32_e32 v40, v39, v44
	v_ldexp_f32 v44, v41, 1
	v_mul_f32_e32 v41, v41, v42
	v_mul_f32_e32 v41, v41, v43
	v_add_f32_e32 v42, v44, v41
	v_sub_f32_e32 v43, v42, v44
	v_ldexp_f32 v38, v38, 1
	v_sub_f32_e32 v41, v41, v43
	v_add_f32_e32 v38, v38, v41
	v_add_f32_e32 v41, v42, v38
	v_sub_f32_e32 v42, v41, v42
	v_sub_f32_e32 v38, v38, v42
	v_add_f32_e32 v42, v39, v41
	v_sub_f32_e32 v43, v42, v39
	v_sub_f32_e32 v44, v42, v43
	v_sub_f32_e32 v40, v45, v40
	v_sub_f32_e32 v39, v39, v44
	v_sub_f32_e32 v41, v41, v43
	v_add_f32_e32 v39, v41, v39
	v_add_f32_e32 v41, v40, v38
	v_sub_f32_e32 v43, v41, v40
	v_sub_f32_e32 v44, v41, v43
	v_sub_f32_e32 v40, v40, v44
	v_sub_f32_e32 v38, v38, v43
	v_add_f32_e32 v39, v41, v39
	v_add_f32_e32 v38, v38, v40
	v_add_f32_e32 v40, v42, v39
	v_sub_f32_e32 v41, v40, v42
	v_sub_f32_e32 v39, v39, v41
	v_add_f32_e32 v38, v38, v39
	v_add_f32_e32 v38, v40, v38
	v_cndmask_b32_e32 v38, v227, v38, vcc
	v_cmp_ngt_f32_e32 vcc, -1.0, v37
	s_nop 1
	v_cndmask_b32_e32 v38, v228, v38, vcc
	v_cmp_neq_f32_e32 vcc, -1.0, v37
	s_nop 1
	v_cndmask_b32_e32 v38, v229, v38, vcc
	v_cmp_lt_f32_e64 vcc, |v37|, s13
	s_nop 1
	v_cndmask_b32_e32 v37, v38, v37, vcc
	v_sub_f32_e32 v36, v36, v37
	flat_store_dword v[6:7], v36 offset:20
	v_mov_b32_e32 v36, v112
	v_add_f32_e32 v35, v35, v36
	flat_store_dword v[6:7], v35 offset:8
	v_mov_b32_e32 v35, v116
	v_add_f32_e32 v35, v34, v35
	v_min_f32_e32 v34, 0, v35
	v_mul_f32_e64 v35, |v35|, s65
	v_exp_f32_e32 v35, v35
	s_nop 0
	v_add_f32_e32 v38, 1.0, v35
	v_add_f32_e32 v36, -1.0, v38
	v_sub_f32_e32 v37, v36, v38
	v_add_f32_e32 v37, 1.0, v37
	v_sub_f32_e32 v36, v35, v36
	v_add_f32_e32 v39, v36, v37
	v_frexp_mant_f32_e32 v36, v38
	v_cmp_gt_f32_e32 vcc, s4, v36
	v_cvt_f64_f32_e32 v[36:37], v38
	v_frexp_exp_i32_f64_e32 v36, v[36:37]
	v_subbrev_co_u32_e32 v36, vcc, 0, v36, vcc
	v_sub_u32_e32 v37, 0, v36
	v_ldexp_f32 v38, v38, v37
	v_ldexp_f32 v37, v39, v37
	v_add_f32_e32 v39, -1.0, v38
	v_add_f32_e32 v40, 1.0, v39
	v_sub_f32_e32 v40, v38, v40
	v_add_f32_e32 v40, v37, v40
	v_add_f32_e32 v41, v39, v40
	v_sub_f32_e32 v39, v41, v39
	v_sub_f32_e32 v39, v40, v39
	v_add_f32_e32 v40, 1.0, v38
	v_add_f32_e32 v42, -1.0, v40
	v_sub_f32_e32 v38, v38, v42
	v_add_f32_e32 v37, v37, v38
	v_add_f32_e32 v38, v40, v37
	v_sub_f32_e32 v40, v38, v40
	v_sub_f32_e32 v37, v37, v40
	v_rcp_f32_e32 v40, v38
	v_cvt_f32_i32_e32 v36, v36
	v_cmp_neq_f32_e32 vcc, s51, v35
	v_mul_f32_e32 v42, v41, v40
	v_mul_f32_e32 v43, v38, v42
	v_fma_f32 v44, v42, v38, -v43
	v_fmac_f32_e32 v44, v42, v37
	v_add_f32_e32 v45, v43, v44
	v_sub_f32_e32 v46, v41, v45
	v_sub_f32_e32 v41, v41, v46
	v_sub_f32_e32 v43, v45, v43
	v_sub_f32_e32 v41, v41, v45
	v_add_f32_e32 v39, v39, v41
	v_sub_f32_e32 v41, v43, v44
	v_add_f32_e32 v39, v41, v39
	v_add_f32_e32 v41, v46, v39
	v_mul_f32_e32 v43, v40, v41
	v_mul_f32_e32 v44, v38, v43
	v_fma_f32 v38, v43, v38, -v44
	v_fmac_f32_e32 v38, v43, v37
	v_sub_f32_e32 v37, v46, v41
	v_add_f32_e32 v37, v39, v37
	v_add_f32_e32 v39, v44, v38
	v_sub_f32_e32 v45, v41, v39
	v_sub_f32_e32 v41, v41, v45
	v_sub_f32_e32 v44, v39, v44
	v_sub_f32_e32 v39, v41, v39
	v_add_f32_e32 v37, v37, v39
	v_sub_f32_e32 v38, v44, v38
	v_add_f32_e32 v37, v38, v37
	v_add_f32_e32 v38, v42, v43
	v_add_f32_e32 v37, v45, v37
	v_sub_f32_e32 v39, v38, v42
	v_mul_f32_e32 v37, v40, v37
	v_sub_f32_e32 v39, v43, v39
	v_add_f32_e32 v37, v39, v37
	v_mul_f32_e32 v42, 0x3f317218, v36
	v_add_f32_e32 v39, v38, v37
	v_fma_f32 v43, v36, s5, -v42
	v_mul_f32_e32 v40, v39, v39
	v_fmac_f32_e32 v43, 0xb102e308, v36
	v_sub_f32_e32 v36, v39, v38
	v_fmamk_f32 v41, v40, 0x3e9b6dac, v226
	v_sub_f32_e32 v36, v37, v36
	v_add_f32_e32 v37, v42, v43
	v_fmaak_f32 v41, v40, v41, 0x3f2aaada
	v_sub_f32_e32 v38, v37, v42
	v_ldexp_f32 v42, v39, 1
	v_mul_f32_e32 v39, v39, v40
	v_mul_f32_e32 v39, v39, v41
	v_add_f32_e32 v40, v42, v39
	v_sub_f32_e32 v41, v40, v42
	v_ldexp_f32 v36, v36, 1
	v_sub_f32_e32 v39, v39, v41
	v_add_f32_e32 v36, v36, v39
	v_add_f32_e32 v39, v40, v36
	v_sub_f32_e32 v40, v39, v40
	v_sub_f32_e32 v36, v36, v40
	v_add_f32_e32 v40, v37, v39
	v_sub_f32_e32 v41, v40, v37
	v_sub_f32_e32 v42, v40, v41
	v_sub_f32_e32 v38, v43, v38
	v_sub_f32_e32 v37, v37, v42
	v_sub_f32_e32 v39, v39, v41
	v_add_f32_e32 v37, v39, v37
	v_add_f32_e32 v39, v38, v36
	v_sub_f32_e32 v41, v39, v38
	v_sub_f32_e32 v42, v39, v41
	v_sub_f32_e32 v38, v38, v42
	v_sub_f32_e32 v36, v36, v41
	v_add_f32_e32 v37, v39, v37
	v_add_f32_e32 v36, v36, v38
	v_add_f32_e32 v38, v40, v37
	v_sub_f32_e32 v39, v38, v40
	v_sub_f32_e32 v37, v37, v39
	v_add_f32_e32 v36, v36, v37
	v_add_f32_e32 v36, v38, v36
	v_cndmask_b32_e32 v36, v227, v36, vcc
	v_cmp_ngt_f32_e32 vcc, -1.0, v35
	s_nop 1
	v_cndmask_b32_e32 v36, v228, v36, vcc
	v_cmp_neq_f32_e32 vcc, -1.0, v35
	s_nop 1
	v_cndmask_b32_e32 v36, v229, v36, vcc
	v_cmp_lt_f32_e64 vcc, |v35|, s13
	s_nop 1
	v_cndmask_b32_e32 v35, v36, v35, vcc
	v_sub_f32_e32 v34, v34, v35
	flat_store_dword v[6:7], v34 offset:24
	v_mov_b32_e32 v34, v113
	v_add_f32_e32 v33, v33, v34
	flat_store_dword v[6:7], v33 offset:12
	v_mov_b32_e32 v33, v117
; __device__ __forceinline__ float logsigmoidf_(float x) { return fminf(x, 0.f) - log1pf(__expf(-fabsf(x))); }
; __device__ __forceinline__ void preproc_phase(Frame& F, int layer, int b, int cu_lo, int ncu) {
;     ...
;         if (F.lane == 0) {
; #pragma unroll
;             for (int a = 0; a < 4; ++a)
; #pragma unroll
;                 for (int hh = 0; hh < 4; ++hh) { MG[(size_t)(t0 + a) * 8 + hh] = ai[a][hh] + INP(I_M_B_I)[layer * 4 + hh]; MG[(size_t)(t0 + a) * 8 + 4 + hh] = logsigmoidf_(af[a][hh] + INP(I_M_B_F)[layer * 4 + hh]); }
;         }
	v_add_f32_e32 v33, v32, v33
	v_min_f32_e32 v32, 0, v33
	v_mul_f32_e64 v33, |v33|, s65
	v_exp_f32_e32 v33, v33
	s_nop 0
	v_add_f32_e32 v36, 1.0, v33
	v_add_f32_e32 v34, -1.0, v36
	v_sub_f32_e32 v35, v34, v36
	v_add_f32_e32 v35, 1.0, v35
	v_sub_f32_e32 v34, v33, v34
	v_add_f32_e32 v37, v34, v35
	v_frexp_mant_f32_e32 v34, v36
	v_cmp_gt_f32_e32 vcc, s4, v34
	v_cvt_f64_f32_e32 v[34:35], v36
	v_frexp_exp_i32_f64_e32 v34, v[34:35]
	v_subbrev_co_u32_e32 v34, vcc, 0, v34, vcc
	v_sub_u32_e32 v35, 0, v34
	v_ldexp_f32 v36, v36, v35
	v_ldexp_f32 v35, v37, v35
	v_add_f32_e32 v37, -1.0, v36
	v_add_f32_e32 v38, 1.0, v37
	v_sub_f32_e32 v38, v36, v38
	v_add_f32_e32 v38, v35, v38
	v_add_f32_e32 v39, v37, v38
	v_sub_f32_e32 v37, v39, v37
	v_sub_f32_e32 v37, v38, v37
	v_add_f32_e32 v38, 1.0, v36
	v_add_f32_e32 v40, -1.0, v38
	v_sub_f32_e32 v36, v36, v40
	v_add_f32_e32 v35, v35, v36
	v_add_f32_e32 v36, v38, v35
	v_sub_f32_e32 v38, v36, v38
	v_sub_f32_e32 v35, v35, v38
	v_rcp_f32_e32 v38, v36
	v_cvt_f32_i32_e32 v34, v34
	v_cmp_neq_f32_e32 vcc, s51, v33
	v_mul_f32_e32 v40, v39, v38
	v_mul_f32_e32 v41, v36, v40
	v_fma_f32 v42, v40, v36, -v41
	v_fmac_f32_e32 v42, v40, v35
	v_add_f32_e32 v43, v41, v42
	v_sub_f32_e32 v44, v39, v43
	v_sub_f32_e32 v39, v39, v44
	v_sub_f32_e32 v41, v43, v41
	v_sub_f32_e32 v39, v39, v43
	v_add_f32_e32 v37, v37, v39
	v_sub_f32_e32 v39, v41, v42
	v_add_f32_e32 v37, v39, v37
	v_add_f32_e32 v39, v44, v37
	v_mul_f32_e32 v41, v38, v39
	v_mul_f32_e32 v42, v36, v41
	v_fma_f32 v36, v41, v36, -v42
	v_fmac_f32_e32 v36, v41, v35
	v_sub_f32_e32 v35, v44, v39
	v_add_f32_e32 v35, v37, v35
	v_add_f32_e32 v37, v42, v36
	v_sub_f32_e32 v43, v39, v37
	v_sub_f32_e32 v39, v39, v43
	v_sub_f32_e32 v42, v37, v42
	v_sub_f32_e32 v37, v39, v37
	v_add_f32_e32 v35, v35, v37
	v_sub_f32_e32 v36, v42, v36
	v_add_f32_e32 v35, v36, v35
	v_add_f32_e32 v36, v40, v41
	v_add_f32_e32 v35, v43, v35
	v_sub_f32_e32 v37, v36, v40
	v_mul_f32_e32 v35, v38, v35
	v_sub_f32_e32 v37, v41, v37
	v_add_f32_e32 v35, v37, v35
	v_mul_f32_e32 v40, 0x3f317218, v34
	v_add_f32_e32 v37, v36, v35
	v_fma_f32 v41, v34, s5, -v40
	v_mul_f32_e32 v38, v37, v37
	v_fmac_f32_e32 v41, 0xb102e308, v34
	v_sub_f32_e32 v34, v37, v36
	v_fmamk_f32 v39, v38, 0x3e9b6dac, v226
	v_sub_f32_e32 v34, v35, v34
	v_add_f32_e32 v35, v40, v41
	v_fmaak_f32 v39, v38, v39, 0x3f2aaada
	v_sub_f32_e32 v36, v35, v40
	v_ldexp_f32 v40, v37, 1
	v_mul_f32_e32 v37, v37, v38
	v_mul_f32_e32 v37, v37, v39
	v_add_f32_e32 v38, v40, v37
	v_sub_f32_e32 v39, v38, v40
	v_ldexp_f32 v34, v34, 1
	v_sub_f32_e32 v37, v37, v39
	v_add_f32_e32 v34, v34, v37
	v_add_f32_e32 v37, v38, v34
	v_sub_f32_e32 v38, v37, v38
	v_sub_f32_e32 v34, v34, v38
	v_add_f32_e32 v38, v35, v37
	v_sub_f32_e32 v39, v38, v35
	v_sub_f32_e32 v40, v38, v39
	v_sub_f32_e32 v36, v41, v36
	v_sub_f32_e32 v35, v35, v40
	v_sub_f32_e32 v37, v37, v39
	v_add_f32_e32 v35, v37, v35
	v_add_f32_e32 v37, v36, v34
	v_sub_f32_e32 v39, v37, v36
	v_sub_f32_e32 v40, v37, v39
	v_sub_f32_e32 v36, v36, v40
	v_sub_f32_e32 v34, v34, v39
	v_add_f32_e32 v35, v37, v35
	v_add_f32_e32 v34, v34, v36
	v_add_f32_e32 v36, v38, v35
	v_sub_f32_e32 v37, v36, v38
	v_sub_f32_e32 v35, v35, v37
	v_add_f32_e32 v34, v34, v35
	v_add_f32_e32 v34, v36, v34
	v_cndmask_b32_e32 v34, v227, v34, vcc
	v_cmp_ngt_f32_e32 vcc, -1.0, v33
	s_nop 1
	v_cndmask_b32_e32 v34, v228, v34, vcc
	v_cmp_neq_f32_e32 vcc, -1.0, v33
	s_nop 1
	v_cndmask_b32_e32 v34, v229, v34, vcc
	v_cmp_lt_f32_e64 vcc, |v33|, s13
	s_nop 1
	v_cndmask_b32_e32 v33, v34, v33, vcc
	v_sub_f32_e32 v32, v32, v33
	flat_store_dword v[6:7], v32 offset:28
	v_mov_b32_e32 v6, v110
	v_add_f32_e32 v31, v31, v6
	v_mov_b64_e32 v[6:7], s[0:1]
	flat_store_dword v[6:7], v31
	v_mov_b32_e32 v31, v114
	s_lshl_b64 s[0:1], s[22:23], 5
	s_add_u32 s0, s45, s0
	s_addc_u32 s1, s49, s1
	v_add_f32_e32 v31, v30, v31
	v_min_f32_e32 v30, 0, v31
	v_mul_f32_e64 v31, |v31|, s65
	v_exp_f32_e32 v31, v31
	s_nop 0
	v_add_f32_e32 v34, 1.0, v31
	v_add_f32_e32 v32, -1.0, v34
	v_sub_f32_e32 v33, v32, v34
	v_add_f32_e32 v33, 1.0, v33
	v_sub_f32_e32 v32, v31, v32
	v_add_f32_e32 v35, v32, v33
	v_frexp_mant_f32_e32 v32, v34
	v_cmp_gt_f32_e32 vcc, s4, v32
	v_cvt_f64_f32_e32 v[32:33], v34
	v_frexp_exp_i32_f64_e32 v32, v[32:33]
	v_subbrev_co_u32_e32 v32, vcc, 0, v32, vcc
	v_sub_u32_e32 v33, 0, v32
	v_ldexp_f32 v34, v34, v33
	v_ldexp_f32 v33, v35, v33
	v_add_f32_e32 v35, -1.0, v34
	v_add_f32_e32 v36, 1.0, v35
	v_sub_f32_e32 v36, v34, v36
	v_add_f32_e32 v36, v33, v36
	v_add_f32_e32 v37, v35, v36
	v_sub_f32_e32 v35, v37, v35
	v_sub_f32_e32 v35, v36, v35
	v_add_f32_e32 v36, 1.0, v34
	v_add_f32_e32 v38, -1.0, v36
	v_sub_f32_e32 v34, v34, v38
	v_add_f32_e32 v33, v33, v34
	v_add_f32_e32 v34, v36, v33
	v_sub_f32_e32 v36, v34, v36
	v_sub_f32_e32 v33, v33, v36
	v_rcp_f32_e32 v36, v34
	v_cvt_f32_i32_e32 v32, v32
	v_cmp_neq_f32_e32 vcc, s51, v31
	v_mul_f32_e32 v38, v37, v36
	v_mul_f32_e32 v39, v34, v38
	v_fma_f32 v40, v38, v34, -v39
	v_fmac_f32_e32 v40, v38, v33
	v_add_f32_e32 v41, v39, v40
	v_sub_f32_e32 v42, v37, v41
	v_sub_f32_e32 v37, v37, v42
	v_sub_f32_e32 v39, v41, v39
	v_sub_f32_e32 v37, v37, v41
	v_add_f32_e32 v35, v35, v37
	v_sub_f32_e32 v37, v39, v40
	v_add_f32_e32 v35, v37, v35
	v_add_f32_e32 v37, v42, v35
	v_mul_f32_e32 v39, v36, v37
	v_mul_f32_e32 v40, v34, v39
	v_fma_f32 v34, v39, v34, -v40
	v_fmac_f32_e32 v34, v39, v33
	v_sub_f32_e32 v33, v42, v37
	v_add_f32_e32 v33, v35, v33
	v_add_f32_e32 v35, v40, v34
	v_sub_f32_e32 v41, v37, v35
	v_sub_f32_e32 v37, v37, v41
	v_sub_f32_e32 v40, v35, v40
	v_sub_f32_e32 v35, v37, v35
	v_add_f32_e32 v33, v33, v35
	v_sub_f32_e32 v34, v40, v34
	v_add_f32_e32 v33, v34, v33
; __device__ __forceinline__ float logsigmoidf_(float x) { return fminf(x, 0.f) - log1pf(__expf(-fabsf(x))); }
; __device__ __forceinline__ void preproc_phase(Frame& F, int layer, int b, int cu_lo, int ncu) {
;     ...
;         if (F.lane == 0) {
; #pragma unroll
;             for (int a = 0; a < 4; ++a)
; #pragma unroll
;                 for (int hh = 0; hh < 4; ++hh) { MG[(size_t)(t0 + a) * 8 + hh] = ai[a][hh] + INP(I_M_B_I)[layer * 4 + hh]; MG[(size_t)(t0 + a) * 8 + 4 + hh] = logsigmoidf_(af[a][hh] + INP(I_M_B_F)[layer * 4 + hh]); }
;         }
	v_add_f32_e32 v34, v38, v39
	v_add_f32_e32 v33, v41, v33
	v_sub_f32_e32 v35, v34, v38
	v_mul_f32_e32 v33, v36, v33
	v_sub_f32_e32 v35, v39, v35
	v_add_f32_e32 v33, v35, v33
	v_mul_f32_e32 v38, 0x3f317218, v32
	v_add_f32_e32 v35, v34, v33
	v_fma_f32 v39, v32, s5, -v38
	v_mul_f32_e32 v36, v35, v35
	v_fmac_f32_e32 v39, 0xb102e308, v32
	v_sub_f32_e32 v32, v35, v34
	v_fmamk_f32 v37, v36, 0x3e9b6dac, v226
	v_sub_f32_e32 v32, v33, v32
	v_add_f32_e32 v33, v38, v39
	v_fmaak_f32 v37, v36, v37, 0x3f2aaada
	v_sub_f32_e32 v34, v33, v38
	v_ldexp_f32 v38, v35, 1
	v_mul_f32_e32 v35, v35, v36
	v_mul_f32_e32 v35, v35, v37
	v_add_f32_e32 v36, v38, v35
	v_sub_f32_e32 v37, v36, v38
	v_ldexp_f32 v32, v32, 1
	v_sub_f32_e32 v35, v35, v37
	v_add_f32_e32 v32, v32, v35
	v_add_f32_e32 v35, v36, v32
	v_sub_f32_e32 v36, v35, v36
	v_sub_f32_e32 v32, v32, v36
	v_add_f32_e32 v36, v33, v35
	v_sub_f32_e32 v37, v36, v33
	v_sub_f32_e32 v38, v36, v37
	v_sub_f32_e32 v34, v39, v34
	v_sub_f32_e32 v33, v33, v38
	v_sub_f32_e32 v35, v35, v37
	v_add_f32_e32 v33, v35, v33
	v_add_f32_e32 v35, v34, v32
	v_sub_f32_e32 v37, v35, v34
	v_sub_f32_e32 v38, v35, v37
	v_sub_f32_e32 v34, v34, v38
	v_sub_f32_e32 v32, v32, v37
	v_add_f32_e32 v33, v35, v33
	v_add_f32_e32 v32, v32, v34
	v_add_f32_e32 v34, v36, v33
	v_sub_f32_e32 v35, v34, v36
	v_sub_f32_e32 v33, v33, v35
	v_add_f32_e32 v32, v32, v33
	v_add_f32_e32 v32, v34, v32
	v_cndmask_b32_e32 v32, v227, v32, vcc
	v_cmp_ngt_f32_e32 vcc, -1.0, v31
	s_nop 1
	v_cndmask_b32_e32 v32, v228, v32, vcc
	v_cmp_neq_f32_e32 vcc, -1.0, v31
	s_nop 1
	v_cndmask_b32_e32 v32, v229, v32, vcc
	v_cmp_lt_f32_e64 vcc, |v31|, s13
	s_nop 1
	v_cndmask_b32_e32 v31, v32, v31, vcc
	v_sub_f32_e32 v30, v30, v31
	flat_store_dword v[6:7], v30 offset:16
	v_mov_b32_e32 v30, v111
	v_add_f32_e32 v29, v29, v30
	flat_store_dword v[6:7], v29 offset:4
	v_mov_b32_e32 v29, v115
	v_add_f32_e32 v29, v28, v29
	v_min_f32_e32 v28, 0, v29
	v_mul_f32_e64 v29, |v29|, s65
	v_exp_f32_e32 v29, v29
	s_nop 0
	v_add_f32_e32 v32, 1.0, v29
	v_add_f32_e32 v30, -1.0, v32
	v_sub_f32_e32 v31, v30, v32
	v_add_f32_e32 v31, 1.0, v31
	v_sub_f32_e32 v30, v29, v30
	v_add_f32_e32 v33, v30, v31
	v_frexp_mant_f32_e32 v30, v32
	v_cmp_gt_f32_e32 vcc, s4, v30
	v_cvt_f64_f32_e32 v[30:31], v32
	v_frexp_exp_i32_f64_e32 v30, v[30:31]
	v_subbrev_co_u32_e32 v30, vcc, 0, v30, vcc
	v_sub_u32_e32 v31, 0, v30
	v_ldexp_f32 v32, v32, v31
	v_ldexp_f32 v31, v33, v31
	v_add_f32_e32 v33, -1.0, v32
	v_add_f32_e32 v34, 1.0, v33
	v_sub_f32_e32 v34, v32, v34
	v_add_f32_e32 v34, v31, v34
	v_add_f32_e32 v35, v33, v34
	v_sub_f32_e32 v33, v35, v33
	v_sub_f32_e32 v33, v34, v33
	v_add_f32_e32 v34, 1.0, v32
	v_add_f32_e32 v36, -1.0, v34
	v_sub_f32_e32 v32, v32, v36
	v_add_f32_e32 v31, v31, v32
	v_add_f32_e32 v32, v34, v31
	v_sub_f32_e32 v34, v32, v34
	v_sub_f32_e32 v31, v31, v34
	v_rcp_f32_e32 v34, v32
	v_cvt_f32_i32_e32 v30, v30
	v_cmp_neq_f32_e32 vcc, s51, v29
	v_mul_f32_e32 v36, v35, v34
	v_mul_f32_e32 v37, v32, v36
	v_fma_f32 v38, v36, v32, -v37
	v_fmac_f32_e32 v38, v36, v31
	v_add_f32_e32 v39, v37, v38
	v_sub_f32_e32 v40, v35, v39
	v_sub_f32_e32 v35, v35, v40
	v_sub_f32_e32 v37, v39, v37
	v_sub_f32_e32 v35, v35, v39
	v_add_f32_e32 v33, v33, v35
	v_sub_f32_e32 v35, v37, v38
	v_add_f32_e32 v33, v35, v33
	v_add_f32_e32 v35, v40, v33
	v_mul_f32_e32 v37, v34, v35
	v_mul_f32_e32 v38, v32, v37
	v_fma_f32 v32, v37, v32, -v38
	v_fmac_f32_e32 v32, v37, v31
	v_sub_f32_e32 v31, v40, v35
	v_add_f32_e32 v31, v33, v31
	v_add_f32_e32 v33, v38, v32
	v_sub_f32_e32 v39, v35, v33
	v_sub_f32_e32 v35, v35, v39
	v_sub_f32_e32 v38, v33, v38
	v_sub_f32_e32 v33, v35, v33
	v_add_f32_e32 v31, v31, v33
	v_sub_f32_e32 v32, v38, v32
	v_add_f32_e32 v31, v32, v31
	v_add_f32_e32 v32, v36, v37
	v_add_f32_e32 v31, v39, v31
	v_sub_f32_e32 v33, v32, v36
	v_mul_f32_e32 v31, v34, v31
	v_sub_f32_e32 v33, v37, v33
	v_add_f32_e32 v31, v33, v31
	v_mul_f32_e32 v36, 0x3f317218, v30
	v_add_f32_e32 v33, v32, v31
	v_fma_f32 v37, v30, s5, -v36
	v_mul_f32_e32 v34, v33, v33
	v_fmac_f32_e32 v37, 0xb102e308, v30
	v_sub_f32_e32 v30, v33, v32
	v_fmamk_f32 v35, v34, 0x3e9b6dac, v226
	v_sub_f32_e32 v30, v31, v30
	v_add_f32_e32 v31, v36, v37
	v_fmaak_f32 v35, v34, v35, 0x3f2aaada
	v_sub_f32_e32 v32, v31, v36
	v_ldexp_f32 v36, v33, 1
	v_mul_f32_e32 v33, v33, v34
	v_mul_f32_e32 v33, v33, v35
	v_add_f32_e32 v34, v36, v33
	v_sub_f32_e32 v35, v34, v36
	v_ldexp_f32 v30, v30, 1
	v_sub_f32_e32 v33, v33, v35
	v_add_f32_e32 v30, v30, v33
	v_add_f32_e32 v33, v34, v30
	v_sub_f32_e32 v34, v33, v34
	v_sub_f32_e32 v30, v30, v34
	v_add_f32_e32 v34, v31, v33
	v_sub_f32_e32 v35, v34, v31
	v_sub_f32_e32 v36, v34, v35
	v_sub_f32_e32 v32, v37, v32
	v_sub_f32_e32 v31, v31, v36
	v_sub_f32_e32 v33, v33, v35
	v_add_f32_e32 v31, v33, v31
	v_add_f32_e32 v33, v32, v30
	v_sub_f32_e32 v35, v33, v32
	v_sub_f32_e32 v36, v33, v35
	v_sub_f32_e32 v32, v32, v36
	v_sub_f32_e32 v30, v30, v35
	v_add_f32_e32 v31, v33, v31
	v_add_f32_e32 v30, v30, v32
	v_add_f32_e32 v32, v34, v31
	v_sub_f32_e32 v33, v32, v34
	v_sub_f32_e32 v31, v31, v33
	v_add_f32_e32 v30, v30, v31
	v_add_f32_e32 v30, v32, v30
	v_cndmask_b32_e32 v30, v227, v30, vcc
	v_cmp_ngt_f32_e32 vcc, -1.0, v29
	s_nop 1
	v_cndmask_b32_e32 v30, v228, v30, vcc
	v_cmp_neq_f32_e32 vcc, -1.0, v29
	s_nop 1
	v_cndmask_b32_e32 v30, v229, v30, vcc
	v_cmp_lt_f32_e64 vcc, |v29|, s13
	s_nop 1
	v_cndmask_b32_e32 v29, v30, v29, vcc
	v_sub_f32_e32 v28, v28, v29
	flat_store_dword v[6:7], v28 offset:20
	v_mov_b32_e32 v28, v112
	v_add_f32_e32 v27, v27, v28
	flat_store_dword v[6:7], v27 offset:8
	v_mov_b32_e32 v27, v116
	v_add_f32_e32 v27, v26, v27
	v_min_f32_e32 v26, 0, v27
	v_mul_f32_e64 v27, |v27|, s65
; __device__ __forceinline__ float logsigmoidf_(float x) { return fminf(x, 0.f) - log1pf(__expf(-fabsf(x))); }
; __device__ __forceinline__ void preproc_phase(Frame& F, int layer, int b, int cu_lo, int ncu) {
;     ...
;         if (F.lane == 0) {
; #pragma unroll
;             for (int a = 0; a < 4; ++a)
; #pragma unroll
;                 for (int hh = 0; hh < 4; ++hh) { MG[(size_t)(t0 + a) * 8 + hh] = ai[a][hh] + INP(I_M_B_I)[layer * 4 + hh]; MG[(size_t)(t0 + a) * 8 + 4 + hh] = logsigmoidf_(af[a][hh] + INP(I_M_B_F)[layer * 4 + hh]); }
;         }
	v_exp_f32_e32 v27, v27
	s_nop 0
	v_add_f32_e32 v30, 1.0, v27
	v_add_f32_e32 v28, -1.0, v30
	v_sub_f32_e32 v29, v28, v30
	v_add_f32_e32 v29, 1.0, v29
	v_sub_f32_e32 v28, v27, v28
	v_add_f32_e32 v31, v28, v29
	v_frexp_mant_f32_e32 v28, v30
	v_cmp_gt_f32_e32 vcc, s4, v28
	v_cvt_f64_f32_e32 v[28:29], v30
	v_frexp_exp_i32_f64_e32 v28, v[28:29]
	v_subbrev_co_u32_e32 v28, vcc, 0, v28, vcc
	v_sub_u32_e32 v29, 0, v28
	v_ldexp_f32 v30, v30, v29
	v_ldexp_f32 v29, v31, v29
	v_add_f32_e32 v31, -1.0, v30
	v_add_f32_e32 v32, 1.0, v31
	v_sub_f32_e32 v32, v30, v32
	v_add_f32_e32 v32, v29, v32
	v_add_f32_e32 v33, v31, v32
	v_sub_f32_e32 v31, v33, v31
	v_sub_f32_e32 v31, v32, v31
	v_add_f32_e32 v32, 1.0, v30
	v_add_f32_e32 v34, -1.0, v32
	v_sub_f32_e32 v30, v30, v34
	v_add_f32_e32 v29, v29, v30
	v_add_f32_e32 v30, v32, v29
	v_sub_f32_e32 v32, v30, v32
	v_sub_f32_e32 v29, v29, v32
	v_rcp_f32_e32 v32, v30
	v_cvt_f32_i32_e32 v28, v28
	v_cmp_neq_f32_e32 vcc, s51, v27
	v_mul_f32_e32 v34, v33, v32
	v_mul_f32_e32 v35, v30, v34
	v_fma_f32 v36, v34, v30, -v35
	v_fmac_f32_e32 v36, v34, v29
	v_add_f32_e32 v37, v35, v36
	v_sub_f32_e32 v38, v33, v37
	v_sub_f32_e32 v33, v33, v38
	v_sub_f32_e32 v35, v37, v35
	v_sub_f32_e32 v33, v33, v37
	v_add_f32_e32 v31, v31, v33
	v_sub_f32_e32 v33, v35, v36
	v_add_f32_e32 v31, v33, v31
	v_add_f32_e32 v33, v38, v31
	v_mul_f32_e32 v35, v32, v33
	v_mul_f32_e32 v36, v30, v35
	v_fma_f32 v30, v35, v30, -v36
	v_fmac_f32_e32 v30, v35, v29
	v_sub_f32_e32 v29, v38, v33
	v_add_f32_e32 v29, v31, v29
	v_add_f32_e32 v31, v36, v30
	v_sub_f32_e32 v37, v33, v31
	v_sub_f32_e32 v33, v33, v37
	v_sub_f32_e32 v36, v31, v36
	v_sub_f32_e32 v31, v33, v31
	v_add_f32_e32 v29, v29, v31
	v_sub_f32_e32 v30, v36, v30
	v_add_f32_e32 v29, v30, v29
	v_add_f32_e32 v30, v34, v35
	v_add_f32_e32 v29, v37, v29
	v_sub_f32_e32 v31, v30, v34
	v_mul_f32_e32 v29, v32, v29
	v_sub_f32_e32 v31, v35, v31
	v_add_f32_e32 v29, v31, v29
	v_mul_f32_e32 v34, 0x3f317218, v28
	v_add_f32_e32 v31, v30, v29
	v_fma_f32 v35, v28, s5, -v34
	v_mul_f32_e32 v32, v31, v31
	v_fmac_f32_e32 v35, 0xb102e308, v28
	v_sub_f32_e32 v28, v31, v30
	v_fmamk_f32 v33, v32, 0x3e9b6dac, v226
	v_sub_f32_e32 v28, v29, v28
	v_add_f32_e32 v29, v34, v35
	v_fmaak_f32 v33, v32, v33, 0x3f2aaada
	v_sub_f32_e32 v30, v29, v34
	v_ldexp_f32 v34, v31, 1
	v_mul_f32_e32 v31, v31, v32
	v_mul_f32_e32 v31, v31, v33
	v_add_f32_e32 v32, v34, v31
	v_sub_f32_e32 v33, v32, v34
	v_ldexp_f32 v28, v28, 1
	v_sub_f32_e32 v31, v31, v33
	v_add_f32_e32 v28, v28, v31
	v_add_f32_e32 v31, v32, v28
	v_sub_f32_e32 v32, v31, v32
	v_sub_f32_e32 v28, v28, v32
	v_add_f32_e32 v32, v29, v31
	v_sub_f32_e32 v33, v32, v29
	v_sub_f32_e32 v34, v32, v33
	v_sub_f32_e32 v30, v35, v30
	v_sub_f32_e32 v29, v29, v34
	v_sub_f32_e32 v31, v31, v33
	v_add_f32_e32 v29, v31, v29
	v_add_f32_e32 v31, v30, v28
	v_sub_f32_e32 v33, v31, v30
	v_sub_f32_e32 v34, v31, v33
	v_sub_f32_e32 v30, v30, v34
	v_sub_f32_e32 v28, v28, v33
	v_add_f32_e32 v29, v31, v29
	v_add_f32_e32 v28, v28, v30
	v_add_f32_e32 v30, v32, v29
	v_sub_f32_e32 v31, v30, v32
	v_sub_f32_e32 v29, v29, v31
	v_add_f32_e32 v28, v28, v29
	v_add_f32_e32 v28, v30, v28
	v_cndmask_b32_e32 v28, v227, v28, vcc
	v_cmp_ngt_f32_e32 vcc, -1.0, v27
	s_nop 1
	v_cndmask_b32_e32 v28, v228, v28, vcc
	v_cmp_neq_f32_e32 vcc, -1.0, v27
	s_nop 1
	v_cndmask_b32_e32 v28, v229, v28, vcc
	v_cmp_lt_f32_e64 vcc, |v27|, s13
	s_nop 1
	v_cndmask_b32_e32 v27, v28, v27, vcc
	v_sub_f32_e32 v26, v26, v27
	flat_store_dword v[6:7], v26 offset:24
	v_mov_b32_e32 v26, v113
	v_add_f32_e32 v25, v25, v26
	flat_store_dword v[6:7], v25 offset:12
	v_mov_b32_e32 v25, v117
	v_add_f32_e32 v25, v24, v25
	v_min_f32_e32 v24, 0, v25
	v_mul_f32_e64 v25, |v25|, s65
	v_exp_f32_e32 v25, v25
	s_nop 0
	v_add_f32_e32 v28, 1.0, v25
	v_add_f32_e32 v26, -1.0, v28
	v_sub_f32_e32 v27, v26, v28
	v_add_f32_e32 v27, 1.0, v27
	v_sub_f32_e32 v26, v25, v26
	v_add_f32_e32 v29, v26, v27
	v_frexp_mant_f32_e32 v26, v28
	v_cmp_gt_f32_e32 vcc, s4, v26
	v_cvt_f64_f32_e32 v[26:27], v28
	v_frexp_exp_i32_f64_e32 v26, v[26:27]
	v_subbrev_co_u32_e32 v26, vcc, 0, v26, vcc
	v_sub_u32_e32 v27, 0, v26
	v_ldexp_f32 v28, v28, v27
	v_ldexp_f32 v27, v29, v27
	v_add_f32_e32 v29, -1.0, v28
	v_add_f32_e32 v30, 1.0, v29
	v_sub_f32_e32 v30, v28, v30
	v_add_f32_e32 v30, v27, v30
	v_add_f32_e32 v31, v29, v30
	v_sub_f32_e32 v29, v31, v29
	v_sub_f32_e32 v29, v30, v29
	v_add_f32_e32 v30, 1.0, v28
	v_add_f32_e32 v32, -1.0, v30
	v_sub_f32_e32 v28, v28, v32
	v_add_f32_e32 v27, v27, v28
	v_add_f32_e32 v28, v30, v27
	v_sub_f32_e32 v30, v28, v30
	v_sub_f32_e32 v27, v27, v30
	v_rcp_f32_e32 v30, v28
	v_cvt_f32_i32_e32 v26, v26
	v_cmp_neq_f32_e32 vcc, s51, v25
	v_mul_f32_e32 v32, v31, v30
	v_mul_f32_e32 v33, v28, v32
	v_fma_f32 v34, v32, v28, -v33
	v_fmac_f32_e32 v34, v32, v27
	v_add_f32_e32 v35, v33, v34
	v_sub_f32_e32 v36, v31, v35
	v_sub_f32_e32 v31, v31, v36
	v_sub_f32_e32 v33, v35, v33
	v_sub_f32_e32 v31, v31, v35
	v_add_f32_e32 v29, v29, v31
	v_sub_f32_e32 v31, v33, v34
	v_add_f32_e32 v29, v31, v29
	v_add_f32_e32 v31, v36, v29
	v_mul_f32_e32 v33, v30, v31
	v_mul_f32_e32 v34, v28, v33
	v_fma_f32 v28, v33, v28, -v34
	v_fmac_f32_e32 v28, v33, v27
	v_sub_f32_e32 v27, v36, v31
	v_add_f32_e32 v27, v29, v27
	v_add_f32_e32 v29, v34, v28
	v_sub_f32_e32 v35, v31, v29
	v_sub_f32_e32 v31, v31, v35
	v_sub_f32_e32 v34, v29, v34
	v_sub_f32_e32 v29, v31, v29
	v_add_f32_e32 v27, v27, v29
	v_sub_f32_e32 v28, v34, v28
	v_add_f32_e32 v27, v28, v27
	v_add_f32_e32 v28, v32, v33
	v_add_f32_e32 v27, v35, v27
	v_sub_f32_e32 v29, v28, v32
	v_mul_f32_e32 v27, v30, v27
	v_sub_f32_e32 v29, v33, v29
	v_add_f32_e32 v27, v29, v27
; __device__ __forceinline__ float logsigmoidf_(float x) { return fminf(x, 0.f) - log1pf(__expf(-fabsf(x))); }
; __device__ __forceinline__ void preproc_phase(Frame& F, int layer, int b, int cu_lo, int ncu) {
;     ...
;         if (F.lane == 0) {
; #pragma unroll
;             for (int a = 0; a < 4; ++a)
; #pragma unroll
;                 for (int hh = 0; hh < 4; ++hh) { MG[(size_t)(t0 + a) * 8 + hh] = ai[a][hh] + INP(I_M_B_I)[layer * 4 + hh]; MG[(size_t)(t0 + a) * 8 + 4 + hh] = logsigmoidf_(af[a][hh] + INP(I_M_B_F)[layer * 4 + hh]); }
;         }
	v_mul_f32_e32 v32, 0x3f317218, v26
	v_add_f32_e32 v29, v28, v27
	v_fma_f32 v33, v26, s5, -v32
	v_mul_f32_e32 v30, v29, v29
	v_fmac_f32_e32 v33, 0xb102e308, v26
	v_sub_f32_e32 v26, v29, v28
	v_fmamk_f32 v31, v30, 0x3e9b6dac, v226
	v_sub_f32_e32 v26, v27, v26
	v_add_f32_e32 v27, v32, v33
	v_fmaak_f32 v31, v30, v31, 0x3f2aaada
	v_sub_f32_e32 v28, v27, v32
	v_ldexp_f32 v32, v29, 1
	v_mul_f32_e32 v29, v29, v30
	v_mul_f32_e32 v29, v29, v31
	v_add_f32_e32 v30, v32, v29
	v_sub_f32_e32 v31, v30, v32
	v_ldexp_f32 v26, v26, 1
	v_sub_f32_e32 v29, v29, v31
	v_add_f32_e32 v26, v26, v29
	v_add_f32_e32 v29, v30, v26
	v_sub_f32_e32 v30, v29, v30
	v_sub_f32_e32 v26, v26, v30
	v_add_f32_e32 v30, v27, v29
	v_sub_f32_e32 v31, v30, v27
	v_sub_f32_e32 v32, v30, v31
	v_sub_f32_e32 v28, v33, v28
	v_sub_f32_e32 v27, v27, v32
	v_sub_f32_e32 v29, v29, v31
	v_add_f32_e32 v27, v29, v27
	v_add_f32_e32 v29, v28, v26
	v_sub_f32_e32 v31, v29, v28
	v_sub_f32_e32 v32, v29, v31
	v_sub_f32_e32 v28, v28, v32
	v_sub_f32_e32 v26, v26, v31
	v_add_f32_e32 v27, v29, v27
	v_add_f32_e32 v26, v26, v28
	v_add_f32_e32 v28, v30, v27
	v_sub_f32_e32 v29, v28, v30
	v_sub_f32_e32 v27, v27, v29
	v_add_f32_e32 v26, v26, v27
	v_add_f32_e32 v26, v28, v26
	v_cndmask_b32_e32 v26, v227, v26, vcc
	v_cmp_ngt_f32_e32 vcc, -1.0, v25
	s_nop 1
	v_cndmask_b32_e32 v26, v228, v26, vcc
	v_cmp_neq_f32_e32 vcc, -1.0, v25
	s_nop 1
	v_cndmask_b32_e32 v26, v229, v26, vcc
	v_cmp_lt_f32_e64 vcc, |v25|, s13
	s_nop 1
	v_cndmask_b32_e32 v25, v26, v25, vcc
	v_sub_f32_e32 v24, v24, v25
	flat_store_dword v[6:7], v24 offset:28
	v_mov_b32_e32 v6, v110
	v_add_f32_e32 v23, v23, v6
	v_mov_b64_e32 v[6:7], s[0:1]
	flat_store_dword v[6:7], v23
	v_mov_b32_e32 v23, v114
	s_lshl_b64 s[0:1], s[20:21], 5
	s_add_u32 s0, s45, s0
	s_addc_u32 s1, s49, s1
	v_add_f32_e32 v23, v22, v23
	v_min_f32_e32 v22, 0, v23
	v_mul_f32_e64 v23, |v23|, s65
	v_exp_f32_e32 v23, v23
	s_nop 0
	v_add_f32_e32 v26, 1.0, v23
	v_add_f32_e32 v24, -1.0, v26
	v_sub_f32_e32 v25, v24, v26
	v_add_f32_e32 v25, 1.0, v25
	v_sub_f32_e32 v24, v23, v24
	v_add_f32_e32 v27, v24, v25
	v_frexp_mant_f32_e32 v24, v26
	v_cmp_gt_f32_e32 vcc, s4, v24
	v_cvt_f64_f32_e32 v[24:25], v26
	v_frexp_exp_i32_f64_e32 v24, v[24:25]
	v_subbrev_co_u32_e32 v24, vcc, 0, v24, vcc
	v_sub_u32_e32 v25, 0, v24
	v_ldexp_f32 v26, v26, v25
	v_ldexp_f32 v25, v27, v25
	v_add_f32_e32 v27, -1.0, v26
	v_add_f32_e32 v28, 1.0, v27
	v_sub_f32_e32 v28, v26, v28
	v_add_f32_e32 v28, v25, v28
	v_add_f32_e32 v29, v27, v28
	v_sub_f32_e32 v27, v29, v27
	v_sub_f32_e32 v27, v28, v27
	v_add_f32_e32 v28, 1.0, v26
	v_add_f32_e32 v30, -1.0, v28
	v_sub_f32_e32 v26, v26, v30
	v_add_f32_e32 v25, v25, v26
	v_add_f32_e32 v26, v28, v25
	v_sub_f32_e32 v28, v26, v28
	v_sub_f32_e32 v25, v25, v28
	v_rcp_f32_e32 v28, v26
	v_cvt_f32_i32_e32 v24, v24
	v_cmp_neq_f32_e32 vcc, s51, v23
	v_mul_f32_e32 v30, v29, v28
	v_mul_f32_e32 v31, v26, v30
	v_fma_f32 v32, v30, v26, -v31
	v_fmac_f32_e32 v32, v30, v25
	v_add_f32_e32 v33, v31, v32
	v_sub_f32_e32 v34, v29, v33
	v_sub_f32_e32 v29, v29, v34
	v_sub_f32_e32 v31, v33, v31
	v_sub_f32_e32 v29, v29, v33
	v_add_f32_e32 v27, v27, v29
	v_sub_f32_e32 v29, v31, v32
	v_add_f32_e32 v27, v29, v27
	v_add_f32_e32 v29, v34, v27
	v_mul_f32_e32 v31, v28, v29
	v_mul_f32_e32 v32, v26, v31
	v_fma_f32 v26, v31, v26, -v32
	v_fmac_f32_e32 v26, v31, v25
	v_sub_f32_e32 v25, v34, v29
	v_add_f32_e32 v25, v27, v25
	v_add_f32_e32 v27, v32, v26
	v_sub_f32_e32 v33, v29, v27
	v_sub_f32_e32 v29, v29, v33
	v_sub_f32_e32 v32, v27, v32
	v_sub_f32_e32 v27, v29, v27
	v_add_f32_e32 v25, v25, v27
	v_sub_f32_e32 v26, v32, v26
	v_add_f32_e32 v25, v26, v25
	v_add_f32_e32 v26, v30, v31
	v_add_f32_e32 v25, v33, v25
	v_sub_f32_e32 v27, v26, v30
	v_mul_f32_e32 v25, v28, v25
	v_sub_f32_e32 v27, v31, v27
	v_add_f32_e32 v25, v27, v25
	v_mul_f32_e32 v30, 0x3f317218, v24
	v_add_f32_e32 v27, v26, v25
	v_fma_f32 v31, v24, s5, -v30
	v_mul_f32_e32 v28, v27, v27
	v_fmac_f32_e32 v31, 0xb102e308, v24
	v_sub_f32_e32 v24, v27, v26
	v_fmamk_f32 v29, v28, 0x3e9b6dac, v226
	v_sub_f32_e32 v24, v25, v24
	v_add_f32_e32 v25, v30, v31
	v_fmaak_f32 v29, v28, v29, 0x3f2aaada
	v_sub_f32_e32 v26, v25, v30
	v_ldexp_f32 v30, v27, 1
	v_mul_f32_e32 v27, v27, v28
	v_mul_f32_e32 v27, v27, v29
	v_add_f32_e32 v28, v30, v27
	v_sub_f32_e32 v29, v28, v30
	v_ldexp_f32 v24, v24, 1
	v_sub_f32_e32 v27, v27, v29
	v_add_f32_e32 v24, v24, v27
	v_add_f32_e32 v27, v28, v24
	v_sub_f32_e32 v28, v27, v28
	v_sub_f32_e32 v24, v24, v28
	v_add_f32_e32 v28, v25, v27
	v_sub_f32_e32 v29, v28, v25
	v_sub_f32_e32 v30, v28, v29
	v_sub_f32_e32 v26, v31, v26
	v_sub_f32_e32 v25, v25, v30
	v_sub_f32_e32 v27, v27, v29
	v_add_f32_e32 v25, v27, v25
	v_add_f32_e32 v27, v26, v24
	v_sub_f32_e32 v29, v27, v26
	v_sub_f32_e32 v30, v27, v29
	v_sub_f32_e32 v26, v26, v30
	v_sub_f32_e32 v24, v24, v29
	v_add_f32_e32 v25, v27, v25
	v_add_f32_e32 v24, v24, v26
	v_add_f32_e32 v26, v28, v25
	v_sub_f32_e32 v27, v26, v28
	v_sub_f32_e32 v25, v25, v27
	v_add_f32_e32 v24, v24, v25
	v_add_f32_e32 v24, v26, v24
	v_cndmask_b32_e32 v24, v227, v24, vcc
	v_cmp_ngt_f32_e32 vcc, -1.0, v23
	s_nop 1
	v_cndmask_b32_e32 v24, v228, v24, vcc
	v_cmp_neq_f32_e32 vcc, -1.0, v23
	s_nop 1
	v_cndmask_b32_e32 v24, v229, v24, vcc
	v_cmp_lt_f32_e64 vcc, |v23|, s13
	s_nop 1
	v_cndmask_b32_e32 v23, v24, v23, vcc
	v_sub_f32_e32 v22, v22, v23
	flat_store_dword v[6:7], v22 offset:16
	v_mov_b32_e32 v22, v111
	v_add_f32_e32 v21, v21, v22
	flat_store_dword v[6:7], v21 offset:4
	v_mov_b32_e32 v21, v115
	v_add_f32_e32 v21, v20, v21
	v_min_f32_e32 v20, 0, v21
	v_mul_f32_e64 v21, |v21|, s65
	v_exp_f32_e32 v21, v21
	s_nop 0
	v_add_f32_e32 v24, 1.0, v21
; __device__ __forceinline__ float logsigmoidf_(float x) { return fminf(x, 0.f) - log1pf(__expf(-fabsf(x))); }
; __device__ __forceinline__ void preproc_phase(Frame& F, int layer, int b, int cu_lo, int ncu) {
;     ...
;         if (F.lane == 0) {
; #pragma unroll
;             for (int a = 0; a < 4; ++a)
; #pragma unroll
;                 for (int hh = 0; hh < 4; ++hh) { MG[(size_t)(t0 + a) * 8 + hh] = ai[a][hh] + INP(I_M_B_I)[layer * 4 + hh]; MG[(size_t)(t0 + a) * 8 + 4 + hh] = logsigmoidf_(af[a][hh] + INP(I_M_B_F)[layer * 4 + hh]); }
;         }
	v_add_f32_e32 v22, -1.0, v24
	v_sub_f32_e32 v23, v22, v24
	v_add_f32_e32 v23, 1.0, v23
	v_sub_f32_e32 v22, v21, v22
	v_add_f32_e32 v25, v22, v23
	v_frexp_mant_f32_e32 v22, v24
	v_cmp_gt_f32_e32 vcc, s4, v22
	v_cvt_f64_f32_e32 v[22:23], v24
	v_frexp_exp_i32_f64_e32 v22, v[22:23]
	v_subbrev_co_u32_e32 v22, vcc, 0, v22, vcc
	v_sub_u32_e32 v23, 0, v22
	v_ldexp_f32 v24, v24, v23
	v_ldexp_f32 v23, v25, v23
	v_add_f32_e32 v25, -1.0, v24
	v_add_f32_e32 v26, 1.0, v25
	v_sub_f32_e32 v26, v24, v26
	v_add_f32_e32 v26, v23, v26
	v_add_f32_e32 v27, v25, v26
	v_sub_f32_e32 v25, v27, v25
	v_sub_f32_e32 v25, v26, v25
	v_add_f32_e32 v26, 1.0, v24
	v_add_f32_e32 v28, -1.0, v26
	v_sub_f32_e32 v24, v24, v28
	v_add_f32_e32 v23, v23, v24
	v_add_f32_e32 v24, v26, v23
	v_sub_f32_e32 v26, v24, v26
	v_sub_f32_e32 v23, v23, v26
	v_rcp_f32_e32 v26, v24
	v_cvt_f32_i32_e32 v22, v22
	v_cmp_neq_f32_e32 vcc, s51, v21
	v_mul_f32_e32 v28, v27, v26
	v_mul_f32_e32 v29, v24, v28
	v_fma_f32 v30, v28, v24, -v29
	v_fmac_f32_e32 v30, v28, v23
	v_add_f32_e32 v31, v29, v30
	v_sub_f32_e32 v32, v27, v31
	v_sub_f32_e32 v27, v27, v32
	v_sub_f32_e32 v29, v31, v29
	v_sub_f32_e32 v27, v27, v31
	v_add_f32_e32 v25, v25, v27
	v_sub_f32_e32 v27, v29, v30
	v_add_f32_e32 v25, v27, v25
	v_add_f32_e32 v27, v32, v25
	v_mul_f32_e32 v29, v26, v27
	v_mul_f32_e32 v30, v24, v29
	v_fma_f32 v24, v29, v24, -v30
	v_fmac_f32_e32 v24, v29, v23
	v_sub_f32_e32 v23, v32, v27
	v_add_f32_e32 v23, v25, v23
	v_add_f32_e32 v25, v30, v24
	v_sub_f32_e32 v31, v27, v25
	v_sub_f32_e32 v27, v27, v31
	v_sub_f32_e32 v30, v25, v30
	v_sub_f32_e32 v25, v27, v25
	v_add_f32_e32 v23, v23, v25
	v_sub_f32_e32 v24, v30, v24
	v_add_f32_e32 v23, v24, v23
	v_add_f32_e32 v24, v28, v29
	v_add_f32_e32 v23, v31, v23
	v_sub_f32_e32 v25, v24, v28
	v_mul_f32_e32 v23, v26, v23
	v_sub_f32_e32 v25, v29, v25
	v_add_f32_e32 v23, v25, v23
	v_mul_f32_e32 v28, 0x3f317218, v22
	v_add_f32_e32 v25, v24, v23
	v_fma_f32 v29, v22, s5, -v28
	v_mul_f32_e32 v26, v25, v25
	v_fmac_f32_e32 v29, 0xb102e308, v22
	v_sub_f32_e32 v22, v25, v24
	v_fmamk_f32 v27, v26, 0x3e9b6dac, v226
	v_sub_f32_e32 v22, v23, v22
	v_add_f32_e32 v23, v28, v29
	v_fmaak_f32 v27, v26, v27, 0x3f2aaada
	v_sub_f32_e32 v24, v23, v28
	v_ldexp_f32 v28, v25, 1
	v_mul_f32_e32 v25, v25, v26
	v_mul_f32_e32 v25, v25, v27
	v_add_f32_e32 v26, v28, v25
	v_sub_f32_e32 v27, v26, v28
	v_ldexp_f32 v22, v22, 1
	v_sub_f32_e32 v25, v25, v27
	v_add_f32_e32 v22, v22, v25
	v_add_f32_e32 v25, v26, v22
	v_sub_f32_e32 v26, v25, v26
	v_sub_f32_e32 v22, v22, v26
	v_add_f32_e32 v26, v23, v25
	v_sub_f32_e32 v27, v26, v23
	v_sub_f32_e32 v28, v26, v27
	v_sub_f32_e32 v24, v29, v24
	v_sub_f32_e32 v23, v23, v28
	v_sub_f32_e32 v25, v25, v27
	v_add_f32_e32 v23, v25, v23
	v_add_f32_e32 v25, v24, v22
	v_sub_f32_e32 v27, v25, v24
	v_sub_f32_e32 v28, v25, v27
	v_sub_f32_e32 v24, v24, v28
	v_sub_f32_e32 v22, v22, v27
	v_add_f32_e32 v23, v25, v23
	v_add_f32_e32 v22, v22, v24
	v_add_f32_e32 v24, v26, v23
	v_sub_f32_e32 v25, v24, v26
	v_sub_f32_e32 v23, v23, v25
	v_add_f32_e32 v22, v22, v23
	v_add_f32_e32 v22, v24, v22
	v_cndmask_b32_e32 v22, v227, v22, vcc
	v_cmp_ngt_f32_e32 vcc, -1.0, v21
	s_nop 1
	v_cndmask_b32_e32 v22, v228, v22, vcc
	v_cmp_neq_f32_e32 vcc, -1.0, v21
	s_nop 1
	v_cndmask_b32_e32 v22, v229, v22, vcc
	v_cmp_lt_f32_e64 vcc, |v21|, s13
	s_nop 1
	v_cndmask_b32_e32 v21, v22, v21, vcc
	v_sub_f32_e32 v20, v20, v21
	flat_store_dword v[6:7], v20 offset:20
	v_mov_b32_e32 v20, v112
	v_add_f32_e32 v19, v19, v20
	flat_store_dword v[6:7], v19 offset:8
	v_mov_b32_e32 v19, v116
	v_add_f32_e32 v19, v18, v19
	v_min_f32_e32 v18, 0, v19
	v_mul_f32_e64 v19, |v19|, s65
	v_exp_f32_e32 v19, v19
	s_nop 0
	v_add_f32_e32 v22, 1.0, v19
	v_add_f32_e32 v20, -1.0, v22
	v_sub_f32_e32 v21, v20, v22
	v_add_f32_e32 v21, 1.0, v21
	v_sub_f32_e32 v20, v19, v20
	v_add_f32_e32 v23, v20, v21
	v_frexp_mant_f32_e32 v20, v22
	v_cmp_gt_f32_e32 vcc, s4, v20
	v_cvt_f64_f32_e32 v[20:21], v22
	v_frexp_exp_i32_f64_e32 v20, v[20:21]
	v_subbrev_co_u32_e32 v20, vcc, 0, v20, vcc
	v_sub_u32_e32 v21, 0, v20
	v_ldexp_f32 v22, v22, v21
	v_ldexp_f32 v21, v23, v21
	v_add_f32_e32 v23, -1.0, v22
	v_add_f32_e32 v24, 1.0, v23
	v_sub_f32_e32 v24, v22, v24
	v_add_f32_e32 v24, v21, v24
	v_add_f32_e32 v25, v23, v24
	v_sub_f32_e32 v23, v25, v23
	v_sub_f32_e32 v23, v24, v23
	v_add_f32_e32 v24, 1.0, v22
	v_add_f32_e32 v26, -1.0, v24
	v_sub_f32_e32 v22, v22, v26
	v_add_f32_e32 v21, v21, v22
	v_add_f32_e32 v22, v24, v21
	v_sub_f32_e32 v24, v22, v24
	v_sub_f32_e32 v21, v21, v24
	v_rcp_f32_e32 v24, v22
	v_cvt_f32_i32_e32 v20, v20
	v_cmp_neq_f32_e32 vcc, s51, v19
	v_mul_f32_e32 v26, v25, v24
	v_mul_f32_e32 v27, v22, v26
	v_fma_f32 v28, v26, v22, -v27
	v_fmac_f32_e32 v28, v26, v21
	v_add_f32_e32 v29, v27, v28
	v_sub_f32_e32 v30, v25, v29
	v_sub_f32_e32 v25, v25, v30
	v_sub_f32_e32 v27, v29, v27
	v_sub_f32_e32 v25, v25, v29
	v_add_f32_e32 v23, v23, v25
	v_sub_f32_e32 v25, v27, v28
	v_add_f32_e32 v23, v25, v23
	v_add_f32_e32 v25, v30, v23
	v_mul_f32_e32 v27, v24, v25
	v_mul_f32_e32 v28, v22, v27
	v_fma_f32 v22, v27, v22, -v28
	v_fmac_f32_e32 v22, v27, v21
	v_sub_f32_e32 v21, v30, v25
	v_add_f32_e32 v21, v23, v21
	v_add_f32_e32 v23, v28, v22
	v_sub_f32_e32 v29, v25, v23
	v_sub_f32_e32 v25, v25, v29
	v_sub_f32_e32 v28, v23, v28
	v_sub_f32_e32 v23, v25, v23
	v_add_f32_e32 v21, v21, v23
	v_sub_f32_e32 v22, v28, v22
	v_add_f32_e32 v21, v22, v21
	v_add_f32_e32 v22, v26, v27
	v_add_f32_e32 v21, v29, v21
	v_sub_f32_e32 v23, v22, v26
	v_mul_f32_e32 v21, v24, v21
	v_sub_f32_e32 v23, v27, v23
	v_add_f32_e32 v21, v23, v21
	v_mul_f32_e32 v26, 0x3f317218, v20
	v_add_f32_e32 v23, v22, v21
; __device__ __forceinline__ float logsigmoidf_(float x) { return fminf(x, 0.f) - log1pf(__expf(-fabsf(x))); }
; __device__ __forceinline__ void preproc_phase(Frame& F, int layer, int b, int cu_lo, int ncu) {
;     ...
;         if (F.lane == 0) {
; #pragma unroll
;             for (int a = 0; a < 4; ++a)
; #pragma unroll
;                 for (int hh = 0; hh < 4; ++hh) { MG[(size_t)(t0 + a) * 8 + hh] = ai[a][hh] + INP(I_M_B_I)[layer * 4 + hh]; MG[(size_t)(t0 + a) * 8 + 4 + hh] = logsigmoidf_(af[a][hh] + INP(I_M_B_F)[layer * 4 + hh]); }
;         }
	v_fma_f32 v27, v20, s5, -v26
	v_mul_f32_e32 v24, v23, v23
	v_fmac_f32_e32 v27, 0xb102e308, v20
	v_sub_f32_e32 v20, v23, v22
	v_fmamk_f32 v25, v24, 0x3e9b6dac, v226
	v_sub_f32_e32 v20, v21, v20
	v_add_f32_e32 v21, v26, v27
	v_fmaak_f32 v25, v24, v25, 0x3f2aaada
	v_sub_f32_e32 v22, v21, v26
	v_ldexp_f32 v26, v23, 1
	v_mul_f32_e32 v23, v23, v24
	v_mul_f32_e32 v23, v23, v25
	v_add_f32_e32 v24, v26, v23
	v_sub_f32_e32 v25, v24, v26
	v_ldexp_f32 v20, v20, 1
	v_sub_f32_e32 v23, v23, v25
	v_add_f32_e32 v20, v20, v23
	v_add_f32_e32 v23, v24, v20
	v_sub_f32_e32 v24, v23, v24
	v_sub_f32_e32 v20, v20, v24
	v_add_f32_e32 v24, v21, v23
	v_sub_f32_e32 v25, v24, v21
	v_sub_f32_e32 v26, v24, v25
	v_sub_f32_e32 v22, v27, v22
	v_sub_f32_e32 v21, v21, v26
	v_sub_f32_e32 v23, v23, v25
	v_add_f32_e32 v21, v23, v21
	v_add_f32_e32 v23, v22, v20
	v_sub_f32_e32 v25, v23, v22
	v_sub_f32_e32 v26, v23, v25
	v_sub_f32_e32 v22, v22, v26
	v_sub_f32_e32 v20, v20, v25
	v_add_f32_e32 v21, v23, v21
	v_add_f32_e32 v20, v20, v22
	v_add_f32_e32 v22, v24, v21
	v_sub_f32_e32 v23, v22, v24
	v_sub_f32_e32 v21, v21, v23
	v_add_f32_e32 v20, v20, v21
	v_add_f32_e32 v20, v22, v20
	v_cndmask_b32_e32 v20, v227, v20, vcc
	v_cmp_ngt_f32_e32 vcc, -1.0, v19
	s_nop 1
	v_cndmask_b32_e32 v20, v228, v20, vcc
	v_cmp_neq_f32_e32 vcc, -1.0, v19
	s_nop 1
	v_cndmask_b32_e32 v20, v229, v20, vcc
	v_cmp_lt_f32_e64 vcc, |v19|, s13
	s_nop 1
	v_cndmask_b32_e32 v19, v20, v19, vcc
	v_sub_f32_e32 v18, v18, v19
	flat_store_dword v[6:7], v18 offset:24
	v_mov_b32_e32 v18, v113
	v_add_f32_e32 v17, v17, v18
	flat_store_dword v[6:7], v17 offset:12
	v_mov_b32_e32 v17, v117
	v_add_f32_e32 v17, v16, v17
	v_min_f32_e32 v16, 0, v17
	v_mul_f32_e64 v17, |v17|, s65
	v_exp_f32_e32 v17, v17
	s_nop 0
	v_add_f32_e32 v20, 1.0, v17
	v_add_f32_e32 v18, -1.0, v20
	v_sub_f32_e32 v19, v18, v20
	v_add_f32_e32 v19, 1.0, v19
	v_sub_f32_e32 v18, v17, v18
	v_add_f32_e32 v21, v18, v19
	v_frexp_mant_f32_e32 v18, v20
	v_cmp_gt_f32_e32 vcc, s4, v18
	v_cvt_f64_f32_e32 v[18:19], v20
	v_frexp_exp_i32_f64_e32 v18, v[18:19]
	v_subbrev_co_u32_e32 v18, vcc, 0, v18, vcc
	v_sub_u32_e32 v19, 0, v18
	v_ldexp_f32 v20, v20, v19
	v_ldexp_f32 v19, v21, v19
	v_add_f32_e32 v21, -1.0, v20
	v_add_f32_e32 v22, 1.0, v21
	v_sub_f32_e32 v22, v20, v22
	v_add_f32_e32 v22, v19, v22
	v_add_f32_e32 v23, v21, v22
	v_sub_f32_e32 v21, v23, v21
	v_sub_f32_e32 v21, v22, v21
	v_add_f32_e32 v22, 1.0, v20
	v_add_f32_e32 v24, -1.0, v22
	v_sub_f32_e32 v20, v20, v24
	v_add_f32_e32 v19, v19, v20
	v_add_f32_e32 v20, v22, v19
	v_sub_f32_e32 v22, v20, v22
	v_sub_f32_e32 v19, v19, v22
	v_rcp_f32_e32 v22, v20
	v_cvt_f32_i32_e32 v18, v18
	v_cmp_neq_f32_e32 vcc, s51, v17
	v_mul_f32_e32 v24, v23, v22
	v_mul_f32_e32 v25, v20, v24
	v_fma_f32 v26, v24, v20, -v25
	v_fmac_f32_e32 v26, v24, v19
	v_add_f32_e32 v27, v25, v26
	v_sub_f32_e32 v28, v23, v27
	v_sub_f32_e32 v23, v23, v28
	v_sub_f32_e32 v25, v27, v25
	v_sub_f32_e32 v23, v23, v27
	v_add_f32_e32 v21, v21, v23
	v_sub_f32_e32 v23, v25, v26
	v_add_f32_e32 v21, v23, v21
	v_add_f32_e32 v23, v28, v21
	v_mul_f32_e32 v25, v22, v23
	v_mul_f32_e32 v26, v20, v25
	v_fma_f32 v20, v25, v20, -v26
	v_fmac_f32_e32 v20, v25, v19
	v_sub_f32_e32 v19, v28, v23
	v_add_f32_e32 v19, v21, v19
	v_add_f32_e32 v21, v26, v20
	v_sub_f32_e32 v27, v23, v21
	v_sub_f32_e32 v23, v23, v27
	v_sub_f32_e32 v26, v21, v26
	v_sub_f32_e32 v21, v23, v21
	v_add_f32_e32 v19, v19, v21
	v_sub_f32_e32 v20, v26, v20
	v_add_f32_e32 v19, v20, v19
	v_add_f32_e32 v20, v24, v25
	v_add_f32_e32 v19, v27, v19
	v_sub_f32_e32 v21, v20, v24
	v_mul_f32_e32 v19, v22, v19
	v_sub_f32_e32 v21, v25, v21
	v_add_f32_e32 v19, v21, v19
	v_mul_f32_e32 v24, 0x3f317218, v18
	v_add_f32_e32 v21, v20, v19
	v_fma_f32 v25, v18, s5, -v24
	v_mul_f32_e32 v22, v21, v21
	v_fmac_f32_e32 v25, 0xb102e308, v18
	v_sub_f32_e32 v18, v21, v20
	v_fmamk_f32 v23, v22, 0x3e9b6dac, v226
	v_sub_f32_e32 v18, v19, v18
	v_add_f32_e32 v19, v24, v25
	v_fmaak_f32 v23, v22, v23, 0x3f2aaada
	v_sub_f32_e32 v20, v19, v24
	v_ldexp_f32 v24, v21, 1
	v_mul_f32_e32 v21, v21, v22
	v_mul_f32_e32 v21, v21, v23
	v_add_f32_e32 v22, v24, v21
	v_sub_f32_e32 v23, v22, v24
	v_ldexp_f32 v18, v18, 1
	v_sub_f32_e32 v21, v21, v23
	v_add_f32_e32 v18, v18, v21
	v_add_f32_e32 v21, v22, v18
	v_sub_f32_e32 v22, v21, v22
	v_sub_f32_e32 v18, v18, v22
	v_add_f32_e32 v22, v19, v21
	v_sub_f32_e32 v23, v22, v19
	v_sub_f32_e32 v24, v22, v23
	v_sub_f32_e32 v20, v25, v20
	v_sub_f32_e32 v19, v19, v24
	v_sub_f32_e32 v21, v21, v23
	v_add_f32_e32 v19, v21, v19
	v_add_f32_e32 v21, v20, v18
	v_sub_f32_e32 v23, v21, v20
	v_sub_f32_e32 v24, v21, v23
	v_sub_f32_e32 v20, v20, v24
	v_sub_f32_e32 v18, v18, v23
	v_add_f32_e32 v19, v21, v19
	v_add_f32_e32 v18, v18, v20
	v_add_f32_e32 v20, v22, v19
	v_sub_f32_e32 v21, v20, v22
	v_sub_f32_e32 v19, v19, v21
	v_add_f32_e32 v18, v18, v19
	v_add_f32_e32 v18, v20, v18
	v_cndmask_b32_e32 v18, v227, v18, vcc
	v_cmp_ngt_f32_e32 vcc, -1.0, v17
	s_nop 1
	v_cndmask_b32_e32 v18, v228, v18, vcc
	v_cmp_neq_f32_e32 vcc, -1.0, v17
	s_nop 1
	v_cndmask_b32_e32 v18, v229, v18, vcc
	v_cmp_lt_f32_e64 vcc, |v17|, s13
	s_nop 1
	v_cndmask_b32_e32 v17, v18, v17, vcc
	v_sub_f32_e32 v16, v16, v17
	flat_store_dword v[6:7], v16 offset:28
	v_mov_b32_e32 v6, v110
	v_add_f32_e32 v15, v15, v6
	v_mov_b64_e32 v[6:7], s[0:1]
	flat_store_dword v[6:7], v15
	v_mov_b32_e32 v15, v114
	v_add_f32_e32 v15, v14, v15
	v_min_f32_e32 v14, 0, v15
	v_mul_f32_e64 v15, |v15|, s65
	v_exp_f32_e32 v15, v15
	s_nop 0
	v_add_f32_e32 v18, 1.0, v15
	v_add_f32_e32 v16, -1.0, v18
	v_sub_f32_e32 v17, v16, v18
	v_add_f32_e32 v17, 1.0, v17
	v_sub_f32_e32 v16, v15, v16
	v_add_f32_e32 v19, v16, v17
; __device__ __forceinline__ float logsigmoidf_(float x) { return fminf(x, 0.f) - log1pf(__expf(-fabsf(x))); }
; __device__ __forceinline__ void preproc_phase(Frame& F, int layer, int b, int cu_lo, int ncu) {
;     ...
;         if (F.lane == 0) {
; #pragma unroll
;             for (int a = 0; a < 4; ++a)
; #pragma unroll
;                 for (int hh = 0; hh < 4; ++hh) { MG[(size_t)(t0 + a) * 8 + hh] = ai[a][hh] + INP(I_M_B_I)[layer * 4 + hh]; MG[(size_t)(t0 + a) * 8 + 4 + hh] = logsigmoidf_(af[a][hh] + INP(I_M_B_F)[layer * 4 + hh]); }
;         }
	v_frexp_mant_f32_e32 v16, v18
	v_cmp_gt_f32_e32 vcc, s4, v16
	v_cvt_f64_f32_e32 v[16:17], v18
	v_frexp_exp_i32_f64_e32 v16, v[16:17]
	v_subbrev_co_u32_e32 v16, vcc, 0, v16, vcc
	v_sub_u32_e32 v17, 0, v16
	v_ldexp_f32 v18, v18, v17
	v_ldexp_f32 v17, v19, v17
	v_add_f32_e32 v19, -1.0, v18
	v_add_f32_e32 v20, 1.0, v19
	v_sub_f32_e32 v20, v18, v20
	v_add_f32_e32 v20, v17, v20
	v_add_f32_e32 v21, v19, v20
	v_sub_f32_e32 v19, v21, v19
	v_sub_f32_e32 v19, v20, v19
	v_add_f32_e32 v20, 1.0, v18
	v_add_f32_e32 v22, -1.0, v20
	v_sub_f32_e32 v18, v18, v22
	v_add_f32_e32 v17, v17, v18
	v_add_f32_e32 v18, v20, v17
	v_sub_f32_e32 v20, v18, v20
	v_sub_f32_e32 v17, v17, v20
	v_rcp_f32_e32 v20, v18
	v_cvt_f32_i32_e32 v16, v16
	v_cmp_neq_f32_e32 vcc, s51, v15
	v_mul_f32_e32 v22, v21, v20
	v_mul_f32_e32 v23, v18, v22
	v_fma_f32 v24, v22, v18, -v23
	v_fmac_f32_e32 v24, v22, v17
	v_add_f32_e32 v25, v23, v24
	v_sub_f32_e32 v26, v21, v25
	v_sub_f32_e32 v21, v21, v26
	v_sub_f32_e32 v23, v25, v23
	v_sub_f32_e32 v21, v21, v25
	v_add_f32_e32 v19, v19, v21
	v_sub_f32_e32 v21, v23, v24
	v_add_f32_e32 v19, v21, v19
	v_add_f32_e32 v21, v26, v19
	v_mul_f32_e32 v23, v20, v21
	v_mul_f32_e32 v24, v18, v23
	v_fma_f32 v18, v23, v18, -v24
	v_fmac_f32_e32 v18, v23, v17
	v_sub_f32_e32 v17, v26, v21
	v_add_f32_e32 v17, v19, v17
	v_add_f32_e32 v19, v24, v18
	v_sub_f32_e32 v25, v21, v19
	v_sub_f32_e32 v21, v21, v25
	v_sub_f32_e32 v24, v19, v24
	v_sub_f32_e32 v19, v21, v19
	v_add_f32_e32 v17, v17, v19
	v_sub_f32_e32 v18, v24, v18
	v_add_f32_e32 v17, v18, v17
	v_add_f32_e32 v18, v22, v23
	v_add_f32_e32 v17, v25, v17
	v_sub_f32_e32 v19, v18, v22
	v_mul_f32_e32 v17, v20, v17
	v_sub_f32_e32 v19, v23, v19
	v_add_f32_e32 v17, v19, v17
	v_mul_f32_e32 v22, 0x3f317218, v16
	v_add_f32_e32 v19, v18, v17
	v_fma_f32 v23, v16, s5, -v22
	v_mul_f32_e32 v20, v19, v19
	v_fmac_f32_e32 v23, 0xb102e308, v16
	v_sub_f32_e32 v16, v19, v18
	v_fmamk_f32 v21, v20, 0x3e9b6dac, v226
	v_sub_f32_e32 v16, v17, v16
	v_add_f32_e32 v17, v22, v23
	v_fmaak_f32 v21, v20, v21, 0x3f2aaada
	v_sub_f32_e32 v18, v17, v22
	v_ldexp_f32 v22, v19, 1
	v_mul_f32_e32 v19, v19, v20
	v_mul_f32_e32 v19, v19, v21
	v_add_f32_e32 v20, v22, v19
	v_sub_f32_e32 v21, v20, v22
	v_ldexp_f32 v16, v16, 1
	v_sub_f32_e32 v19, v19, v21
	v_add_f32_e32 v16, v16, v19
	v_add_f32_e32 v19, v20, v16
	v_sub_f32_e32 v20, v19, v20
	v_sub_f32_e32 v16, v16, v20
	v_add_f32_e32 v20, v17, v19
	v_sub_f32_e32 v21, v20, v17
	v_sub_f32_e32 v22, v20, v21
	v_sub_f32_e32 v18, v23, v18
	v_sub_f32_e32 v17, v17, v22
	v_sub_f32_e32 v19, v19, v21
	v_add_f32_e32 v17, v19, v17
	v_add_f32_e32 v19, v18, v16
	v_sub_f32_e32 v21, v19, v18
	v_sub_f32_e32 v22, v19, v21
	v_sub_f32_e32 v18, v18, v22
	v_sub_f32_e32 v16, v16, v21
	v_add_f32_e32 v17, v19, v17
	v_add_f32_e32 v16, v16, v18
	v_add_f32_e32 v18, v20, v17
	v_sub_f32_e32 v19, v18, v20
	v_sub_f32_e32 v17, v17, v19
	v_add_f32_e32 v16, v16, v17
	v_add_f32_e32 v16, v18, v16
	v_cndmask_b32_e32 v16, v227, v16, vcc
	v_cmp_ngt_f32_e32 vcc, -1.0, v15
	s_nop 1
	v_cndmask_b32_e32 v16, v228, v16, vcc
	v_cmp_neq_f32_e32 vcc, -1.0, v15
	s_nop 1
	v_cndmask_b32_e32 v16, v229, v16, vcc
	v_cmp_lt_f32_e64 vcc, |v15|, s13
	s_nop 1
	v_cndmask_b32_e32 v15, v16, v15, vcc
	v_sub_f32_e32 v14, v14, v15
	flat_store_dword v[6:7], v14 offset:16
	v_mov_b32_e32 v14, v111
	v_add_f32_e32 v13, v13, v14
	flat_store_dword v[6:7], v13 offset:4
	v_mov_b32_e32 v13, v115
	v_add_f32_e32 v13, v12, v13
	v_min_f32_e32 v12, 0, v13
	v_mul_f32_e64 v13, |v13|, s65
	v_exp_f32_e32 v13, v13
	s_nop 0
	v_add_f32_e32 v16, 1.0, v13
	v_add_f32_e32 v14, -1.0, v16
	v_sub_f32_e32 v15, v14, v16
	v_add_f32_e32 v15, 1.0, v15
	v_sub_f32_e32 v14, v13, v14
	v_add_f32_e32 v17, v14, v15
	v_frexp_mant_f32_e32 v14, v16
	v_cmp_gt_f32_e32 vcc, s4, v14
	v_cvt_f64_f32_e32 v[14:15], v16
	v_frexp_exp_i32_f64_e32 v14, v[14:15]
	v_subbrev_co_u32_e32 v14, vcc, 0, v14, vcc
	v_sub_u32_e32 v15, 0, v14
	v_ldexp_f32 v16, v16, v15
	v_ldexp_f32 v15, v17, v15
	v_add_f32_e32 v17, -1.0, v16
	v_add_f32_e32 v18, 1.0, v17
	v_sub_f32_e32 v18, v16, v18
	v_add_f32_e32 v18, v15, v18
	v_add_f32_e32 v19, v17, v18
	v_sub_f32_e32 v17, v19, v17
	v_sub_f32_e32 v17, v18, v17
	v_add_f32_e32 v18, 1.0, v16
	v_add_f32_e32 v20, -1.0, v18
	v_sub_f32_e32 v16, v16, v20
	v_add_f32_e32 v15, v15, v16
	v_add_f32_e32 v16, v18, v15
	v_sub_f32_e32 v18, v16, v18
	v_sub_f32_e32 v15, v15, v18
	v_rcp_f32_e32 v18, v16
	v_cvt_f32_i32_e32 v14, v14
	v_cmp_neq_f32_e32 vcc, s51, v13
	v_mul_f32_e32 v20, v19, v18
	v_mul_f32_e32 v21, v16, v20
	v_fma_f32 v22, v20, v16, -v21
	v_fmac_f32_e32 v22, v20, v15
	v_add_f32_e32 v23, v21, v22
	v_sub_f32_e32 v24, v19, v23
	v_sub_f32_e32 v19, v19, v24
	v_sub_f32_e32 v21, v23, v21
	v_sub_f32_e32 v19, v19, v23
	v_add_f32_e32 v17, v17, v19
	v_sub_f32_e32 v19, v21, v22
	v_add_f32_e32 v17, v19, v17
	v_add_f32_e32 v19, v24, v17
	v_mul_f32_e32 v21, v18, v19
	v_mul_f32_e32 v22, v16, v21
	v_fma_f32 v16, v21, v16, -v22
	v_fmac_f32_e32 v16, v21, v15
	v_sub_f32_e32 v15, v24, v19
	v_add_f32_e32 v15, v17, v15
	v_add_f32_e32 v17, v22, v16
	v_sub_f32_e32 v23, v19, v17
	v_sub_f32_e32 v19, v19, v23
	v_sub_f32_e32 v22, v17, v22
	v_sub_f32_e32 v17, v19, v17
	v_add_f32_e32 v15, v15, v17
	v_sub_f32_e32 v16, v22, v16
	v_add_f32_e32 v15, v16, v15
	v_add_f32_e32 v16, v20, v21
	v_add_f32_e32 v15, v23, v15
	v_sub_f32_e32 v17, v16, v20
	v_mul_f32_e32 v15, v18, v15
	v_sub_f32_e32 v17, v21, v17
	v_add_f32_e32 v15, v17, v15
	v_mul_f32_e32 v20, 0x3f317218, v14
	v_add_f32_e32 v17, v16, v15
	v_fma_f32 v21, v14, s5, -v20
	v_mul_f32_e32 v18, v17, v17
	v_fmac_f32_e32 v21, 0xb102e308, v14
	v_sub_f32_e32 v14, v17, v16
	v_fmamk_f32 v19, v18, 0x3e9b6dac, v226
; __device__ __forceinline__ float logsigmoidf_(float x) { return fminf(x, 0.f) - log1pf(__expf(-fabsf(x))); }
; __device__ __forceinline__ void preproc_phase(Frame& F, int layer, int b, int cu_lo, int ncu) {
;     ...
;         if (F.lane == 0) {
; #pragma unroll
;             for (int a = 0; a < 4; ++a)
; #pragma unroll
;                 for (int hh = 0; hh < 4; ++hh) { MG[(size_t)(t0 + a) * 8 + hh] = ai[a][hh] + INP(I_M_B_I)[layer * 4 + hh]; MG[(size_t)(t0 + a) * 8 + 4 + hh] = logsigmoidf_(af[a][hh] + INP(I_M_B_F)[layer * 4 + hh]); }
;         }
	v_sub_f32_e32 v14, v15, v14
	v_add_f32_e32 v15, v20, v21
	v_fmaak_f32 v19, v18, v19, 0x3f2aaada
	v_sub_f32_e32 v16, v15, v20
	v_ldexp_f32 v20, v17, 1
	v_mul_f32_e32 v17, v17, v18
	v_mul_f32_e32 v17, v17, v19
	v_add_f32_e32 v18, v20, v17
	v_sub_f32_e32 v19, v18, v20
	v_ldexp_f32 v14, v14, 1
	v_sub_f32_e32 v17, v17, v19
	v_add_f32_e32 v14, v14, v17
	v_add_f32_e32 v17, v18, v14
	v_sub_f32_e32 v18, v17, v18
	v_sub_f32_e32 v14, v14, v18
	v_add_f32_e32 v18, v15, v17
	v_sub_f32_e32 v19, v18, v15
	v_sub_f32_e32 v20, v18, v19
	v_sub_f32_e32 v16, v21, v16
	v_sub_f32_e32 v15, v15, v20
	v_sub_f32_e32 v17, v17, v19
	v_add_f32_e32 v15, v17, v15
	v_add_f32_e32 v17, v16, v14
	v_sub_f32_e32 v19, v17, v16
	v_sub_f32_e32 v20, v17, v19
	v_sub_f32_e32 v16, v16, v20
	v_sub_f32_e32 v14, v14, v19
	v_add_f32_e32 v15, v17, v15
	v_add_f32_e32 v14, v14, v16
	v_add_f32_e32 v16, v18, v15
	v_sub_f32_e32 v17, v16, v18
	v_sub_f32_e32 v15, v15, v17
	v_add_f32_e32 v14, v14, v15
	v_add_f32_e32 v14, v16, v14
	v_cndmask_b32_e32 v14, v227, v14, vcc
	v_cmp_ngt_f32_e32 vcc, -1.0, v13
	s_nop 1
	v_cndmask_b32_e32 v14, v228, v14, vcc
	v_cmp_neq_f32_e32 vcc, -1.0, v13
	s_nop 1
	v_cndmask_b32_e32 v14, v229, v14, vcc
	v_cmp_lt_f32_e64 vcc, |v13|, s13
	s_nop 1
	v_cndmask_b32_e32 v13, v14, v13, vcc
	v_sub_f32_e32 v12, v12, v13
	flat_store_dword v[6:7], v12 offset:20
	v_mov_b32_e32 v12, v112
	v_add_f32_e32 v11, v11, v12
	flat_store_dword v[6:7], v11 offset:8
	v_mov_b32_e32 v11, v116
	v_add_f32_e32 v11, v10, v11
	v_min_f32_e32 v10, 0, v11
	v_mul_f32_e64 v11, |v11|, s65
	v_exp_f32_e32 v11, v11
	s_nop 0
	v_add_f32_e32 v14, 1.0, v11
	v_add_f32_e32 v12, -1.0, v14
	v_sub_f32_e32 v13, v12, v14
	v_add_f32_e32 v13, 1.0, v13
	v_sub_f32_e32 v12, v11, v12
	v_add_f32_e32 v15, v12, v13
	v_frexp_mant_f32_e32 v12, v14
	v_cmp_gt_f32_e32 vcc, s4, v12
	v_cvt_f64_f32_e32 v[12:13], v14
	v_frexp_exp_i32_f64_e32 v12, v[12:13]
	v_subbrev_co_u32_e32 v12, vcc, 0, v12, vcc
	v_sub_u32_e32 v13, 0, v12
	v_ldexp_f32 v14, v14, v13
	v_ldexp_f32 v13, v15, v13
	v_add_f32_e32 v15, -1.0, v14
	v_add_f32_e32 v16, 1.0, v15
	v_sub_f32_e32 v16, v14, v16
	v_add_f32_e32 v16, v13, v16
	v_add_f32_e32 v17, v15, v16
	v_sub_f32_e32 v15, v17, v15
	v_sub_f32_e32 v15, v16, v15
	v_add_f32_e32 v16, 1.0, v14
	v_add_f32_e32 v18, -1.0, v16
	v_sub_f32_e32 v14, v14, v18
	v_add_f32_e32 v13, v13, v14
	v_add_f32_e32 v14, v16, v13
	v_sub_f32_e32 v16, v14, v16
	v_sub_f32_e32 v13, v13, v16
	v_rcp_f32_e32 v16, v14
	v_cvt_f32_i32_e32 v12, v12
	v_cmp_neq_f32_e32 vcc, s51, v11
	v_mul_f32_e32 v18, v17, v16
	v_mul_f32_e32 v19, v14, v18
	v_fma_f32 v20, v18, v14, -v19
	v_fmac_f32_e32 v20, v18, v13
	v_add_f32_e32 v21, v19, v20
	v_sub_f32_e32 v22, v17, v21
	v_sub_f32_e32 v17, v17, v22
	v_sub_f32_e32 v19, v21, v19
	v_sub_f32_e32 v17, v17, v21
	v_add_f32_e32 v15, v15, v17
	v_sub_f32_e32 v17, v19, v20
	v_add_f32_e32 v15, v17, v15
	v_add_f32_e32 v17, v22, v15
	v_mul_f32_e32 v19, v16, v17
	v_mul_f32_e32 v20, v14, v19
	v_fma_f32 v14, v19, v14, -v20
	v_fmac_f32_e32 v14, v19, v13
	v_sub_f32_e32 v13, v22, v17
	v_add_f32_e32 v13, v15, v13
	v_add_f32_e32 v15, v20, v14
	v_sub_f32_e32 v21, v17, v15
	v_sub_f32_e32 v17, v17, v21
	v_sub_f32_e32 v20, v15, v20
	v_sub_f32_e32 v15, v17, v15
	v_add_f32_e32 v13, v13, v15
	v_sub_f32_e32 v14, v20, v14
	v_add_f32_e32 v13, v14, v13
	v_add_f32_e32 v14, v18, v19
	v_add_f32_e32 v13, v21, v13
	v_sub_f32_e32 v15, v14, v18
	v_mul_f32_e32 v13, v16, v13
	v_sub_f32_e32 v15, v19, v15
	v_add_f32_e32 v13, v15, v13
	v_mul_f32_e32 v18, 0x3f317218, v12
	v_add_f32_e32 v15, v14, v13
	v_fma_f32 v19, v12, s5, -v18
	v_mul_f32_e32 v16, v15, v15
	v_fmac_f32_e32 v19, 0xb102e308, v12
	v_sub_f32_e32 v12, v15, v14
	v_fmamk_f32 v17, v16, 0x3e9b6dac, v226
	v_sub_f32_e32 v12, v13, v12
	v_add_f32_e32 v13, v18, v19
	v_fmaak_f32 v17, v16, v17, 0x3f2aaada
	v_sub_f32_e32 v14, v13, v18
	v_ldexp_f32 v18, v15, 1
	v_mul_f32_e32 v15, v15, v16
	v_mul_f32_e32 v15, v15, v17
	v_add_f32_e32 v16, v18, v15
	v_sub_f32_e32 v17, v16, v18
	v_ldexp_f32 v12, v12, 1
	v_sub_f32_e32 v15, v15, v17
	v_add_f32_e32 v12, v12, v15
	v_add_f32_e32 v15, v16, v12
	v_sub_f32_e32 v16, v15, v16
	v_sub_f32_e32 v12, v12, v16
	v_add_f32_e32 v16, v13, v15
	v_sub_f32_e32 v17, v16, v13
	v_sub_f32_e32 v18, v16, v17
	v_sub_f32_e32 v14, v19, v14
	v_sub_f32_e32 v13, v13, v18
; __device__ __forceinline__ float logsigmoidf_(float x) { return fminf(x, 0.f) - log1pf(__expf(-fabsf(x))); }
; __device__ __forceinline__ void preproc_phase(Frame& F, int layer, int b, int cu_lo, int ncu) {
;     ...
;         if (F.lane == 0) {
; #pragma unroll
;             for (int a = 0; a < 4; ++a)
; #pragma unroll
;                 for (int hh = 0; hh < 4; ++hh) { MG[(size_t)(t0 + a) * 8 + hh] = ai[a][hh] + INP(I_M_B_I)[layer * 4 + hh]; MG[(size_t)(t0 + a) * 8 + 4 + hh] = logsigmoidf_(af[a][hh] + INP(I_M_B_F)[layer * 4 + hh]); }
;         }
	v_sub_f32_e32 v15, v15, v17
	v_add_f32_e32 v13, v15, v13
	v_add_f32_e32 v15, v14, v12
	v_sub_f32_e32 v17, v15, v14
	v_sub_f32_e32 v18, v15, v17
	v_sub_f32_e32 v14, v14, v18
	v_sub_f32_e32 v12, v12, v17
	v_add_f32_e32 v13, v15, v13
	v_add_f32_e32 v12, v12, v14
	v_add_f32_e32 v14, v16, v13
	v_sub_f32_e32 v15, v14, v16
	v_sub_f32_e32 v13, v13, v15
	v_add_f32_e32 v12, v12, v13
	v_add_f32_e32 v12, v14, v12
	v_cndmask_b32_e32 v12, v227, v12, vcc
	v_cmp_ngt_f32_e32 vcc, -1.0, v11
	s_nop 1
	v_cndmask_b32_e32 v12, v228, v12, vcc
	v_cmp_neq_f32_e32 vcc, -1.0, v11
	s_nop 1
	v_cndmask_b32_e32 v12, v229, v12, vcc
	v_cmp_lt_f32_e64 vcc, |v11|, s13
	s_nop 1
	v_cndmask_b32_e32 v11, v12, v11, vcc
	v_sub_f32_e32 v10, v10, v11
	flat_store_dword v[6:7], v10 offset:24
	v_mov_b32_e32 v2, v113
	v_add_f32_e32 v2, v9, v2
	flat_store_dword v[6:7], v2 offset:12
	v_mov_b32_e32 v2, v117
	v_add_f32_e32 v3, v8, v2
	v_min_f32_e32 v2, 0, v3
	v_mul_f32_e64 v3, |v3|, s65
	v_exp_f32_e32 v3, v3
	s_nop 0
	v_add_f32_e32 v8, 1.0, v3
	v_add_f32_e32 v4, -1.0, v8
	v_sub_f32_e32 v5, v4, v8
	v_add_f32_e32 v5, 1.0, v5
	v_sub_f32_e32 v4, v3, v4
	v_add_f32_e32 v9, v4, v5
	v_frexp_mant_f32_e32 v4, v8
	v_cmp_gt_f32_e32 vcc, s4, v4
	v_cvt_f64_f32_e32 v[4:5], v8
	v_frexp_exp_i32_f64_e32 v4, v[4:5]
	v_subbrev_co_u32_e32 v4, vcc, 0, v4, vcc
	v_sub_u32_e32 v5, 0, v4
	v_ldexp_f32 v8, v8, v5
	v_ldexp_f32 v5, v9, v5
	v_add_f32_e32 v9, -1.0, v8
	v_add_f32_e32 v10, 1.0, v9
	v_sub_f32_e32 v10, v8, v10
	v_add_f32_e32 v10, v5, v10
	v_add_f32_e32 v11, v9, v10
	v_sub_f32_e32 v9, v11, v9
	v_sub_f32_e32 v9, v10, v9
	v_add_f32_e32 v10, 1.0, v8
	v_add_f32_e32 v12, -1.0, v10
	v_sub_f32_e32 v8, v8, v12
	v_add_f32_e32 v5, v5, v8
	v_add_f32_e32 v8, v10, v5
	v_sub_f32_e32 v10, v8, v10
	v_sub_f32_e32 v5, v5, v10
	v_rcp_f32_e32 v10, v8
	v_cvt_f32_i32_e32 v4, v4
	v_cmp_neq_f32_e32 vcc, s51, v3
	v_mul_f32_e32 v12, v11, v10
	v_mul_f32_e32 v13, v8, v12
	v_fma_f32 v14, v12, v8, -v13
	v_fmac_f32_e32 v14, v12, v5
	v_add_f32_e32 v15, v13, v14
	v_sub_f32_e32 v16, v11, v15
	v_sub_f32_e32 v11, v11, v16
	v_sub_f32_e32 v13, v15, v13
	v_sub_f32_e32 v11, v11, v15
	v_add_f32_e32 v9, v9, v11
	v_sub_f32_e32 v11, v13, v14
	v_add_f32_e32 v9, v11, v9
	v_add_f32_e32 v11, v16, v9
	v_mul_f32_e32 v13, v10, v11
	v_mul_f32_e32 v14, v8, v13
	v_fma_f32 v8, v13, v8, -v14
	v_fmac_f32_e32 v8, v13, v5
	v_sub_f32_e32 v5, v16, v11
	v_add_f32_e32 v5, v9, v5
	v_add_f32_e32 v9, v14, v8
	v_sub_f32_e32 v15, v11, v9
	v_sub_f32_e32 v11, v11, v15
	v_sub_f32_e32 v14, v9, v14
	v_sub_f32_e32 v9, v11, v9
	v_add_f32_e32 v5, v5, v9
	v_sub_f32_e32 v8, v14, v8
	v_add_f32_e32 v5, v8, v5
	v_add_f32_e32 v8, v12, v13
	v_add_f32_e32 v5, v15, v5
	v_sub_f32_e32 v9, v8, v12
	v_mul_f32_e32 v5, v10, v5
	v_sub_f32_e32 v9, v13, v9
	v_add_f32_e32 v5, v9, v5
	v_mul_f32_e32 v12, 0x3f317218, v4
	v_add_f32_e32 v9, v8, v5
	v_fma_f32 v13, v4, s5, -v12
	v_mul_f32_e32 v10, v9, v9
	v_fmac_f32_e32 v13, 0xb102e308, v4
	v_sub_f32_e32 v4, v9, v8
	v_fmamk_f32 v11, v10, 0x3e9b6dac, v226
	v_sub_f32_e32 v4, v5, v4
	v_add_f32_e32 v5, v12, v13
	v_fmaak_f32 v11, v10, v11, 0x3f2aaada
	v_sub_f32_e32 v8, v5, v12
	v_ldexp_f32 v12, v9, 1
	v_mul_f32_e32 v9, v9, v10
	v_mul_f32_e32 v9, v9, v11
	v_add_f32_e32 v10, v12, v9
	v_sub_f32_e32 v11, v10, v12
	v_ldexp_f32 v4, v4, 1
	v_sub_f32_e32 v9, v9, v11
	v_add_f32_e32 v4, v4, v9
	v_add_f32_e32 v9, v10, v4
	v_sub_f32_e32 v10, v9, v10
	v_sub_f32_e32 v4, v4, v10
	v_add_f32_e32 v10, v5, v9
	v_sub_f32_e32 v11, v10, v5
	v_sub_f32_e32 v12, v10, v11
	v_sub_f32_e32 v8, v13, v8
	v_sub_f32_e32 v5, v5, v12
	v_sub_f32_e32 v9, v9, v11
	v_add_f32_e32 v5, v9, v5
	v_add_f32_e32 v9, v8, v4
	v_sub_f32_e32 v11, v9, v8
	v_sub_f32_e32 v12, v9, v11
	v_sub_f32_e32 v8, v8, v12
	v_sub_f32_e32 v4, v4, v11
	v_add_f32_e32 v5, v9, v5
	v_add_f32_e32 v4, v4, v8
	v_add_f32_e32 v8, v10, v5
	v_sub_f32_e32 v9, v8, v10
	v_sub_f32_e32 v5, v5, v9
	v_add_f32_e32 v4, v4, v5
	v_add_f32_e32 v4, v8, v4
	v_cndmask_b32_e32 v4, v227, v4, vcc
	v_cmp_ngt_f32_e32 vcc, -1.0, v3
	s_nop 1
	v_cndmask_b32_e32 v4, v228, v4, vcc
	v_cmp_neq_f32_e32 vcc, -1.0, v3
	s_nop 1
	v_cndmask_b32_e32 v4, v229, v4, vcc
	v_cmp_lt_f32_e64 vcc, |v3|, s13
	s_nop 1
	v_cndmask_b32_e32 v3, v4, v3, vcc
	v_sub_f32_e32 v2, v2, v3
	flat_store_dword v[6:7], v2 offset:28
	s_branch .LBB0_322

; template <bool MAPPED>
; __device__ __forceinline__ void transpose_item(const float* W, int K, int Nsrc, bf16_t* WT, const float* gk, LAS float* scr, int item, int nblk, int lane) {
;     ...
; #pragma unroll 8
;     for (int i = 0; i < 32; ++i) { const int kk = 2 * i + (lane >> 5); float v = (sc >= 0) ? W[(size_t)(k0 + kk) * Nsrc + sc] : 0.f; if (gk) v *= gk[k0 + kk]; scr[kk * 33 + (lane & 31)] = v; }
.LBB0_805:
	v_add_u32_e32 v33, s1, v32
	v_add_u32_e32 v34, 0xffffa900, v33
	v_ashrrev_i32_e32 v35, 31, v34
	v_lshlrev_b64 v[34:35], 12, v[34:35]
	v_lshl_add_u64 v[34:35], v[30:31], 0, v[34:35]
	global_load_dword v90, v[34:35], off
	s_add_i32 s1, s1, 16
	s_cmp_lg_u32 s1, 64
	v_add_u32_e32 v34, 0xffffa902, v33
	v_ashrrev_i32_e32 v35, 31, v34
	v_lshlrev_b64 v[34:35], 12, v[34:35]
	v_lshl_add_u64 v[34:35], v[30:31], 0, v[34:35]
	global_load_dword v91, v[34:35], off
	v_add_u32_e32 v34, 0xffffa904, v33
	v_ashrrev_i32_e32 v35, 31, v34
	v_lshlrev_b64 v[34:35], 12, v[34:35]
	v_lshl_add_u64 v[34:35], v[30:31], 0, v[34:35]
	global_load_dword v92, v[34:35], off
	v_add_u32_e32 v34, 0xffffa906, v33
	v_ashrrev_i32_e32 v35, 31, v34
	v_lshlrev_b64 v[34:35], 12, v[34:35]
	v_lshl_add_u64 v[34:35], v[30:31], 0, v[34:35]
	global_load_dword v93, v[34:35], off
	v_add_u32_e32 v34, 0xffffa908, v33
	v_ashrrev_i32_e32 v35, 31, v34
	v_lshlrev_b64 v[34:35], 12, v[34:35]
	v_lshl_add_u64 v[34:35], v[30:31], 0, v[34:35]
	global_load_dword v94, v[34:35], off
	v_add_u32_e32 v34, 0xffffa90a, v33
	v_ashrrev_i32_e32 v35, 31, v34
	v_lshlrev_b64 v[34:35], 12, v[34:35]
	v_lshl_add_u64 v[34:35], v[30:31], 0, v[34:35]
	global_load_dword v95, v[34:35], off
	v_add_u32_e32 v34, 0xffffa90c, v33
	v_ashrrev_i32_e32 v35, 31, v34
	v_lshlrev_b64 v[34:35], 12, v[34:35]
	v_lshl_add_u64 v[34:35], v[30:31], 0, v[34:35]
	global_load_dword v96, v[34:35], off
	v_add_u32_e32 v34, 0xffffa90e, v33
	v_ashrrev_i32_e32 v35, 31, v34
	v_lshlrev_b64 v[34:35], 12, v[34:35]
	v_lshl_add_u64 v[34:35], v[30:31], 0, v[34:35]
	global_load_dword v97, v[34:35], off
	s_waitcnt vmcnt(7)
	ds_write_b32 v0, v90
	s_waitcnt vmcnt(6)
	ds_write_b32 v0, v91 offset:264
	s_waitcnt vmcnt(5)
	ds_write_b32 v0, v92 offset:528
	s_waitcnt vmcnt(4)
	ds_write_b32 v0, v93 offset:792
	s_waitcnt vmcnt(3)
	ds_write_b32 v0, v94 offset:1056
	s_waitcnt vmcnt(2)
	ds_write_b32 v0, v95 offset:1320
	s_waitcnt vmcnt(1)
	ds_write_b32 v0, v96 offset:1584
	s_waitcnt vmcnt(0)
	ds_write_b32 v0, v97 offset:1848
	v_add_u32_e32 v0, 0x840, v0
	s_cbranch_scc1 .LBB0_805
; #define LAS __attribute__((address_space(3)))
; __device__ __forceinline__ unsigned pk2(float lo, float hi) { return f2bf(lo) | (f2bf(hi) << 16); }
; template <bool MAPPED>
; __device__ __forceinline__ void transpose_item(const float* W, int K, int Nsrc, bf16_t* WT, const float* gk, LAS float* scr, int item, int nblk, int lane) {
;     ...
;     asm volatile("s_waitcnt lgkmcnt(0)" ::: "memory");
;     const int c = lane & 7;
; #pragma unroll
;     for (int j = 0; j < 4; ++j) { const int n = (lane >> 3) + 8 * j; const LAS float* s = scr + (8 * c) * 33 + n;
;         u32x4 o; o.x = pk2(s[0 * 33], s[1 * 33]); o.y = pk2(s[2 * 33], s[3 * 33]); o.z = pk2(s[4 * 33], s[5 * 33]); o.w = pk2(s[6 * 33], s[7 * 33]);
;         *(u32x4*)(WT + (size_t)(j0 + n) * K + k0 + 8 * c) = o; }
;     asm volatile("s_waitcnt lgkmcnt(0)" ::: "memory");
	s_waitcnt lgkmcnt(0)
	ds_read_b32 v0, v67
	ds_read_b32 v32, v67 offset:132
	s_lshl_b32 s1, s19, 1
	s_andn2_b32 s1, s1, 63
	s_add_i32 s62, s1, 0xffffa900
	s_waitcnt lgkmcnt(1)
	v_bfe_u32 v33, v0, 16, 1
	v_add3_u32 v0, v0, v33, s81
	s_waitcnt lgkmcnt(0)
	v_bfe_u32 v33, v32, 16, 1
	v_lshrrev_b32_e32 v0, 16, v0
	v_add3_u32 v32, v32, v33, s81
	v_and_or_b32 v32, v32, s46, v0
	ds_read_b32 v0, v67 offset:264
	ds_read_b32 v33, v67 offset:396
	v_lshl_add_u64 v[30:31], s[62:63], 1, v[8:9]
	s_waitcnt lgkmcnt(1)
	v_bfe_u32 v34, v0, 16, 1
	v_add3_u32 v0, v0, v34, s81
	s_waitcnt lgkmcnt(0)
	v_bfe_u32 v34, v33, 16, 1
	v_lshrrev_b32_e32 v0, 16, v0
	v_add3_u32 v33, v33, v34, s81
	v_and_or_b32 v33, v33, s46, v0
	ds_read_b32 v0, v67 offset:528
	ds_read_b32 v34, v67 offset:660
	s_waitcnt lgkmcnt(1)
	v_bfe_u32 v35, v0, 16, 1
	v_add3_u32 v0, v0, v35, s81
	s_waitcnt lgkmcnt(0)
	v_bfe_u32 v35, v34, 16, 1
	v_lshrrev_b32_e32 v0, 16, v0
	v_add3_u32 v34, v34, v35, s81
	v_and_or_b32 v34, v34, s46, v0
	ds_read_b32 v0, v67 offset:792
	ds_read_b32 v35, v67 offset:924
	s_waitcnt lgkmcnt(1)
	v_bfe_u32 v36, v0, 16, 1
	v_add3_u32 v0, v0, v36, s81
	s_waitcnt lgkmcnt(0)
	v_bfe_u32 v36, v35, 16, 1
	v_lshrrev_b32_e32 v0, 16, v0
	v_add3_u32 v35, v35, v36, s81
	v_and_or_b32 v35, v35, s46, v0
	v_or_b32_e32 v0, s0, v66
	v_mul_u32_u24_e32 v0, 0x1600, v0
	v_lshl_add_u64 v[36:37], v[30:31], 0, v[0:1]
	flat_store_dwordx4 v[36:37], v[32:35]
	ds_read_b32 v0, v67 offset:32
	ds_read_b32 v32, v67 offset:164
	s_waitcnt lgkmcnt(0)
	v_bfe_u32 v33, v0, 16, 1
	v_add3_u32 v0, v0, v33, s81
	v_bfe_u32 v33, v32, 16, 1
	v_lshrrev_b32_e32 v0, 16, v0
	v_add3_u32 v32, v32, v33, s81
	v_and_or_b32 v32, v32, s46, v0
	ds_read_b32 v0, v67 offset:296
	ds_read_b32 v33, v67 offset:428
	s_waitcnt lgkmcnt(0)
	v_bfe_u32 v34, v0, 16, 1
	v_add3_u32 v0, v0, v34, s81
	v_bfe_u32 v34, v33, 16, 1
	v_lshrrev_b32_e32 v0, 16, v0
	v_add3_u32 v33, v33, v34, s81
	v_and_or_b32 v33, v33, s46, v0
	ds_read_b32 v0, v67 offset:560
	ds_read_b32 v34, v67 offset:692
	s_waitcnt lgkmcnt(0)
	v_bfe_u32 v35, v0, 16, 1
	v_add3_u32 v0, v0, v35, s81
	v_bfe_u32 v35, v34, 16, 1
	v_lshrrev_b32_e32 v0, 16, v0
	v_add3_u32 v34, v34, v35, s81
	v_and_or_b32 v34, v34, s46, v0
	ds_read_b32 v0, v67 offset:824
	ds_read_b32 v35, v67 offset:956
	s_waitcnt lgkmcnt(0)
	v_bfe_u32 v36, v0, 16, 1
	v_add3_u32 v0, v0, v36, s81
	v_bfe_u32 v36, v35, 16, 1
	v_lshrrev_b32_e32 v0, 16, v0
	v_add3_u32 v35, v35, v36, s81
	v_and_or_b32 v35, v35, s46, v0
	v_or_b32_e32 v0, s0, v68
	v_mul_u32_u24_e32 v0, 0x1600, v0
	v_lshl_add_u64 v[36:37], v[30:31], 0, v[0:1]
	flat_store_dwordx4 v[36:37], v[32:35]
	ds_read_b32 v0, v67 offset:64
	ds_read_b32 v32, v67 offset:196
	s_waitcnt lgkmcnt(0)
	v_bfe_u32 v33, v0, 16, 1
	v_add3_u32 v0, v0, v33, s81
	v_bfe_u32 v33, v32, 16, 1
	v_lshrrev_b32_e32 v0, 16, v0
	v_add3_u32 v32, v32, v33, s81
	v_and_or_b32 v32, v32, s46, v0
	ds_read_b32 v0, v67 offset:328
	ds_read_b32 v33, v67 offset:460
	s_waitcnt lgkmcnt(0)
	v_bfe_u32 v34, v0, 16, 1
	v_add3_u32 v0, v0, v34, s81
	v_bfe_u32 v34, v33, 16, 1
	v_lshrrev_b32_e32 v0, 16, v0
	v_add3_u32 v33, v33, v34, s81
	v_and_or_b32 v33, v33, s46, v0
	ds_read_b32 v0, v67 offset:592
	ds_read_b32 v34, v67 offset:724
	s_waitcnt lgkmcnt(0)
	v_bfe_u32 v35, v0, 16, 1
	v_add3_u32 v0, v0, v35, s81
	v_bfe_u32 v35, v34, 16, 1
	v_lshrrev_b32_e32 v0, 16, v0
	v_add3_u32 v34, v34, v35, s81
	v_and_or_b32 v34, v34, s46, v0
	ds_read_b32 v0, v67 offset:856
	ds_read_b32 v35, v67 offset:988
	s_waitcnt lgkmcnt(0)
	v_bfe_u32 v36, v0, 16, 1
	v_add3_u32 v0, v0, v36, s81
	v_bfe_u32 v36, v35, 16, 1
	v_lshrrev_b32_e32 v0, 16, v0
	v_add3_u32 v35, v35, v36, s81
	v_and_or_b32 v35, v35, s46, v0
	v_or_b32_e32 v0, s0, v69
	v_mul_u32_u24_e32 v0, 0x1600, v0
	v_lshl_add_u64 v[36:37], v[30:31], 0, v[0:1]
	flat_store_dwordx4 v[36:37], v[32:35]
	ds_read_b32 v0, v67 offset:96
	ds_read_b32 v32, v67 offset:228
	s_waitcnt lgkmcnt(0)
	v_bfe_u32 v33, v0, 16, 1
	v_add3_u32 v0, v0, v33, s81
	v_bfe_u32 v33, v32, 16, 1
	v_lshrrev_b32_e32 v0, 16, v0
	v_add3_u32 v32, v32, v33, s81
	v_and_or_b32 v32, v32, s46, v0
	ds_read_b32 v0, v67 offset:360
	ds_read_b32 v33, v67 offset:492
	s_waitcnt lgkmcnt(0)
	v_bfe_u32 v34, v0, 16, 1
	v_add3_u32 v0, v0, v34, s81
	v_bfe_u32 v34, v33, 16, 1
	v_lshrrev_b32_e32 v0, 16, v0
	v_add3_u32 v33, v33, v34, s81
	v_and_or_b32 v33, v33, s46, v0
	ds_read_b32 v0, v67 offset:624
	ds_read_b32 v34, v67 offset:756
	s_waitcnt lgkmcnt(0)
	v_bfe_u32 v35, v0, 16, 1
	v_add3_u32 v0, v0, v35, s81
	v_bfe_u32 v35, v34, 16, 1
	v_lshrrev_b32_e32 v0, 16, v0
	v_add3_u32 v34, v34, v35, s81
	v_and_or_b32 v34, v34, s46, v0
	ds_read_b32 v0, v67 offset:888
	ds_read_b32 v35, v67 offset:1020
	s_waitcnt lgkmcnt(0)
	v_bfe_u32 v36, v0, 16, 1
	v_add3_u32 v0, v0, v36, s81
	v_bfe_u32 v36, v35, 16, 1
	v_lshrrev_b32_e32 v0, 16, v0
	v_add3_u32 v35, v35, v36, s81
	v_and_or_b32 v35, v35, s46, v0
	v_or_b32_e32 v0, s0, v70
	v_mul_u32_u24_e32 v0, 0x1600, v0
	v_lshl_add_u64 v[30:31], v[30:31], 0, v[0:1]
	flat_store_dwordx4 v[30:31], v[32:35]
	s_waitcnt lgkmcnt(0)
	s_mov_b64 s[0:1], 0

; template <bool MAPPED>
; __device__ __forceinline__ void transpose_item(const float* W, int K, int Nsrc, bf16_t* WT, const float* gk, LAS float* scr, int item, int nblk, int lane) {
;     ...
; #pragma unroll 8
;     for (int i = 0; i < 32; ++i) { const int kk = 2 * i + (lane >> 5); float v = (sc >= 0) ? W[(size_t)(k0 + kk) * Nsrc + sc] : 0.f; if (gk) v *= gk[k0 + kk]; scr[kk * 33 + (lane & 31)] = v; }
.LBB0_809:
	s_add_u32 s12, s12, 64
	s_addc_u32 s13, s13, 0
	s_mov_b64 s[4:5], 0x58000
	v_add_u32_e32 v0, 0x840, v0
	s_cmpk_lg_i32 s12, 0x100
	v_lshl_add_u64 v[34:35], v[34:35], 0, s[4:5]
	s_cbranch_scc0 .LBB0_826
.LBB0_810:
	v_cndmask_b32_e64 v80, 0, 1, s[6:7]
	v_cmp_ne_u32_e64 s[10:11], 1, v80
	v_lshl_add_u64 v[80:81], v[34:35], 0, v[60:61]
	global_load_dword v90, v[80:81], off
	v_lshl_add_u64 v[80:81], v[34:35], 0, v[58:59]
	global_load_dword v91, v[80:81], off
	v_lshl_add_u64 v[80:81], v[34:35], 0, v[54:55]
	global_load_dword v92, v[80:81], off
	v_lshl_add_u64 v[80:81], v[34:35], 0, v[50:51]
	global_load_dword v93, v[80:81], off
	v_lshl_add_u64 v[80:81], v[34:35], 0, v[46:47]
	global_load_dword v94, v[80:81], off
	v_lshl_add_u64 v[80:81], v[34:35], 0, v[42:43]
	global_load_dword v95, v[80:81], off
	v_lshl_add_u64 v[80:81], v[34:35], 0, v[38:39]
	global_load_dword v96, v[80:81], off
	v_lshl_add_u64 v[80:81], v[34:35], 0, v[32:33]
	global_load_dword v97, v[80:81], off
	s_andn2_b64 vcc, exec, s[6:7]
	s_cbranch_vccnz .Ltpn_2
	v_lshl_add_u64 v[80:81], v[62:63], 0, s[12:13]
	global_load_dword v98, v[80:81], off
	v_lshl_add_u64 v[80:81], v[56:57], 0, s[12:13]
	global_load_dword v99, v[80:81], off
	v_lshl_add_u64 v[80:81], v[52:53], 0, s[12:13]
	global_load_dword v100, v[80:81], off
	v_lshl_add_u64 v[80:81], v[48:49], 0, s[12:13]
	global_load_dword v101, v[80:81], off
	v_lshl_add_u64 v[80:81], v[44:45], 0, s[12:13]
	global_load_dword v102, v[80:81], off
	v_lshl_add_u64 v[80:81], v[40:41], 0, s[12:13]
	global_load_dword v103, v[80:81], off
	v_lshl_add_u64 v[80:81], v[36:37], 0, s[12:13]
	global_load_dword v104, v[80:81], off
	v_lshl_add_u64 v[80:81], v[30:31], 0, s[12:13]
	global_load_dword v105, v[80:81], off
	s_waitcnt vmcnt(7)
	v_mul_f32_e32 v90, v90, v98
	ds_write_b32 v0, v90
	s_waitcnt vmcnt(6)
	v_mul_f32_e32 v91, v91, v99
	ds_write_b32 v0, v91 offset:264
	s_waitcnt vmcnt(5)
	v_mul_f32_e32 v92, v92, v100
	ds_write_b32 v0, v92 offset:528
	s_waitcnt vmcnt(4)
	v_mul_f32_e32 v93, v93, v101
	ds_write_b32 v0, v93 offset:792
	s_waitcnt vmcnt(3)
	v_mul_f32_e32 v94, v94, v102
	ds_write_b32 v0, v94 offset:1056
	s_waitcnt vmcnt(2)
	v_mul_f32_e32 v95, v95, v103
	ds_write_b32 v0, v95 offset:1320
	s_waitcnt vmcnt(1)
	v_mul_f32_e32 v96, v96, v104
	ds_write_b32 v0, v96 offset:1584
	s_waitcnt vmcnt(0)
	v_mul_f32_e32 v97, v97, v105
	ds_write_b32 v0, v97 offset:1848
	s_branch .LBB0_809
.Ltpn_2:
	s_waitcnt vmcnt(7)
	ds_write_b32 v0, v90
	s_waitcnt vmcnt(6)
	ds_write_b32 v0, v91 offset:264
	s_waitcnt vmcnt(5)
	ds_write_b32 v0, v92 offset:528
	s_waitcnt vmcnt(4)
	ds_write_b32 v0, v93 offset:792
	s_waitcnt vmcnt(3)
	ds_write_b32 v0, v94 offset:1056
	s_waitcnt vmcnt(2)
	ds_write_b32 v0, v95 offset:1320
	s_waitcnt vmcnt(1)
	ds_write_b32 v0, v96 offset:1584
	s_waitcnt vmcnt(0)
	ds_write_b32 v0, v97 offset:1848
	s_branch .LBB0_809

; #define LAS __attribute__((address_space(3)))
; __device__ __forceinline__ unsigned pk2(float lo, float hi) { return f2bf(lo) | (f2bf(hi) << 16); }
; template <bool MAPPED>
; __device__ __forceinline__ void transpose_item(const float* W, int K, int Nsrc, bf16_t* WT, const float* gk, LAS float* scr, int item, int nblk, int lane) {
;     ...
; #pragma unroll 8
;     for (int i = 0; i < 32; ++i) { const int kk = 2 * i + (lane >> 5); float v = (sc >= 0) ? W[(size_t)(k0 + kk) * Nsrc + sc] : 0.f; if (gk) v *= gk[k0 + kk]; scr[kk * 33 + (lane & 31)] = v; }
;     asm volatile("s_waitcnt lgkmcnt(0)" ::: "memory");
;     const int c = lane & 7;
; #pragma unroll
;     for (int j = 0; j < 4; ++j) { const int n = (lane >> 3) + 8 * j; const LAS float* s = scr + (8 * c) * 33 + n;
;         u32x4 o; o.x = pk2(s[0 * 33], s[1 * 33]); o.y = pk2(s[2 * 33], s[3 * 33]); o.z = pk2(s[4 * 33], s[5 * 33]); o.w = pk2(s[6 * 33], s[7 * 33]);
;         *(u32x4*)(WT + (size_t)(j0 + n) * K + k0 + 8 * c) = o; }
;     asm volatile("s_waitcnt lgkmcnt(0)" ::: "memory");
.LBB0_830:
	v_lshl_add_u64 v[46:47], v[44:45], 0, s[0:1]
	global_load_dword v90, v[46:47], off
	v_lshl_add_u64 v[46:47], v[42:43], 0, s[0:1]
	global_load_dword v91, v[46:47], off
	v_lshl_add_u64 v[46:47], v[40:41], 0, s[0:1]
	global_load_dword v92, v[46:47], off
	v_lshl_add_u64 v[46:47], v[38:39], 0, s[0:1]
	global_load_dword v93, v[46:47], off
	v_lshl_add_u64 v[46:47], v[36:37], 0, s[0:1]
	global_load_dword v94, v[46:47], off
	v_lshl_add_u64 v[46:47], v[34:35], 0, s[0:1]
	global_load_dword v95, v[46:47], off
	v_lshl_add_u64 v[46:47], v[32:33], 0, s[0:1]
	global_load_dword v96, v[46:47], off
	v_lshl_add_u64 v[46:47], v[30:31], 0, s[0:1]
	s_add_u32 s0, s0, 0x10000
	s_addc_u32 s1, s1, 0
	s_cmp_lg_u32 s0, 0x40000
	global_load_dword v97, v[46:47], off
	s_waitcnt vmcnt(7)
	ds_write_b32 v0, v90
	s_waitcnt vmcnt(6)
	ds_write_b32 v0, v91 offset:264
	s_waitcnt vmcnt(5)
	ds_write_b32 v0, v92 offset:528
	s_waitcnt vmcnt(4)
	ds_write_b32 v0, v93 offset:792
	s_waitcnt vmcnt(3)
	ds_write_b32 v0, v94 offset:1056
	s_waitcnt vmcnt(2)
	ds_write_b32 v0, v95 offset:1320
	s_waitcnt vmcnt(1)
	ds_write_b32 v0, v96 offset:1584
	s_waitcnt vmcnt(0)
	ds_write_b32 v0, v97 offset:1848
	v_add_u32_e32 v0, 0x840, v0
	s_cbranch_scc1 .LBB0_830
	s_waitcnt lgkmcnt(0)
	ds_read_b32 v0, v67
	ds_read_b32 v32, v67 offset:132
	s_lshl_b32 s0, s19, 1
	s_add_i32 s0, s0, 0x1c300
	s_and_b32 s1, s0, 0x1ffc0
	s_waitcnt lgkmcnt(1)
	v_bfe_u32 v33, v0, 16, 1
	v_add3_u32 v0, v0, v33, s81
	s_waitcnt lgkmcnt(0)
	v_bfe_u32 v33, v32, 16, 1
	v_lshrrev_b32_e32 v0, 16, v0
	v_add3_u32 v32, v32, v33, s81
	v_and_or_b32 v32, v32, s46, v0
	ds_read_b32 v0, v67 offset:264
	ds_read_b32 v33, v67 offset:396
	s_lshl_b32 s0, s19, 5
	s_and_b32 s0, s0, 0x3e0
	s_lshl_b32 s62, s1, 1
	s_waitcnt lgkmcnt(1)
	v_bfe_u32 v34, v0, 16, 1
	v_add3_u32 v0, v0, v34, s81
	s_waitcnt lgkmcnt(0)
	v_bfe_u32 v34, v33, 16, 1
	v_lshrrev_b32_e32 v0, 16, v0
	v_add3_u32 v33, v33, v34, s81
	v_and_or_b32 v33, v33, s46, v0
	ds_read_b32 v0, v67 offset:528
	ds_read_b32 v34, v67 offset:660
	v_lshl_add_u64 v[30:31], v[12:13], 0, s[62:63]
	s_waitcnt lgkmcnt(1)
	v_bfe_u32 v35, v0, 16, 1
	v_add3_u32 v0, v0, v35, s81
	s_waitcnt lgkmcnt(0)
	v_bfe_u32 v35, v34, 16, 1
	v_lshrrev_b32_e32 v0, 16, v0
	v_add3_u32 v34, v34, v35, s81
	v_and_or_b32 v34, v34, s46, v0
	ds_read_b32 v0, v67 offset:792
	ds_read_b32 v35, v67 offset:924
	s_waitcnt lgkmcnt(1)
	v_bfe_u32 v36, v0, 16, 1
	v_add3_u32 v0, v0, v36, s81
	s_waitcnt lgkmcnt(0)
	v_bfe_u32 v36, v35, 16, 1
	v_lshrrev_b32_e32 v0, 16, v0
	v_add3_u32 v35, v35, v36, s81
	v_and_or_b32 v35, v35, s46, v0
	v_or_b32_e32 v0, s0, v66
	v_lshlrev_b32_e32 v0, 11, v0
	v_lshl_add_u64 v[36:37], v[30:31], 0, v[0:1]
	flat_store_dwordx4 v[36:37], v[32:35]
	ds_read_b32 v0, v67 offset:32
	ds_read_b32 v32, v67 offset:164
	s_waitcnt lgkmcnt(0)
	v_bfe_u32 v33, v0, 16, 1
	v_add3_u32 v0, v0, v33, s81
	v_bfe_u32 v33, v32, 16, 1
	v_lshrrev_b32_e32 v0, 16, v0
	v_add3_u32 v32, v32, v33, s81
	v_and_or_b32 v32, v32, s46, v0
	ds_read_b32 v0, v67 offset:296
	ds_read_b32 v33, v67 offset:428
	s_waitcnt lgkmcnt(0)
	v_bfe_u32 v34, v0, 16, 1
	v_add3_u32 v0, v0, v34, s81
	v_bfe_u32 v34, v33, 16, 1
	v_lshrrev_b32_e32 v0, 16, v0
	v_add3_u32 v33, v33, v34, s81
	v_and_or_b32 v33, v33, s46, v0
	ds_read_b32 v0, v67 offset:560
	ds_read_b32 v34, v67 offset:692
	s_waitcnt lgkmcnt(0)
	v_bfe_u32 v35, v0, 16, 1
	v_add3_u32 v0, v0, v35, s81
	v_bfe_u32 v35, v34, 16, 1
	v_lshrrev_b32_e32 v0, 16, v0
	v_add3_u32 v34, v34, v35, s81
	v_and_or_b32 v34, v34, s46, v0
	ds_read_b32 v0, v67 offset:824
	ds_read_b32 v35, v67 offset:956
	s_waitcnt lgkmcnt(0)
	v_bfe_u32 v36, v0, 16, 1
	v_add3_u32 v0, v0, v36, s81
	v_bfe_u32 v36, v35, 16, 1
	v_lshrrev_b32_e32 v0, 16, v0
	v_add3_u32 v35, v35, v36, s81
	v_and_or_b32 v35, v35, s46, v0
	v_or_b32_e32 v0, s0, v68
	v_lshlrev_b32_e32 v0, 11, v0
	v_lshl_add_u64 v[36:37], v[30:31], 0, v[0:1]
	flat_store_dwordx4 v[36:37], v[32:35]
	ds_read_b32 v0, v67 offset:64
	ds_read_b32 v32, v67 offset:196
	s_waitcnt lgkmcnt(0)
	v_bfe_u32 v33, v0, 16, 1
	v_add3_u32 v0, v0, v33, s81
	v_bfe_u32 v33, v32, 16, 1
	v_lshrrev_b32_e32 v0, 16, v0
	v_add3_u32 v32, v32, v33, s81
	v_and_or_b32 v32, v32, s46, v0
	ds_read_b32 v0, v67 offset:328
	ds_read_b32 v33, v67 offset:460
	s_waitcnt lgkmcnt(0)
	v_bfe_u32 v34, v0, 16, 1
	v_add3_u32 v0, v0, v34, s81
	v_bfe_u32 v34, v33, 16, 1
	v_lshrrev_b32_e32 v0, 16, v0
	v_add3_u32 v33, v33, v34, s81
	v_and_or_b32 v33, v33, s46, v0
	ds_read_b32 v0, v67 offset:592
	ds_read_b32 v34, v67 offset:724
	s_waitcnt lgkmcnt(0)
	v_bfe_u32 v35, v0, 16, 1
	v_add3_u32 v0, v0, v35, s81
	v_bfe_u32 v35, v34, 16, 1
	v_lshrrev_b32_e32 v0, 16, v0
	v_add3_u32 v34, v34, v35, s81
	v_and_or_b32 v34, v34, s46, v0
	ds_read_b32 v0, v67 offset:856
	ds_read_b32 v35, v67 offset:988
	s_waitcnt lgkmcnt(0)
	v_bfe_u32 v36, v0, 16, 1
	v_add3_u32 v0, v0, v36, s81
	v_bfe_u32 v36, v35, 16, 1
	v_lshrrev_b32_e32 v0, 16, v0
	v_add3_u32 v35, v35, v36, s81
	v_and_or_b32 v35, v35, s46, v0
	v_or_b32_e32 v0, s0, v69
	v_lshlrev_b32_e32 v0, 11, v0
	v_lshl_add_u64 v[36:37], v[30:31], 0, v[0:1]
	flat_store_dwordx4 v[36:37], v[32:35]
	ds_read_b32 v0, v67 offset:96
	ds_read_b32 v32, v67 offset:228
	s_waitcnt lgkmcnt(0)
	v_bfe_u32 v33, v0, 16, 1
	v_add3_u32 v0, v0, v33, s81
	v_bfe_u32 v33, v32, 16, 1
	v_lshrrev_b32_e32 v0, 16, v0
	v_add3_u32 v32, v32, v33, s81
	v_and_or_b32 v32, v32, s46, v0
	ds_read_b32 v0, v67 offset:360
	ds_read_b32 v33, v67 offset:492
	s_waitcnt lgkmcnt(0)
	v_bfe_u32 v34, v0, 16, 1
	v_add3_u32 v0, v0, v34, s81
	v_bfe_u32 v34, v33, 16, 1
	v_lshrrev_b32_e32 v0, 16, v0
	v_add3_u32 v33, v33, v34, s81
	v_and_or_b32 v33, v33, s46, v0
	ds_read_b32 v0, v67 offset:624
	ds_read_b32 v34, v67 offset:756
	s_waitcnt lgkmcnt(0)
	v_bfe_u32 v35, v0, 16, 1
	v_add3_u32 v0, v0, v35, s81
	v_bfe_u32 v35, v34, 16, 1
	v_lshrrev_b32_e32 v0, 16, v0
	v_add3_u32 v34, v34, v35, s81
	v_and_or_b32 v34, v34, s46, v0
	ds_read_b32 v0, v67 offset:888
	ds_read_b32 v35, v67 offset:1020
	s_waitcnt lgkmcnt(0)
	v_bfe_u32 v36, v0, 16, 1
	v_add3_u32 v0, v0, v36, s81
	v_bfe_u32 v36, v35, 16, 1
	v_lshrrev_b32_e32 v0, 16, v0
	v_add3_u32 v35, v35, v36, s81
	v_and_or_b32 v35, v35, s46, v0
	v_or_b32_e32 v0, s0, v70
	v_lshlrev_b32_e32 v0, 11, v0
	v_lshl_add_u64 v[30:31], v[30:31], 0, v[0:1]
	flat_store_dwordx4 v[30:31], v[32:35]
	s_waitcnt lgkmcnt(0)

; #define LAS __attribute__((address_space(3)))
; __device__ __forceinline__ unsigned pk2(float lo, float hi) { return f2bf(lo) | (f2bf(hi) << 16); }
; template <bool MAPPED>
; __device__ __forceinline__ void transpose_item(const float* W, int K, int Nsrc, bf16_t* WT, const float* gk, LAS float* scr, int item, int nblk, int lane) {
;     ...
; #pragma unroll 8
;     for (int i = 0; i < 32; ++i) { const int kk = 2 * i + (lane >> 5); float v = (sc >= 0) ? W[(size_t)(k0 + kk) * Nsrc + sc] : 0.f; if (gk) v *= gk[k0 + kk]; scr[kk * 33 + (lane & 31)] = v; }
;     asm volatile("s_waitcnt lgkmcnt(0)" ::: "memory");
;     const int c = lane & 7;
; #pragma unroll
;     for (int j = 0; j < 4; ++j) { const int n = (lane >> 3) + 8 * j; const LAS float* s = scr + (8 * c) * 33 + n;
;         u32x4 o; o.x = pk2(s[0 * 33], s[1 * 33]); o.y = pk2(s[2 * 33], s[3 * 33]); o.z = pk2(s[4 * 33], s[5 * 33]); o.w = pk2(s[6 * 33], s[7 * 33]);
;         *(u32x4*)(WT + (size_t)(j0 + n) * K + k0 + 8 * c) = o; }
;     asm volatile("s_waitcnt lgkmcnt(0)" ::: "memory");
.LBB0_835:
	v_lshl_add_u64 v[46:47], v[44:45], 0, s[0:1]
	global_load_dword v90, v[46:47], off
	v_lshl_add_u64 v[46:47], v[42:43], 0, s[0:1]
	global_load_dword v91, v[46:47], off
	v_lshl_add_u64 v[46:47], v[40:41], 0, s[0:1]
	global_load_dword v92, v[46:47], off
	v_lshl_add_u64 v[46:47], v[38:39], 0, s[0:1]
	global_load_dword v93, v[46:47], off
	v_lshl_add_u64 v[46:47], v[36:37], 0, s[0:1]
	global_load_dword v94, v[46:47], off
	v_lshl_add_u64 v[46:47], v[34:35], 0, s[0:1]
	global_load_dword v95, v[46:47], off
	v_lshl_add_u64 v[46:47], v[32:33], 0, s[0:1]
	global_load_dword v96, v[46:47], off
	v_lshl_add_u64 v[46:47], v[30:31], 0, s[0:1]
	s_add_u32 s0, s0, 0x10000
	s_addc_u32 s1, s1, 0
	s_cmp_lg_u32 s0, 0x40000
	global_load_dword v97, v[46:47], off
	s_waitcnt vmcnt(7)
	ds_write_b32 v0, v90
	s_waitcnt vmcnt(6)
	ds_write_b32 v0, v91 offset:264
	s_waitcnt vmcnt(5)
	ds_write_b32 v0, v92 offset:528
	s_waitcnt vmcnt(4)
	ds_write_b32 v0, v93 offset:792
	s_waitcnt vmcnt(3)
	ds_write_b32 v0, v94 offset:1056
	s_waitcnt vmcnt(2)
	ds_write_b32 v0, v95 offset:1320
	s_waitcnt vmcnt(1)
	ds_write_b32 v0, v96 offset:1584
	s_waitcnt vmcnt(0)
	ds_write_b32 v0, v97 offset:1848
	v_add_u32_e32 v0, 0x840, v0
	s_cbranch_scc1 .LBB0_835
	s_add_i32 s1, s19, 0xffffe780
	s_lshr_b32 s62, s1, 9
	s_lshl_b32 s0, s19, 5
	s_and_b32 s0, s0, 0x3e0
	s_lshl_b64 s[4:5], s[62:63], 21
	s_add_u32 s4, s20, s4
	s_addc_u32 s5, s21, s5
	s_lshl_b32 s1, s1, 2
	s_and_b32 s1, s1, 0x780
	s_add_u32 s4, s4, s1
	s_waitcnt lgkmcnt(0)
	s_addc_u32 s5, s5, 0
	v_mov_b32_e32 v29, v1
	v_lshl_add_u64 v[30:31], s[4:5], 0, v[28:29]
	ds_read_b32 v0, v67
	ds_read_b32 v29, v67 offset:132
	s_waitcnt lgkmcnt(1)
	v_bfe_u32 v32, v0, 16, 1
	v_add3_u32 v0, v0, v32, s81
	s_waitcnt lgkmcnt(0)
	v_bfe_u32 v32, v29, 16, 1
	v_lshrrev_b32_e32 v0, 16, v0
	v_add3_u32 v29, v29, v32, s81
	v_and_or_b32 v32, v29, s46, v0
	ds_read_b32 v0, v67 offset:264
	ds_read_b32 v29, v67 offset:396
	s_waitcnt lgkmcnt(1)
	v_bfe_u32 v33, v0, 16, 1
	v_add3_u32 v0, v0, v33, s81
	s_waitcnt lgkmcnt(0)
	v_bfe_u32 v33, v29, 16, 1
	v_lshrrev_b32_e32 v0, 16, v0
	v_add3_u32 v29, v29, v33, s81
	v_and_or_b32 v33, v29, s46, v0
	ds_read_b32 v0, v67 offset:528
	ds_read_b32 v29, v67 offset:660
	s_waitcnt lgkmcnt(1)
	v_bfe_u32 v34, v0, 16, 1
	v_add3_u32 v0, v0, v34, s81
	s_waitcnt lgkmcnt(0)
	v_bfe_u32 v34, v29, 16, 1
	v_lshrrev_b32_e32 v0, 16, v0
	v_add3_u32 v29, v29, v34, s81
	v_and_or_b32 v34, v29, s46, v0
	ds_read_b32 v0, v67 offset:792
	ds_read_b32 v29, v67 offset:924
	s_waitcnt lgkmcnt(1)
	v_bfe_u32 v35, v0, 16, 1
	v_add3_u32 v0, v0, v35, s81
	s_waitcnt lgkmcnt(0)
	v_bfe_u32 v35, v29, 16, 1
	v_lshrrev_b32_e32 v0, 16, v0
	v_add3_u32 v29, v29, v35, s81
	v_and_or_b32 v35, v29, s46, v0
	v_or_b32_e32 v0, s0, v66
	v_lshlrev_b32_e32 v0, 11, v0
	v_lshl_add_u64 v[36:37], v[30:31], 0, v[0:1]
	flat_store_dwordx4 v[36:37], v[32:35]
	ds_read_b32 v0, v67 offset:32
	ds_read_b32 v29, v67 offset:164
	s_waitcnt lgkmcnt(0)
	v_bfe_u32 v32, v0, 16, 1
	v_add3_u32 v0, v0, v32, s81
	v_bfe_u32 v32, v29, 16, 1
	v_lshrrev_b32_e32 v0, 16, v0
	v_add3_u32 v29, v29, v32, s81
	v_and_or_b32 v32, v29, s46, v0
	ds_read_b32 v0, v67 offset:296
	ds_read_b32 v29, v67 offset:428
	s_waitcnt lgkmcnt(0)
	v_bfe_u32 v33, v0, 16, 1
	v_add3_u32 v0, v0, v33, s81
	v_bfe_u32 v33, v29, 16, 1
	v_lshrrev_b32_e32 v0, 16, v0
	v_add3_u32 v29, v29, v33, s81
	v_and_or_b32 v33, v29, s46, v0
	ds_read_b32 v0, v67 offset:560
	ds_read_b32 v29, v67 offset:692
	s_waitcnt lgkmcnt(0)
	v_bfe_u32 v34, v0, 16, 1
	v_add3_u32 v0, v0, v34, s81
	v_bfe_u32 v34, v29, 16, 1
	v_lshrrev_b32_e32 v0, 16, v0
	v_add3_u32 v29, v29, v34, s81
	v_and_or_b32 v34, v29, s46, v0
	ds_read_b32 v0, v67 offset:824
	ds_read_b32 v29, v67 offset:956
	s_waitcnt lgkmcnt(0)
	v_bfe_u32 v35, v0, 16, 1
	v_add3_u32 v0, v0, v35, s81
	v_bfe_u32 v35, v29, 16, 1
	v_lshrrev_b32_e32 v0, 16, v0
	v_add3_u32 v29, v29, v35, s81
	v_and_or_b32 v35, v29, s46, v0
	v_or_b32_e32 v0, s0, v68
	v_lshlrev_b32_e32 v0, 11, v0
	v_lshl_add_u64 v[36:37], v[30:31], 0, v[0:1]
	flat_store_dwordx4 v[36:37], v[32:35]
	ds_read_b32 v0, v67 offset:64
	ds_read_b32 v29, v67 offset:196
	s_waitcnt lgkmcnt(0)
	v_bfe_u32 v32, v0, 16, 1
	v_add3_u32 v0, v0, v32, s81
	v_bfe_u32 v32, v29, 16, 1
	v_lshrrev_b32_e32 v0, 16, v0
	v_add3_u32 v29, v29, v32, s81
	v_and_or_b32 v32, v29, s46, v0
	ds_read_b32 v0, v67 offset:328
	ds_read_b32 v29, v67 offset:460
	s_waitcnt lgkmcnt(0)
	v_bfe_u32 v33, v0, 16, 1
	v_add3_u32 v0, v0, v33, s81
	v_bfe_u32 v33, v29, 16, 1
	v_lshrrev_b32_e32 v0, 16, v0
	v_add3_u32 v29, v29, v33, s81
	v_and_or_b32 v33, v29, s46, v0
	ds_read_b32 v0, v67 offset:592
	ds_read_b32 v29, v67 offset:724
	s_waitcnt lgkmcnt(0)
	v_bfe_u32 v34, v0, 16, 1
	v_add3_u32 v0, v0, v34, s81
	v_bfe_u32 v34, v29, 16, 1
	v_lshrrev_b32_e32 v0, 16, v0
	v_add3_u32 v29, v29, v34, s81
	v_and_or_b32 v34, v29, s46, v0
	ds_read_b32 v0, v67 offset:856
	ds_read_b32 v29, v67 offset:988
	s_waitcnt lgkmcnt(0)
	v_bfe_u32 v35, v0, 16, 1
	v_add3_u32 v0, v0, v35, s81
	v_bfe_u32 v35, v29, 16, 1
	v_lshrrev_b32_e32 v0, 16, v0
	v_add3_u32 v29, v29, v35, s81
	v_and_or_b32 v35, v29, s46, v0
	v_or_b32_e32 v0, s0, v69
	v_lshlrev_b32_e32 v0, 11, v0
	v_lshl_add_u64 v[36:37], v[30:31], 0, v[0:1]
	flat_store_dwordx4 v[36:37], v[32:35]
	ds_read_b32 v0, v67 offset:96
	ds_read_b32 v29, v67 offset:228
	s_waitcnt lgkmcnt(0)
	v_bfe_u32 v32, v0, 16, 1
	v_add3_u32 v0, v0, v32, s81
	v_bfe_u32 v32, v29, 16, 1
	v_lshrrev_b32_e32 v0, 16, v0
	v_add3_u32 v29, v29, v32, s81
	v_and_or_b32 v32, v29, s46, v0
	ds_read_b32 v0, v67 offset:360
	ds_read_b32 v29, v67 offset:492
	s_waitcnt lgkmcnt(0)
	v_bfe_u32 v33, v0, 16, 1
	v_add3_u32 v0, v0, v33, s81
	v_bfe_u32 v33, v29, 16, 1
	v_lshrrev_b32_e32 v0, 16, v0
	v_add3_u32 v29, v29, v33, s81
	v_and_or_b32 v33, v29, s46, v0
	ds_read_b32 v0, v67 offset:624
	ds_read_b32 v29, v67 offset:756
	s_waitcnt lgkmcnt(0)
	v_bfe_u32 v34, v0, 16, 1
	v_add3_u32 v0, v0, v34, s81
	v_bfe_u32 v34, v29, 16, 1
	v_lshrrev_b32_e32 v0, 16, v0
	v_add3_u32 v29, v29, v34, s81
	v_and_or_b32 v34, v29, s46, v0
	ds_read_b32 v0, v67 offset:888
	ds_read_b32 v29, v67 offset:1020
	s_waitcnt lgkmcnt(0)
	v_bfe_u32 v35, v0, 16, 1
	v_add3_u32 v0, v0, v35, s81
	v_bfe_u32 v35, v29, 16, 1
	v_lshrrev_b32_e32 v0, 16, v0
	v_add3_u32 v29, v29, v35, s81
	v_and_or_b32 v35, v29, s46, v0
	v_or_b32_e32 v0, s0, v70
	v_lshlrev_b32_e32 v0, 11, v0
	v_lshl_add_u64 v[30:31], v[30:31], 0, v[0:1]
	flat_store_dwordx4 v[30:31], v[32:35]
	s_waitcnt lgkmcnt(0)

; template <bool MAPPED>
; __device__ __forceinline__ void transpose_item(const float* W, int K, int Nsrc, bf16_t* WT, const float* gk, LAS float* scr, int item, int nblk, int lane) {
;     ...
;     const int sc = MAPPED ? in_map(j0 + (lane & 31)) : (j0 + (lane & 31));
; #pragma unroll 8
;     for (int i = 0; i < 32; ++i) { const int kk = 2 * i + (lane >> 5); float v = (sc >= 0) ? W[(size_t)(k0 + kk) * Nsrc + sc] : 0.f; if (gk) v *= gk[k0 + kk]; scr[kk * 33 + (lane & 31)] = v; }
.LBB0_850:
	s_add_u32 s16, s16, 64
	s_addc_u32 s17, s17, 0
	v_add_u32_e32 v0, 0x840, v0
	v_lshl_add_u64 v[34:35], v[34:35], 0, s[92:93]
	v_lshl_add_u64 v[38:39], v[38:39], 0, s[92:93]
	v_lshl_add_u64 v[42:43], v[42:43], 0, s[92:93]
	v_lshl_add_u64 v[46:47], v[46:47], 0, s[92:93]
	v_lshl_add_u64 v[50:51], v[50:51], 0, s[92:93]
	v_lshl_add_u64 v[54:55], v[54:55], 0, s[92:93]
	v_lshl_add_u64 v[58:59], v[58:59], 0, s[92:93]
	s_cmpk_lg_i32 s16, 0x100
	v_lshl_add_u64 v[62:63], v[62:63], 0, s[92:93]
	s_cbranch_scc0 .LBB0_798
.LBB0_851:
	v_cndmask_b32_e64 v79, 0, 1, s[8:9]
	v_cmp_ne_u32_e64 s[12:13], 1, v79
	v_mov_b32_e32 v90, 0
	v_mov_b32_e32 v91, 0
	v_mov_b32_e32 v92, 0
	v_mov_b32_e32 v93, 0
	v_mov_b32_e32 v94, 0
	v_mov_b32_e32 v95, 0
	v_mov_b32_e32 v96, 0
	v_mov_b32_e32 v97, 0
	s_and_saveexec_b64 s[0:1], s[10:11]
	s_cbranch_execz .Ltpx_1
	v_lshl_add_u64 v[80:81], v[62:63], 0, v[32:33]
	global_load_dword v90, v[80:81], off
	v_lshl_add_u64 v[80:81], v[58:59], 0, v[32:33]
	global_load_dword v91, v[80:81], off
	v_lshl_add_u64 v[80:81], v[54:55], 0, v[32:33]
	global_load_dword v92, v[80:81], off
	v_lshl_add_u64 v[80:81], v[50:51], 0, v[32:33]
	global_load_dword v93, v[80:81], off
	v_lshl_add_u64 v[80:81], v[46:47], 0, v[32:33]
	global_load_dword v94, v[80:81], off
	v_lshl_add_u64 v[80:81], v[42:43], 0, v[32:33]
	global_load_dword v95, v[80:81], off
	v_lshl_add_u64 v[80:81], v[38:39], 0, v[32:33]
	global_load_dword v96, v[80:81], off
	v_lshl_add_u64 v[80:81], v[34:35], 0, v[32:33]
	global_load_dword v97, v[80:81], off
.Ltpx_1:
	s_or_b64 exec, exec, s[0:1]
	s_andn2_b64 vcc, exec, s[8:9]
	s_cbranch_vccnz .Ltpn_1
	v_lshl_add_u64 v[80:81], v[60:61], 0, s[16:17]
	global_load_dword v98, v[80:81], off
	v_lshl_add_u64 v[80:81], v[56:57], 0, s[16:17]
	global_load_dword v99, v[80:81], off
	v_lshl_add_u64 v[80:81], v[52:53], 0, s[16:17]
	global_load_dword v100, v[80:81], off
	v_lshl_add_u64 v[80:81], v[48:49], 0, s[16:17]
	global_load_dword v101, v[80:81], off
	v_lshl_add_u64 v[80:81], v[44:45], 0, s[16:17]
	global_load_dword v102, v[80:81], off
	v_lshl_add_u64 v[80:81], v[40:41], 0, s[16:17]
	global_load_dword v103, v[80:81], off
	v_lshl_add_u64 v[80:81], v[36:37], 0, s[16:17]
	global_load_dword v104, v[80:81], off
	v_lshl_add_u64 v[80:81], v[30:31], 0, s[16:17]
	global_load_dword v105, v[80:81], off
	s_waitcnt vmcnt(7)
	v_mul_f32_e32 v90, v90, v98
	ds_write_b32 v0, v90
	s_waitcnt vmcnt(6)
	v_mul_f32_e32 v91, v91, v99
	ds_write_b32 v0, v91 offset:264
	s_waitcnt vmcnt(5)
	v_mul_f32_e32 v92, v92, v100
	ds_write_b32 v0, v92 offset:528
	s_waitcnt vmcnt(4)
	v_mul_f32_e32 v93, v93, v101
	ds_write_b32 v0, v93 offset:792
	s_waitcnt vmcnt(3)
	v_mul_f32_e32 v94, v94, v102
	ds_write_b32 v0, v94 offset:1056
	s_waitcnt vmcnt(2)
	v_mul_f32_e32 v95, v95, v103
	ds_write_b32 v0, v95 offset:1320
	s_waitcnt vmcnt(1)
	v_mul_f32_e32 v96, v96, v104
	ds_write_b32 v0, v96 offset:1584
	s_waitcnt vmcnt(0)
	v_mul_f32_e32 v97, v97, v105
	ds_write_b32 v0, v97 offset:1848
	s_branch .LBB0_850

; __device__ __forceinline__ unsigned pk2hw(float lo, float hi) { unsigned r; asm("s_nop 1\n\tv_cvt_pk_bf16_f32 %0, %1, %2" : "=v"(r) : "v"(lo), "v"(hi)); return r; }
;     __device__ __forceinline__ void operator()(const f32x4 (&acc)[2][2][4][2], const Unit& u, int wr, int wc, int fr, int fq) const {
;     ...
;         const int row0 = u.pm * 256 + wr * 64 + fr, col0 = u.pn * 256 + wc * 32 + 8 * fq;
; #pragma unroll
;         for (int ai = 0; ai < 2; ++ai)
; #pragma unroll
;             for (int m = 0; m < 4; ++m) { const int row = row0 + ai * 128 + m * 16; float sq = 0.f;
; #pragma unroll
;                 for (int bj = 0; bj < 2; ++bj) { const size_t off = (size_t)row * D + col0 + bj * 128;
;                     const f32x4 x0 = *(const f32x4*)(xin + off) + acc[ai][bj][m][0], x1 = *(const f32x4*)(xin + off + 4) + acc[ai][bj][m][1];
;                     *(f32x4*)(xout + off) = x0; *(f32x4*)(xout + off + 4) = x1;
;                     u32x4 w; w.x = pk2hw(x0[0], x0[1]); w.y = pk2hw(x0[2], x0[3]); w.z = pk2hw(x1[0], x1[1]); w.w = pk2hw(x1[2], x1[3]); *(u32x4*)(xb + off) = w;
;                     sq += ((x0[0] * x0[0] + x0[1] * x0[1]) + (x0[2] * x0[2] + x0[3] * x0[3])) + ((x1[0] * x1[0] + x1[1] * x1[1]) + (x1[2] * x1[2] + x1[3] * x1[3])); }
;                 sq += __shfl_xor(sq, 16); sq += __shfl_xor(sq, 32);
;                 if (fq == 0) ssn[(size_t)row * 16 + u.pn * 4 + wc] = sq; }
.LBB0_949:
	s_lshl_b32 s0, s30, 8
	v_mov_b32_e32 v145, v148
	v_mov_b32_e32 v142, v149
	s_add_i32 s0, s0, s49
	s_nop 0
	v_add_u32_e32 v144, s0, v142
	s_lshl_b32 s0, s28, 8
	s_or_b32 s0, s0, s52
	v_lshl_add_u32 v142, v145, 3, s0
	v_cmp_eq_u32_e32 vcc, 0, v145
	v_ashrrev_i32_e32 v145, 31, v144
	v_ashrrev_i32_e32 v143, 31, v142
	v_lshlrev_b64 v[166:167], 10, v[144:145]
	v_lshl_add_u64 v[166:167], v[166:167], 0, v[142:143]
	v_lshlrev_b64 v[176:177], 2, v[166:167]
	v_lshl_add_u64 v[178:179], v[136:137], 0, v[176:177]
	s_mov_b64 s[36:37], vcc
	s_mov_b32 s35, 0
	v_lshl_add_u64 v[176:177], s[12:13], 0, v[176:177]
	s_lshl_b32 s28, s28, 2
	s_ashr_i32 s29, s28, 31
	v_lshl_add_u64 v[166:167], v[166:167], 1, s[14:15]
	v_lshlrev_b64 v[248:249], 6, v[144:145]
	v_lshl_add_u64 v[248:249], s[16:17], 0, v[248:249]
	v_lshl_add_u64 v[248:249], s[28:29], 2, v[248:249]
	s_lshl_b32 s62, s48, 2
	v_lshl_add_u64 v[248:249], v[248:249], 0, s[62:63]
	s_movk_i32 s34, 0x2000
	v_lshl_add_u64 v[144:145], s[34:35], 0, v[248:249]
	v_xor_b32_e32 v235, 16, v225
	v_xor_b32_e32 v236, 32, v225
	v_lshlrev_b32_e32 v235, 2, v235
	v_lshlrev_b32_e32 v236, 2, v236
	s_mov_b32 s34, 0x0
	v_lshl_add_u64 v[242:243], s[34:35], 0, v[178:179]
	global_load_dwordx4 v[180:183], v[242:243], off
	global_load_dwordx4 v[184:187], v[242:243], off offset:16
	global_load_dwordx4 v[188:191], v[242:243], off offset:512
	global_load_dwordx4 v[192:195], v[242:243], off offset:528
	s_mov_b32 s34, 0x10000
	v_lshl_add_u64 v[242:243], s[34:35], 0, v[178:179]
	global_load_dwordx4 v[196:199], v[242:243], off
	global_load_dwordx4 v[200:203], v[242:243], off offset:16
	global_load_dwordx4 v[204:207], v[242:243], off offset:512
	global_load_dwordx4 v[208:211], v[242:243], off offset:528
	s_mov_b32 s34, 0x20000
	v_lshl_add_u64 v[242:243], s[34:35], 0, v[178:179]
	global_load_dwordx4 v[212:215], v[242:243], off
	global_load_dwordx4 v[216:219], v[242:243], off offset:16
	s_waitcnt vmcnt(8)
	v_pk_add_f32 v[126:127], v[126:127], v[180:181]
	v_pk_add_f32 v[128:129], v[128:129], v[182:183]
	v_pk_add_f32 v[122:123], v[122:123], v[184:185]
	v_pk_add_f32 v[124:125], v[124:125], v[186:187]
	s_mov_b32 s34, 0x0
	v_lshl_add_u64 v[244:245], s[34:35], 0, v[176:177]
	s_mov_b32 s34, 0x0
	v_lshl_add_u64 v[246:247], s[34:35], 0, v[166:167]
	global_store_dwordx4 v[244:245], v[126:129], off
	global_store_dwordx4 v[244:245], v[122:125], off offset:16
	v_cvt_pk_bf16_f32 v172, v126, v127
	v_cvt_pk_bf16_f32 v173, v128, v129
	v_cvt_pk_bf16_f32 v174, v122, v123
	v_cvt_pk_bf16_f32 v175, v124, v125
	v_mul_f32_e32 v238, v127, v127
	v_mul_f32_e32 v240, v123, v123
	v_fmac_f32_e32 v238, v126, v126
	v_mul_f32_e32 v239, v129, v129
	v_fmac_f32_e32 v240, v122, v122
	v_mul_f32_e32 v241, v125, v125
	v_fmac_f32_e32 v239, v128, v128
	v_fmac_f32_e32 v241, v124, v124
	global_store_dwordx4 v[246:247], v[172:175], off
	v_add_f32_e32 v238, v238, v239
	v_add_f32_e32 v240, v240, v241
	v_add_f32_e32 v237, v238, v240
	global_load_dwordx4 v[126:129], v[242:243], off offset:512
	global_load_dwordx4 v[122:125], v[242:243], off offset:528
	s_waitcnt vmcnt(11)
	v_pk_add_f32 v[118:119], v[118:119], v[188:189]
	v_pk_add_f32 v[120:121], v[120:121], v[190:191]
	v_pk_add_f32 v[114:115], v[114:115], v[192:193]
	v_pk_add_f32 v[116:117], v[116:117], v[194:195]
	global_store_dwordx4 v[244:245], v[118:121], off offset:512
	global_store_dwordx4 v[244:245], v[114:117], off offset:528
	v_cvt_pk_bf16_f32 v220, v118, v119
	v_cvt_pk_bf16_f32 v221, v120, v121
	v_cvt_pk_bf16_f32 v222, v114, v115
	v_cvt_pk_bf16_f32 v223, v116, v117
	v_mul_f32_e32 v238, v119, v119
	v_mul_f32_e32 v240, v115, v115
	v_fmac_f32_e32 v238, v118, v118
	v_mul_f32_e32 v239, v121, v121
	v_fmac_f32_e32 v240, v114, v114
	v_mul_f32_e32 v241, v117, v117
	v_fmac_f32_e32 v239, v120, v120
	v_fmac_f32_e32 v241, v116, v116
	global_store_dwordx4 v[246:247], v[220:223], off offset:256
	v_add_f32_e32 v238, v238, v239
	v_add_f32_e32 v240, v240, v241
	v_add_f32_e32 v238, v238, v240
	v_add_f32_e32 v237, v237, v238
	ds_bpermute_b32 v250, v235, v237
	s_mov_b32 s34, 0x30000
	v_lshl_add_u64 v[242:243], s[34:35], 0, v[178:179]
	global_load_dwordx4 v[118:121], v[242:243], off
	global_load_dwordx4 v[114:117], v[242:243], off offset:16
	s_waitcnt lgkmcnt(0)
	v_add_f32_e32 v237, v237, v250
	ds_bpermute_b32 v250, v236, v237
	s_waitcnt lgkmcnt(0)
	s_and_saveexec_b64 s[0:1], s[36:37]
	v_add_f32_e32 v237, v237, v250
	global_store_dword v[248:249], v237, off
	s_or_b64 exec, exec, s[0:1]
	s_waitcnt vmcnt(14)
	v_pk_add_f32 v[110:111], v[110:111], v[196:197]
	v_pk_add_f32 v[112:113], v[112:113], v[198:199]
	v_pk_add_f32 v[106:107], v[106:107], v[200:201]
	v_pk_add_f32 v[108:109], v[108:109], v[202:203]
	s_mov_b32 s34, 0x10000
	v_lshl_add_u64 v[244:245], s[34:35], 0, v[176:177]
	s_mov_b32 s34, 0x8000
	v_lshl_add_u64 v[246:247], s[34:35], 0, v[166:167]
	global_store_dwordx4 v[244:245], v[110:113], off
	global_store_dwordx4 v[244:245], v[106:109], off offset:16
	v_cvt_pk_bf16_f32 v172, v110, v111
	v_cvt_pk_bf16_f32 v173, v112, v113
	v_cvt_pk_bf16_f32 v174, v106, v107
	v_cvt_pk_bf16_f32 v175, v108, v109
	v_mul_f32_e32 v238, v111, v111
	v_mul_f32_e32 v240, v107, v107
	v_fmac_f32_e32 v238, v110, v110
	v_mul_f32_e32 v239, v113, v113
	v_fmac_f32_e32 v240, v106, v106
	v_mul_f32_e32 v241, v109, v109
	v_fmac_f32_e32 v239, v112, v112
	v_fmac_f32_e32 v241, v108, v108
	global_store_dwordx4 v[246:247], v[172:175], off
	v_add_f32_e32 v238, v238, v239
	v_add_f32_e32 v240, v240, v241
	v_add_f32_e32 v237, v238, v240
	global_load_dwordx4 v[110:113], v[242:243], off offset:512
	global_load_dwordx4 v[106:109], v[242:243], off offset:528
	s_waitcnt vmcnt(17)
; __device__ __forceinline__ unsigned pk2hw(float lo, float hi) { unsigned r; asm("s_nop 1\n\tv_cvt_pk_bf16_f32 %0, %1, %2" : "=v"(r) : "v"(lo), "v"(hi)); return r; }
;     __device__ __forceinline__ void operator()(const f32x4 (&acc)[2][2][4][2], const Unit& u, int wr, int wc, int fr, int fq) const {
;     ...
;         const int row0 = u.pm * 256 + wr * 64 + fr, col0 = u.pn * 256 + wc * 32 + 8 * fq;
; #pragma unroll
;         for (int ai = 0; ai < 2; ++ai)
; #pragma unroll
;             for (int m = 0; m < 4; ++m) { const int row = row0 + ai * 128 + m * 16; float sq = 0.f;
; #pragma unroll
;                 for (int bj = 0; bj < 2; ++bj) { const size_t off = (size_t)row * D + col0 + bj * 128;
;                     const f32x4 x0 = *(const f32x4*)(xin + off) + acc[ai][bj][m][0], x1 = *(const f32x4*)(xin + off + 4) + acc[ai][bj][m][1];
;                     *(f32x4*)(xout + off) = x0; *(f32x4*)(xout + off + 4) = x1;
;                     u32x4 w; w.x = pk2hw(x0[0], x0[1]); w.y = pk2hw(x0[2], x0[3]); w.z = pk2hw(x1[0], x1[1]); w.w = pk2hw(x1[2], x1[3]); *(u32x4*)(xb + off) = w;
;                     sq += ((x0[0] * x0[0] + x0[1] * x0[1]) + (x0[2] * x0[2] + x0[3] * x0[3])) + ((x1[0] * x1[0] + x1[1] * x1[1]) + (x1[2] * x1[2] + x1[3] * x1[3])); }
;                 sq += __shfl_xor(sq, 16); sq += __shfl_xor(sq, 32);
;                 if (fq == 0) ssn[(size_t)row * 16 + u.pn * 4 + wc] = sq; }
	v_pk_add_f32 v[102:103], v[102:103], v[204:205]
	v_pk_add_f32 v[104:105], v[104:105], v[206:207]
	v_pk_add_f32 v[98:99], v[98:99], v[208:209]
	v_pk_add_f32 v[100:101], v[100:101], v[210:211]
	global_store_dwordx4 v[244:245], v[102:105], off offset:512
	global_store_dwordx4 v[244:245], v[98:101], off offset:528
	v_cvt_pk_bf16_f32 v220, v102, v103
	v_cvt_pk_bf16_f32 v221, v104, v105
	v_cvt_pk_bf16_f32 v222, v98, v99
	v_cvt_pk_bf16_f32 v223, v100, v101
	v_mul_f32_e32 v238, v103, v103
	v_mul_f32_e32 v240, v99, v99
	v_fmac_f32_e32 v238, v102, v102
	v_mul_f32_e32 v239, v105, v105
	v_fmac_f32_e32 v240, v98, v98
	v_mul_f32_e32 v241, v101, v101
	v_fmac_f32_e32 v239, v104, v104
	v_fmac_f32_e32 v241, v100, v100
	global_store_dwordx4 v[246:247], v[220:223], off offset:256
	v_add_f32_e32 v238, v238, v239
	v_add_f32_e32 v240, v240, v241
	v_add_f32_e32 v238, v238, v240
	v_add_f32_e32 v237, v237, v238
	ds_bpermute_b32 v250, v235, v237
	s_mov_b32 s34, 0x80000
	v_lshl_add_u64 v[242:243], s[34:35], 0, v[178:179]
	global_load_dwordx4 v[102:105], v[242:243], off
	global_load_dwordx4 v[98:101], v[242:243], off offset:16
	s_waitcnt lgkmcnt(0)
	v_add_f32_e32 v237, v237, v250
	ds_bpermute_b32 v250, v236, v237
	s_waitcnt lgkmcnt(0)
	s_and_saveexec_b64 s[0:1], s[36:37]
	v_add_f32_e32 v237, v237, v250
	global_store_dword v[248:249], v237, off offset:1024
	s_or_b64 exec, exec, s[0:1]
	s_waitcnt vmcnt(20)
	v_pk_add_f32 v[94:95], v[94:95], v[212:213]
	v_pk_add_f32 v[96:97], v[96:97], v[214:215]
	v_pk_add_f32 v[90:91], v[90:91], v[216:217]
	v_pk_add_f32 v[92:93], v[92:93], v[218:219]
	s_mov_b32 s34, 0x20000
	v_lshl_add_u64 v[244:245], s[34:35], 0, v[176:177]
	s_mov_b32 s34, 0x10000
	v_lshl_add_u64 v[246:247], s[34:35], 0, v[166:167]
	global_store_dwordx4 v[244:245], v[94:97], off
	global_store_dwordx4 v[244:245], v[90:93], off offset:16
	v_cvt_pk_bf16_f32 v172, v94, v95
	v_cvt_pk_bf16_f32 v173, v96, v97
	v_cvt_pk_bf16_f32 v174, v90, v91
	v_cvt_pk_bf16_f32 v175, v92, v93
	v_mul_f32_e32 v238, v95, v95
	v_mul_f32_e32 v240, v91, v91
	v_fmac_f32_e32 v238, v94, v94
	v_mul_f32_e32 v239, v97, v97
	v_fmac_f32_e32 v240, v90, v90
	v_mul_f32_e32 v241, v93, v93
	v_fmac_f32_e32 v239, v96, v96
	v_fmac_f32_e32 v241, v92, v92
	global_store_dwordx4 v[246:247], v[172:175], off
	v_add_f32_e32 v238, v238, v239
	v_add_f32_e32 v240, v240, v241
	v_add_f32_e32 v237, v238, v240
	global_load_dwordx4 v[94:97], v[242:243], off offset:512
	global_load_dwordx4 v[90:93], v[242:243], off offset:528
	s_waitcnt vmcnt(20)
	v_pk_add_f32 v[86:87], v[86:87], v[126:127]
	v_pk_add_f32 v[88:89], v[88:89], v[128:129]
	v_pk_add_f32 v[82:83], v[82:83], v[122:123]
	v_pk_add_f32 v[84:85], v[84:85], v[124:125]
	global_store_dwordx4 v[244:245], v[86:89], off offset:512
	global_store_dwordx4 v[244:245], v[82:85], off offset:528
	v_cvt_pk_bf16_f32 v220, v86, v87
	v_cvt_pk_bf16_f32 v221, v88, v89
	v_cvt_pk_bf16_f32 v222, v82, v83
	v_cvt_pk_bf16_f32 v223, v84, v85
	v_mul_f32_e32 v238, v87, v87
	v_mul_f32_e32 v240, v83, v83
	v_fmac_f32_e32 v238, v86, v86
	v_mul_f32_e32 v239, v89, v89
	v_fmac_f32_e32 v240, v82, v82
	v_mul_f32_e32 v241, v85, v85
	v_fmac_f32_e32 v239, v88, v88
	v_fmac_f32_e32 v241, v84, v84
	global_store_dwordx4 v[246:247], v[220:223], off offset:256
	v_add_f32_e32 v238, v238, v239
	v_add_f32_e32 v240, v240, v241
	v_add_f32_e32 v238, v238, v240
	v_add_f32_e32 v237, v237, v238
	ds_bpermute_b32 v250, v235, v237
	s_mov_b32 s34, 0x90000
	v_lshl_add_u64 v[242:243], s[34:35], 0, v[178:179]
	global_load_dwordx4 v[86:89], v[242:243], off
	global_load_dwordx4 v[82:85], v[242:243], off offset:16
	s_waitcnt lgkmcnt(0)
	v_add_f32_e32 v237, v237, v250
	ds_bpermute_b32 v250, v236, v237
	s_waitcnt lgkmcnt(0)
	s_and_saveexec_b64 s[0:1], s[36:37]
	v_add_f32_e32 v237, v237, v250
	global_store_dword v[248:249], v237, off offset:2048
	s_or_b64 exec, exec, s[0:1]
	s_waitcnt vmcnt(20)
	v_pk_add_f32 v[78:79], v[78:79], v[118:119]
	v_pk_add_f32 v[80:81], v[80:81], v[120:121]
	v_pk_add_f32 v[74:75], v[74:75], v[114:115]
	v_pk_add_f32 v[76:77], v[76:77], v[116:117]
	s_mov_b32 s34, 0x30000
	v_lshl_add_u64 v[244:245], s[34:35], 0, v[176:177]
	s_mov_b32 s34, 0x18000
	v_lshl_add_u64 v[246:247], s[34:35], 0, v[166:167]
	global_store_dwordx4 v[244:245], v[78:81], off
	global_store_dwordx4 v[244:245], v[74:77], off offset:16
	v_cvt_pk_bf16_f32 v172, v78, v79
	v_cvt_pk_bf16_f32 v173, v80, v81
	v_cvt_pk_bf16_f32 v174, v74, v75
	v_cvt_pk_bf16_f32 v175, v76, v77
	v_mul_f32_e32 v238, v79, v79
	v_mul_f32_e32 v240, v75, v75
	v_fmac_f32_e32 v238, v78, v78
	v_mul_f32_e32 v239, v81, v81
	v_fmac_f32_e32 v240, v74, v74
	v_mul_f32_e32 v241, v77, v77
	v_fmac_f32_e32 v239, v80, v80
	v_fmac_f32_e32 v241, v76, v76
	global_store_dwordx4 v[246:247], v[172:175], off
	v_add_f32_e32 v238, v238, v239
	v_add_f32_e32 v240, v240, v241
	v_add_f32_e32 v237, v238, v240
	global_load_dwordx4 v[78:81], v[242:243], off offset:512
	global_load_dwordx4 v[74:77], v[242:243], off offset:528
	s_waitcnt vmcnt(20)
	v_pk_add_f32 v[70:71], v[70:71], v[110:111]
	v_pk_add_f32 v[72:73], v[72:73], v[112:113]
	v_pk_add_f32 v[66:67], v[66:67], v[106:107]
	v_pk_add_f32 v[68:69], v[68:69], v[108:109]
	global_store_dwordx4 v[244:245], v[70:73], off offset:512
	global_store_dwordx4 v[244:245], v[66:69], off offset:528
	v_cvt_pk_bf16_f32 v220, v70, v71
	v_cvt_pk_bf16_f32 v221, v72, v73
	v_cvt_pk_bf16_f32 v222, v66, v67
	v_cvt_pk_bf16_f32 v223, v68, v69
	v_mul_f32_e32 v238, v71, v71
	v_mul_f32_e32 v240, v67, v67
	v_fmac_f32_e32 v238, v70, v70
	v_mul_f32_e32 v239, v73, v73
	v_fmac_f32_e32 v240, v66, v66
	v_mul_f32_e32 v241, v69, v69
	v_fmac_f32_e32 v239, v72, v72
	v_fmac_f32_e32 v241, v68, v68
	global_store_dwordx4 v[246:247], v[220:223], off offset:256
	v_add_f32_e32 v238, v238, v239
	v_add_f32_e32 v240, v240, v241
	v_add_f32_e32 v238, v238, v240
	v_add_f32_e32 v237, v237, v238
	ds_bpermute_b32 v250, v235, v237
	s_mov_b32 s34, 0xa0000
	v_lshl_add_u64 v[242:243], s[34:35], 0, v[178:179]
	global_load_dwordx4 v[70:73], v[242:243], off
	global_load_dwordx4 v[66:69], v[242:243], off offset:16
	s_waitcnt lgkmcnt(0)
; __device__ __forceinline__ unsigned pk2hw(float lo, float hi) { unsigned r; asm("s_nop 1\n\tv_cvt_pk_bf16_f32 %0, %1, %2" : "=v"(r) : "v"(lo), "v"(hi)); return r; }
;     __device__ __forceinline__ void operator()(const f32x4 (&acc)[2][2][4][2], const Unit& u, int wr, int wc, int fr, int fq) const {
;     ...
;         const int row0 = u.pm * 256 + wr * 64 + fr, col0 = u.pn * 256 + wc * 32 + 8 * fq;
; #pragma unroll
;         for (int ai = 0; ai < 2; ++ai)
; #pragma unroll
;             for (int m = 0; m < 4; ++m) { const int row = row0 + ai * 128 + m * 16; float sq = 0.f;
; #pragma unroll
;                 for (int bj = 0; bj < 2; ++bj) { const size_t off = (size_t)row * D + col0 + bj * 128;
;                     const f32x4 x0 = *(const f32x4*)(xin + off) + acc[ai][bj][m][0], x1 = *(const f32x4*)(xin + off + 4) + acc[ai][bj][m][1];
;                     *(f32x4*)(xout + off) = x0; *(f32x4*)(xout + off + 4) = x1;
;                     u32x4 w; w.x = pk2hw(x0[0], x0[1]); w.y = pk2hw(x0[2], x0[3]); w.z = pk2hw(x1[0], x1[1]); w.w = pk2hw(x1[2], x1[3]); *(u32x4*)(xb + off) = w;
;                     sq += ((x0[0] * x0[0] + x0[1] * x0[1]) + (x0[2] * x0[2] + x0[3] * x0[3])) + ((x1[0] * x1[0] + x1[1] * x1[1]) + (x1[2] * x1[2] + x1[3] * x1[3])); }
;                 sq += __shfl_xor(sq, 16); sq += __shfl_xor(sq, 32);
;                 if (fq == 0) ssn[(size_t)row * 16 + u.pn * 4 + wc] = sq; }
	v_add_f32_e32 v237, v237, v250
	ds_bpermute_b32 v250, v236, v237
	s_waitcnt lgkmcnt(0)
	s_and_saveexec_b64 s[0:1], s[36:37]
	v_add_f32_e32 v237, v237, v250
	global_store_dword v[248:249], v237, off offset:3072
	s_or_b64 exec, exec, s[0:1]
	s_waitcnt vmcnt(20)
	v_pk_add_f32 v[62:63], v[62:63], v[102:103]
	v_pk_add_f32 v[64:65], v[64:65], v[104:105]
	v_pk_add_f32 v[58:59], v[58:59], v[98:99]
	v_pk_add_f32 v[60:61], v[60:61], v[100:101]
	s_mov_b32 s34, 0x80000
	v_lshl_add_u64 v[244:245], s[34:35], 0, v[176:177]
	s_mov_b32 s34, 0x40000
	v_lshl_add_u64 v[246:247], s[34:35], 0, v[166:167]
	global_store_dwordx4 v[244:245], v[62:65], off
	global_store_dwordx4 v[244:245], v[58:61], off offset:16
	v_cvt_pk_bf16_f32 v172, v62, v63
	v_cvt_pk_bf16_f32 v173, v64, v65
	v_cvt_pk_bf16_f32 v174, v58, v59
	v_cvt_pk_bf16_f32 v175, v60, v61
	v_mul_f32_e32 v238, v63, v63
	v_mul_f32_e32 v240, v59, v59
	v_fmac_f32_e32 v238, v62, v62
	v_mul_f32_e32 v239, v65, v65
	v_fmac_f32_e32 v240, v58, v58
	v_mul_f32_e32 v241, v61, v61
	v_fmac_f32_e32 v239, v64, v64
	v_fmac_f32_e32 v241, v60, v60
	global_store_dwordx4 v[246:247], v[172:175], off
	v_add_f32_e32 v238, v238, v239
	v_add_f32_e32 v240, v240, v241
	v_add_f32_e32 v237, v238, v240
	global_load_dwordx4 v[62:65], v[242:243], off offset:512
	global_load_dwordx4 v[58:61], v[242:243], off offset:528
	s_waitcnt vmcnt(20)
	v_pk_add_f32 v[54:55], v[54:55], v[94:95]
	v_pk_add_f32 v[56:57], v[56:57], v[96:97]
	v_pk_add_f32 v[50:51], v[50:51], v[90:91]
	v_pk_add_f32 v[52:53], v[52:53], v[92:93]
	global_store_dwordx4 v[244:245], v[54:57], off offset:512
	global_store_dwordx4 v[244:245], v[50:53], off offset:528
	v_cvt_pk_bf16_f32 v220, v54, v55
	v_cvt_pk_bf16_f32 v221, v56, v57
	v_cvt_pk_bf16_f32 v222, v50, v51
	v_cvt_pk_bf16_f32 v223, v52, v53
	v_mul_f32_e32 v238, v55, v55
	v_mul_f32_e32 v240, v51, v51
	v_fmac_f32_e32 v238, v54, v54
	v_mul_f32_e32 v239, v57, v57
	v_fmac_f32_e32 v240, v50, v50
	v_mul_f32_e32 v241, v53, v53
	v_fmac_f32_e32 v239, v56, v56
	v_fmac_f32_e32 v241, v52, v52
	global_store_dwordx4 v[246:247], v[220:223], off offset:256
	v_add_f32_e32 v238, v238, v239
	v_add_f32_e32 v240, v240, v241
	v_add_f32_e32 v238, v238, v240
	v_add_f32_e32 v237, v237, v238
	ds_bpermute_b32 v250, v235, v237
	s_mov_b32 s34, 0xb0000
	v_lshl_add_u64 v[242:243], s[34:35], 0, v[178:179]
	global_load_dwordx4 v[54:57], v[242:243], off
	global_load_dwordx4 v[50:53], v[242:243], off offset:16
	s_waitcnt lgkmcnt(0)
	v_add_f32_e32 v237, v237, v250
	ds_bpermute_b32 v250, v236, v237
	s_waitcnt lgkmcnt(0)
	s_and_saveexec_b64 s[0:1], s[36:37]
	v_add_f32_e32 v237, v237, v250
	global_store_dword v[144:145], v237, off
	s_or_b64 exec, exec, s[0:1]
	s_waitcnt vmcnt(20)
	v_pk_add_f32 v[46:47], v[46:47], v[86:87]
	v_pk_add_f32 v[48:49], v[48:49], v[88:89]
	v_pk_add_f32 v[42:43], v[42:43], v[82:83]
	v_pk_add_f32 v[44:45], v[44:45], v[84:85]
	s_mov_b32 s34, 0x90000
	v_lshl_add_u64 v[244:245], s[34:35], 0, v[176:177]
	s_mov_b32 s34, 0x48000
	v_lshl_add_u64 v[246:247], s[34:35], 0, v[166:167]
	global_store_dwordx4 v[244:245], v[46:49], off
	global_store_dwordx4 v[244:245], v[42:45], off offset:16
	v_cvt_pk_bf16_f32 v172, v46, v47
	v_cvt_pk_bf16_f32 v173, v48, v49
	v_cvt_pk_bf16_f32 v174, v42, v43
	v_cvt_pk_bf16_f32 v175, v44, v45
	v_mul_f32_e32 v238, v47, v47
	v_mul_f32_e32 v240, v43, v43
	v_fmac_f32_e32 v238, v46, v46
	v_mul_f32_e32 v239, v49, v49
	v_fmac_f32_e32 v240, v42, v42
	v_mul_f32_e32 v241, v45, v45
	v_fmac_f32_e32 v239, v48, v48
	v_fmac_f32_e32 v241, v44, v44
	global_store_dwordx4 v[246:247], v[172:175], off
	v_add_f32_e32 v238, v238, v239
	v_add_f32_e32 v240, v240, v241
	v_add_f32_e32 v237, v238, v240
	global_load_dwordx4 v[46:49], v[242:243], off offset:512
	global_load_dwordx4 v[42:45], v[242:243], off offset:528
	s_waitcnt vmcnt(20)
	v_pk_add_f32 v[38:39], v[38:39], v[78:79]
	v_pk_add_f32 v[40:41], v[40:41], v[80:81]
	v_pk_add_f32 v[34:35], v[34:35], v[74:75]
	v_pk_add_f32 v[36:37], v[36:37], v[76:77]
	global_store_dwordx4 v[244:245], v[38:41], off offset:512
	global_store_dwordx4 v[244:245], v[34:37], off offset:528
	v_cvt_pk_bf16_f32 v220, v38, v39
	v_cvt_pk_bf16_f32 v221, v40, v41
	v_cvt_pk_bf16_f32 v222, v34, v35
	v_cvt_pk_bf16_f32 v223, v36, v37
	v_mul_f32_e32 v238, v39, v39
	v_mul_f32_e32 v240, v35, v35
	v_fmac_f32_e32 v238, v38, v38
	v_mul_f32_e32 v239, v41, v41
	v_fmac_f32_e32 v240, v34, v34
	v_mul_f32_e32 v241, v37, v37
	v_fmac_f32_e32 v239, v40, v40
	v_fmac_f32_e32 v241, v36, v36
	global_store_dwordx4 v[246:247], v[220:223], off offset:256
	v_add_f32_e32 v238, v238, v239
	v_add_f32_e32 v240, v240, v241
	v_add_f32_e32 v238, v238, v240
	v_add_f32_e32 v237, v237, v238
	ds_bpermute_b32 v250, v235, v237
	s_waitcnt lgkmcnt(0)
; #define PG8_BAR __builtin_amdgcn_s_barrier()
; __device__ __forceinline__ unsigned pk2hw(float lo, float hi) { unsigned r; asm("s_nop 1\n\tv_cvt_pk_bf16_f32 %0, %1, %2" : "=v"(r) : "v"(lo), "v"(hi)); return r; }
; template <class Epi, class Sched, bool ALIGN_EPI = false, bool SP2 = false>
; __device__ __forceinline__ void gemm_phase(PG8_LAS unsigned char* lds, const Gemm g, const Sched& S, const Epi& E) {
;     ...
;         if constexpr (ALIGN_EPI) { if (wr == 0) PG8_BAR; }
;         if constexpr (!Epi::AFTER_DRAIN) { E(acc, cur, wr, wc, fr, fq); S.done(cur); }
;         if (!has_next) break;
; #pragma unroll
;         for (int a = 0; a < 2; ++a)
; #pragma unroll
;             for (int b = 0; b < 2; ++b)
; #pragma unroll
;                 for (int m = 0; m < 4; ++m)
; #pragma unroll
;                     for (int n = 0; n < 2; ++n) acc[a][b][m][n] = (f32x4){0.f, 0.f, 0.f, 0.f};
;         cur = nxt; cA = nA; cB = nB; ++ui;
;         if constexpr (ALIGN_EPI) { if (wr == 1) PG8_BAR; }
;     __device__ __forceinline__ void operator()(const f32x4 (&acc)[2][2][4][2], const Unit& u, int wr, int wc, int fr, int fq) const {
;     ...
;         const int row0 = u.pm * 256 + wr * 64 + fr, col0 = u.pn * 256 + wc * 32 + 8 * fq;
; #pragma unroll
;         for (int ai = 0; ai < 2; ++ai)
; #pragma unroll
;             for (int m = 0; m < 4; ++m) { const int row = row0 + ai * 128 + m * 16; float sq = 0.f;
; #pragma unroll
;                 for (int bj = 0; bj < 2; ++bj) { const size_t off = (size_t)row * D + col0 + bj * 128;
;                     const f32x4 x0 = *(const f32x4*)(xin + off) + acc[ai][bj][m][0], x1 = *(const f32x4*)(xin + off + 4) + acc[ai][bj][m][1];
;                     *(f32x4*)(xout + off) = x0; *(f32x4*)(xout + off + 4) = x1;
;                     u32x4 w; w.x = pk2hw(x0[0], x0[1]); w.y = pk2hw(x0[2], x0[3]); w.z = pk2hw(x1[0], x1[1]); w.w = pk2hw(x1[2], x1[3]); *(u32x4*)(xb + off) = w;
;                     sq += ((x0[0] * x0[0] + x0[1] * x0[1]) + (x0[2] * x0[2] + x0[3] * x0[3])) + ((x1[0] * x1[0] + x1[1] * x1[1]) + (x1[2] * x1[2] + x1[3] * x1[3])); }
;                 sq += __shfl_xor(sq, 16); sq += __shfl_xor(sq, 32);
;                 if (fq == 0) ssn[(size_t)row * 16 + u.pn * 4 + wc] = sq; }
	v_add_f32_e32 v237, v237, v250
	ds_bpermute_b32 v250, v236, v237
	s_waitcnt lgkmcnt(0)
	s_and_saveexec_b64 s[0:1], s[36:37]
	v_add_f32_e32 v237, v237, v250
	global_store_dword v[144:145], v237, off offset:1024
	s_or_b64 exec, exec, s[0:1]
	s_waitcnt vmcnt(18)
	v_pk_add_f32 v[30:31], v[30:31], v[70:71]
	v_pk_add_f32 v[32:33], v[32:33], v[72:73]
	v_pk_add_f32 v[26:27], v[26:27], v[66:67]
	v_pk_add_f32 v[28:29], v[28:29], v[68:69]
	s_mov_b32 s34, 0xa0000
	v_lshl_add_u64 v[244:245], s[34:35], 0, v[176:177]
	s_mov_b32 s34, 0x50000
	v_lshl_add_u64 v[246:247], s[34:35], 0, v[166:167]
	global_store_dwordx4 v[244:245], v[30:33], off
	global_store_dwordx4 v[244:245], v[26:29], off offset:16
	v_cvt_pk_bf16_f32 v172, v30, v31
	v_cvt_pk_bf16_f32 v173, v32, v33
	v_cvt_pk_bf16_f32 v174, v26, v27
	v_cvt_pk_bf16_f32 v175, v28, v29
	v_mul_f32_e32 v238, v31, v31
	v_mul_f32_e32 v240, v27, v27
	v_fmac_f32_e32 v238, v30, v30
	v_mul_f32_e32 v239, v33, v33
	v_fmac_f32_e32 v240, v26, v26
	v_mul_f32_e32 v241, v29, v29
	v_fmac_f32_e32 v239, v32, v32
	v_fmac_f32_e32 v241, v28, v28
	global_store_dwordx4 v[246:247], v[172:175], off
	v_add_f32_e32 v238, v238, v239
	v_add_f32_e32 v240, v240, v241
	v_add_f32_e32 v237, v238, v240
	s_waitcnt vmcnt(16)
	v_pk_add_f32 v[22:23], v[22:23], v[62:63]
	v_pk_add_f32 v[24:25], v[24:25], v[64:65]
	v_pk_add_f32 v[18:19], v[18:19], v[58:59]
	v_pk_add_f32 v[20:21], v[20:21], v[60:61]
	global_store_dwordx4 v[244:245], v[22:25], off offset:512
	global_store_dwordx4 v[244:245], v[18:21], off offset:528
	v_cvt_pk_bf16_f32 v220, v22, v23
	v_cvt_pk_bf16_f32 v221, v24, v25
	v_cvt_pk_bf16_f32 v222, v18, v19
	v_cvt_pk_bf16_f32 v223, v20, v21
	v_mul_f32_e32 v238, v23, v23
	v_mul_f32_e32 v240, v19, v19
	v_fmac_f32_e32 v238, v22, v22
	v_mul_f32_e32 v239, v25, v25
	v_fmac_f32_e32 v240, v18, v18
	v_mul_f32_e32 v241, v21, v21
	v_fmac_f32_e32 v239, v24, v24
	v_fmac_f32_e32 v241, v20, v20
	global_store_dwordx4 v[246:247], v[220:223], off offset:256
	v_add_f32_e32 v238, v238, v239
	v_add_f32_e32 v240, v240, v241
	v_add_f32_e32 v238, v238, v240
	v_add_f32_e32 v237, v237, v238
	ds_bpermute_b32 v250, v235, v237
	s_waitcnt lgkmcnt(0)
	v_add_f32_e32 v237, v237, v250
	ds_bpermute_b32 v250, v236, v237
	s_waitcnt lgkmcnt(0)
	s_and_saveexec_b64 s[0:1], s[36:37]
	v_add_f32_e32 v237, v237, v250
	global_store_dword v[144:145], v237, off offset:2048
	s_or_b64 exec, exec, s[0:1]
	s_waitcnt vmcnt(14)
	v_pk_add_f32 v[14:15], v[14:15], v[54:55]
	v_pk_add_f32 v[16:17], v[16:17], v[56:57]
	v_pk_add_f32 v[10:11], v[10:11], v[50:51]
	v_pk_add_f32 v[12:13], v[12:13], v[52:53]
	s_mov_b32 s34, 0xb0000
	v_lshl_add_u64 v[244:245], s[34:35], 0, v[176:177]
	s_mov_b32 s34, 0x58000
	v_lshl_add_u64 v[246:247], s[34:35], 0, v[166:167]
	global_store_dwordx4 v[244:245], v[14:17], off
	global_store_dwordx4 v[244:245], v[10:13], off offset:16
	v_cvt_pk_bf16_f32 v172, v14, v15
	v_cvt_pk_bf16_f32 v173, v16, v17
	v_cvt_pk_bf16_f32 v174, v10, v11
	v_cvt_pk_bf16_f32 v175, v12, v13
	v_mul_f32_e32 v238, v15, v15
	v_mul_f32_e32 v240, v11, v11
	v_fmac_f32_e32 v238, v14, v14
	v_mul_f32_e32 v239, v17, v17
	v_fmac_f32_e32 v240, v10, v10
	v_mul_f32_e32 v241, v13, v13
	v_fmac_f32_e32 v239, v16, v16
	v_fmac_f32_e32 v241, v12, v12
	global_store_dwordx4 v[246:247], v[172:175], off
	v_add_f32_e32 v238, v238, v239
	v_add_f32_e32 v240, v240, v241
	v_add_f32_e32 v237, v238, v240
	s_waitcnt vmcnt(12)
	v_pk_add_f32 v[6:7], v[6:7], v[46:47]
	v_pk_add_f32 v[8:9], v[8:9], v[48:49]
	v_pk_add_f32 v[2:3], v[2:3], v[42:43]
	v_pk_add_f32 v[4:5], v[4:5], v[44:45]
	global_store_dwordx4 v[244:245], v[6:9], off offset:512
	global_store_dwordx4 v[244:245], v[2:5], off offset:528
	v_cvt_pk_bf16_f32 v220, v6, v7
	v_cvt_pk_bf16_f32 v221, v8, v9
	v_cvt_pk_bf16_f32 v222, v2, v3
	v_cvt_pk_bf16_f32 v223, v4, v5
	v_mul_f32_e32 v238, v7, v7
	v_mul_f32_e32 v240, v3, v3
	v_fmac_f32_e32 v238, v6, v6
	v_mul_f32_e32 v239, v9, v9
	v_fmac_f32_e32 v240, v2, v2
	v_mul_f32_e32 v241, v5, v5
	v_fmac_f32_e32 v239, v8, v8
	v_fmac_f32_e32 v241, v4, v4
	global_store_dwordx4 v[246:247], v[220:223], off offset:256
	v_add_f32_e32 v238, v238, v239
	v_add_f32_e32 v240, v240, v241
	v_add_f32_e32 v238, v238, v240
	v_add_f32_e32 v237, v237, v238
	ds_bpermute_b32 v250, v235, v237
	s_waitcnt lgkmcnt(0)
	v_add_f32_e32 v237, v237, v250
	ds_bpermute_b32 v250, v236, v237
	s_waitcnt lgkmcnt(0)
	s_and_saveexec_b64 s[0:1], s[36:37]
	v_add_f32_e32 v237, v237, v250
	global_store_dword v[144:145], v237, off offset:3072
	s_or_b64 exec, exec, s[0:1]
	s_andn2_b64 vcc, exec, s[6:7]
	s_mov_b64 s[0:1], -1
	s_cbranch_vccnz .LBB0_938
	s_andn2_b64 vcc, exec, s[10:11]
	s_cbranch_vccnz .LBB0_937
	s_barrier
	s_branch .LBB0_937
